# streaming hints: x row loads in P1/P6/P11 and the final out stores marked non-temporal (single-use data), keeps L2/MALL for y0/y1/H
# speedup vs baseline: 1.0140x; 1.0107x over previous
; __device__ __forceinline__ unsigned cvt_pk_bf16(float lo, float hi) { unsigned r; asm volatile("v_cvt_pk_bf16_f32 %0, %1, %2" : "=v"(r) : "v"(lo), "v"(hi)); return r; }
; __device__ __forceinline__ void modulate_store(const f32x4 (&v)[8], float rstd, const float* pn, const float* modr, bf16_t* orow, int lane) {
; #pragma unroll
;     for (int j = 0; j < 8; ++j) { const int col = 4 * lane + 256 * j;
;         const f32x4 g = *(const f32x4*)(pn + col), sh = *(const f32x4*)(modr + col), sc = *(const f32x4*)(modr + DM + col);
;         const f32x4 hh = v[j] * rstd * g * (sc + 1.f) + sh;
;         u32x2 w; w.x = cvt_pk_bf16(hh[0], hh[1]); w.y = cvt_pk_bf16(hh[2], hh[3]);
;         *(u32x2*)(orow + col) = w; }
; __global__ void __launch_bounds__(NWAVES * 64, 2) mk_fwd(Args args) {
;     ...
;         for (int row0 = F.gw * 3; row0 < MT; row0 += F.NGW * 3) {
;             f32x4 v[3][8];
; #pragma unroll
;             for (int q = 0; q < 3; ++q) { const int row = row0 + q; const float* src = row < ML ? x + (size_t)row * DM : ctx + (size_t)(row - ML) * DM; load_row_f32(src, F.lane, v[q]); }
; #pragma unroll
;             for (int q = 0; q < 3; ++q) { const int row = row0 + q; const int r = row < ML ? row / SEQ : 8;
;                 const float rstd = __builtin_amdgcn_rsqf(sumsq8(v[q]) * (1.f / DM) + EPS);
;                 modulate_store(v[q], rstd, pre_norm, mod + (size_t)r * 6144, H + (size_t)row * DM, F.lane); }
.LBB0_184:
	s_cmp_lt_i32 s86, 2
	s_cselect_b64 s[0:1], -1, 0
	s_add_u32 s12, s84, 0x4000000
	s_addc_u32 s13, s85, 0
	s_and_b64 s[4:5], s[0:1], s[4:5]
	s_andn2_b64 vcc, exec, s[4:5]
	s_cbranch_vccnz .LBB0_194
	s_cmpk_lg_i32 s63, 0x100
	s_cbranch_scc1 .Lp1_generic
	v_and_b32_e32 v130, 63, v198
	v_lshlrev_b32_e32 v128, 4, v130
	v_add_u32_e32 v129, 0x1000, v128
	v_lshlrev_b32_e32 v130, 3, v130
	v_mov_b32_e32 v131, 0x358637bd
	s_mul_i32 s6, s33, 9
	s_mov_b32 s7, -1
	s_add_i32 s4, s6, 0
	s_cmp_lt_u32 s4, 0x4000
	s_cselect_b32 s10, s68, s72
	s_cselect_b32 s11, s69, s73
	s_cselect_b32 s5, 0, 0x4000
	s_sub_i32 s5, s4, s5
	s_lshl_b32 s5, s5, 13
	s_add_u32 s10, s10, s5
	s_addc_u32 s11, s11, 0
	global_load_dwordx4 v[0:3], v128, s[10:11] offset:0 nt
	global_load_dwordx4 v[4:7], v128, s[10:11] offset:1024 nt
	global_load_dwordx4 v[8:11], v128, s[10:11] offset:2048 nt
	global_load_dwordx4 v[12:15], v128, s[10:11] offset:3072 nt
	global_load_dwordx4 v[16:19], v129, s[10:11] offset:0 nt
	global_load_dwordx4 v[20:23], v129, s[10:11] offset:1024 nt
	global_load_dwordx4 v[24:27], v129, s[10:11] offset:2048 nt
	global_load_dwordx4 v[28:31], v129, s[10:11] offset:3072 nt
	s_add_i32 s4, s6, 0
	s_add_i32 s4, s6, 0
	s_lshr_b32 s8, s4, 11
	s_cmp_lt_u32 s4, 0x4000
	s_cselect_b32 s8, s8, 8
	s_cmp_eq_u32 s8, s7
	s_cbranch_scc1 .Lp1_np0
	s_mov_b32 s7, s8
	s_add_i32 s5, s8, 0
	s_mul_i32 s5, s5, 0x6000
	s_add_u32 s24, s84, s5
	s_addc_u32 s25, s85, 0
	s_add_u32 s24, s24, 0x2000
	s_addc_u32 s25, s25, 0
	s_add_i32 s5, s8, 0
	s_mul_i32 s5, s5, 0x6000
	s_add_u32 s16, s84, s5
	s_addc_u32 s17, s85, 0
	s_add_u32 s18, s80, 0x0
	s_addc_u32 s19, s81, 0
	global_load_dwordx4 v[64:67], v128, s[18:19] offset:0
	global_load_dwordx4 v[96:99], v128, s[16:17] offset:0
	global_load_dwordx4 v[68:71], v128, s[18:19] offset:1024
	global_load_dwordx4 v[100:103], v128, s[16:17] offset:1024
	global_load_dwordx4 v[72:75], v128, s[18:19] offset:2048
	global_load_dwordx4 v[104:107], v128, s[16:17] offset:2048
	global_load_dwordx4 v[76:79], v128, s[18:19] offset:3072
	global_load_dwordx4 v[108:111], v128, s[16:17] offset:3072
	global_load_dwordx4 v[80:83], v129, s[18:19] offset:0
	global_load_dwordx4 v[112:115], v129, s[16:17] offset:0
	global_load_dwordx4 v[84:87], v129, s[18:19] offset:1024
	global_load_dwordx4 v[116:119], v129, s[16:17] offset:1024
	global_load_dwordx4 v[88:91], v129, s[18:19] offset:2048
	global_load_dwordx4 v[120:123], v129, s[16:17] offset:2048
	global_load_dwordx4 v[92:95], v129, s[18:19] offset:3072
	global_load_dwordx4 v[124:127], v129, s[16:17] offset:3072
	global_load_dwordx4 v[32:35], v128, s[24:25] offset:0
	global_load_dwordx4 v[36:39], v128, s[24:25] offset:1024
	global_load_dwordx4 v[40:43], v128, s[24:25] offset:2048
	global_load_dwordx4 v[44:47], v128, s[24:25] offset:3072
	global_load_dwordx4 v[48:51], v129, s[24:25] offset:0
	global_load_dwordx4 v[52:55], v129, s[24:25] offset:1024
	global_load_dwordx4 v[56:59], v129, s[24:25] offset:2048
	global_load_dwordx4 v[60:63], v129, s[24:25] offset:3072
	s_waitcnt vmcnt(0)
	v_add_f32_e32 v32, 1.0, v32
	v_add_f32_e32 v33, 1.0, v33
	v_add_f32_e32 v34, 1.0, v34
	v_add_f32_e32 v35, 1.0, v35
	v_add_f32_e32 v36, 1.0, v36
	v_add_f32_e32 v37, 1.0, v37
	v_add_f32_e32 v38, 1.0, v38
	v_add_f32_e32 v39, 1.0, v39
	v_add_f32_e32 v40, 1.0, v40
	v_add_f32_e32 v41, 1.0, v41
	v_add_f32_e32 v42, 1.0, v42
	v_add_f32_e32 v43, 1.0, v43
	v_add_f32_e32 v44, 1.0, v44
	v_add_f32_e32 v45, 1.0, v45
	v_add_f32_e32 v46, 1.0, v46
	v_add_f32_e32 v47, 1.0, v47
	v_add_f32_e32 v48, 1.0, v48
	v_add_f32_e32 v49, 1.0, v49
	v_add_f32_e32 v50, 1.0, v50
	v_add_f32_e32 v51, 1.0, v51
	v_add_f32_e32 v52, 1.0, v52
	v_add_f32_e32 v53, 1.0, v53
	v_add_f32_e32 v54, 1.0, v54
	v_add_f32_e32 v55, 1.0, v55
	v_add_f32_e32 v56, 1.0, v56
	v_add_f32_e32 v57, 1.0, v57
	v_add_f32_e32 v58, 1.0, v58
	v_add_f32_e32 v59, 1.0, v59
	v_add_f32_e32 v60, 1.0, v60
	v_add_f32_e32 v61, 1.0, v61
	v_add_f32_e32 v62, 1.0, v62
	v_add_f32_e32 v63, 1.0, v63
	v_mul_f32_e32 v64, v64, v32
	v_mul_f32_e32 v65, v65, v33
	v_mul_f32_e32 v66, v66, v34
	v_mul_f32_e32 v67, v67, v35
	v_mul_f32_e32 v68, v68, v36
	v_mul_f32_e32 v69, v69, v37
	v_mul_f32_e32 v70, v70, v38
	v_mul_f32_e32 v71, v71, v39
	v_mul_f32_e32 v72, v72, v40
	v_mul_f32_e32 v73, v73, v41
	v_mul_f32_e32 v74, v74, v42
	v_mul_f32_e32 v75, v75, v43
	v_mul_f32_e32 v76, v76, v44
	v_mul_f32_e32 v77, v77, v45
	v_mul_f32_e32 v78, v78, v46
	v_mul_f32_e32 v79, v79, v47
	v_mul_f32_e32 v80, v80, v48
	v_mul_f32_e32 v81, v81, v49
	v_mul_f32_e32 v82, v82, v50
	v_mul_f32_e32 v83, v83, v51
	v_mul_f32_e32 v84, v84, v52
	v_mul_f32_e32 v85, v85, v53
	v_mul_f32_e32 v86, v86, v54
	v_mul_f32_e32 v87, v87, v55
	v_mul_f32_e32 v88, v88, v56
	v_mul_f32_e32 v89, v89, v57
	v_mul_f32_e32 v90, v90, v58
	v_mul_f32_e32 v91, v91, v59
	v_mul_f32_e32 v92, v92, v60
	v_mul_f32_e32 v93, v93, v61
	v_mul_f32_e32 v94, v94, v62
	v_mul_f32_e32 v95, v95, v63
; __device__ __forceinline__ unsigned cvt_pk_bf16(float lo, float hi) { unsigned r; asm volatile("v_cvt_pk_bf16_f32 %0, %1, %2" : "=v"(r) : "v"(lo), "v"(hi)); return r; }
; __device__ __forceinline__ void load_row_f32(const float* p, int lane, f32x4 (&v)[8]) {
; #pragma unroll
;     for (int j = 0; j < 8; ++j) v[j] = *(const f32x4*)(p + 4 * lane + 256 * j);
; }
; __device__ __forceinline__ float sumsq8(const f32x4 (&v)[8]) {
;     float s = 0.f;
; #pragma unroll
;     for (int j = 0; j < 8; ++j) s += (v[j][0] * v[j][0] + v[j][1] * v[j][1]) + (v[j][2] * v[j][2] + v[j][3] * v[j][3]);
;     return wave_sum(s);
; }
; __device__ __forceinline__ void modulate_store(const f32x4 (&v)[8], float rstd, const float* pn, const float* modr, bf16_t* orow, int lane) {
; #pragma unroll
;     for (int j = 0; j < 8; ++j) { const int col = 4 * lane + 256 * j;
;         const f32x4 g = *(const f32x4*)(pn + col), sh = *(const f32x4*)(modr + col), sc = *(const f32x4*)(modr + DM + col);
;         const f32x4 hh = v[j] * rstd * g * (sc + 1.f) + sh;
;         u32x2 w; w.x = cvt_pk_bf16(hh[0], hh[1]); w.y = cvt_pk_bf16(hh[2], hh[3]);
;         *(u32x2*)(orow + col) = w; }
; __global__ void __launch_bounds__(NWAVES * 64, 2) mk_fwd(Args args) {
;     ...
;             for (int q = 0; q < 3; ++q) { const int row = row0 + q; const float* src = row < ML ? x + (size_t)row * DM : ctx + (size_t)(row - ML) * DM; load_row_f32(src, F.lane, v[q]); }
; #pragma unroll
;             for (int q = 0; q < 3; ++q) { const int row = row0 + q; const int r = row < ML ? row / SEQ : 8;
;                 const float rstd = __builtin_amdgcn_rsqf(sumsq8(v[q]) * (1.f / DM) + EPS);
;                 modulate_store(v[q], rstd, pre_norm, mod + (size_t)r * 6144, H + (size_t)row * DM, F.lane); }
.Lp1_np0:
	s_add_i32 s4, s6, 1
	s_cmp_lt_u32 s4, 0x4000
	s_cselect_b32 s10, s68, s72
	s_cselect_b32 s11, s69, s73
	s_cselect_b32 s5, 0, 0x4000
	s_sub_i32 s5, s4, s5
	s_lshl_b32 s5, s5, 13
	s_add_u32 s10, s10, s5
	s_addc_u32 s11, s11, 0
	global_load_dwordx4 v[32:35], v128, s[10:11] offset:0 nt
	global_load_dwordx4 v[36:39], v128, s[10:11] offset:1024 nt
	global_load_dwordx4 v[40:43], v128, s[10:11] offset:2048 nt
	global_load_dwordx4 v[44:47], v128, s[10:11] offset:3072 nt
	global_load_dwordx4 v[48:51], v129, s[10:11] offset:0 nt
	global_load_dwordx4 v[52:55], v129, s[10:11] offset:1024 nt
	global_load_dwordx4 v[56:59], v129, s[10:11] offset:2048 nt
	global_load_dwordx4 v[60:63], v129, s[10:11] offset:3072 nt
	s_waitcnt vmcnt(8)
	v_mul_f32_e32 v140, v0, v0
	v_mul_f32_e32 v141, v1, v1
	v_fmac_f32_e32 v140, v2, v2
	v_fmac_f32_e32 v141, v3, v3
	v_fmac_f32_e32 v140, v4, v4
	v_fmac_f32_e32 v141, v5, v5
	v_fmac_f32_e32 v140, v6, v6
	v_fmac_f32_e32 v141, v7, v7
	v_fmac_f32_e32 v140, v8, v8
	v_fmac_f32_e32 v141, v9, v9
	v_fmac_f32_e32 v140, v10, v10
	v_fmac_f32_e32 v141, v11, v11
	v_fmac_f32_e32 v140, v12, v12
	v_fmac_f32_e32 v141, v13, v13
	v_fmac_f32_e32 v140, v14, v14
	v_fmac_f32_e32 v141, v15, v15
	v_fmac_f32_e32 v140, v16, v16
	v_fmac_f32_e32 v141, v17, v17
	v_fmac_f32_e32 v140, v18, v18
	v_fmac_f32_e32 v141, v19, v19
	v_fmac_f32_e32 v140, v20, v20
	v_fmac_f32_e32 v141, v21, v21
	v_fmac_f32_e32 v140, v22, v22
	v_fmac_f32_e32 v141, v23, v23
	v_fmac_f32_e32 v140, v24, v24
	v_fmac_f32_e32 v141, v25, v25
	v_fmac_f32_e32 v140, v26, v26
	v_fmac_f32_e32 v141, v27, v27
	v_fmac_f32_e32 v140, v28, v28
	v_fmac_f32_e32 v141, v29, v29
	v_fmac_f32_e32 v140, v30, v30
	v_fmac_f32_e32 v141, v31, v31
	v_add_f32_e32 v140, v140, v141
	s_nop 1
	v_add_f32_dpp v142, v140, v140 quad_perm:[1,0,3,2] row_mask:0xf bank_mask:0xf
	s_nop 1
	v_add_f32_dpp v142, v142, v142 quad_perm:[2,3,0,1] row_mask:0xf bank_mask:0xf
	s_nop 1
	v_add_f32_dpp v142, v142, v142 row_half_mirror row_mask:0xf bank_mask:0xf
	s_nop 1
	v_add_f32_dpp v142, v142, v142 row_mirror row_mask:0xf bank_mask:0xf
	s_nop 1
	v_readlane_b32 s20, v142, 0
	v_readlane_b32 s21, v142, 16
	v_readlane_b32 s22, v142, 32
	v_readlane_b32 s23, v142, 48
	s_nop 1
	v_mov_b32_e32 v143, s20
	v_add_f32_e32 v143, s21, v143
	v_add_f32_e32 v143, s22, v143
	v_add_f32_e32 v143, s23, v143
	v_fmamk_f32 v143, v143, 0x3a000000, v131
	v_rsq_f32_e32 v143, v143
	s_nop 0
	s_add_i32 s4, s6, 0
	s_lshl_b32 s5, s4, 12
	s_add_u32 s14, s84, s5
	s_addc_u32 s15, s85, 0
	s_add_u32 s14, s14, 0x4000000
	s_addc_u32 s15, s15, 0
	v_mul_f32_e32 v136, v143, v0
	v_mul_f32_e32 v137, v143, v1
	v_mul_f32_e32 v138, v143, v2
	v_mul_f32_e32 v139, v143, v3
	v_fma_f32 v136, v136, v64, v96
	v_fma_f32 v137, v137, v65, v97
	v_fma_f32 v138, v138, v66, v98
	v_fma_f32 v139, v139, v67, v99
	v_cvt_pk_bf16_f32 v132, v136, v137
	v_cvt_pk_bf16_f32 v133, v138, v139
	global_store_dwordx2 v130, v[132:133], s[14:15] offset:0
	v_mul_f32_e32 v136, v143, v4
	v_mul_f32_e32 v137, v143, v5
	v_mul_f32_e32 v138, v143, v6
	v_mul_f32_e32 v139, v143, v7
	v_fma_f32 v136, v136, v68, v100
	v_fma_f32 v137, v137, v69, v101
	v_fma_f32 v138, v138, v70, v102
	v_fma_f32 v139, v139, v71, v103
	v_cvt_pk_bf16_f32 v134, v136, v137
	v_cvt_pk_bf16_f32 v135, v138, v139
	global_store_dwordx2 v130, v[134:135], s[14:15] offset:512
	v_mul_f32_e32 v136, v143, v8
	v_mul_f32_e32 v137, v143, v9
	v_mul_f32_e32 v138, v143, v10
	v_mul_f32_e32 v139, v143, v11
	v_fma_f32 v136, v136, v72, v104
	v_fma_f32 v137, v137, v73, v105
	v_fma_f32 v138, v138, v74, v106
	v_fma_f32 v139, v139, v75, v107
	v_cvt_pk_bf16_f32 v132, v136, v137
	v_cvt_pk_bf16_f32 v133, v138, v139
	global_store_dwordx2 v130, v[132:133], s[14:15] offset:1024
	v_mul_f32_e32 v136, v143, v12
	v_mul_f32_e32 v137, v143, v13
	v_mul_f32_e32 v138, v143, v14
	v_mul_f32_e32 v139, v143, v15
	v_fma_f32 v136, v136, v76, v108
	v_fma_f32 v137, v137, v77, v109
	v_fma_f32 v138, v138, v78, v110
	v_fma_f32 v139, v139, v79, v111
	v_cvt_pk_bf16_f32 v134, v136, v137
	v_cvt_pk_bf16_f32 v135, v138, v139
	global_store_dwordx2 v130, v[134:135], s[14:15] offset:1536
	v_mul_f32_e32 v136, v143, v16
	v_mul_f32_e32 v137, v143, v17
	v_mul_f32_e32 v138, v143, v18
	v_mul_f32_e32 v139, v143, v19
	v_fma_f32 v136, v136, v80, v112
	v_fma_f32 v137, v137, v81, v113
	v_fma_f32 v138, v138, v82, v114
	v_fma_f32 v139, v139, v83, v115
	v_cvt_pk_bf16_f32 v132, v136, v137
	v_cvt_pk_bf16_f32 v133, v138, v139
	global_store_dwordx2 v130, v[132:133], s[14:15] offset:2048
	v_mul_f32_e32 v136, v143, v20
	v_mul_f32_e32 v137, v143, v21
	v_mul_f32_e32 v138, v143, v22
	v_mul_f32_e32 v139, v143, v23
	v_fma_f32 v136, v136, v84, v116
	v_fma_f32 v137, v137, v85, v117
	v_fma_f32 v138, v138, v86, v118
	v_fma_f32 v139, v139, v87, v119
	v_cvt_pk_bf16_f32 v134, v136, v137
	v_cvt_pk_bf16_f32 v135, v138, v139
	global_store_dwordx2 v130, v[134:135], s[14:15] offset:2560
	v_mul_f32_e32 v136, v143, v24
	v_mul_f32_e32 v137, v143, v25
	v_mul_f32_e32 v138, v143, v26
	v_mul_f32_e32 v139, v143, v27
	v_fma_f32 v136, v136, v88, v120
	v_fma_f32 v137, v137, v89, v121
	v_fma_f32 v138, v138, v90, v122
	v_fma_f32 v139, v139, v91, v123
	v_cvt_pk_bf16_f32 v132, v136, v137
	v_cvt_pk_bf16_f32 v133, v138, v139
	global_store_dwordx2 v130, v[132:133], s[14:15] offset:3072
	v_mul_f32_e32 v136, v143, v28
	v_mul_f32_e32 v137, v143, v29
	v_mul_f32_e32 v138, v143, v30
	v_mul_f32_e32 v139, v143, v31
	v_fma_f32 v136, v136, v92, v124
	v_fma_f32 v137, v137, v93, v125
	v_fma_f32 v138, v138, v94, v126
	v_fma_f32 v139, v139, v95, v127
	v_cvt_pk_bf16_f32 v134, v136, v137
	v_cvt_pk_bf16_f32 v135, v138, v139
	global_store_dwordx2 v130, v[134:135], s[14:15] offset:3584
	s_add_i32 s4, s6, 2
	s_cmp_lt_u32 s4, 0x4000
	s_cselect_b32 s10, s68, s72
	s_cselect_b32 s11, s69, s73
	s_cselect_b32 s5, 0, 0x4000
	s_sub_i32 s5, s4, s5
	s_lshl_b32 s5, s5, 13
	s_add_u32 s10, s10, s5
	s_addc_u32 s11, s11, 0
	global_load_dwordx4 v[0:3], v128, s[10:11] offset:0 nt
	global_load_dwordx4 v[4:7], v128, s[10:11] offset:1024 nt
	global_load_dwordx4 v[8:11], v128, s[10:11] offset:2048 nt
	global_load_dwordx4 v[12:15], v128, s[10:11] offset:3072 nt
	global_load_dwordx4 v[16:19], v129, s[10:11] offset:0 nt
	global_load_dwordx4 v[20:23], v129, s[10:11] offset:1024 nt
	global_load_dwordx4 v[24:27], v129, s[10:11] offset:2048 nt
	global_load_dwordx4 v[28:31], v129, s[10:11] offset:3072 nt
	s_add_i32 s4, s6, 1
	s_add_i32 s4, s6, 1
	s_lshr_b32 s8, s4, 11
	s_cmp_lt_u32 s4, 0x4000
	s_cselect_b32 s8, s8, 8
	s_cmp_eq_u32 s8, s7
	s_cbranch_scc1 .Lp1_np1
; __device__ __forceinline__ unsigned cvt_pk_bf16(float lo, float hi) { unsigned r; asm volatile("v_cvt_pk_bf16_f32 %0, %1, %2" : "=v"(r) : "v"(lo), "v"(hi)); return r; }
; __device__ __forceinline__ void modulate_store(const f32x4 (&v)[8], float rstd, const float* pn, const float* modr, bf16_t* orow, int lane) {
; #pragma unroll
;     for (int j = 0; j < 8; ++j) { const int col = 4 * lane + 256 * j;
;         const f32x4 g = *(const f32x4*)(pn + col), sh = *(const f32x4*)(modr + col), sc = *(const f32x4*)(modr + DM + col);
;         const f32x4 hh = v[j] * rstd * g * (sc + 1.f) + sh;
;         u32x2 w; w.x = cvt_pk_bf16(hh[0], hh[1]); w.y = cvt_pk_bf16(hh[2], hh[3]);
;         *(u32x2*)(orow + col) = w; }
; __global__ void __launch_bounds__(NWAVES * 64, 2) mk_fwd(Args args) {
;     ...
;             for (int q = 0; q < 3; ++q) { const int row = row0 + q; const int r = row < ML ? row / SEQ : 8;
;                 const float rstd = __builtin_amdgcn_rsqf(sumsq8(v[q]) * (1.f / DM) + EPS);
;                 modulate_store(v[q], rstd, pre_norm, mod + (size_t)r * 6144, H + (size_t)row * DM, F.lane); }
	s_mov_b32 s7, s8
	s_add_i32 s5, s8, 0
	s_mul_i32 s5, s5, 0x6000
	s_add_u32 s24, s84, s5
	s_addc_u32 s25, s85, 0
	s_add_u32 s24, s24, 0x2000
	s_addc_u32 s25, s25, 0
	s_add_i32 s5, s8, 0
	s_mul_i32 s5, s5, 0x6000
	s_add_u32 s16, s84, s5
	s_addc_u32 s17, s85, 0
	s_add_u32 s18, s80, 0x0
	s_addc_u32 s19, s81, 0
	global_load_dwordx4 v[64:67], v128, s[18:19] offset:0
	global_load_dwordx4 v[96:99], v128, s[16:17] offset:0
	global_load_dwordx4 v[68:71], v128, s[18:19] offset:1024
	global_load_dwordx4 v[100:103], v128, s[16:17] offset:1024
	global_load_dwordx4 v[72:75], v128, s[18:19] offset:2048
	global_load_dwordx4 v[104:107], v128, s[16:17] offset:2048
	global_load_dwordx4 v[76:79], v128, s[18:19] offset:3072
	global_load_dwordx4 v[108:111], v128, s[16:17] offset:3072
	global_load_dwordx4 v[80:83], v129, s[18:19] offset:0
	global_load_dwordx4 v[112:115], v129, s[16:17] offset:0
	global_load_dwordx4 v[84:87], v129, s[18:19] offset:1024
	global_load_dwordx4 v[116:119], v129, s[16:17] offset:1024
	global_load_dwordx4 v[88:91], v129, s[18:19] offset:2048
	global_load_dwordx4 v[120:123], v129, s[16:17] offset:2048
	global_load_dwordx4 v[92:95], v129, s[18:19] offset:3072
	global_load_dwordx4 v[124:127], v129, s[16:17] offset:3072
	global_load_dwordx4 v[136:139], v128, s[24:25] offset:0
	s_waitcnt vmcnt(0)
	v_add_f32_e32 v136, 1.0, v136
	v_add_f32_e32 v137, 1.0, v137
	v_add_f32_e32 v138, 1.0, v138
	v_add_f32_e32 v139, 1.0, v139
	v_mul_f32_e32 v64, v64, v136
	v_mul_f32_e32 v65, v65, v137
	v_mul_f32_e32 v66, v66, v138
	v_mul_f32_e32 v67, v67, v139
	global_load_dwordx4 v[136:139], v128, s[24:25] offset:1024
	s_waitcnt vmcnt(0)
	v_add_f32_e32 v136, 1.0, v136
	v_add_f32_e32 v137, 1.0, v137
	v_add_f32_e32 v138, 1.0, v138
	v_add_f32_e32 v139, 1.0, v139
	v_mul_f32_e32 v68, v68, v136
	v_mul_f32_e32 v69, v69, v137
	v_mul_f32_e32 v70, v70, v138
	v_mul_f32_e32 v71, v71, v139
	global_load_dwordx4 v[136:139], v128, s[24:25] offset:2048
	s_waitcnt vmcnt(0)
	v_add_f32_e32 v136, 1.0, v136
	v_add_f32_e32 v137, 1.0, v137
	v_add_f32_e32 v138, 1.0, v138
	v_add_f32_e32 v139, 1.0, v139
	v_mul_f32_e32 v72, v72, v136
	v_mul_f32_e32 v73, v73, v137
	v_mul_f32_e32 v74, v74, v138
	v_mul_f32_e32 v75, v75, v139
	global_load_dwordx4 v[136:139], v128, s[24:25] offset:3072
	s_waitcnt vmcnt(0)
	v_add_f32_e32 v136, 1.0, v136
	v_add_f32_e32 v137, 1.0, v137
	v_add_f32_e32 v138, 1.0, v138
	v_add_f32_e32 v139, 1.0, v139
	v_mul_f32_e32 v76, v76, v136
	v_mul_f32_e32 v77, v77, v137
	v_mul_f32_e32 v78, v78, v138
	v_mul_f32_e32 v79, v79, v139
	global_load_dwordx4 v[136:139], v129, s[24:25] offset:0
	s_waitcnt vmcnt(0)
	v_add_f32_e32 v136, 1.0, v136
	v_add_f32_e32 v137, 1.0, v137
	v_add_f32_e32 v138, 1.0, v138
	v_add_f32_e32 v139, 1.0, v139
	v_mul_f32_e32 v80, v80, v136
	v_mul_f32_e32 v81, v81, v137
	v_mul_f32_e32 v82, v82, v138
	v_mul_f32_e32 v83, v83, v139
	global_load_dwordx4 v[136:139], v129, s[24:25] offset:1024
	s_waitcnt vmcnt(0)
	v_add_f32_e32 v136, 1.0, v136
	v_add_f32_e32 v137, 1.0, v137
	v_add_f32_e32 v138, 1.0, v138
	v_add_f32_e32 v139, 1.0, v139
	v_mul_f32_e32 v84, v84, v136
	v_mul_f32_e32 v85, v85, v137
	v_mul_f32_e32 v86, v86, v138
	v_mul_f32_e32 v87, v87, v139
	global_load_dwordx4 v[136:139], v129, s[24:25] offset:2048
	s_waitcnt vmcnt(0)
	v_add_f32_e32 v136, 1.0, v136
	v_add_f32_e32 v137, 1.0, v137
	v_add_f32_e32 v138, 1.0, v138
	v_add_f32_e32 v139, 1.0, v139
	v_mul_f32_e32 v88, v88, v136
	v_mul_f32_e32 v89, v89, v137
	v_mul_f32_e32 v90, v90, v138
	v_mul_f32_e32 v91, v91, v139
	global_load_dwordx4 v[136:139], v129, s[24:25] offset:3072
	s_waitcnt vmcnt(0)
	v_add_f32_e32 v136, 1.0, v136
	v_add_f32_e32 v137, 1.0, v137
	v_add_f32_e32 v138, 1.0, v138
	v_add_f32_e32 v139, 1.0, v139
	v_mul_f32_e32 v92, v92, v136
	v_mul_f32_e32 v93, v93, v137
	v_mul_f32_e32 v94, v94, v138
	v_mul_f32_e32 v95, v95, v139
.Lp1_np1:
	s_waitcnt vmcnt(16)
	v_mul_f32_e32 v140, v32, v32
	v_mul_f32_e32 v141, v33, v33
	v_fmac_f32_e32 v140, v34, v34
	v_fmac_f32_e32 v141, v35, v35
	v_fmac_f32_e32 v140, v36, v36
	v_fmac_f32_e32 v141, v37, v37
	v_fmac_f32_e32 v140, v38, v38
	v_fmac_f32_e32 v141, v39, v39
	v_fmac_f32_e32 v140, v40, v40
	v_fmac_f32_e32 v141, v41, v41
	v_fmac_f32_e32 v140, v42, v42
	v_fmac_f32_e32 v141, v43, v43
	v_fmac_f32_e32 v140, v44, v44
	v_fmac_f32_e32 v141, v45, v45
	v_fmac_f32_e32 v140, v46, v46
	v_fmac_f32_e32 v141, v47, v47
	v_fmac_f32_e32 v140, v48, v48
	v_fmac_f32_e32 v141, v49, v49
	v_fmac_f32_e32 v140, v50, v50
	v_fmac_f32_e32 v141, v51, v51
	v_fmac_f32_e32 v140, v52, v52
	v_fmac_f32_e32 v141, v53, v53
	v_fmac_f32_e32 v140, v54, v54
	v_fmac_f32_e32 v141, v55, v55
	v_fmac_f32_e32 v140, v56, v56
	v_fmac_f32_e32 v141, v57, v57
	v_fmac_f32_e32 v140, v58, v58
	v_fmac_f32_e32 v141, v59, v59
	v_fmac_f32_e32 v140, v60, v60
	v_fmac_f32_e32 v141, v61, v61
	v_fmac_f32_e32 v140, v62, v62
	v_fmac_f32_e32 v141, v63, v63
	v_add_f32_e32 v140, v140, v141
	s_nop 1
	v_add_f32_dpp v142, v140, v140 quad_perm:[1,0,3,2] row_mask:0xf bank_mask:0xf
	s_nop 1
	v_add_f32_dpp v142, v142, v142 quad_perm:[2,3,0,1] row_mask:0xf bank_mask:0xf
	s_nop 1
	v_add_f32_dpp v142, v142, v142 row_half_mirror row_mask:0xf bank_mask:0xf
	s_nop 1
	v_add_f32_dpp v142, v142, v142 row_mirror row_mask:0xf bank_mask:0xf
	s_nop 1
	v_readlane_b32 s20, v142, 0
	v_readlane_b32 s21, v142, 16
	v_readlane_b32 s22, v142, 32
	v_readlane_b32 s23, v142, 48
	s_nop 1
	v_mov_b32_e32 v143, s20
	v_add_f32_e32 v143, s21, v143
	v_add_f32_e32 v143, s22, v143
	v_add_f32_e32 v143, s23, v143
	v_fmamk_f32 v143, v143, 0x3a000000, v131
	v_rsq_f32_e32 v143, v143
	s_nop 0
	s_add_i32 s4, s6, 1
	s_lshl_b32 s5, s4, 12
	s_add_u32 s14, s84, s5
	s_addc_u32 s15, s85, 0
; __device__ __forceinline__ unsigned cvt_pk_bf16(float lo, float hi) { unsigned r; asm volatile("v_cvt_pk_bf16_f32 %0, %1, %2" : "=v"(r) : "v"(lo), "v"(hi)); return r; }
; __device__ __forceinline__ void modulate_store(const f32x4 (&v)[8], float rstd, const float* pn, const float* modr, bf16_t* orow, int lane) {
; #pragma unroll
;     for (int j = 0; j < 8; ++j) { const int col = 4 * lane + 256 * j;
;         const f32x4 g = *(const f32x4*)(pn + col), sh = *(const f32x4*)(modr + col), sc = *(const f32x4*)(modr + DM + col);
;         const f32x4 hh = v[j] * rstd * g * (sc + 1.f) + sh;
;         u32x2 w; w.x = cvt_pk_bf16(hh[0], hh[1]); w.y = cvt_pk_bf16(hh[2], hh[3]);
;         *(u32x2*)(orow + col) = w; }
; __global__ void __launch_bounds__(NWAVES * 64, 2) mk_fwd(Args args) {
;     ...
;             for (int q = 0; q < 3; ++q) { const int row = row0 + q; const float* src = row < ML ? x + (size_t)row * DM : ctx + (size_t)(row - ML) * DM; load_row_f32(src, F.lane, v[q]); }
; #pragma unroll
;             for (int q = 0; q < 3; ++q) { const int row = row0 + q; const int r = row < ML ? row / SEQ : 8;
;                 const float rstd = __builtin_amdgcn_rsqf(sumsq8(v[q]) * (1.f / DM) + EPS);
;                 modulate_store(v[q], rstd, pre_norm, mod + (size_t)r * 6144, H + (size_t)row * DM, F.lane); }
	s_add_u32 s14, s14, 0x4000000
	s_addc_u32 s15, s15, 0
	v_mul_f32_e32 v136, v143, v32
	v_mul_f32_e32 v137, v143, v33
	v_mul_f32_e32 v138, v143, v34
	v_mul_f32_e32 v139, v143, v35
	v_fma_f32 v136, v136, v64, v96
	v_fma_f32 v137, v137, v65, v97
	v_fma_f32 v138, v138, v66, v98
	v_fma_f32 v139, v139, v67, v99
	v_cvt_pk_bf16_f32 v132, v136, v137
	v_cvt_pk_bf16_f32 v133, v138, v139
	global_store_dwordx2 v130, v[132:133], s[14:15] offset:0
	v_mul_f32_e32 v136, v143, v36
	v_mul_f32_e32 v137, v143, v37
	v_mul_f32_e32 v138, v143, v38
	v_mul_f32_e32 v139, v143, v39
	v_fma_f32 v136, v136, v68, v100
	v_fma_f32 v137, v137, v69, v101
	v_fma_f32 v138, v138, v70, v102
	v_fma_f32 v139, v139, v71, v103
	v_cvt_pk_bf16_f32 v134, v136, v137
	v_cvt_pk_bf16_f32 v135, v138, v139
	global_store_dwordx2 v130, v[134:135], s[14:15] offset:512
	v_mul_f32_e32 v136, v143, v40
	v_mul_f32_e32 v137, v143, v41
	v_mul_f32_e32 v138, v143, v42
	v_mul_f32_e32 v139, v143, v43
	v_fma_f32 v136, v136, v72, v104
	v_fma_f32 v137, v137, v73, v105
	v_fma_f32 v138, v138, v74, v106
	v_fma_f32 v139, v139, v75, v107
	v_cvt_pk_bf16_f32 v132, v136, v137
	v_cvt_pk_bf16_f32 v133, v138, v139
	global_store_dwordx2 v130, v[132:133], s[14:15] offset:1024
	v_mul_f32_e32 v136, v143, v44
	v_mul_f32_e32 v137, v143, v45
	v_mul_f32_e32 v138, v143, v46
	v_mul_f32_e32 v139, v143, v47
	v_fma_f32 v136, v136, v76, v108
	v_fma_f32 v137, v137, v77, v109
	v_fma_f32 v138, v138, v78, v110
	v_fma_f32 v139, v139, v79, v111
	v_cvt_pk_bf16_f32 v134, v136, v137
	v_cvt_pk_bf16_f32 v135, v138, v139
	global_store_dwordx2 v130, v[134:135], s[14:15] offset:1536
	v_mul_f32_e32 v136, v143, v48
	v_mul_f32_e32 v137, v143, v49
	v_mul_f32_e32 v138, v143, v50
	v_mul_f32_e32 v139, v143, v51
	v_fma_f32 v136, v136, v80, v112
	v_fma_f32 v137, v137, v81, v113
	v_fma_f32 v138, v138, v82, v114
	v_fma_f32 v139, v139, v83, v115
	v_cvt_pk_bf16_f32 v132, v136, v137
	v_cvt_pk_bf16_f32 v133, v138, v139
	global_store_dwordx2 v130, v[132:133], s[14:15] offset:2048
	v_mul_f32_e32 v136, v143, v52
	v_mul_f32_e32 v137, v143, v53
	v_mul_f32_e32 v138, v143, v54
	v_mul_f32_e32 v139, v143, v55
	v_fma_f32 v136, v136, v84, v116
	v_fma_f32 v137, v137, v85, v117
	v_fma_f32 v138, v138, v86, v118
	v_fma_f32 v139, v139, v87, v119
	v_cvt_pk_bf16_f32 v134, v136, v137
	v_cvt_pk_bf16_f32 v135, v138, v139
	global_store_dwordx2 v130, v[134:135], s[14:15] offset:2560
	v_mul_f32_e32 v136, v143, v56
	v_mul_f32_e32 v137, v143, v57
	v_mul_f32_e32 v138, v143, v58
	v_mul_f32_e32 v139, v143, v59
	v_fma_f32 v136, v136, v88, v120
	v_fma_f32 v137, v137, v89, v121
	v_fma_f32 v138, v138, v90, v122
	v_fma_f32 v139, v139, v91, v123
	v_cvt_pk_bf16_f32 v132, v136, v137
	v_cvt_pk_bf16_f32 v133, v138, v139
	global_store_dwordx2 v130, v[132:133], s[14:15] offset:3072
	v_mul_f32_e32 v136, v143, v60
	v_mul_f32_e32 v137, v143, v61
	v_mul_f32_e32 v138, v143, v62
	v_mul_f32_e32 v139, v143, v63
	v_fma_f32 v136, v136, v92, v124
	v_fma_f32 v137, v137, v93, v125
	v_fma_f32 v138, v138, v94, v126
	v_fma_f32 v139, v139, v95, v127
	v_cvt_pk_bf16_f32 v134, v136, v137
	v_cvt_pk_bf16_f32 v135, v138, v139
	global_store_dwordx2 v130, v[134:135], s[14:15] offset:3584
	s_add_i32 s4, s6, 3
	s_cmp_lt_u32 s4, 0x4000
	s_cselect_b32 s10, s68, s72
	s_cselect_b32 s11, s69, s73
	s_cselect_b32 s5, 0, 0x4000
	s_sub_i32 s5, s4, s5
	s_lshl_b32 s5, s5, 13
	s_add_u32 s10, s10, s5
	s_addc_u32 s11, s11, 0
	global_load_dwordx4 v[32:35], v128, s[10:11] offset:0 nt
	global_load_dwordx4 v[36:39], v128, s[10:11] offset:1024 nt
	global_load_dwordx4 v[40:43], v128, s[10:11] offset:2048 nt
	global_load_dwordx4 v[44:47], v128, s[10:11] offset:3072 nt
	global_load_dwordx4 v[48:51], v129, s[10:11] offset:0 nt
	global_load_dwordx4 v[52:55], v129, s[10:11] offset:1024 nt
	global_load_dwordx4 v[56:59], v129, s[10:11] offset:2048 nt
	global_load_dwordx4 v[60:63], v129, s[10:11] offset:3072 nt
	s_add_i32 s4, s6, 2
	s_add_i32 s4, s6, 2
	s_lshr_b32 s8, s4, 11
	s_cmp_lt_u32 s4, 0x4000
	s_cselect_b32 s8, s8, 8
	s_cmp_eq_u32 s8, s7
	s_cbranch_scc1 .Lp1_np2
	s_mov_b32 s7, s8
	s_add_i32 s5, s8, 0
	s_mul_i32 s5, s5, 0x6000
	s_add_u32 s24, s84, s5
	s_addc_u32 s25, s85, 0
	s_add_u32 s24, s24, 0x2000
	s_addc_u32 s25, s25, 0
	s_add_i32 s5, s8, 0
	s_mul_i32 s5, s5, 0x6000
	s_add_u32 s16, s84, s5
	s_addc_u32 s17, s85, 0
	s_add_u32 s18, s80, 0x0
	s_addc_u32 s19, s81, 0
	global_load_dwordx4 v[64:67], v128, s[18:19] offset:0
	global_load_dwordx4 v[96:99], v128, s[16:17] offset:0
	global_load_dwordx4 v[68:71], v128, s[18:19] offset:1024
	global_load_dwordx4 v[100:103], v128, s[16:17] offset:1024
	global_load_dwordx4 v[72:75], v128, s[18:19] offset:2048
	global_load_dwordx4 v[104:107], v128, s[16:17] offset:2048
	global_load_dwordx4 v[76:79], v128, s[18:19] offset:3072
	global_load_dwordx4 v[108:111], v128, s[16:17] offset:3072
	global_load_dwordx4 v[80:83], v129, s[18:19] offset:0
	global_load_dwordx4 v[112:115], v129, s[16:17] offset:0
	global_load_dwordx4 v[84:87], v129, s[18:19] offset:1024
	global_load_dwordx4 v[116:119], v129, s[16:17] offset:1024
	global_load_dwordx4 v[88:91], v129, s[18:19] offset:2048
	global_load_dwordx4 v[120:123], v129, s[16:17] offset:2048
	global_load_dwordx4 v[92:95], v129, s[18:19] offset:3072
	global_load_dwordx4 v[124:127], v129, s[16:17] offset:3072
	global_load_dwordx4 v[136:139], v128, s[24:25] offset:0
	s_waitcnt vmcnt(0)
	v_add_f32_e32 v136, 1.0, v136
	v_add_f32_e32 v137, 1.0, v137
	v_add_f32_e32 v138, 1.0, v138
	v_add_f32_e32 v139, 1.0, v139
	v_mul_f32_e32 v64, v64, v136
	v_mul_f32_e32 v65, v65, v137
	v_mul_f32_e32 v66, v66, v138
	v_mul_f32_e32 v67, v67, v139
	global_load_dwordx4 v[136:139], v128, s[24:25] offset:1024
	s_waitcnt vmcnt(0)
; __device__ __forceinline__ unsigned cvt_pk_bf16(float lo, float hi) { unsigned r; asm volatile("v_cvt_pk_bf16_f32 %0, %1, %2" : "=v"(r) : "v"(lo), "v"(hi)); return r; }
; __device__ __forceinline__ void load_row_f32(const float* p, int lane, f32x4 (&v)[8]) {
; #pragma unroll
;     for (int j = 0; j < 8; ++j) v[j] = *(const f32x4*)(p + 4 * lane + 256 * j);
; }
; __device__ __forceinline__ float sumsq8(const f32x4 (&v)[8]) {
;     float s = 0.f;
; #pragma unroll
;     for (int j = 0; j < 8; ++j) s += (v[j][0] * v[j][0] + v[j][1] * v[j][1]) + (v[j][2] * v[j][2] + v[j][3] * v[j][3]);
;     return wave_sum(s);
; }
; __device__ __forceinline__ void modulate_store(const f32x4 (&v)[8], float rstd, const float* pn, const float* modr, bf16_t* orow, int lane) {
; #pragma unroll
;     for (int j = 0; j < 8; ++j) { const int col = 4 * lane + 256 * j;
;         const f32x4 g = *(const f32x4*)(pn + col), sh = *(const f32x4*)(modr + col), sc = *(const f32x4*)(modr + DM + col);
;         const f32x4 hh = v[j] * rstd * g * (sc + 1.f) + sh;
;         u32x2 w; w.x = cvt_pk_bf16(hh[0], hh[1]); w.y = cvt_pk_bf16(hh[2], hh[3]);
;         *(u32x2*)(orow + col) = w; }
; __global__ void __launch_bounds__(NWAVES * 64, 2) mk_fwd(Args args) {
;     ...
;             for (int q = 0; q < 3; ++q) { const int row = row0 + q; const int r = row < ML ? row / SEQ : 8;
;                 const float rstd = __builtin_amdgcn_rsqf(sumsq8(v[q]) * (1.f / DM) + EPS);
;                 modulate_store(v[q], rstd, pre_norm, mod + (size_t)r * 6144, H + (size_t)row * DM, F.lane); }
	v_add_f32_e32 v136, 1.0, v136
	v_add_f32_e32 v137, 1.0, v137
	v_add_f32_e32 v138, 1.0, v138
	v_add_f32_e32 v139, 1.0, v139
	v_mul_f32_e32 v68, v68, v136
	v_mul_f32_e32 v69, v69, v137
	v_mul_f32_e32 v70, v70, v138
	v_mul_f32_e32 v71, v71, v139
	global_load_dwordx4 v[136:139], v128, s[24:25] offset:2048
	s_waitcnt vmcnt(0)
	v_add_f32_e32 v136, 1.0, v136
	v_add_f32_e32 v137, 1.0, v137
	v_add_f32_e32 v138, 1.0, v138
	v_add_f32_e32 v139, 1.0, v139
	v_mul_f32_e32 v72, v72, v136
	v_mul_f32_e32 v73, v73, v137
	v_mul_f32_e32 v74, v74, v138
	v_mul_f32_e32 v75, v75, v139
	global_load_dwordx4 v[136:139], v128, s[24:25] offset:3072
	s_waitcnt vmcnt(0)
	v_add_f32_e32 v136, 1.0, v136
	v_add_f32_e32 v137, 1.0, v137
	v_add_f32_e32 v138, 1.0, v138
	v_add_f32_e32 v139, 1.0, v139
	v_mul_f32_e32 v76, v76, v136
	v_mul_f32_e32 v77, v77, v137
	v_mul_f32_e32 v78, v78, v138
	v_mul_f32_e32 v79, v79, v139
	global_load_dwordx4 v[136:139], v129, s[24:25] offset:0
	s_waitcnt vmcnt(0)
	v_add_f32_e32 v136, 1.0, v136
	v_add_f32_e32 v137, 1.0, v137
	v_add_f32_e32 v138, 1.0, v138
	v_add_f32_e32 v139, 1.0, v139
	v_mul_f32_e32 v80, v80, v136
	v_mul_f32_e32 v81, v81, v137
	v_mul_f32_e32 v82, v82, v138
	v_mul_f32_e32 v83, v83, v139
	global_load_dwordx4 v[136:139], v129, s[24:25] offset:1024
	s_waitcnt vmcnt(0)
	v_add_f32_e32 v136, 1.0, v136
	v_add_f32_e32 v137, 1.0, v137
	v_add_f32_e32 v138, 1.0, v138
	v_add_f32_e32 v139, 1.0, v139
	v_mul_f32_e32 v84, v84, v136
	v_mul_f32_e32 v85, v85, v137
	v_mul_f32_e32 v86, v86, v138
	v_mul_f32_e32 v87, v87, v139
	global_load_dwordx4 v[136:139], v129, s[24:25] offset:2048
	s_waitcnt vmcnt(0)
	v_add_f32_e32 v136, 1.0, v136
	v_add_f32_e32 v137, 1.0, v137
	v_add_f32_e32 v138, 1.0, v138
	v_add_f32_e32 v139, 1.0, v139
	v_mul_f32_e32 v88, v88, v136
	v_mul_f32_e32 v89, v89, v137
	v_mul_f32_e32 v90, v90, v138
	v_mul_f32_e32 v91, v91, v139
	global_load_dwordx4 v[136:139], v129, s[24:25] offset:3072
	s_waitcnt vmcnt(0)
	v_add_f32_e32 v136, 1.0, v136
	v_add_f32_e32 v137, 1.0, v137
	v_add_f32_e32 v138, 1.0, v138
	v_add_f32_e32 v139, 1.0, v139
	v_mul_f32_e32 v92, v92, v136
	v_mul_f32_e32 v93, v93, v137
	v_mul_f32_e32 v94, v94, v138
	v_mul_f32_e32 v95, v95, v139
.Lp1_np2:
	s_waitcnt vmcnt(16)
	v_mul_f32_e32 v140, v0, v0
	v_mul_f32_e32 v141, v1, v1
	v_fmac_f32_e32 v140, v2, v2
	v_fmac_f32_e32 v141, v3, v3
	v_fmac_f32_e32 v140, v4, v4
	v_fmac_f32_e32 v141, v5, v5
	v_fmac_f32_e32 v140, v6, v6
	v_fmac_f32_e32 v141, v7, v7
	v_fmac_f32_e32 v140, v8, v8
	v_fmac_f32_e32 v141, v9, v9
	v_fmac_f32_e32 v140, v10, v10
	v_fmac_f32_e32 v141, v11, v11
	v_fmac_f32_e32 v140, v12, v12
	v_fmac_f32_e32 v141, v13, v13
	v_fmac_f32_e32 v140, v14, v14
	v_fmac_f32_e32 v141, v15, v15
	v_fmac_f32_e32 v140, v16, v16
	v_fmac_f32_e32 v141, v17, v17
	v_fmac_f32_e32 v140, v18, v18
	v_fmac_f32_e32 v141, v19, v19
	v_fmac_f32_e32 v140, v20, v20
	v_fmac_f32_e32 v141, v21, v21
	v_fmac_f32_e32 v140, v22, v22
	v_fmac_f32_e32 v141, v23, v23
	v_fmac_f32_e32 v140, v24, v24
	v_fmac_f32_e32 v141, v25, v25
	v_fmac_f32_e32 v140, v26, v26
	v_fmac_f32_e32 v141, v27, v27
	v_fmac_f32_e32 v140, v28, v28
	v_fmac_f32_e32 v141, v29, v29
	v_fmac_f32_e32 v140, v30, v30
	v_fmac_f32_e32 v141, v31, v31
	v_add_f32_e32 v140, v140, v141
	s_nop 1
	v_add_f32_dpp v142, v140, v140 quad_perm:[1,0,3,2] row_mask:0xf bank_mask:0xf
	s_nop 1
	v_add_f32_dpp v142, v142, v142 quad_perm:[2,3,0,1] row_mask:0xf bank_mask:0xf
	s_nop 1
	v_add_f32_dpp v142, v142, v142 row_half_mirror row_mask:0xf bank_mask:0xf
	s_nop 1
	v_add_f32_dpp v142, v142, v142 row_mirror row_mask:0xf bank_mask:0xf
	s_nop 1
	v_readlane_b32 s20, v142, 0
	v_readlane_b32 s21, v142, 16
	v_readlane_b32 s22, v142, 32
	v_readlane_b32 s23, v142, 48
	s_nop 1
	v_mov_b32_e32 v143, s20
	v_add_f32_e32 v143, s21, v143
	v_add_f32_e32 v143, s22, v143
	v_add_f32_e32 v143, s23, v143
	v_fmamk_f32 v143, v143, 0x3a000000, v131
	v_rsq_f32_e32 v143, v143
	s_nop 0
	s_add_i32 s4, s6, 2
	s_lshl_b32 s5, s4, 12
	s_add_u32 s14, s84, s5
	s_addc_u32 s15, s85, 0
	s_add_u32 s14, s14, 0x4000000
	s_addc_u32 s15, s15, 0
	v_mul_f32_e32 v136, v143, v0
	v_mul_f32_e32 v137, v143, v1
	v_mul_f32_e32 v138, v143, v2
	v_mul_f32_e32 v139, v143, v3
	v_fma_f32 v136, v136, v64, v96
	v_fma_f32 v137, v137, v65, v97
	v_fma_f32 v138, v138, v66, v98
	v_fma_f32 v139, v139, v67, v99
	v_cvt_pk_bf16_f32 v132, v136, v137
	v_cvt_pk_bf16_f32 v133, v138, v139
	global_store_dwordx2 v130, v[132:133], s[14:15] offset:0
	v_mul_f32_e32 v136, v143, v4
	v_mul_f32_e32 v137, v143, v5
	v_mul_f32_e32 v138, v143, v6
	v_mul_f32_e32 v139, v143, v7
	v_fma_f32 v136, v136, v68, v100
	v_fma_f32 v137, v137, v69, v101
	v_fma_f32 v138, v138, v70, v102
	v_fma_f32 v139, v139, v71, v103
	v_cvt_pk_bf16_f32 v134, v136, v137
	v_cvt_pk_bf16_f32 v135, v138, v139
	global_store_dwordx2 v130, v[134:135], s[14:15] offset:512
	v_mul_f32_e32 v136, v143, v8
	v_mul_f32_e32 v137, v143, v9
	v_mul_f32_e32 v138, v143, v10
	v_mul_f32_e32 v139, v143, v11
	v_fma_f32 v136, v136, v72, v104
	v_fma_f32 v137, v137, v73, v105
	v_fma_f32 v138, v138, v74, v106
	v_fma_f32 v139, v139, v75, v107
	v_cvt_pk_bf16_f32 v132, v136, v137
	v_cvt_pk_bf16_f32 v133, v138, v139
	global_store_dwordx2 v130, v[132:133], s[14:15] offset:1024
	v_mul_f32_e32 v136, v143, v12
	v_mul_f32_e32 v137, v143, v13
	v_mul_f32_e32 v138, v143, v14
	v_mul_f32_e32 v139, v143, v15
	v_fma_f32 v136, v136, v76, v108
	v_fma_f32 v137, v137, v77, v109
	v_fma_f32 v138, v138, v78, v110
	v_fma_f32 v139, v139, v79, v111
	v_cvt_pk_bf16_f32 v134, v136, v137
	v_cvt_pk_bf16_f32 v135, v138, v139
	global_store_dwordx2 v130, v[134:135], s[14:15] offset:1536
	v_mul_f32_e32 v136, v143, v16
	v_mul_f32_e32 v137, v143, v17
; __device__ __forceinline__ unsigned cvt_pk_bf16(float lo, float hi) { unsigned r; asm volatile("v_cvt_pk_bf16_f32 %0, %1, %2" : "=v"(r) : "v"(lo), "v"(hi)); return r; }
; __device__ __forceinline__ void modulate_store(const f32x4 (&v)[8], float rstd, const float* pn, const float* modr, bf16_t* orow, int lane) {
; #pragma unroll
;     for (int j = 0; j < 8; ++j) { const int col = 4 * lane + 256 * j;
;         const f32x4 g = *(const f32x4*)(pn + col), sh = *(const f32x4*)(modr + col), sc = *(const f32x4*)(modr + DM + col);
;         const f32x4 hh = v[j] * rstd * g * (sc + 1.f) + sh;
;         u32x2 w; w.x = cvt_pk_bf16(hh[0], hh[1]); w.y = cvt_pk_bf16(hh[2], hh[3]);
;         *(u32x2*)(orow + col) = w; }
; __global__ void __launch_bounds__(NWAVES * 64, 2) mk_fwd(Args args) {
;     ...
;             for (int q = 0; q < 3; ++q) { const int row = row0 + q; const float* src = row < ML ? x + (size_t)row * DM : ctx + (size_t)(row - ML) * DM; load_row_f32(src, F.lane, v[q]); }
; #pragma unroll
;             for (int q = 0; q < 3; ++q) { const int row = row0 + q; const int r = row < ML ? row / SEQ : 8;
;                 const float rstd = __builtin_amdgcn_rsqf(sumsq8(v[q]) * (1.f / DM) + EPS);
;                 modulate_store(v[q], rstd, pre_norm, mod + (size_t)r * 6144, H + (size_t)row * DM, F.lane); }
	v_mul_f32_e32 v138, v143, v18
	v_mul_f32_e32 v139, v143, v19
	v_fma_f32 v136, v136, v80, v112
	v_fma_f32 v137, v137, v81, v113
	v_fma_f32 v138, v138, v82, v114
	v_fma_f32 v139, v139, v83, v115
	v_cvt_pk_bf16_f32 v132, v136, v137
	v_cvt_pk_bf16_f32 v133, v138, v139
	global_store_dwordx2 v130, v[132:133], s[14:15] offset:2048
	v_mul_f32_e32 v136, v143, v20
	v_mul_f32_e32 v137, v143, v21
	v_mul_f32_e32 v138, v143, v22
	v_mul_f32_e32 v139, v143, v23
	v_fma_f32 v136, v136, v84, v116
	v_fma_f32 v137, v137, v85, v117
	v_fma_f32 v138, v138, v86, v118
	v_fma_f32 v139, v139, v87, v119
	v_cvt_pk_bf16_f32 v134, v136, v137
	v_cvt_pk_bf16_f32 v135, v138, v139
	global_store_dwordx2 v130, v[134:135], s[14:15] offset:2560
	v_mul_f32_e32 v136, v143, v24
	v_mul_f32_e32 v137, v143, v25
	v_mul_f32_e32 v138, v143, v26
	v_mul_f32_e32 v139, v143, v27
	v_fma_f32 v136, v136, v88, v120
	v_fma_f32 v137, v137, v89, v121
	v_fma_f32 v138, v138, v90, v122
	v_fma_f32 v139, v139, v91, v123
	v_cvt_pk_bf16_f32 v132, v136, v137
	v_cvt_pk_bf16_f32 v133, v138, v139
	global_store_dwordx2 v130, v[132:133], s[14:15] offset:3072
	v_mul_f32_e32 v136, v143, v28
	v_mul_f32_e32 v137, v143, v29
	v_mul_f32_e32 v138, v143, v30
	v_mul_f32_e32 v139, v143, v31
	v_fma_f32 v136, v136, v92, v124
	v_fma_f32 v137, v137, v93, v125
	v_fma_f32 v138, v138, v94, v126
	v_fma_f32 v139, v139, v95, v127
	v_cvt_pk_bf16_f32 v134, v136, v137
	v_cvt_pk_bf16_f32 v135, v138, v139
	global_store_dwordx2 v130, v[134:135], s[14:15] offset:3584
	s_add_i32 s4, s6, 4
	s_cmp_lt_u32 s4, 0x4000
	s_cselect_b32 s10, s68, s72
	s_cselect_b32 s11, s69, s73
	s_cselect_b32 s5, 0, 0x4000
	s_sub_i32 s5, s4, s5
	s_lshl_b32 s5, s5, 13
	s_add_u32 s10, s10, s5
	s_addc_u32 s11, s11, 0
	global_load_dwordx4 v[0:3], v128, s[10:11] offset:0 nt
	global_load_dwordx4 v[4:7], v128, s[10:11] offset:1024 nt
	global_load_dwordx4 v[8:11], v128, s[10:11] offset:2048 nt
	global_load_dwordx4 v[12:15], v128, s[10:11] offset:3072 nt
	global_load_dwordx4 v[16:19], v129, s[10:11] offset:0 nt
	global_load_dwordx4 v[20:23], v129, s[10:11] offset:1024 nt
	global_load_dwordx4 v[24:27], v129, s[10:11] offset:2048 nt
	global_load_dwordx4 v[28:31], v129, s[10:11] offset:3072 nt
	s_add_i32 s4, s6, 3
	s_add_i32 s4, s6, 3
	s_lshr_b32 s8, s4, 11
	s_cmp_lt_u32 s4, 0x4000
	s_cselect_b32 s8, s8, 8
	s_cmp_eq_u32 s8, s7
	s_cbranch_scc1 .Lp1_np3
	s_mov_b32 s7, s8
	s_add_i32 s5, s8, 0
	s_mul_i32 s5, s5, 0x6000
	s_add_u32 s24, s84, s5
	s_addc_u32 s25, s85, 0
	s_add_u32 s24, s24, 0x2000
	s_addc_u32 s25, s25, 0
	s_add_i32 s5, s8, 0
	s_mul_i32 s5, s5, 0x6000
	s_add_u32 s16, s84, s5
	s_addc_u32 s17, s85, 0
	s_add_u32 s18, s80, 0x0
	s_addc_u32 s19, s81, 0
	global_load_dwordx4 v[64:67], v128, s[18:19] offset:0
	global_load_dwordx4 v[96:99], v128, s[16:17] offset:0
	global_load_dwordx4 v[68:71], v128, s[18:19] offset:1024
	global_load_dwordx4 v[100:103], v128, s[16:17] offset:1024
	global_load_dwordx4 v[72:75], v128, s[18:19] offset:2048
	global_load_dwordx4 v[104:107], v128, s[16:17] offset:2048
	global_load_dwordx4 v[76:79], v128, s[18:19] offset:3072
	global_load_dwordx4 v[108:111], v128, s[16:17] offset:3072
	global_load_dwordx4 v[80:83], v129, s[18:19] offset:0
	global_load_dwordx4 v[112:115], v129, s[16:17] offset:0
	global_load_dwordx4 v[84:87], v129, s[18:19] offset:1024
	global_load_dwordx4 v[116:119], v129, s[16:17] offset:1024
	global_load_dwordx4 v[88:91], v129, s[18:19] offset:2048
	global_load_dwordx4 v[120:123], v129, s[16:17] offset:2048
	global_load_dwordx4 v[92:95], v129, s[18:19] offset:3072
	global_load_dwordx4 v[124:127], v129, s[16:17] offset:3072
	global_load_dwordx4 v[136:139], v128, s[24:25] offset:0
	s_waitcnt vmcnt(0)
	v_add_f32_e32 v136, 1.0, v136
	v_add_f32_e32 v137, 1.0, v137
	v_add_f32_e32 v138, 1.0, v138
	v_add_f32_e32 v139, 1.0, v139
	v_mul_f32_e32 v64, v64, v136
	v_mul_f32_e32 v65, v65, v137
	v_mul_f32_e32 v66, v66, v138
	v_mul_f32_e32 v67, v67, v139
	global_load_dwordx4 v[136:139], v128, s[24:25] offset:1024
	s_waitcnt vmcnt(0)
	v_add_f32_e32 v136, 1.0, v136
	v_add_f32_e32 v137, 1.0, v137
	v_add_f32_e32 v138, 1.0, v138
	v_add_f32_e32 v139, 1.0, v139
	v_mul_f32_e32 v68, v68, v136
	v_mul_f32_e32 v69, v69, v137
	v_mul_f32_e32 v70, v70, v138
	v_mul_f32_e32 v71, v71, v139
	global_load_dwordx4 v[136:139], v128, s[24:25] offset:2048
	s_waitcnt vmcnt(0)
	v_add_f32_e32 v136, 1.0, v136
	v_add_f32_e32 v137, 1.0, v137
	v_add_f32_e32 v138, 1.0, v138
	v_add_f32_e32 v139, 1.0, v139
	v_mul_f32_e32 v72, v72, v136
	v_mul_f32_e32 v73, v73, v137
	v_mul_f32_e32 v74, v74, v138
	v_mul_f32_e32 v75, v75, v139
	global_load_dwordx4 v[136:139], v128, s[24:25] offset:3072
	s_waitcnt vmcnt(0)
	v_add_f32_e32 v136, 1.0, v136
	v_add_f32_e32 v137, 1.0, v137
	v_add_f32_e32 v138, 1.0, v138
	v_add_f32_e32 v139, 1.0, v139
	v_mul_f32_e32 v76, v76, v136
	v_mul_f32_e32 v77, v77, v137
	v_mul_f32_e32 v78, v78, v138
	v_mul_f32_e32 v79, v79, v139
	global_load_dwordx4 v[136:139], v129, s[24:25] offset:0
	s_waitcnt vmcnt(0)
	v_add_f32_e32 v136, 1.0, v136
	v_add_f32_e32 v137, 1.0, v137
	v_add_f32_e32 v138, 1.0, v138
	v_add_f32_e32 v139, 1.0, v139
	v_mul_f32_e32 v80, v80, v136
	v_mul_f32_e32 v81, v81, v137
	v_mul_f32_e32 v82, v82, v138
	v_mul_f32_e32 v83, v83, v139
	global_load_dwordx4 v[136:139], v129, s[24:25] offset:1024
	s_waitcnt vmcnt(0)
	v_add_f32_e32 v136, 1.0, v136
	v_add_f32_e32 v137, 1.0, v137
	v_add_f32_e32 v138, 1.0, v138
	v_add_f32_e32 v139, 1.0, v139
	v_mul_f32_e32 v84, v84, v136
	v_mul_f32_e32 v85, v85, v137
	v_mul_f32_e32 v86, v86, v138
	v_mul_f32_e32 v87, v87, v139
	global_load_dwordx4 v[136:139], v129, s[24:25] offset:2048
	s_waitcnt vmcnt(0)
	v_add_f32_e32 v136, 1.0, v136
	v_add_f32_e32 v137, 1.0, v137
	v_add_f32_e32 v138, 1.0, v138
	v_add_f32_e32 v139, 1.0, v139
	v_mul_f32_e32 v88, v88, v136
	v_mul_f32_e32 v89, v89, v137
	v_mul_f32_e32 v90, v90, v138
	v_mul_f32_e32 v91, v91, v139
	global_load_dwordx4 v[136:139], v129, s[24:25] offset:3072
	s_waitcnt vmcnt(0)
	v_add_f32_e32 v136, 1.0, v136
	v_add_f32_e32 v137, 1.0, v137
	v_add_f32_e32 v138, 1.0, v138
	v_add_f32_e32 v139, 1.0, v139
	v_mul_f32_e32 v92, v92, v136
	v_mul_f32_e32 v93, v93, v137
	v_mul_f32_e32 v94, v94, v138
	v_mul_f32_e32 v95, v95, v139
; __device__ __forceinline__ unsigned cvt_pk_bf16(float lo, float hi) { unsigned r; asm volatile("v_cvt_pk_bf16_f32 %0, %1, %2" : "=v"(r) : "v"(lo), "v"(hi)); return r; }
; __device__ __forceinline__ void load_row_f32(const float* p, int lane, f32x4 (&v)[8]) {
; #pragma unroll
;     for (int j = 0; j < 8; ++j) v[j] = *(const f32x4*)(p + 4 * lane + 256 * j);
; }
; __device__ __forceinline__ float sumsq8(const f32x4 (&v)[8]) {
;     float s = 0.f;
; #pragma unroll
;     for (int j = 0; j < 8; ++j) s += (v[j][0] * v[j][0] + v[j][1] * v[j][1]) + (v[j][2] * v[j][2] + v[j][3] * v[j][3]);
;     return wave_sum(s);
; }
; __device__ __forceinline__ void modulate_store(const f32x4 (&v)[8], float rstd, const float* pn, const float* modr, bf16_t* orow, int lane) {
; #pragma unroll
;     for (int j = 0; j < 8; ++j) { const int col = 4 * lane + 256 * j;
;         const f32x4 g = *(const f32x4*)(pn + col), sh = *(const f32x4*)(modr + col), sc = *(const f32x4*)(modr + DM + col);
;         const f32x4 hh = v[j] * rstd * g * (sc + 1.f) + sh;
;         u32x2 w; w.x = cvt_pk_bf16(hh[0], hh[1]); w.y = cvt_pk_bf16(hh[2], hh[3]);
;         *(u32x2*)(orow + col) = w; }
; __global__ void __launch_bounds__(NWAVES * 64, 2) mk_fwd(Args args) {
;     ...
;             for (int q = 0; q < 3; ++q) { const int row = row0 + q; const float* src = row < ML ? x + (size_t)row * DM : ctx + (size_t)(row - ML) * DM; load_row_f32(src, F.lane, v[q]); }
; #pragma unroll
;             for (int q = 0; q < 3; ++q) { const int row = row0 + q; const int r = row < ML ? row / SEQ : 8;
;                 const float rstd = __builtin_amdgcn_rsqf(sumsq8(v[q]) * (1.f / DM) + EPS);
;                 modulate_store(v[q], rstd, pre_norm, mod + (size_t)r * 6144, H + (size_t)row * DM, F.lane); }
.Lp1_np3:
	s_waitcnt vmcnt(16)
	v_mul_f32_e32 v140, v32, v32
	v_mul_f32_e32 v141, v33, v33
	v_fmac_f32_e32 v140, v34, v34
	v_fmac_f32_e32 v141, v35, v35
	v_fmac_f32_e32 v140, v36, v36
	v_fmac_f32_e32 v141, v37, v37
	v_fmac_f32_e32 v140, v38, v38
	v_fmac_f32_e32 v141, v39, v39
	v_fmac_f32_e32 v140, v40, v40
	v_fmac_f32_e32 v141, v41, v41
	v_fmac_f32_e32 v140, v42, v42
	v_fmac_f32_e32 v141, v43, v43
	v_fmac_f32_e32 v140, v44, v44
	v_fmac_f32_e32 v141, v45, v45
	v_fmac_f32_e32 v140, v46, v46
	v_fmac_f32_e32 v141, v47, v47
	v_fmac_f32_e32 v140, v48, v48
	v_fmac_f32_e32 v141, v49, v49
	v_fmac_f32_e32 v140, v50, v50
	v_fmac_f32_e32 v141, v51, v51
	v_fmac_f32_e32 v140, v52, v52
	v_fmac_f32_e32 v141, v53, v53
	v_fmac_f32_e32 v140, v54, v54
	v_fmac_f32_e32 v141, v55, v55
	v_fmac_f32_e32 v140, v56, v56
	v_fmac_f32_e32 v141, v57, v57
	v_fmac_f32_e32 v140, v58, v58
	v_fmac_f32_e32 v141, v59, v59
	v_fmac_f32_e32 v140, v60, v60
	v_fmac_f32_e32 v141, v61, v61
	v_fmac_f32_e32 v140, v62, v62
	v_fmac_f32_e32 v141, v63, v63
	v_add_f32_e32 v140, v140, v141
	s_nop 1
	v_add_f32_dpp v142, v140, v140 quad_perm:[1,0,3,2] row_mask:0xf bank_mask:0xf
	s_nop 1
	v_add_f32_dpp v142, v142, v142 quad_perm:[2,3,0,1] row_mask:0xf bank_mask:0xf
	s_nop 1
	v_add_f32_dpp v142, v142, v142 row_half_mirror row_mask:0xf bank_mask:0xf
	s_nop 1
	v_add_f32_dpp v142, v142, v142 row_mirror row_mask:0xf bank_mask:0xf
	s_nop 1
	v_readlane_b32 s20, v142, 0
	v_readlane_b32 s21, v142, 16
	v_readlane_b32 s22, v142, 32
	v_readlane_b32 s23, v142, 48
	s_nop 1
	v_mov_b32_e32 v143, s20
	v_add_f32_e32 v143, s21, v143
	v_add_f32_e32 v143, s22, v143
	v_add_f32_e32 v143, s23, v143
	v_fmamk_f32 v143, v143, 0x3a000000, v131
	v_rsq_f32_e32 v143, v143
	s_nop 0
	s_add_i32 s4, s6, 3
	s_lshl_b32 s5, s4, 12
	s_add_u32 s14, s84, s5
	s_addc_u32 s15, s85, 0
	s_add_u32 s14, s14, 0x4000000
	s_addc_u32 s15, s15, 0
	v_mul_f32_e32 v136, v143, v32
	v_mul_f32_e32 v137, v143, v33
	v_mul_f32_e32 v138, v143, v34
	v_mul_f32_e32 v139, v143, v35
	v_fma_f32 v136, v136, v64, v96
	v_fma_f32 v137, v137, v65, v97
	v_fma_f32 v138, v138, v66, v98
	v_fma_f32 v139, v139, v67, v99
	v_cvt_pk_bf16_f32 v132, v136, v137
	v_cvt_pk_bf16_f32 v133, v138, v139
	global_store_dwordx2 v130, v[132:133], s[14:15] offset:0
	v_mul_f32_e32 v136, v143, v36
	v_mul_f32_e32 v137, v143, v37
	v_mul_f32_e32 v138, v143, v38
	v_mul_f32_e32 v139, v143, v39
	v_fma_f32 v136, v136, v68, v100
	v_fma_f32 v137, v137, v69, v101
	v_fma_f32 v138, v138, v70, v102
	v_fma_f32 v139, v139, v71, v103
	v_cvt_pk_bf16_f32 v134, v136, v137
	v_cvt_pk_bf16_f32 v135, v138, v139
	global_store_dwordx2 v130, v[134:135], s[14:15] offset:512
	v_mul_f32_e32 v136, v143, v40
	v_mul_f32_e32 v137, v143, v41
	v_mul_f32_e32 v138, v143, v42
	v_mul_f32_e32 v139, v143, v43
	v_fma_f32 v136, v136, v72, v104
	v_fma_f32 v137, v137, v73, v105
	v_fma_f32 v138, v138, v74, v106
	v_fma_f32 v139, v139, v75, v107
	v_cvt_pk_bf16_f32 v132, v136, v137
	v_cvt_pk_bf16_f32 v133, v138, v139
	global_store_dwordx2 v130, v[132:133], s[14:15] offset:1024
	v_mul_f32_e32 v136, v143, v44
	v_mul_f32_e32 v137, v143, v45
	v_mul_f32_e32 v138, v143, v46
	v_mul_f32_e32 v139, v143, v47
	v_fma_f32 v136, v136, v76, v108
	v_fma_f32 v137, v137, v77, v109
	v_fma_f32 v138, v138, v78, v110
	v_fma_f32 v139, v139, v79, v111
	v_cvt_pk_bf16_f32 v134, v136, v137
	v_cvt_pk_bf16_f32 v135, v138, v139
	global_store_dwordx2 v130, v[134:135], s[14:15] offset:1536
	v_mul_f32_e32 v136, v143, v48
	v_mul_f32_e32 v137, v143, v49
	v_mul_f32_e32 v138, v143, v50
	v_mul_f32_e32 v139, v143, v51
	v_fma_f32 v136, v136, v80, v112
	v_fma_f32 v137, v137, v81, v113
	v_fma_f32 v138, v138, v82, v114
	v_fma_f32 v139, v139, v83, v115
	v_cvt_pk_bf16_f32 v132, v136, v137
	v_cvt_pk_bf16_f32 v133, v138, v139
	global_store_dwordx2 v130, v[132:133], s[14:15] offset:2048
	v_mul_f32_e32 v136, v143, v52
	v_mul_f32_e32 v137, v143, v53
	v_mul_f32_e32 v138, v143, v54
	v_mul_f32_e32 v139, v143, v55
	v_fma_f32 v136, v136, v84, v116
	v_fma_f32 v137, v137, v85, v117
	v_fma_f32 v138, v138, v86, v118
	v_fma_f32 v139, v139, v87, v119
	v_cvt_pk_bf16_f32 v134, v136, v137
	v_cvt_pk_bf16_f32 v135, v138, v139
	global_store_dwordx2 v130, v[134:135], s[14:15] offset:2560
	v_mul_f32_e32 v136, v143, v56
	v_mul_f32_e32 v137, v143, v57
	v_mul_f32_e32 v138, v143, v58
	v_mul_f32_e32 v139, v143, v59
	v_fma_f32 v136, v136, v88, v120
	v_fma_f32 v137, v137, v89, v121
	v_fma_f32 v138, v138, v90, v122
	v_fma_f32 v139, v139, v91, v123
	v_cvt_pk_bf16_f32 v132, v136, v137
	v_cvt_pk_bf16_f32 v133, v138, v139
	global_store_dwordx2 v130, v[132:133], s[14:15] offset:3072
	v_mul_f32_e32 v136, v143, v60
	v_mul_f32_e32 v137, v143, v61
	v_mul_f32_e32 v138, v143, v62
	v_mul_f32_e32 v139, v143, v63
	v_fma_f32 v136, v136, v92, v124
	v_fma_f32 v137, v137, v93, v125
	v_fma_f32 v138, v138, v94, v126
	v_fma_f32 v139, v139, v95, v127
	v_cvt_pk_bf16_f32 v134, v136, v137
	v_cvt_pk_bf16_f32 v135, v138, v139
	global_store_dwordx2 v130, v[134:135], s[14:15] offset:3584
	s_add_i32 s4, s6, 5
	s_cmp_lt_u32 s4, 0x4000
	s_cselect_b32 s10, s68, s72
	s_cselect_b32 s11, s69, s73
	s_cselect_b32 s5, 0, 0x4000
	s_sub_i32 s5, s4, s5
	s_lshl_b32 s5, s5, 13
	s_add_u32 s10, s10, s5
	s_addc_u32 s11, s11, 0
	global_load_dwordx4 v[32:35], v128, s[10:11] offset:0 nt
	global_load_dwordx4 v[36:39], v128, s[10:11] offset:1024 nt
	global_load_dwordx4 v[40:43], v128, s[10:11] offset:2048 nt
	global_load_dwordx4 v[44:47], v128, s[10:11] offset:3072 nt
	global_load_dwordx4 v[48:51], v129, s[10:11] offset:0 nt
	global_load_dwordx4 v[52:55], v129, s[10:11] offset:1024 nt
	global_load_dwordx4 v[56:59], v129, s[10:11] offset:2048 nt
	global_load_dwordx4 v[60:63], v129, s[10:11] offset:3072 nt
	s_add_i32 s4, s6, 4
	s_add_i32 s4, s6, 4
	s_lshr_b32 s8, s4, 11
	s_cmp_lt_u32 s4, 0x4000
	s_cselect_b32 s8, s8, 8
	s_cmp_eq_u32 s8, s7
	s_cbranch_scc1 .Lp1_np4
; __device__ __forceinline__ unsigned cvt_pk_bf16(float lo, float hi) { unsigned r; asm volatile("v_cvt_pk_bf16_f32 %0, %1, %2" : "=v"(r) : "v"(lo), "v"(hi)); return r; }
; __device__ __forceinline__ void load_row_f32(const float* p, int lane, f32x4 (&v)[8]) {
; #pragma unroll
;     for (int j = 0; j < 8; ++j) v[j] = *(const f32x4*)(p + 4 * lane + 256 * j);
; }
; __device__ __forceinline__ float sumsq8(const f32x4 (&v)[8]) {
;     float s = 0.f;
; #pragma unroll
;     for (int j = 0; j < 8; ++j) s += (v[j][0] * v[j][0] + v[j][1] * v[j][1]) + (v[j][2] * v[j][2] + v[j][3] * v[j][3]);
;     return wave_sum(s);
; }
; __device__ __forceinline__ void modulate_store(const f32x4 (&v)[8], float rstd, const float* pn, const float* modr, bf16_t* orow, int lane) {
; #pragma unroll
;     for (int j = 0; j < 8; ++j) { const int col = 4 * lane + 256 * j;
;         const f32x4 g = *(const f32x4*)(pn + col), sh = *(const f32x4*)(modr + col), sc = *(const f32x4*)(modr + DM + col);
;         const f32x4 hh = v[j] * rstd * g * (sc + 1.f) + sh;
;         u32x2 w; w.x = cvt_pk_bf16(hh[0], hh[1]); w.y = cvt_pk_bf16(hh[2], hh[3]);
;         *(u32x2*)(orow + col) = w; }
; __global__ void __launch_bounds__(NWAVES * 64, 2) mk_fwd(Args args) {
;     ...
;             for (int q = 0; q < 3; ++q) { const int row = row0 + q; const int r = row < ML ? row / SEQ : 8;
;                 const float rstd = __builtin_amdgcn_rsqf(sumsq8(v[q]) * (1.f / DM) + EPS);
;                 modulate_store(v[q], rstd, pre_norm, mod + (size_t)r * 6144, H + (size_t)row * DM, F.lane); }
	s_mov_b32 s7, s8
	s_add_i32 s5, s8, 0
	s_mul_i32 s5, s5, 0x6000
	s_add_u32 s24, s84, s5
	s_addc_u32 s25, s85, 0
	s_add_u32 s24, s24, 0x2000
	s_addc_u32 s25, s25, 0
	s_add_i32 s5, s8, 0
	s_mul_i32 s5, s5, 0x6000
	s_add_u32 s16, s84, s5
	s_addc_u32 s17, s85, 0
	s_add_u32 s18, s80, 0x0
	s_addc_u32 s19, s81, 0
	global_load_dwordx4 v[64:67], v128, s[18:19] offset:0
	global_load_dwordx4 v[96:99], v128, s[16:17] offset:0
	global_load_dwordx4 v[68:71], v128, s[18:19] offset:1024
	global_load_dwordx4 v[100:103], v128, s[16:17] offset:1024
	global_load_dwordx4 v[72:75], v128, s[18:19] offset:2048
	global_load_dwordx4 v[104:107], v128, s[16:17] offset:2048
	global_load_dwordx4 v[76:79], v128, s[18:19] offset:3072
	global_load_dwordx4 v[108:111], v128, s[16:17] offset:3072
	global_load_dwordx4 v[80:83], v129, s[18:19] offset:0
	global_load_dwordx4 v[112:115], v129, s[16:17] offset:0
	global_load_dwordx4 v[84:87], v129, s[18:19] offset:1024
	global_load_dwordx4 v[116:119], v129, s[16:17] offset:1024
	global_load_dwordx4 v[88:91], v129, s[18:19] offset:2048
	global_load_dwordx4 v[120:123], v129, s[16:17] offset:2048
	global_load_dwordx4 v[92:95], v129, s[18:19] offset:3072
	global_load_dwordx4 v[124:127], v129, s[16:17] offset:3072
	global_load_dwordx4 v[136:139], v128, s[24:25] offset:0
	s_waitcnt vmcnt(0)
	v_add_f32_e32 v136, 1.0, v136
	v_add_f32_e32 v137, 1.0, v137
	v_add_f32_e32 v138, 1.0, v138
	v_add_f32_e32 v139, 1.0, v139
	v_mul_f32_e32 v64, v64, v136
	v_mul_f32_e32 v65, v65, v137
	v_mul_f32_e32 v66, v66, v138
	v_mul_f32_e32 v67, v67, v139
	global_load_dwordx4 v[136:139], v128, s[24:25] offset:1024
	s_waitcnt vmcnt(0)
	v_add_f32_e32 v136, 1.0, v136
	v_add_f32_e32 v137, 1.0, v137
	v_add_f32_e32 v138, 1.0, v138
	v_add_f32_e32 v139, 1.0, v139
	v_mul_f32_e32 v68, v68, v136
	v_mul_f32_e32 v69, v69, v137
	v_mul_f32_e32 v70, v70, v138
	v_mul_f32_e32 v71, v71, v139
	global_load_dwordx4 v[136:139], v128, s[24:25] offset:2048
	s_waitcnt vmcnt(0)
	v_add_f32_e32 v136, 1.0, v136
	v_add_f32_e32 v137, 1.0, v137
	v_add_f32_e32 v138, 1.0, v138
	v_add_f32_e32 v139, 1.0, v139
	v_mul_f32_e32 v72, v72, v136
	v_mul_f32_e32 v73, v73, v137
	v_mul_f32_e32 v74, v74, v138
	v_mul_f32_e32 v75, v75, v139
	global_load_dwordx4 v[136:139], v128, s[24:25] offset:3072
	s_waitcnt vmcnt(0)
	v_add_f32_e32 v136, 1.0, v136
	v_add_f32_e32 v137, 1.0, v137
	v_add_f32_e32 v138, 1.0, v138
	v_add_f32_e32 v139, 1.0, v139
	v_mul_f32_e32 v76, v76, v136
	v_mul_f32_e32 v77, v77, v137
	v_mul_f32_e32 v78, v78, v138
	v_mul_f32_e32 v79, v79, v139
	global_load_dwordx4 v[136:139], v129, s[24:25] offset:0
	s_waitcnt vmcnt(0)
	v_add_f32_e32 v136, 1.0, v136
	v_add_f32_e32 v137, 1.0, v137
	v_add_f32_e32 v138, 1.0, v138
	v_add_f32_e32 v139, 1.0, v139
	v_mul_f32_e32 v80, v80, v136
	v_mul_f32_e32 v81, v81, v137
	v_mul_f32_e32 v82, v82, v138
	v_mul_f32_e32 v83, v83, v139
	global_load_dwordx4 v[136:139], v129, s[24:25] offset:1024
	s_waitcnt vmcnt(0)
	v_add_f32_e32 v136, 1.0, v136
	v_add_f32_e32 v137, 1.0, v137
	v_add_f32_e32 v138, 1.0, v138
	v_add_f32_e32 v139, 1.0, v139
	v_mul_f32_e32 v84, v84, v136
	v_mul_f32_e32 v85, v85, v137
	v_mul_f32_e32 v86, v86, v138
	v_mul_f32_e32 v87, v87, v139
	global_load_dwordx4 v[136:139], v129, s[24:25] offset:2048
	s_waitcnt vmcnt(0)
	v_add_f32_e32 v136, 1.0, v136
	v_add_f32_e32 v137, 1.0, v137
	v_add_f32_e32 v138, 1.0, v138
	v_add_f32_e32 v139, 1.0, v139
	v_mul_f32_e32 v88, v88, v136
	v_mul_f32_e32 v89, v89, v137
	v_mul_f32_e32 v90, v90, v138
	v_mul_f32_e32 v91, v91, v139
	global_load_dwordx4 v[136:139], v129, s[24:25] offset:3072
	s_waitcnt vmcnt(0)
	v_add_f32_e32 v136, 1.0, v136
	v_add_f32_e32 v137, 1.0, v137
	v_add_f32_e32 v138, 1.0, v138
	v_add_f32_e32 v139, 1.0, v139
	v_mul_f32_e32 v92, v92, v136
	v_mul_f32_e32 v93, v93, v137
	v_mul_f32_e32 v94, v94, v138
	v_mul_f32_e32 v95, v95, v139
.Lp1_np4:
	s_waitcnt vmcnt(16)
	v_mul_f32_e32 v140, v0, v0
	v_mul_f32_e32 v141, v1, v1
	v_fmac_f32_e32 v140, v2, v2
	v_fmac_f32_e32 v141, v3, v3
	v_fmac_f32_e32 v140, v4, v4
	v_fmac_f32_e32 v141, v5, v5
	v_fmac_f32_e32 v140, v6, v6
	v_fmac_f32_e32 v141, v7, v7
	v_fmac_f32_e32 v140, v8, v8
	v_fmac_f32_e32 v141, v9, v9
	v_fmac_f32_e32 v140, v10, v10
	v_fmac_f32_e32 v141, v11, v11
	v_fmac_f32_e32 v140, v12, v12
	v_fmac_f32_e32 v141, v13, v13
	v_fmac_f32_e32 v140, v14, v14
	v_fmac_f32_e32 v141, v15, v15
	v_fmac_f32_e32 v140, v16, v16
	v_fmac_f32_e32 v141, v17, v17
	v_fmac_f32_e32 v140, v18, v18
	v_fmac_f32_e32 v141, v19, v19
	v_fmac_f32_e32 v140, v20, v20
	v_fmac_f32_e32 v141, v21, v21
	v_fmac_f32_e32 v140, v22, v22
	v_fmac_f32_e32 v141, v23, v23
	v_fmac_f32_e32 v140, v24, v24
	v_fmac_f32_e32 v141, v25, v25
	v_fmac_f32_e32 v140, v26, v26
	v_fmac_f32_e32 v141, v27, v27
	v_fmac_f32_e32 v140, v28, v28
	v_fmac_f32_e32 v141, v29, v29
	v_fmac_f32_e32 v140, v30, v30
	v_fmac_f32_e32 v141, v31, v31
	v_add_f32_e32 v140, v140, v141
	s_nop 1
	v_add_f32_dpp v142, v140, v140 quad_perm:[1,0,3,2] row_mask:0xf bank_mask:0xf
	s_nop 1
	v_add_f32_dpp v142, v142, v142 quad_perm:[2,3,0,1] row_mask:0xf bank_mask:0xf
	s_nop 1
	v_add_f32_dpp v142, v142, v142 row_half_mirror row_mask:0xf bank_mask:0xf
	s_nop 1
	v_add_f32_dpp v142, v142, v142 row_mirror row_mask:0xf bank_mask:0xf
	s_nop 1
	v_readlane_b32 s20, v142, 0
	v_readlane_b32 s21, v142, 16
	v_readlane_b32 s22, v142, 32
	v_readlane_b32 s23, v142, 48
	s_nop 1
	v_mov_b32_e32 v143, s20
	v_add_f32_e32 v143, s21, v143
	v_add_f32_e32 v143, s22, v143
	v_add_f32_e32 v143, s23, v143
	v_fmamk_f32 v143, v143, 0x3a000000, v131
	v_rsq_f32_e32 v143, v143
	s_nop 0
	s_add_i32 s4, s6, 4
	s_lshl_b32 s5, s4, 12
	s_add_u32 s14, s84, s5
	s_addc_u32 s15, s85, 0
	s_add_u32 s14, s14, 0x4000000
; __device__ __forceinline__ unsigned cvt_pk_bf16(float lo, float hi) { unsigned r; asm volatile("v_cvt_pk_bf16_f32 %0, %1, %2" : "=v"(r) : "v"(lo), "v"(hi)); return r; }
; __device__ __forceinline__ void modulate_store(const f32x4 (&v)[8], float rstd, const float* pn, const float* modr, bf16_t* orow, int lane) {
; #pragma unroll
;     for (int j = 0; j < 8; ++j) { const int col = 4 * lane + 256 * j;
;         const f32x4 g = *(const f32x4*)(pn + col), sh = *(const f32x4*)(modr + col), sc = *(const f32x4*)(modr + DM + col);
;         const f32x4 hh = v[j] * rstd * g * (sc + 1.f) + sh;
;         u32x2 w; w.x = cvt_pk_bf16(hh[0], hh[1]); w.y = cvt_pk_bf16(hh[2], hh[3]);
;         *(u32x2*)(orow + col) = w; }
; __global__ void __launch_bounds__(NWAVES * 64, 2) mk_fwd(Args args) {
;     ...
;             for (int q = 0; q < 3; ++q) { const int row = row0 + q; const float* src = row < ML ? x + (size_t)row * DM : ctx + (size_t)(row - ML) * DM; load_row_f32(src, F.lane, v[q]); }
; #pragma unroll
;             for (int q = 0; q < 3; ++q) { const int row = row0 + q; const int r = row < ML ? row / SEQ : 8;
;                 const float rstd = __builtin_amdgcn_rsqf(sumsq8(v[q]) * (1.f / DM) + EPS);
;                 modulate_store(v[q], rstd, pre_norm, mod + (size_t)r * 6144, H + (size_t)row * DM, F.lane); }
	s_addc_u32 s15, s15, 0
	v_mul_f32_e32 v136, v143, v0
	v_mul_f32_e32 v137, v143, v1
	v_mul_f32_e32 v138, v143, v2
	v_mul_f32_e32 v139, v143, v3
	v_fma_f32 v136, v136, v64, v96
	v_fma_f32 v137, v137, v65, v97
	v_fma_f32 v138, v138, v66, v98
	v_fma_f32 v139, v139, v67, v99
	v_cvt_pk_bf16_f32 v132, v136, v137
	v_cvt_pk_bf16_f32 v133, v138, v139
	global_store_dwordx2 v130, v[132:133], s[14:15] offset:0
	v_mul_f32_e32 v136, v143, v4
	v_mul_f32_e32 v137, v143, v5
	v_mul_f32_e32 v138, v143, v6
	v_mul_f32_e32 v139, v143, v7
	v_fma_f32 v136, v136, v68, v100
	v_fma_f32 v137, v137, v69, v101
	v_fma_f32 v138, v138, v70, v102
	v_fma_f32 v139, v139, v71, v103
	v_cvt_pk_bf16_f32 v134, v136, v137
	v_cvt_pk_bf16_f32 v135, v138, v139
	global_store_dwordx2 v130, v[134:135], s[14:15] offset:512
	v_mul_f32_e32 v136, v143, v8
	v_mul_f32_e32 v137, v143, v9
	v_mul_f32_e32 v138, v143, v10
	v_mul_f32_e32 v139, v143, v11
	v_fma_f32 v136, v136, v72, v104
	v_fma_f32 v137, v137, v73, v105
	v_fma_f32 v138, v138, v74, v106
	v_fma_f32 v139, v139, v75, v107
	v_cvt_pk_bf16_f32 v132, v136, v137
	v_cvt_pk_bf16_f32 v133, v138, v139
	global_store_dwordx2 v130, v[132:133], s[14:15] offset:1024
	v_mul_f32_e32 v136, v143, v12
	v_mul_f32_e32 v137, v143, v13
	v_mul_f32_e32 v138, v143, v14
	v_mul_f32_e32 v139, v143, v15
	v_fma_f32 v136, v136, v76, v108
	v_fma_f32 v137, v137, v77, v109
	v_fma_f32 v138, v138, v78, v110
	v_fma_f32 v139, v139, v79, v111
	v_cvt_pk_bf16_f32 v134, v136, v137
	v_cvt_pk_bf16_f32 v135, v138, v139
	global_store_dwordx2 v130, v[134:135], s[14:15] offset:1536
	v_mul_f32_e32 v136, v143, v16
	v_mul_f32_e32 v137, v143, v17
	v_mul_f32_e32 v138, v143, v18
	v_mul_f32_e32 v139, v143, v19
	v_fma_f32 v136, v136, v80, v112
	v_fma_f32 v137, v137, v81, v113
	v_fma_f32 v138, v138, v82, v114
	v_fma_f32 v139, v139, v83, v115
	v_cvt_pk_bf16_f32 v132, v136, v137
	v_cvt_pk_bf16_f32 v133, v138, v139
	global_store_dwordx2 v130, v[132:133], s[14:15] offset:2048
	v_mul_f32_e32 v136, v143, v20
	v_mul_f32_e32 v137, v143, v21
	v_mul_f32_e32 v138, v143, v22
	v_mul_f32_e32 v139, v143, v23
	v_fma_f32 v136, v136, v84, v116
	v_fma_f32 v137, v137, v85, v117
	v_fma_f32 v138, v138, v86, v118
	v_fma_f32 v139, v139, v87, v119
	v_cvt_pk_bf16_f32 v134, v136, v137
	v_cvt_pk_bf16_f32 v135, v138, v139
	global_store_dwordx2 v130, v[134:135], s[14:15] offset:2560
	v_mul_f32_e32 v136, v143, v24
	v_mul_f32_e32 v137, v143, v25
	v_mul_f32_e32 v138, v143, v26
	v_mul_f32_e32 v139, v143, v27
	v_fma_f32 v136, v136, v88, v120
	v_fma_f32 v137, v137, v89, v121
	v_fma_f32 v138, v138, v90, v122
	v_fma_f32 v139, v139, v91, v123
	v_cvt_pk_bf16_f32 v132, v136, v137
	v_cvt_pk_bf16_f32 v133, v138, v139
	global_store_dwordx2 v130, v[132:133], s[14:15] offset:3072
	v_mul_f32_e32 v136, v143, v28
	v_mul_f32_e32 v137, v143, v29
	v_mul_f32_e32 v138, v143, v30
	v_mul_f32_e32 v139, v143, v31
	v_fma_f32 v136, v136, v92, v124
	v_fma_f32 v137, v137, v93, v125
	v_fma_f32 v138, v138, v94, v126
	v_fma_f32 v139, v139, v95, v127
	v_cvt_pk_bf16_f32 v134, v136, v137
	v_cvt_pk_bf16_f32 v135, v138, v139
	global_store_dwordx2 v130, v[134:135], s[14:15] offset:3584
	s_add_i32 s4, s6, 6
	s_cmp_lt_u32 s4, 0x4000
	s_cselect_b32 s10, s68, s72
	s_cselect_b32 s11, s69, s73
	s_cselect_b32 s5, 0, 0x4000
	s_sub_i32 s5, s4, s5
	s_lshl_b32 s5, s5, 13
	s_add_u32 s10, s10, s5
	s_addc_u32 s11, s11, 0
	global_load_dwordx4 v[0:3], v128, s[10:11] offset:0 nt
	global_load_dwordx4 v[4:7], v128, s[10:11] offset:1024 nt
	global_load_dwordx4 v[8:11], v128, s[10:11] offset:2048 nt
	global_load_dwordx4 v[12:15], v128, s[10:11] offset:3072 nt
	global_load_dwordx4 v[16:19], v129, s[10:11] offset:0 nt
	global_load_dwordx4 v[20:23], v129, s[10:11] offset:1024 nt
	global_load_dwordx4 v[24:27], v129, s[10:11] offset:2048 nt
	global_load_dwordx4 v[28:31], v129, s[10:11] offset:3072 nt
	s_add_i32 s4, s6, 5
	s_add_i32 s4, s6, 5
	s_lshr_b32 s8, s4, 11
	s_cmp_lt_u32 s4, 0x4000
	s_cselect_b32 s8, s8, 8
	s_cmp_eq_u32 s8, s7
	s_cbranch_scc1 .Lp1_np5
	s_mov_b32 s7, s8
	s_add_i32 s5, s8, 0
	s_mul_i32 s5, s5, 0x6000
	s_add_u32 s24, s84, s5
	s_addc_u32 s25, s85, 0
	s_add_u32 s24, s24, 0x2000
	s_addc_u32 s25, s25, 0
	s_add_i32 s5, s8, 0
	s_mul_i32 s5, s5, 0x6000
	s_add_u32 s16, s84, s5
	s_addc_u32 s17, s85, 0
	s_add_u32 s18, s80, 0x0
	s_addc_u32 s19, s81, 0
	global_load_dwordx4 v[64:67], v128, s[18:19] offset:0
	global_load_dwordx4 v[96:99], v128, s[16:17] offset:0
	global_load_dwordx4 v[68:71], v128, s[18:19] offset:1024
	global_load_dwordx4 v[100:103], v128, s[16:17] offset:1024
	global_load_dwordx4 v[72:75], v128, s[18:19] offset:2048
	global_load_dwordx4 v[104:107], v128, s[16:17] offset:2048
	global_load_dwordx4 v[76:79], v128, s[18:19] offset:3072
	global_load_dwordx4 v[108:111], v128, s[16:17] offset:3072
	global_load_dwordx4 v[80:83], v129, s[18:19] offset:0
	global_load_dwordx4 v[112:115], v129, s[16:17] offset:0
	global_load_dwordx4 v[84:87], v129, s[18:19] offset:1024
	global_load_dwordx4 v[116:119], v129, s[16:17] offset:1024
	global_load_dwordx4 v[88:91], v129, s[18:19] offset:2048
	global_load_dwordx4 v[120:123], v129, s[16:17] offset:2048
	global_load_dwordx4 v[92:95], v129, s[18:19] offset:3072
	global_load_dwordx4 v[124:127], v129, s[16:17] offset:3072
	global_load_dwordx4 v[136:139], v128, s[24:25] offset:0
	s_waitcnt vmcnt(0)
	v_add_f32_e32 v136, 1.0, v136
	v_add_f32_e32 v137, 1.0, v137
	v_add_f32_e32 v138, 1.0, v138
	v_add_f32_e32 v139, 1.0, v139
	v_mul_f32_e32 v64, v64, v136
	v_mul_f32_e32 v65, v65, v137
	v_mul_f32_e32 v66, v66, v138
	v_mul_f32_e32 v67, v67, v139
	global_load_dwordx4 v[136:139], v128, s[24:25] offset:1024
	s_waitcnt vmcnt(0)
; __device__ __forceinline__ unsigned cvt_pk_bf16(float lo, float hi) { unsigned r; asm volatile("v_cvt_pk_bf16_f32 %0, %1, %2" : "=v"(r) : "v"(lo), "v"(hi)); return r; }
; __device__ __forceinline__ void load_row_f32(const float* p, int lane, f32x4 (&v)[8]) {
; #pragma unroll
;     for (int j = 0; j < 8; ++j) v[j] = *(const f32x4*)(p + 4 * lane + 256 * j);
; }
; __device__ __forceinline__ float sumsq8(const f32x4 (&v)[8]) {
;     float s = 0.f;
; #pragma unroll
;     for (int j = 0; j < 8; ++j) s += (v[j][0] * v[j][0] + v[j][1] * v[j][1]) + (v[j][2] * v[j][2] + v[j][3] * v[j][3]);
;     return wave_sum(s);
; }
; __device__ __forceinline__ void modulate_store(const f32x4 (&v)[8], float rstd, const float* pn, const float* modr, bf16_t* orow, int lane) {
; #pragma unroll
;     for (int j = 0; j < 8; ++j) { const int col = 4 * lane + 256 * j;
;         const f32x4 g = *(const f32x4*)(pn + col), sh = *(const f32x4*)(modr + col), sc = *(const f32x4*)(modr + DM + col);
;         const f32x4 hh = v[j] * rstd * g * (sc + 1.f) + sh;
;         u32x2 w; w.x = cvt_pk_bf16(hh[0], hh[1]); w.y = cvt_pk_bf16(hh[2], hh[3]);
;         *(u32x2*)(orow + col) = w; }
; __global__ void __launch_bounds__(NWAVES * 64, 2) mk_fwd(Args args) {
;     ...
;             for (int q = 0; q < 3; ++q) { const int row = row0 + q; const int r = row < ML ? row / SEQ : 8;
;                 const float rstd = __builtin_amdgcn_rsqf(sumsq8(v[q]) * (1.f / DM) + EPS);
;                 modulate_store(v[q], rstd, pre_norm, mod + (size_t)r * 6144, H + (size_t)row * DM, F.lane); }
	v_add_f32_e32 v136, 1.0, v136
	v_add_f32_e32 v137, 1.0, v137
	v_add_f32_e32 v138, 1.0, v138
	v_add_f32_e32 v139, 1.0, v139
	v_mul_f32_e32 v68, v68, v136
	v_mul_f32_e32 v69, v69, v137
	v_mul_f32_e32 v70, v70, v138
	v_mul_f32_e32 v71, v71, v139
	global_load_dwordx4 v[136:139], v128, s[24:25] offset:2048
	s_waitcnt vmcnt(0)
	v_add_f32_e32 v136, 1.0, v136
	v_add_f32_e32 v137, 1.0, v137
	v_add_f32_e32 v138, 1.0, v138
	v_add_f32_e32 v139, 1.0, v139
	v_mul_f32_e32 v72, v72, v136
	v_mul_f32_e32 v73, v73, v137
	v_mul_f32_e32 v74, v74, v138
	v_mul_f32_e32 v75, v75, v139
	global_load_dwordx4 v[136:139], v128, s[24:25] offset:3072
	s_waitcnt vmcnt(0)
	v_add_f32_e32 v136, 1.0, v136
	v_add_f32_e32 v137, 1.0, v137
	v_add_f32_e32 v138, 1.0, v138
	v_add_f32_e32 v139, 1.0, v139
	v_mul_f32_e32 v76, v76, v136
	v_mul_f32_e32 v77, v77, v137
	v_mul_f32_e32 v78, v78, v138
	v_mul_f32_e32 v79, v79, v139
	global_load_dwordx4 v[136:139], v129, s[24:25] offset:0
	s_waitcnt vmcnt(0)
	v_add_f32_e32 v136, 1.0, v136
	v_add_f32_e32 v137, 1.0, v137
	v_add_f32_e32 v138, 1.0, v138
	v_add_f32_e32 v139, 1.0, v139
	v_mul_f32_e32 v80, v80, v136
	v_mul_f32_e32 v81, v81, v137
	v_mul_f32_e32 v82, v82, v138
	v_mul_f32_e32 v83, v83, v139
	global_load_dwordx4 v[136:139], v129, s[24:25] offset:1024
	s_waitcnt vmcnt(0)
	v_add_f32_e32 v136, 1.0, v136
	v_add_f32_e32 v137, 1.0, v137
	v_add_f32_e32 v138, 1.0, v138
	v_add_f32_e32 v139, 1.0, v139
	v_mul_f32_e32 v84, v84, v136
	v_mul_f32_e32 v85, v85, v137
	v_mul_f32_e32 v86, v86, v138
	v_mul_f32_e32 v87, v87, v139
	global_load_dwordx4 v[136:139], v129, s[24:25] offset:2048
	s_waitcnt vmcnt(0)
	v_add_f32_e32 v136, 1.0, v136
	v_add_f32_e32 v137, 1.0, v137
	v_add_f32_e32 v138, 1.0, v138
	v_add_f32_e32 v139, 1.0, v139
	v_mul_f32_e32 v88, v88, v136
	v_mul_f32_e32 v89, v89, v137
	v_mul_f32_e32 v90, v90, v138
	v_mul_f32_e32 v91, v91, v139
	global_load_dwordx4 v[136:139], v129, s[24:25] offset:3072
	s_waitcnt vmcnt(0)
	v_add_f32_e32 v136, 1.0, v136
	v_add_f32_e32 v137, 1.0, v137
	v_add_f32_e32 v138, 1.0, v138
	v_add_f32_e32 v139, 1.0, v139
	v_mul_f32_e32 v92, v92, v136
	v_mul_f32_e32 v93, v93, v137
	v_mul_f32_e32 v94, v94, v138
	v_mul_f32_e32 v95, v95, v139
.Lp1_np5:
	s_waitcnt vmcnt(16)
	v_mul_f32_e32 v140, v32, v32
	v_mul_f32_e32 v141, v33, v33
	v_fmac_f32_e32 v140, v34, v34
	v_fmac_f32_e32 v141, v35, v35
	v_fmac_f32_e32 v140, v36, v36
	v_fmac_f32_e32 v141, v37, v37
	v_fmac_f32_e32 v140, v38, v38
	v_fmac_f32_e32 v141, v39, v39
	v_fmac_f32_e32 v140, v40, v40
	v_fmac_f32_e32 v141, v41, v41
	v_fmac_f32_e32 v140, v42, v42
	v_fmac_f32_e32 v141, v43, v43
	v_fmac_f32_e32 v140, v44, v44
	v_fmac_f32_e32 v141, v45, v45
	v_fmac_f32_e32 v140, v46, v46
	v_fmac_f32_e32 v141, v47, v47
	v_fmac_f32_e32 v140, v48, v48
	v_fmac_f32_e32 v141, v49, v49
	v_fmac_f32_e32 v140, v50, v50
	v_fmac_f32_e32 v141, v51, v51
	v_fmac_f32_e32 v140, v52, v52
	v_fmac_f32_e32 v141, v53, v53
	v_fmac_f32_e32 v140, v54, v54
	v_fmac_f32_e32 v141, v55, v55
	v_fmac_f32_e32 v140, v56, v56
	v_fmac_f32_e32 v141, v57, v57
	v_fmac_f32_e32 v140, v58, v58
	v_fmac_f32_e32 v141, v59, v59
	v_fmac_f32_e32 v140, v60, v60
	v_fmac_f32_e32 v141, v61, v61
	v_fmac_f32_e32 v140, v62, v62
	v_fmac_f32_e32 v141, v63, v63
	v_add_f32_e32 v140, v140, v141
	s_nop 1
	v_add_f32_dpp v142, v140, v140 quad_perm:[1,0,3,2] row_mask:0xf bank_mask:0xf
	s_nop 1
	v_add_f32_dpp v142, v142, v142 quad_perm:[2,3,0,1] row_mask:0xf bank_mask:0xf
	s_nop 1
	v_add_f32_dpp v142, v142, v142 row_half_mirror row_mask:0xf bank_mask:0xf
	s_nop 1
	v_add_f32_dpp v142, v142, v142 row_mirror row_mask:0xf bank_mask:0xf
	s_nop 1
	v_readlane_b32 s20, v142, 0
	v_readlane_b32 s21, v142, 16
	v_readlane_b32 s22, v142, 32
	v_readlane_b32 s23, v142, 48
	s_nop 1
	v_mov_b32_e32 v143, s20
	v_add_f32_e32 v143, s21, v143
	v_add_f32_e32 v143, s22, v143
	v_add_f32_e32 v143, s23, v143
	v_fmamk_f32 v143, v143, 0x3a000000, v131
	v_rsq_f32_e32 v143, v143
	s_nop 0
	s_add_i32 s4, s6, 5
	s_lshl_b32 s5, s4, 12
	s_add_u32 s14, s84, s5
	s_addc_u32 s15, s85, 0
	s_add_u32 s14, s14, 0x4000000
	s_addc_u32 s15, s15, 0
	v_mul_f32_e32 v136, v143, v32
	v_mul_f32_e32 v137, v143, v33
	v_mul_f32_e32 v138, v143, v34
	v_mul_f32_e32 v139, v143, v35
	v_fma_f32 v136, v136, v64, v96
	v_fma_f32 v137, v137, v65, v97
	v_fma_f32 v138, v138, v66, v98
	v_fma_f32 v139, v139, v67, v99
	v_cvt_pk_bf16_f32 v132, v136, v137
	v_cvt_pk_bf16_f32 v133, v138, v139
	global_store_dwordx2 v130, v[132:133], s[14:15] offset:0
	v_mul_f32_e32 v136, v143, v36
	v_mul_f32_e32 v137, v143, v37
	v_mul_f32_e32 v138, v143, v38
	v_mul_f32_e32 v139, v143, v39
	v_fma_f32 v136, v136, v68, v100
	v_fma_f32 v137, v137, v69, v101
	v_fma_f32 v138, v138, v70, v102
	v_fma_f32 v139, v139, v71, v103
	v_cvt_pk_bf16_f32 v134, v136, v137
	v_cvt_pk_bf16_f32 v135, v138, v139
	global_store_dwordx2 v130, v[134:135], s[14:15] offset:512
	v_mul_f32_e32 v136, v143, v40
	v_mul_f32_e32 v137, v143, v41
	v_mul_f32_e32 v138, v143, v42
	v_mul_f32_e32 v139, v143, v43
	v_fma_f32 v136, v136, v72, v104
	v_fma_f32 v137, v137, v73, v105
	v_fma_f32 v138, v138, v74, v106
	v_fma_f32 v139, v139, v75, v107
	v_cvt_pk_bf16_f32 v132, v136, v137
	v_cvt_pk_bf16_f32 v133, v138, v139
	global_store_dwordx2 v130, v[132:133], s[14:15] offset:1024
	v_mul_f32_e32 v136, v143, v44
	v_mul_f32_e32 v137, v143, v45
	v_mul_f32_e32 v138, v143, v46
	v_mul_f32_e32 v139, v143, v47
	v_fma_f32 v136, v136, v76, v108
	v_fma_f32 v137, v137, v77, v109
	v_fma_f32 v138, v138, v78, v110
	v_fma_f32 v139, v139, v79, v111
	v_cvt_pk_bf16_f32 v134, v136, v137
	v_cvt_pk_bf16_f32 v135, v138, v139
	global_store_dwordx2 v130, v[134:135], s[14:15] offset:1536
	v_mul_f32_e32 v136, v143, v48
; __device__ __forceinline__ unsigned cvt_pk_bf16(float lo, float hi) { unsigned r; asm volatile("v_cvt_pk_bf16_f32 %0, %1, %2" : "=v"(r) : "v"(lo), "v"(hi)); return r; }
; __device__ __forceinline__ void modulate_store(const f32x4 (&v)[8], float rstd, const float* pn, const float* modr, bf16_t* orow, int lane) {
; #pragma unroll
;     for (int j = 0; j < 8; ++j) { const int col = 4 * lane + 256 * j;
;         const f32x4 g = *(const f32x4*)(pn + col), sh = *(const f32x4*)(modr + col), sc = *(const f32x4*)(modr + DM + col);
;         const f32x4 hh = v[j] * rstd * g * (sc + 1.f) + sh;
;         u32x2 w; w.x = cvt_pk_bf16(hh[0], hh[1]); w.y = cvt_pk_bf16(hh[2], hh[3]);
;         *(u32x2*)(orow + col) = w; }
; __global__ void __launch_bounds__(NWAVES * 64, 2) mk_fwd(Args args) {
;     ...
;             for (int q = 0; q < 3; ++q) { const int row = row0 + q; const float* src = row < ML ? x + (size_t)row * DM : ctx + (size_t)(row - ML) * DM; load_row_f32(src, F.lane, v[q]); }
; #pragma unroll
;             for (int q = 0; q < 3; ++q) { const int row = row0 + q; const int r = row < ML ? row / SEQ : 8;
;                 const float rstd = __builtin_amdgcn_rsqf(sumsq8(v[q]) * (1.f / DM) + EPS);
;                 modulate_store(v[q], rstd, pre_norm, mod + (size_t)r * 6144, H + (size_t)row * DM, F.lane); }
	v_mul_f32_e32 v137, v143, v49
	v_mul_f32_e32 v138, v143, v50
	v_mul_f32_e32 v139, v143, v51
	v_fma_f32 v136, v136, v80, v112
	v_fma_f32 v137, v137, v81, v113
	v_fma_f32 v138, v138, v82, v114
	v_fma_f32 v139, v139, v83, v115
	v_cvt_pk_bf16_f32 v132, v136, v137
	v_cvt_pk_bf16_f32 v133, v138, v139
	global_store_dwordx2 v130, v[132:133], s[14:15] offset:2048
	v_mul_f32_e32 v136, v143, v52
	v_mul_f32_e32 v137, v143, v53
	v_mul_f32_e32 v138, v143, v54
	v_mul_f32_e32 v139, v143, v55
	v_fma_f32 v136, v136, v84, v116
	v_fma_f32 v137, v137, v85, v117
	v_fma_f32 v138, v138, v86, v118
	v_fma_f32 v139, v139, v87, v119
	v_cvt_pk_bf16_f32 v134, v136, v137
	v_cvt_pk_bf16_f32 v135, v138, v139
	global_store_dwordx2 v130, v[134:135], s[14:15] offset:2560
	v_mul_f32_e32 v136, v143, v56
	v_mul_f32_e32 v137, v143, v57
	v_mul_f32_e32 v138, v143, v58
	v_mul_f32_e32 v139, v143, v59
	v_fma_f32 v136, v136, v88, v120
	v_fma_f32 v137, v137, v89, v121
	v_fma_f32 v138, v138, v90, v122
	v_fma_f32 v139, v139, v91, v123
	v_cvt_pk_bf16_f32 v132, v136, v137
	v_cvt_pk_bf16_f32 v133, v138, v139
	global_store_dwordx2 v130, v[132:133], s[14:15] offset:3072
	v_mul_f32_e32 v136, v143, v60
	v_mul_f32_e32 v137, v143, v61
	v_mul_f32_e32 v138, v143, v62
	v_mul_f32_e32 v139, v143, v63
	v_fma_f32 v136, v136, v92, v124
	v_fma_f32 v137, v137, v93, v125
	v_fma_f32 v138, v138, v94, v126
	v_fma_f32 v139, v139, v95, v127
	v_cvt_pk_bf16_f32 v134, v136, v137
	v_cvt_pk_bf16_f32 v135, v138, v139
	global_store_dwordx2 v130, v[134:135], s[14:15] offset:3584
	s_add_i32 s4, s6, 7
	s_cmp_lt_u32 s4, 0x4000
	s_cselect_b32 s10, s68, s72
	s_cselect_b32 s11, s69, s73
	s_cselect_b32 s5, 0, 0x4000
	s_sub_i32 s5, s4, s5
	s_lshl_b32 s5, s5, 13
	s_add_u32 s10, s10, s5
	s_addc_u32 s11, s11, 0
	global_load_dwordx4 v[32:35], v128, s[10:11] offset:0 nt
	global_load_dwordx4 v[36:39], v128, s[10:11] offset:1024 nt
	global_load_dwordx4 v[40:43], v128, s[10:11] offset:2048 nt
	global_load_dwordx4 v[44:47], v128, s[10:11] offset:3072 nt
	global_load_dwordx4 v[48:51], v129, s[10:11] offset:0 nt
	global_load_dwordx4 v[52:55], v129, s[10:11] offset:1024 nt
	global_load_dwordx4 v[56:59], v129, s[10:11] offset:2048 nt
	global_load_dwordx4 v[60:63], v129, s[10:11] offset:3072 nt
	s_add_i32 s4, s6, 6
	s_add_i32 s4, s6, 6
	s_lshr_b32 s8, s4, 11
	s_cmp_lt_u32 s4, 0x4000
	s_cselect_b32 s8, s8, 8
	s_cmp_eq_u32 s8, s7
	s_cbranch_scc1 .Lp1_np6
	s_mov_b32 s7, s8
	s_add_i32 s5, s8, 0
	s_mul_i32 s5, s5, 0x6000
	s_add_u32 s24, s84, s5
	s_addc_u32 s25, s85, 0
	s_add_u32 s24, s24, 0x2000
	s_addc_u32 s25, s25, 0
	s_add_i32 s5, s8, 0
	s_mul_i32 s5, s5, 0x6000
	s_add_u32 s16, s84, s5
	s_addc_u32 s17, s85, 0
	s_add_u32 s18, s80, 0x0
	s_addc_u32 s19, s81, 0
	global_load_dwordx4 v[64:67], v128, s[18:19] offset:0
	global_load_dwordx4 v[96:99], v128, s[16:17] offset:0
	global_load_dwordx4 v[68:71], v128, s[18:19] offset:1024
	global_load_dwordx4 v[100:103], v128, s[16:17] offset:1024
	global_load_dwordx4 v[72:75], v128, s[18:19] offset:2048
	global_load_dwordx4 v[104:107], v128, s[16:17] offset:2048
	global_load_dwordx4 v[76:79], v128, s[18:19] offset:3072
	global_load_dwordx4 v[108:111], v128, s[16:17] offset:3072
	global_load_dwordx4 v[80:83], v129, s[18:19] offset:0
	global_load_dwordx4 v[112:115], v129, s[16:17] offset:0
	global_load_dwordx4 v[84:87], v129, s[18:19] offset:1024
	global_load_dwordx4 v[116:119], v129, s[16:17] offset:1024
	global_load_dwordx4 v[88:91], v129, s[18:19] offset:2048
	global_load_dwordx4 v[120:123], v129, s[16:17] offset:2048
	global_load_dwordx4 v[92:95], v129, s[18:19] offset:3072
	global_load_dwordx4 v[124:127], v129, s[16:17] offset:3072
	global_load_dwordx4 v[136:139], v128, s[24:25] offset:0
	s_waitcnt vmcnt(0)
	v_add_f32_e32 v136, 1.0, v136
	v_add_f32_e32 v137, 1.0, v137
	v_add_f32_e32 v138, 1.0, v138
	v_add_f32_e32 v139, 1.0, v139
	v_mul_f32_e32 v64, v64, v136
	v_mul_f32_e32 v65, v65, v137
	v_mul_f32_e32 v66, v66, v138
	v_mul_f32_e32 v67, v67, v139
	global_load_dwordx4 v[136:139], v128, s[24:25] offset:1024
	s_waitcnt vmcnt(0)
	v_add_f32_e32 v136, 1.0, v136
	v_add_f32_e32 v137, 1.0, v137
	v_add_f32_e32 v138, 1.0, v138
	v_add_f32_e32 v139, 1.0, v139
	v_mul_f32_e32 v68, v68, v136
	v_mul_f32_e32 v69, v69, v137
	v_mul_f32_e32 v70, v70, v138
	v_mul_f32_e32 v71, v71, v139
	global_load_dwordx4 v[136:139], v128, s[24:25] offset:2048
	s_waitcnt vmcnt(0)
	v_add_f32_e32 v136, 1.0, v136
	v_add_f32_e32 v137, 1.0, v137
	v_add_f32_e32 v138, 1.0, v138
	v_add_f32_e32 v139, 1.0, v139
	v_mul_f32_e32 v72, v72, v136
	v_mul_f32_e32 v73, v73, v137
	v_mul_f32_e32 v74, v74, v138
	v_mul_f32_e32 v75, v75, v139
	global_load_dwordx4 v[136:139], v128, s[24:25] offset:3072
	s_waitcnt vmcnt(0)
	v_add_f32_e32 v136, 1.0, v136
	v_add_f32_e32 v137, 1.0, v137
	v_add_f32_e32 v138, 1.0, v138
	v_add_f32_e32 v139, 1.0, v139
	v_mul_f32_e32 v76, v76, v136
	v_mul_f32_e32 v77, v77, v137
	v_mul_f32_e32 v78, v78, v138
	v_mul_f32_e32 v79, v79, v139
	global_load_dwordx4 v[136:139], v129, s[24:25] offset:0
	s_waitcnt vmcnt(0)
	v_add_f32_e32 v136, 1.0, v136
	v_add_f32_e32 v137, 1.0, v137
	v_add_f32_e32 v138, 1.0, v138
	v_add_f32_e32 v139, 1.0, v139
	v_mul_f32_e32 v80, v80, v136
	v_mul_f32_e32 v81, v81, v137
	v_mul_f32_e32 v82, v82, v138
	v_mul_f32_e32 v83, v83, v139
	global_load_dwordx4 v[136:139], v129, s[24:25] offset:1024
	s_waitcnt vmcnt(0)
	v_add_f32_e32 v136, 1.0, v136
	v_add_f32_e32 v137, 1.0, v137
	v_add_f32_e32 v138, 1.0, v138
	v_add_f32_e32 v139, 1.0, v139
	v_mul_f32_e32 v84, v84, v136
	v_mul_f32_e32 v85, v85, v137
	v_mul_f32_e32 v86, v86, v138
	v_mul_f32_e32 v87, v87, v139
	global_load_dwordx4 v[136:139], v129, s[24:25] offset:2048
	s_waitcnt vmcnt(0)
	v_add_f32_e32 v136, 1.0, v136
	v_add_f32_e32 v137, 1.0, v137
	v_add_f32_e32 v138, 1.0, v138
	v_add_f32_e32 v139, 1.0, v139
	v_mul_f32_e32 v88, v88, v136
	v_mul_f32_e32 v89, v89, v137
	v_mul_f32_e32 v90, v90, v138
	v_mul_f32_e32 v91, v91, v139
	global_load_dwordx4 v[136:139], v129, s[24:25] offset:3072
	s_waitcnt vmcnt(0)
	v_add_f32_e32 v136, 1.0, v136
	v_add_f32_e32 v137, 1.0, v137
	v_add_f32_e32 v138, 1.0, v138
	v_add_f32_e32 v139, 1.0, v139
	v_mul_f32_e32 v92, v92, v136
	v_mul_f32_e32 v93, v93, v137
	v_mul_f32_e32 v94, v94, v138
	v_mul_f32_e32 v95, v95, v139
; __device__ __forceinline__ unsigned cvt_pk_bf16(float lo, float hi) { unsigned r; asm volatile("v_cvt_pk_bf16_f32 %0, %1, %2" : "=v"(r) : "v"(lo), "v"(hi)); return r; }
; __device__ __forceinline__ void load_row_f32(const float* p, int lane, f32x4 (&v)[8]) {
; #pragma unroll
;     for (int j = 0; j < 8; ++j) v[j] = *(const f32x4*)(p + 4 * lane + 256 * j);
; }
; __device__ __forceinline__ float sumsq8(const f32x4 (&v)[8]) {
;     float s = 0.f;
; #pragma unroll
;     for (int j = 0; j < 8; ++j) s += (v[j][0] * v[j][0] + v[j][1] * v[j][1]) + (v[j][2] * v[j][2] + v[j][3] * v[j][3]);
;     return wave_sum(s);
; }
; __device__ __forceinline__ void modulate_store(const f32x4 (&v)[8], float rstd, const float* pn, const float* modr, bf16_t* orow, int lane) {
; #pragma unroll
;     for (int j = 0; j < 8; ++j) { const int col = 4 * lane + 256 * j;
;         const f32x4 g = *(const f32x4*)(pn + col), sh = *(const f32x4*)(modr + col), sc = *(const f32x4*)(modr + DM + col);
;         const f32x4 hh = v[j] * rstd * g * (sc + 1.f) + sh;
;         u32x2 w; w.x = cvt_pk_bf16(hh[0], hh[1]); w.y = cvt_pk_bf16(hh[2], hh[3]);
;         *(u32x2*)(orow + col) = w; }
; __global__ void __launch_bounds__(NWAVES * 64, 2) mk_fwd(Args args) {
;     ...
;             for (int q = 0; q < 3; ++q) { const int row = row0 + q; const float* src = row < ML ? x + (size_t)row * DM : ctx + (size_t)(row - ML) * DM; load_row_f32(src, F.lane, v[q]); }
; #pragma unroll
;             for (int q = 0; q < 3; ++q) { const int row = row0 + q; const int r = row < ML ? row / SEQ : 8;
;                 const float rstd = __builtin_amdgcn_rsqf(sumsq8(v[q]) * (1.f / DM) + EPS);
;                 modulate_store(v[q], rstd, pre_norm, mod + (size_t)r * 6144, H + (size_t)row * DM, F.lane); }
.Lp1_np6:
	s_waitcnt vmcnt(16)
	v_mul_f32_e32 v140, v0, v0
	v_mul_f32_e32 v141, v1, v1
	v_fmac_f32_e32 v140, v2, v2
	v_fmac_f32_e32 v141, v3, v3
	v_fmac_f32_e32 v140, v4, v4
	v_fmac_f32_e32 v141, v5, v5
	v_fmac_f32_e32 v140, v6, v6
	v_fmac_f32_e32 v141, v7, v7
	v_fmac_f32_e32 v140, v8, v8
	v_fmac_f32_e32 v141, v9, v9
	v_fmac_f32_e32 v140, v10, v10
	v_fmac_f32_e32 v141, v11, v11
	v_fmac_f32_e32 v140, v12, v12
	v_fmac_f32_e32 v141, v13, v13
	v_fmac_f32_e32 v140, v14, v14
	v_fmac_f32_e32 v141, v15, v15
	v_fmac_f32_e32 v140, v16, v16
	v_fmac_f32_e32 v141, v17, v17
	v_fmac_f32_e32 v140, v18, v18
	v_fmac_f32_e32 v141, v19, v19
	v_fmac_f32_e32 v140, v20, v20
	v_fmac_f32_e32 v141, v21, v21
	v_fmac_f32_e32 v140, v22, v22
	v_fmac_f32_e32 v141, v23, v23
	v_fmac_f32_e32 v140, v24, v24
	v_fmac_f32_e32 v141, v25, v25
	v_fmac_f32_e32 v140, v26, v26
	v_fmac_f32_e32 v141, v27, v27
	v_fmac_f32_e32 v140, v28, v28
	v_fmac_f32_e32 v141, v29, v29
	v_fmac_f32_e32 v140, v30, v30
	v_fmac_f32_e32 v141, v31, v31
	v_add_f32_e32 v140, v140, v141
	s_nop 1
	v_add_f32_dpp v142, v140, v140 quad_perm:[1,0,3,2] row_mask:0xf bank_mask:0xf
	s_nop 1
	v_add_f32_dpp v142, v142, v142 quad_perm:[2,3,0,1] row_mask:0xf bank_mask:0xf
	s_nop 1
	v_add_f32_dpp v142, v142, v142 row_half_mirror row_mask:0xf bank_mask:0xf
	s_nop 1
	v_add_f32_dpp v142, v142, v142 row_mirror row_mask:0xf bank_mask:0xf
	s_nop 1
	v_readlane_b32 s20, v142, 0
	v_readlane_b32 s21, v142, 16
	v_readlane_b32 s22, v142, 32
	v_readlane_b32 s23, v142, 48
	s_nop 1
	v_mov_b32_e32 v143, s20
	v_add_f32_e32 v143, s21, v143
	v_add_f32_e32 v143, s22, v143
	v_add_f32_e32 v143, s23, v143
	v_fmamk_f32 v143, v143, 0x3a000000, v131
	v_rsq_f32_e32 v143, v143
	s_nop 0
	s_add_i32 s4, s6, 6
	s_lshl_b32 s5, s4, 12
	s_add_u32 s14, s84, s5
	s_addc_u32 s15, s85, 0
	s_add_u32 s14, s14, 0x4000000
	s_addc_u32 s15, s15, 0
	v_mul_f32_e32 v136, v143, v0
	v_mul_f32_e32 v137, v143, v1
	v_mul_f32_e32 v138, v143, v2
	v_mul_f32_e32 v139, v143, v3
	v_fma_f32 v136, v136, v64, v96
	v_fma_f32 v137, v137, v65, v97
	v_fma_f32 v138, v138, v66, v98
	v_fma_f32 v139, v139, v67, v99
	v_cvt_pk_bf16_f32 v132, v136, v137
	v_cvt_pk_bf16_f32 v133, v138, v139
	global_store_dwordx2 v130, v[132:133], s[14:15] offset:0
	v_mul_f32_e32 v136, v143, v4
	v_mul_f32_e32 v137, v143, v5
	v_mul_f32_e32 v138, v143, v6
	v_mul_f32_e32 v139, v143, v7
	v_fma_f32 v136, v136, v68, v100
	v_fma_f32 v137, v137, v69, v101
	v_fma_f32 v138, v138, v70, v102
	v_fma_f32 v139, v139, v71, v103
	v_cvt_pk_bf16_f32 v134, v136, v137
	v_cvt_pk_bf16_f32 v135, v138, v139
	global_store_dwordx2 v130, v[134:135], s[14:15] offset:512
	v_mul_f32_e32 v136, v143, v8
	v_mul_f32_e32 v137, v143, v9
	v_mul_f32_e32 v138, v143, v10
	v_mul_f32_e32 v139, v143, v11
	v_fma_f32 v136, v136, v72, v104
	v_fma_f32 v137, v137, v73, v105
	v_fma_f32 v138, v138, v74, v106
	v_fma_f32 v139, v139, v75, v107
	v_cvt_pk_bf16_f32 v132, v136, v137
	v_cvt_pk_bf16_f32 v133, v138, v139
	global_store_dwordx2 v130, v[132:133], s[14:15] offset:1024
	v_mul_f32_e32 v136, v143, v12
	v_mul_f32_e32 v137, v143, v13
	v_mul_f32_e32 v138, v143, v14
	v_mul_f32_e32 v139, v143, v15
	v_fma_f32 v136, v136, v76, v108
	v_fma_f32 v137, v137, v77, v109
	v_fma_f32 v138, v138, v78, v110
	v_fma_f32 v139, v139, v79, v111
	v_cvt_pk_bf16_f32 v134, v136, v137
	v_cvt_pk_bf16_f32 v135, v138, v139
	global_store_dwordx2 v130, v[134:135], s[14:15] offset:1536
	v_mul_f32_e32 v136, v143, v16
	v_mul_f32_e32 v137, v143, v17
	v_mul_f32_e32 v138, v143, v18
	v_mul_f32_e32 v139, v143, v19
	v_fma_f32 v136, v136, v80, v112
	v_fma_f32 v137, v137, v81, v113
	v_fma_f32 v138, v138, v82, v114
	v_fma_f32 v139, v139, v83, v115
	v_cvt_pk_bf16_f32 v132, v136, v137
	v_cvt_pk_bf16_f32 v133, v138, v139
	global_store_dwordx2 v130, v[132:133], s[14:15] offset:2048
	v_mul_f32_e32 v136, v143, v20
	v_mul_f32_e32 v137, v143, v21
	v_mul_f32_e32 v138, v143, v22
	v_mul_f32_e32 v139, v143, v23
	v_fma_f32 v136, v136, v84, v116
	v_fma_f32 v137, v137, v85, v117
	v_fma_f32 v138, v138, v86, v118
	v_fma_f32 v139, v139, v87, v119
	v_cvt_pk_bf16_f32 v134, v136, v137
	v_cvt_pk_bf16_f32 v135, v138, v139
	global_store_dwordx2 v130, v[134:135], s[14:15] offset:2560
	v_mul_f32_e32 v136, v143, v24
	v_mul_f32_e32 v137, v143, v25
	v_mul_f32_e32 v138, v143, v26
	v_mul_f32_e32 v139, v143, v27
	v_fma_f32 v136, v136, v88, v120
	v_fma_f32 v137, v137, v89, v121
	v_fma_f32 v138, v138, v90, v122
	v_fma_f32 v139, v139, v91, v123
	v_cvt_pk_bf16_f32 v132, v136, v137
	v_cvt_pk_bf16_f32 v133, v138, v139
	global_store_dwordx2 v130, v[132:133], s[14:15] offset:3072
	v_mul_f32_e32 v136, v143, v28
	v_mul_f32_e32 v137, v143, v29
	v_mul_f32_e32 v138, v143, v30
	v_mul_f32_e32 v139, v143, v31
	v_fma_f32 v136, v136, v92, v124
	v_fma_f32 v137, v137, v93, v125
	v_fma_f32 v138, v138, v94, v126
	v_fma_f32 v139, v139, v95, v127
	v_cvt_pk_bf16_f32 v134, v136, v137
	v_cvt_pk_bf16_f32 v135, v138, v139
	global_store_dwordx2 v130, v[134:135], s[14:15] offset:3584
	s_add_i32 s4, s6, 8
	s_cmp_lt_u32 s4, 0x4000
	s_cselect_b32 s10, s68, s72
	s_cselect_b32 s11, s69, s73
	s_cselect_b32 s5, 0, 0x4000
	s_sub_i32 s5, s4, s5
	s_lshl_b32 s5, s5, 13
	s_add_u32 s10, s10, s5
	s_addc_u32 s11, s11, 0
	global_load_dwordx4 v[0:3], v128, s[10:11] offset:0 nt
	global_load_dwordx4 v[4:7], v128, s[10:11] offset:1024 nt
	global_load_dwordx4 v[8:11], v128, s[10:11] offset:2048 nt
	global_load_dwordx4 v[12:15], v128, s[10:11] offset:3072 nt
	global_load_dwordx4 v[16:19], v129, s[10:11] offset:0 nt
	global_load_dwordx4 v[20:23], v129, s[10:11] offset:1024 nt
	global_load_dwordx4 v[24:27], v129, s[10:11] offset:2048 nt
	global_load_dwordx4 v[28:31], v129, s[10:11] offset:3072 nt
	s_add_i32 s4, s6, 7
	s_add_i32 s4, s6, 7
	s_lshr_b32 s8, s4, 11
	s_cmp_lt_u32 s4, 0x4000
	s_cselect_b32 s8, s8, 8
	s_cmp_eq_u32 s8, s7
	s_cbranch_scc1 .Lp1_np7
; __device__ __forceinline__ unsigned cvt_pk_bf16(float lo, float hi) { unsigned r; asm volatile("v_cvt_pk_bf16_f32 %0, %1, %2" : "=v"(r) : "v"(lo), "v"(hi)); return r; }
; __device__ __forceinline__ void modulate_store(const f32x4 (&v)[8], float rstd, const float* pn, const float* modr, bf16_t* orow, int lane) {
; #pragma unroll
;     for (int j = 0; j < 8; ++j) { const int col = 4 * lane + 256 * j;
;         const f32x4 g = *(const f32x4*)(pn + col), sh = *(const f32x4*)(modr + col), sc = *(const f32x4*)(modr + DM + col);
;         const f32x4 hh = v[j] * rstd * g * (sc + 1.f) + sh;
;         u32x2 w; w.x = cvt_pk_bf16(hh[0], hh[1]); w.y = cvt_pk_bf16(hh[2], hh[3]);
;         *(u32x2*)(orow + col) = w; }
; __global__ void __launch_bounds__(NWAVES * 64, 2) mk_fwd(Args args) {
;     ...
;             for (int q = 0; q < 3; ++q) { const int row = row0 + q; const int r = row < ML ? row / SEQ : 8;
;                 const float rstd = __builtin_amdgcn_rsqf(sumsq8(v[q]) * (1.f / DM) + EPS);
;                 modulate_store(v[q], rstd, pre_norm, mod + (size_t)r * 6144, H + (size_t)row * DM, F.lane); }
	s_mov_b32 s7, s8
	s_add_i32 s5, s8, 0
	s_mul_i32 s5, s5, 0x6000
	s_add_u32 s24, s84, s5
	s_addc_u32 s25, s85, 0
	s_add_u32 s24, s24, 0x2000
	s_addc_u32 s25, s25, 0
	s_add_i32 s5, s8, 0
	s_mul_i32 s5, s5, 0x6000
	s_add_u32 s16, s84, s5
	s_addc_u32 s17, s85, 0
	s_add_u32 s18, s80, 0x0
	s_addc_u32 s19, s81, 0
	global_load_dwordx4 v[64:67], v128, s[18:19] offset:0
	global_load_dwordx4 v[96:99], v128, s[16:17] offset:0
	global_load_dwordx4 v[68:71], v128, s[18:19] offset:1024
	global_load_dwordx4 v[100:103], v128, s[16:17] offset:1024
	global_load_dwordx4 v[72:75], v128, s[18:19] offset:2048
	global_load_dwordx4 v[104:107], v128, s[16:17] offset:2048
	global_load_dwordx4 v[76:79], v128, s[18:19] offset:3072
	global_load_dwordx4 v[108:111], v128, s[16:17] offset:3072
	global_load_dwordx4 v[80:83], v129, s[18:19] offset:0
	global_load_dwordx4 v[112:115], v129, s[16:17] offset:0
	global_load_dwordx4 v[84:87], v129, s[18:19] offset:1024
	global_load_dwordx4 v[116:119], v129, s[16:17] offset:1024
	global_load_dwordx4 v[88:91], v129, s[18:19] offset:2048
	global_load_dwordx4 v[120:123], v129, s[16:17] offset:2048
	global_load_dwordx4 v[92:95], v129, s[18:19] offset:3072
	global_load_dwordx4 v[124:127], v129, s[16:17] offset:3072
	global_load_dwordx4 v[136:139], v128, s[24:25] offset:0
	s_waitcnt vmcnt(0)
	v_add_f32_e32 v136, 1.0, v136
	v_add_f32_e32 v137, 1.0, v137
	v_add_f32_e32 v138, 1.0, v138
	v_add_f32_e32 v139, 1.0, v139
	v_mul_f32_e32 v64, v64, v136
	v_mul_f32_e32 v65, v65, v137
	v_mul_f32_e32 v66, v66, v138
	v_mul_f32_e32 v67, v67, v139
	global_load_dwordx4 v[136:139], v128, s[24:25] offset:1024
	s_waitcnt vmcnt(0)
	v_add_f32_e32 v136, 1.0, v136
	v_add_f32_e32 v137, 1.0, v137
	v_add_f32_e32 v138, 1.0, v138
	v_add_f32_e32 v139, 1.0, v139
	v_mul_f32_e32 v68, v68, v136
	v_mul_f32_e32 v69, v69, v137
	v_mul_f32_e32 v70, v70, v138
	v_mul_f32_e32 v71, v71, v139
	global_load_dwordx4 v[136:139], v128, s[24:25] offset:2048
	s_waitcnt vmcnt(0)
	v_add_f32_e32 v136, 1.0, v136
	v_add_f32_e32 v137, 1.0, v137
	v_add_f32_e32 v138, 1.0, v138
	v_add_f32_e32 v139, 1.0, v139
	v_mul_f32_e32 v72, v72, v136
	v_mul_f32_e32 v73, v73, v137
	v_mul_f32_e32 v74, v74, v138
	v_mul_f32_e32 v75, v75, v139
	global_load_dwordx4 v[136:139], v128, s[24:25] offset:3072
	s_waitcnt vmcnt(0)
	v_add_f32_e32 v136, 1.0, v136
	v_add_f32_e32 v137, 1.0, v137
	v_add_f32_e32 v138, 1.0, v138
	v_add_f32_e32 v139, 1.0, v139
	v_mul_f32_e32 v76, v76, v136
	v_mul_f32_e32 v77, v77, v137
	v_mul_f32_e32 v78, v78, v138
	v_mul_f32_e32 v79, v79, v139
	global_load_dwordx4 v[136:139], v129, s[24:25] offset:0
	s_waitcnt vmcnt(0)
	v_add_f32_e32 v136, 1.0, v136
	v_add_f32_e32 v137, 1.0, v137
	v_add_f32_e32 v138, 1.0, v138
	v_add_f32_e32 v139, 1.0, v139
	v_mul_f32_e32 v80, v80, v136
	v_mul_f32_e32 v81, v81, v137
	v_mul_f32_e32 v82, v82, v138
	v_mul_f32_e32 v83, v83, v139
	global_load_dwordx4 v[136:139], v129, s[24:25] offset:1024
	s_waitcnt vmcnt(0)
	v_add_f32_e32 v136, 1.0, v136
	v_add_f32_e32 v137, 1.0, v137
	v_add_f32_e32 v138, 1.0, v138
	v_add_f32_e32 v139, 1.0, v139
	v_mul_f32_e32 v84, v84, v136
	v_mul_f32_e32 v85, v85, v137
	v_mul_f32_e32 v86, v86, v138
	v_mul_f32_e32 v87, v87, v139
	global_load_dwordx4 v[136:139], v129, s[24:25] offset:2048
	s_waitcnt vmcnt(0)
	v_add_f32_e32 v136, 1.0, v136
	v_add_f32_e32 v137, 1.0, v137
	v_add_f32_e32 v138, 1.0, v138
	v_add_f32_e32 v139, 1.0, v139
	v_mul_f32_e32 v88, v88, v136
	v_mul_f32_e32 v89, v89, v137
	v_mul_f32_e32 v90, v90, v138
	v_mul_f32_e32 v91, v91, v139
	global_load_dwordx4 v[136:139], v129, s[24:25] offset:3072
	s_waitcnt vmcnt(0)
	v_add_f32_e32 v136, 1.0, v136
	v_add_f32_e32 v137, 1.0, v137
	v_add_f32_e32 v138, 1.0, v138
	v_add_f32_e32 v139, 1.0, v139
	v_mul_f32_e32 v92, v92, v136
	v_mul_f32_e32 v93, v93, v137
	v_mul_f32_e32 v94, v94, v138
	v_mul_f32_e32 v95, v95, v139

; __global__ void __launch_bounds__(NWAVES * 64, 2) mk_fwd(Args args) {
;     ...
;         for (int row0 = F.gw * 3; row0 < MT; row0 += F.NGW * 3) {
;             f32x4 v[3][8]; u32x2 yw[3][8];
; #pragma unroll
;             for (int q = 0; q < 3; ++q) { const int row = row0 + q; const float* src = row < ML ? x + (size_t)row * DM : ctx + (size_t)(row - ML) * DM; load_row_f32(src, F.lane, v[q]);
;                 const bf16_t* yr = Y + (size_t)row * DM;
; #pragma unroll
;                 for (int j = 0; j < 8; ++j) yw[q][j] = *(const u32x2*)(yr + 4 * F.lane + 256 * j); }
;     ...
;                 const float* m0 = mod + (size_t)r * 6144;
; #pragma unroll
;                 for (int j = 0; j < 8; ++j) { const int col = 4 * F.lane + 256 * j; const f32x4 gt = *(const f32x4*)(m0 + 2 * DM + col), pn = *(const f32x4*)(post_norm + col);
.LBB0_716:
	s_cmp_lt_i32 s86, 7
	s_cselect_b64 s[4:5], -1, 0
	s_and_b64 s[0:1], s[4:5], s[0:1]
	s_andn2_b64 vcc, exec, s[0:1]
	s_cbranch_vccnz .LBB0_778
	s_cmpk_lg_i32 s63, 0x100
	s_cbranch_scc1 .Lp6_generic
	v_and_b32_e32 v194, 63, v198
	v_lshlrev_b32_e32 v192, 4, v194
	v_add_u32_e32 v193, 0x1000, v192
	v_lshlrev_b32_e32 v194, 3, v194
	v_mov_b32_e32 v195, 0x358637bd
	s_mul_i32 s6, s33, 9
	s_mov_b32 s7, -1
	s_add_i32 s0, s6, 0
	s_cmp_lt_u32 s0, 0x4000
	s_cselect_b32 s10, s68, s72
	s_cselect_b32 s11, s69, s73
	s_cselect_b32 s1, 0, 0x4000
	s_sub_i32 s1, s0, s1
	s_lshl_b32 s1, s1, 13
	s_add_u32 s10, s10, s1
	s_addc_u32 s11, s11, 0
	s_add_i32 s0, s6, 0
	s_lshl_b32 s1, s0, 12
	s_add_u32 s22, s84, s1
	s_addc_u32 s23, s85, 0
	s_add_u32 s22, s22, 0x11800000
	s_addc_u32 s23, s23, 0
	global_load_dwordx4 v[0:3], v192, s[10:11] offset:0 nt
	global_load_dwordx4 v[4:7], v192, s[10:11] offset:1024 nt
	global_load_dwordx4 v[8:11], v192, s[10:11] offset:2048 nt
	global_load_dwordx4 v[12:15], v192, s[10:11] offset:3072 nt
	global_load_dwordx4 v[16:19], v193, s[10:11] offset:0 nt
	global_load_dwordx4 v[20:23], v193, s[10:11] offset:1024 nt
	global_load_dwordx4 v[24:27], v193, s[10:11] offset:2048 nt
	global_load_dwordx4 v[28:31], v193, s[10:11] offset:3072 nt
	global_load_dwordx2 v[32:33], v194, s[22:23] offset:0
	global_load_dwordx2 v[34:35], v194, s[22:23] offset:512
	global_load_dwordx2 v[36:37], v194, s[22:23] offset:1024
	global_load_dwordx2 v[38:39], v194, s[22:23] offset:1536
	global_load_dwordx2 v[40:41], v194, s[22:23] offset:2048
	global_load_dwordx2 v[42:43], v194, s[22:23] offset:2560
	global_load_dwordx2 v[44:45], v194, s[22:23] offset:3072
	global_load_dwordx2 v[46:47], v194, s[22:23] offset:3584
	s_add_i32 s0, s6, 1
	s_cmp_lt_u32 s0, 0x4000
	s_cselect_b32 s10, s68, s72
	s_cselect_b32 s11, s69, s73
	s_cselect_b32 s1, 0, 0x4000
	s_sub_i32 s1, s0, s1
	s_lshl_b32 s1, s1, 13
	s_add_u32 s10, s10, s1
	s_addc_u32 s11, s11, 0
	s_add_i32 s0, s6, 1
	s_lshl_b32 s1, s0, 12
	s_add_u32 s22, s84, s1
	s_addc_u32 s23, s85, 0
	s_add_u32 s22, s22, 0x11800000
	s_addc_u32 s23, s23, 0
	global_load_dwordx4 v[48:51], v192, s[10:11] offset:0 nt
	global_load_dwordx4 v[52:55], v192, s[10:11] offset:1024 nt
	global_load_dwordx4 v[56:59], v192, s[10:11] offset:2048 nt
	global_load_dwordx4 v[60:63], v192, s[10:11] offset:3072 nt
	global_load_dwordx4 v[64:67], v193, s[10:11] offset:0 nt
	global_load_dwordx4 v[68:71], v193, s[10:11] offset:1024 nt
	global_load_dwordx4 v[72:75], v193, s[10:11] offset:2048 nt
	global_load_dwordx4 v[76:79], v193, s[10:11] offset:3072 nt
	global_load_dwordx2 v[80:81], v194, s[22:23] offset:0
	global_load_dwordx2 v[82:83], v194, s[22:23] offset:512
	global_load_dwordx2 v[84:85], v194, s[22:23] offset:1024
	global_load_dwordx2 v[86:87], v194, s[22:23] offset:1536
	global_load_dwordx2 v[88:89], v194, s[22:23] offset:2048
	global_load_dwordx2 v[90:91], v194, s[22:23] offset:2560
	global_load_dwordx2 v[92:93], v194, s[22:23] offset:3072
	global_load_dwordx2 v[94:95], v194, s[22:23] offset:3584
	s_add_i32 s0, s6, 0
	s_add_i32 s0, s6, 0
	s_lshr_b32 s8, s0, 11
	s_cmp_lt_u32 s0, 0x4000
	s_cselect_b32 s8, s8, 8
	s_cmp_eq_u32 s8, s7
	s_cbranch_scc1 .Lp6_np0
	s_mov_b32 s7, s8
	s_add_i32 s1, s8, 9
	s_mul_i32 s1, s1, 0x6000
	s_add_u32 s44, s84, s1
	s_addc_u32 s45, s85, 0
	s_add_u32 s44, s44, 0x2000
	s_addc_u32 s45, s45, 0
	s_add_i32 s1, s8, 9
	s_mul_i32 s1, s1, 0x6000
	s_add_u32 s36, s84, s1
	s_addc_u32 s37, s85, 0
	s_add_u32 s38, s80, 0x2000
	s_addc_u32 s39, s81, 0
	s_mul_i32 s1, s8, 0x6000
	s_add_u32 s34, s84, s1
	s_addc_u32 s35, s85, 0
	s_add_u32 s34, s34, 0x4000
	s_addc_u32 s35, s35, 0
	global_load_dwordx4 v[96:99], v192, s[34:35] offset:0
	global_load_dwordx4 v[200:203], v192, s[82:83] offset:0
	global_load_dwordx4 v[100:103], v192, s[34:35] offset:1024
	global_load_dwordx4 v[204:207], v192, s[82:83] offset:1024
	global_load_dwordx4 v[104:107], v192, s[34:35] offset:2048
	global_load_dwordx4 v[208:211], v192, s[82:83] offset:2048
	global_load_dwordx4 v[108:111], v192, s[34:35] offset:3072
	global_load_dwordx4 v[212:215], v192, s[82:83] offset:3072
	s_waitcnt vmcnt(0)
	v_mul_f32_e32 v96, v96, v200
	v_mul_f32_e32 v97, v97, v201
	v_mul_f32_e32 v98, v98, v202
	v_mul_f32_e32 v99, v99, v203
	v_mul_f32_e32 v100, v100, v204
	v_mul_f32_e32 v101, v101, v205
	v_mul_f32_e32 v102, v102, v206
	v_mul_f32_e32 v103, v103, v207
	v_mul_f32_e32 v104, v104, v208
	v_mul_f32_e32 v105, v105, v209
	v_mul_f32_e32 v106, v106, v210
	v_mul_f32_e32 v107, v107, v211
	v_mul_f32_e32 v108, v108, v212
	v_mul_f32_e32 v109, v109, v213
	v_mul_f32_e32 v110, v110, v214
	v_mul_f32_e32 v111, v111, v215
	global_load_dwordx4 v[128:131], v192, s[38:39] offset:0
	global_load_dwordx4 v[200:203], v192, s[44:45] offset:0
	global_load_dwordx4 v[160:163], v192, s[36:37] offset:0
	global_load_dwordx4 v[132:135], v192, s[38:39] offset:1024
	global_load_dwordx4 v[204:207], v192, s[44:45] offset:1024
	global_load_dwordx4 v[164:167], v192, s[36:37] offset:1024
	global_load_dwordx4 v[136:139], v192, s[38:39] offset:2048
	global_load_dwordx4 v[208:211], v192, s[44:45] offset:2048
	global_load_dwordx4 v[168:171], v192, s[36:37] offset:2048
	global_load_dwordx4 v[140:143], v192, s[38:39] offset:3072
	global_load_dwordx4 v[212:215], v192, s[44:45] offset:3072
	global_load_dwordx4 v[172:175], v192, s[36:37] offset:3072
	s_waitcnt vmcnt(0)
; __device__ __forceinline__ float bf_lo(unsigned w) { return __uint_as_float(w << 16); }
; __device__ __forceinline__ float bf_hi(unsigned w) { return __uint_as_float(w & 0xffff0000u); }
; __global__ void __launch_bounds__(NWAVES * 64, 2) mk_fwd(Args args) {
;     ...
;             for (int q = 0; q < 3; ++q) { const int row = row0 + q; const bool lat = row < ML; const int r = lat ? row / SEQ : 8;
;                 float sy = 0.f;
; #pragma unroll
;                 for (int j = 0; j < 8; ++j) { const float a = bf_lo(yw[q][j].x), b = bf_hi(yw[q][j].x), c2 = bf_lo(yw[q][j].y), d = bf_hi(yw[q][j].y); sy += (a * a + b * b) + (c2 * c2 + d * d); }
;                 const float rsy = __builtin_amdgcn_rsqf(wave_sum(sy) * (1.f / DM) + EPS);
;                 const float* m0 = mod + (size_t)r * 6144;
; #pragma unroll
;                 for (int j = 0; j < 8; ++j) { const int col = 4 * F.lane + 256 * j; const f32x4 gt = *(const f32x4*)(m0 + 2 * DM + col), pn = *(const f32x4*)(post_norm + col);
	v_add_f32_e32 v200, 1.0, v200
	v_add_f32_e32 v201, 1.0, v201
	v_add_f32_e32 v202, 1.0, v202
	v_add_f32_e32 v203, 1.0, v203
	v_mul_f32_e32 v128, v128, v200
	v_mul_f32_e32 v129, v129, v201
	v_mul_f32_e32 v130, v130, v202
	v_mul_f32_e32 v131, v131, v203
	v_add_f32_e32 v204, 1.0, v204
	v_add_f32_e32 v205, 1.0, v205
	v_add_f32_e32 v206, 1.0, v206
	v_add_f32_e32 v207, 1.0, v207
	v_mul_f32_e32 v132, v132, v204
	v_mul_f32_e32 v133, v133, v205
	v_mul_f32_e32 v134, v134, v206
	v_mul_f32_e32 v135, v135, v207
	v_add_f32_e32 v208, 1.0, v208
	v_add_f32_e32 v209, 1.0, v209
	v_add_f32_e32 v210, 1.0, v210
	v_add_f32_e32 v211, 1.0, v211
	v_mul_f32_e32 v136, v136, v208
	v_mul_f32_e32 v137, v137, v209
	v_mul_f32_e32 v138, v138, v210
	v_mul_f32_e32 v139, v139, v211
	v_add_f32_e32 v212, 1.0, v212
	v_add_f32_e32 v213, 1.0, v213
	v_add_f32_e32 v214, 1.0, v214
	v_add_f32_e32 v215, 1.0, v215
	v_mul_f32_e32 v140, v140, v212
	v_mul_f32_e32 v141, v141, v213
	v_mul_f32_e32 v142, v142, v214
	v_mul_f32_e32 v143, v143, v215
	global_load_dwordx4 v[112:115], v193, s[34:35] offset:0
	global_load_dwordx4 v[200:203], v193, s[82:83] offset:0
	global_load_dwordx4 v[116:119], v193, s[34:35] offset:1024
	global_load_dwordx4 v[204:207], v193, s[82:83] offset:1024
	global_load_dwordx4 v[120:123], v193, s[34:35] offset:2048
	global_load_dwordx4 v[208:211], v193, s[82:83] offset:2048
	global_load_dwordx4 v[124:127], v193, s[34:35] offset:3072
	global_load_dwordx4 v[212:215], v193, s[82:83] offset:3072
	s_waitcnt vmcnt(0)
	v_mul_f32_e32 v112, v112, v200
	v_mul_f32_e32 v113, v113, v201
	v_mul_f32_e32 v114, v114, v202
	v_mul_f32_e32 v115, v115, v203
	v_mul_f32_e32 v116, v116, v204
	v_mul_f32_e32 v117, v117, v205
	v_mul_f32_e32 v118, v118, v206
	v_mul_f32_e32 v119, v119, v207
	v_mul_f32_e32 v120, v120, v208
	v_mul_f32_e32 v121, v121, v209
	v_mul_f32_e32 v122, v122, v210
	v_mul_f32_e32 v123, v123, v211
	v_mul_f32_e32 v124, v124, v212
	v_mul_f32_e32 v125, v125, v213
	v_mul_f32_e32 v126, v126, v214
	v_mul_f32_e32 v127, v127, v215
	global_load_dwordx4 v[144:147], v193, s[38:39] offset:0
	global_load_dwordx4 v[200:203], v193, s[44:45] offset:0
	global_load_dwordx4 v[176:179], v193, s[36:37] offset:0
	global_load_dwordx4 v[148:151], v193, s[38:39] offset:1024
	global_load_dwordx4 v[204:207], v193, s[44:45] offset:1024
	global_load_dwordx4 v[180:183], v193, s[36:37] offset:1024
	global_load_dwordx4 v[152:155], v193, s[38:39] offset:2048
	global_load_dwordx4 v[208:211], v193, s[44:45] offset:2048
	global_load_dwordx4 v[184:187], v193, s[36:37] offset:2048
	global_load_dwordx4 v[156:159], v193, s[38:39] offset:3072
	global_load_dwordx4 v[212:215], v193, s[44:45] offset:3072
	global_load_dwordx4 v[188:191], v193, s[36:37] offset:3072
	s_waitcnt vmcnt(0)
	v_add_f32_e32 v200, 1.0, v200
	v_add_f32_e32 v201, 1.0, v201
	v_add_f32_e32 v202, 1.0, v202
	v_add_f32_e32 v203, 1.0, v203
	v_mul_f32_e32 v144, v144, v200
	v_mul_f32_e32 v145, v145, v201
	v_mul_f32_e32 v146, v146, v202
	v_mul_f32_e32 v147, v147, v203
	v_add_f32_e32 v204, 1.0, v204
	v_add_f32_e32 v205, 1.0, v205
	v_add_f32_e32 v206, 1.0, v206
	v_add_f32_e32 v207, 1.0, v207
	v_mul_f32_e32 v148, v148, v204
	v_mul_f32_e32 v149, v149, v205
	v_mul_f32_e32 v150, v150, v206
	v_mul_f32_e32 v151, v151, v207
	v_add_f32_e32 v208, 1.0, v208
	v_add_f32_e32 v209, 1.0, v209
	v_add_f32_e32 v210, 1.0, v210
	v_add_f32_e32 v211, 1.0, v211
	v_mul_f32_e32 v152, v152, v208
	v_mul_f32_e32 v153, v153, v209
	v_mul_f32_e32 v154, v154, v210
	v_mul_f32_e32 v155, v155, v211
	v_add_f32_e32 v212, 1.0, v212
	v_add_f32_e32 v213, 1.0, v213
	v_add_f32_e32 v214, 1.0, v214
	v_add_f32_e32 v215, 1.0, v215
	v_mul_f32_e32 v156, v156, v212
	v_mul_f32_e32 v157, v157, v213
	v_mul_f32_e32 v158, v158, v214
	v_mul_f32_e32 v159, v159, v215
.Lp6_np0:
	s_waitcnt vmcnt(16)
	v_lshlrev_b32_e32 v216, 16, v32
	v_and_b32_e32 v217, 0xffff0000, v32
	v_lshlrev_b32_e32 v218, 16, v33
	v_and_b32_e32 v219, 0xffff0000, v33
	v_mul_f32_e32 v222, v216, v216
	v_mul_f32_e32 v223, v217, v217
	v_fmac_f32_e32 v222, v218, v218
	v_fmac_f32_e32 v223, v219, v219
	v_lshlrev_b32_e32 v216, 16, v34
	v_and_b32_e32 v217, 0xffff0000, v34
	v_lshlrev_b32_e32 v218, 16, v35
	v_and_b32_e32 v219, 0xffff0000, v35
	v_fmac_f32_e32 v222, v216, v216
	v_fmac_f32_e32 v223, v217, v217
	v_fmac_f32_e32 v222, v218, v218
	v_fmac_f32_e32 v223, v219, v219
	v_lshlrev_b32_e32 v216, 16, v36
	v_and_b32_e32 v217, 0xffff0000, v36
	v_lshlrev_b32_e32 v218, 16, v37
	v_and_b32_e32 v219, 0xffff0000, v37
	v_fmac_f32_e32 v222, v216, v216
	v_fmac_f32_e32 v223, v217, v217
	v_fmac_f32_e32 v222, v218, v218
	v_fmac_f32_e32 v223, v219, v219
	v_lshlrev_b32_e32 v216, 16, v38
	v_and_b32_e32 v217, 0xffff0000, v38
	v_lshlrev_b32_e32 v218, 16, v39
	v_and_b32_e32 v219, 0xffff0000, v39
	v_fmac_f32_e32 v222, v216, v216
	v_fmac_f32_e32 v223, v217, v217
	v_fmac_f32_e32 v222, v218, v218
	v_fmac_f32_e32 v223, v219, v219
	v_lshlrev_b32_e32 v216, 16, v40
	v_and_b32_e32 v217, 0xffff0000, v40
	v_lshlrev_b32_e32 v218, 16, v41
	v_and_b32_e32 v219, 0xffff0000, v41
	v_fmac_f32_e32 v222, v216, v216
	v_fmac_f32_e32 v223, v217, v217
	v_fmac_f32_e32 v222, v218, v218
	v_fmac_f32_e32 v223, v219, v219
	v_lshlrev_b32_e32 v216, 16, v42
	v_and_b32_e32 v217, 0xffff0000, v42
	v_lshlrev_b32_e32 v218, 16, v43
	v_and_b32_e32 v219, 0xffff0000, v43
	v_fmac_f32_e32 v222, v216, v216
	v_fmac_f32_e32 v223, v217, v217
	v_fmac_f32_e32 v222, v218, v218
	v_fmac_f32_e32 v223, v219, v219
	v_lshlrev_b32_e32 v216, 16, v44
	v_and_b32_e32 v217, 0xffff0000, v44
	v_lshlrev_b32_e32 v218, 16, v45
	v_and_b32_e32 v219, 0xffff0000, v45
	v_fmac_f32_e32 v222, v216, v216
	v_fmac_f32_e32 v223, v217, v217
	v_fmac_f32_e32 v222, v218, v218
; __device__ __forceinline__ float bf_lo(unsigned w) { return __uint_as_float(w << 16); }
; __device__ __forceinline__ float bf_hi(unsigned w) { return __uint_as_float(w & 0xffff0000u); }
; __global__ void __launch_bounds__(NWAVES * 64, 2) mk_fwd(Args args) {
;     ...
;                 for (int j = 0; j < 8; ++j) { const float a = bf_lo(yw[q][j].x), b = bf_hi(yw[q][j].x), c2 = bf_lo(yw[q][j].y), d = bf_hi(yw[q][j].y); sy += (a * a + b * b) + (c2 * c2 + d * d); }
;                 const float rsy = __builtin_amdgcn_rsqf(wave_sum(sy) * (1.f / DM) + EPS);
;                 const float* m0 = mod + (size_t)r * 6144;
; #pragma unroll
;                 for (int j = 0; j < 8; ++j) { const int col = 4 * F.lane + 256 * j; const f32x4 gt = *(const f32x4*)(m0 + 2 * DM + col), pn = *(const f32x4*)(post_norm + col);
;                     const f32x4 y4 = (f32x4){bf_lo(yw[q][j].x), bf_hi(yw[q][j].x), bf_lo(yw[q][j].y), bf_hi(yw[q][j].y)};
;                     v[q][j] = v[q][j] + gt * (y4 * rsy * pn);
;                     if (lat) *(f32x4*)(args.out + (size_t)row * DM + col) = v[q][j]; }
;                 const float rstd = __builtin_amdgcn_rsqf(sumsq8(v[q]) * (1.f / DM) + EPS);
	v_fmac_f32_e32 v223, v219, v219
	v_lshlrev_b32_e32 v216, 16, v46
	v_and_b32_e32 v217, 0xffff0000, v46
	v_lshlrev_b32_e32 v218, 16, v47
	v_and_b32_e32 v219, 0xffff0000, v47
	v_fmac_f32_e32 v222, v216, v216
	v_fmac_f32_e32 v223, v217, v217
	v_fmac_f32_e32 v222, v218, v218
	v_fmac_f32_e32 v223, v219, v219
	v_add_f32_e32 v222, v222, v223
	s_nop 1
	v_add_f32_dpp v224, v222, v222 quad_perm:[1,0,3,2] row_mask:0xf bank_mask:0xf
	s_nop 1
	v_add_f32_dpp v224, v224, v224 quad_perm:[2,3,0,1] row_mask:0xf bank_mask:0xf
	s_nop 1
	v_add_f32_dpp v224, v224, v224 row_half_mirror row_mask:0xf bank_mask:0xf
	s_nop 1
	v_add_f32_dpp v224, v224, v224 row_mirror row_mask:0xf bank_mask:0xf
	s_nop 1
	v_readlane_b32 s40, v224, 0
	v_readlane_b32 s41, v224, 16
	v_readlane_b32 s42, v224, 32
	v_readlane_b32 s43, v224, 48
	s_nop 1
	v_mov_b32_e32 v225, s40
	v_add_f32_e32 v225, s41, v225
	v_add_f32_e32 v225, s42, v225
	v_add_f32_e32 v225, s43, v225
	v_fmamk_f32 v225, v225, 0x3a000000, v195
	v_rsq_f32_e32 v225, v225
	s_nop 0
	v_lshlrev_b32_e32 v216, 16, v32
	v_and_b32_e32 v217, 0xffff0000, v32
	v_lshlrev_b32_e32 v218, 16, v33
	v_and_b32_e32 v219, 0xffff0000, v33
	v_mul_f32_e32 v216, v225, v216
	v_mul_f32_e32 v217, v225, v217
	v_mul_f32_e32 v218, v225, v218
	v_mul_f32_e32 v219, v225, v219
	v_fmac_f32_e32 v0, v96, v216
	v_fmac_f32_e32 v1, v97, v217
	v_fmac_f32_e32 v2, v98, v218
	v_fmac_f32_e32 v3, v99, v219
	v_lshlrev_b32_e32 v216, 16, v34
	v_and_b32_e32 v217, 0xffff0000, v34
	v_lshlrev_b32_e32 v218, 16, v35
	v_and_b32_e32 v219, 0xffff0000, v35
	v_mul_f32_e32 v216, v225, v216
	v_mul_f32_e32 v217, v225, v217
	v_mul_f32_e32 v218, v225, v218
	v_mul_f32_e32 v219, v225, v219
	v_fmac_f32_e32 v4, v100, v216
	v_fmac_f32_e32 v5, v101, v217
	v_fmac_f32_e32 v6, v102, v218
	v_fmac_f32_e32 v7, v103, v219
	v_lshlrev_b32_e32 v216, 16, v36
	v_and_b32_e32 v217, 0xffff0000, v36
	v_lshlrev_b32_e32 v218, 16, v37
	v_and_b32_e32 v219, 0xffff0000, v37
	v_mul_f32_e32 v216, v225, v216
	v_mul_f32_e32 v217, v225, v217
	v_mul_f32_e32 v218, v225, v218
	v_mul_f32_e32 v219, v225, v219
	v_fmac_f32_e32 v8, v104, v216
	v_fmac_f32_e32 v9, v105, v217
	v_fmac_f32_e32 v10, v106, v218
	v_fmac_f32_e32 v11, v107, v219
	v_lshlrev_b32_e32 v216, 16, v38
	v_and_b32_e32 v217, 0xffff0000, v38
	v_lshlrev_b32_e32 v218, 16, v39
	v_and_b32_e32 v219, 0xffff0000, v39
	v_mul_f32_e32 v216, v225, v216
	v_mul_f32_e32 v217, v225, v217
	v_mul_f32_e32 v218, v225, v218
	v_mul_f32_e32 v219, v225, v219
	v_fmac_f32_e32 v12, v108, v216
	v_fmac_f32_e32 v13, v109, v217
	v_fmac_f32_e32 v14, v110, v218
	v_fmac_f32_e32 v15, v111, v219
	v_lshlrev_b32_e32 v216, 16, v40
	v_and_b32_e32 v217, 0xffff0000, v40
	v_lshlrev_b32_e32 v218, 16, v41
	v_and_b32_e32 v219, 0xffff0000, v41
	v_mul_f32_e32 v216, v225, v216
	v_mul_f32_e32 v217, v225, v217
	v_mul_f32_e32 v218, v225, v218
	v_mul_f32_e32 v219, v225, v219
	v_fmac_f32_e32 v16, v112, v216
	v_fmac_f32_e32 v17, v113, v217
	v_fmac_f32_e32 v18, v114, v218
	v_fmac_f32_e32 v19, v115, v219
	v_lshlrev_b32_e32 v216, 16, v42
	v_and_b32_e32 v217, 0xffff0000, v42
	v_lshlrev_b32_e32 v218, 16, v43
	v_and_b32_e32 v219, 0xffff0000, v43
	v_mul_f32_e32 v216, v225, v216
	v_mul_f32_e32 v217, v225, v217
	v_mul_f32_e32 v218, v225, v218
	v_mul_f32_e32 v219, v225, v219
	v_fmac_f32_e32 v20, v116, v216
	v_fmac_f32_e32 v21, v117, v217
	v_fmac_f32_e32 v22, v118, v218
	v_fmac_f32_e32 v23, v119, v219
	v_lshlrev_b32_e32 v216, 16, v44
	v_and_b32_e32 v217, 0xffff0000, v44
	v_lshlrev_b32_e32 v218, 16, v45
	v_and_b32_e32 v219, 0xffff0000, v45
	v_mul_f32_e32 v216, v225, v216
	v_mul_f32_e32 v217, v225, v217
	v_mul_f32_e32 v218, v225, v218
	v_mul_f32_e32 v219, v225, v219
	v_fmac_f32_e32 v24, v120, v216
	v_fmac_f32_e32 v25, v121, v217
	v_fmac_f32_e32 v26, v122, v218
	v_fmac_f32_e32 v27, v123, v219
	v_lshlrev_b32_e32 v216, 16, v46
	v_and_b32_e32 v217, 0xffff0000, v46
	v_lshlrev_b32_e32 v218, 16, v47
	v_and_b32_e32 v219, 0xffff0000, v47
	v_mul_f32_e32 v216, v225, v216
	v_mul_f32_e32 v217, v225, v217
	v_mul_f32_e32 v218, v225, v218
	v_mul_f32_e32 v219, v225, v219
	v_fmac_f32_e32 v28, v124, v216
	v_fmac_f32_e32 v29, v125, v217
	v_fmac_f32_e32 v30, v126, v218
	v_fmac_f32_e32 v31, v127, v219
	v_mul_f32_e32 v222, v0, v0
	v_mul_f32_e32 v223, v1, v1
	v_fmac_f32_e32 v222, v2, v2
	v_fmac_f32_e32 v223, v3, v3
	v_fmac_f32_e32 v222, v4, v4
	v_fmac_f32_e32 v223, v5, v5
	v_fmac_f32_e32 v222, v6, v6
	v_fmac_f32_e32 v223, v7, v7
	v_fmac_f32_e32 v222, v8, v8
	v_fmac_f32_e32 v223, v9, v9
	v_fmac_f32_e32 v222, v10, v10
	v_fmac_f32_e32 v223, v11, v11
	v_fmac_f32_e32 v222, v12, v12
	v_fmac_f32_e32 v223, v13, v13
	v_fmac_f32_e32 v222, v14, v14
	v_fmac_f32_e32 v223, v15, v15
	v_fmac_f32_e32 v222, v16, v16
	v_fmac_f32_e32 v223, v17, v17
	v_fmac_f32_e32 v222, v18, v18
	v_fmac_f32_e32 v223, v19, v19
	v_fmac_f32_e32 v222, v20, v20
	v_fmac_f32_e32 v223, v21, v21
	v_fmac_f32_e32 v222, v22, v22
	v_fmac_f32_e32 v223, v23, v23
	v_fmac_f32_e32 v222, v24, v24
	v_fmac_f32_e32 v223, v25, v25
	v_fmac_f32_e32 v222, v26, v26
	v_fmac_f32_e32 v223, v27, v27
	v_fmac_f32_e32 v222, v28, v28
	v_fmac_f32_e32 v223, v29, v29
	v_fmac_f32_e32 v222, v30, v30
	v_fmac_f32_e32 v223, v31, v31
	v_add_f32_e32 v222, v222, v223
	s_nop 1
	v_add_f32_dpp v224, v222, v222 quad_perm:[1,0,3,2] row_mask:0xf bank_mask:0xf
	s_nop 1
	v_add_f32_dpp v224, v224, v224 quad_perm:[2,3,0,1] row_mask:0xf bank_mask:0xf
	s_nop 1
	v_add_f32_dpp v224, v224, v224 row_half_mirror row_mask:0xf bank_mask:0xf
	s_nop 1
	v_add_f32_dpp v224, v224, v224 row_mirror row_mask:0xf bank_mask:0xf
	s_nop 1
	v_readlane_b32 s40, v224, 0
	v_readlane_b32 s41, v224, 16
	v_readlane_b32 s42, v224, 32
	v_readlane_b32 s43, v224, 48
	s_nop 1
; __device__ __forceinline__ unsigned cvt_pk_bf16(float lo, float hi) { unsigned r; asm volatile("v_cvt_pk_bf16_f32 %0, %1, %2" : "=v"(r) : "v"(lo), "v"(hi)); return r; }
; __device__ __forceinline__ void modulate_store(const f32x4 (&v)[8], float rstd, const float* pn, const float* modr, bf16_t* orow, int lane) {
; #pragma unroll
;     for (int j = 0; j < 8; ++j) { const int col = 4 * lane + 256 * j;
;         const f32x4 g = *(const f32x4*)(pn + col), sh = *(const f32x4*)(modr + col), sc = *(const f32x4*)(modr + DM + col);
;         const f32x4 hh = v[j] * rstd * g * (sc + 1.f) + sh;
;         u32x2 w; w.x = cvt_pk_bf16(hh[0], hh[1]); w.y = cvt_pk_bf16(hh[2], hh[3]);
;         *(u32x2*)(orow + col) = w; }
; __global__ void __launch_bounds__(NWAVES * 64, 2) mk_fwd(Args args) {
;     ...
;             for (int q = 0; q < 3; ++q) { const int row = row0 + q; const float* src = row < ML ? x + (size_t)row * DM : ctx + (size_t)(row - ML) * DM; load_row_f32(src, F.lane, v[q]);
;                 const bf16_t* yr = Y + (size_t)row * DM;
; #pragma unroll
;                 for (int j = 0; j < 8; ++j) yw[q][j] = *(const u32x2*)(yr + 4 * F.lane + 256 * j); }
;     ...
;                 const float rstd = __builtin_amdgcn_rsqf(sumsq8(v[q]) * (1.f / DM) + EPS);
;                 modulate_store(v[q], rstd, pre_norm + DM, mod + (size_t)(9 + r) * 6144, H + (size_t)row * DM, F.lane); }
	v_mov_b32_e32 v225, s40
	v_add_f32_e32 v225, s41, v225
	v_add_f32_e32 v225, s42, v225
	v_add_f32_e32 v225, s43, v225
	v_fmamk_f32 v225, v225, 0x3a000000, v195
	v_rsq_f32_e32 v225, v225
	s_nop 0
	s_add_i32 s0, s6, 0
	s_lshl_b32 s1, s0, 12
	s_add_u32 s26, s84, s1
	s_addc_u32 s27, s85, 0
	s_add_u32 s26, s26, 0x4000000
	s_addc_u32 s27, s27, 0
	v_mul_f32_e32 v216, v225, v0
	v_mul_f32_e32 v217, v225, v1
	v_mul_f32_e32 v218, v225, v2
	v_mul_f32_e32 v219, v225, v3
	v_fma_f32 v216, v216, v128, v160
	v_fma_f32 v217, v217, v129, v161
	v_fma_f32 v218, v218, v130, v162
	v_fma_f32 v219, v219, v131, v163
	v_cvt_pk_bf16_f32 v196, v216, v217
	v_cvt_pk_bf16_f32 v197, v218, v219
	global_store_dwordx2 v194, v[196:197], s[26:27] offset:0
	v_mul_f32_e32 v216, v225, v4
	v_mul_f32_e32 v217, v225, v5
	v_mul_f32_e32 v218, v225, v6
	v_mul_f32_e32 v219, v225, v7
	v_fma_f32 v216, v216, v132, v164
	v_fma_f32 v217, v217, v133, v165
	v_fma_f32 v218, v218, v134, v166
	v_fma_f32 v219, v219, v135, v167
	v_cvt_pk_bf16_f32 v220, v216, v217
	v_cvt_pk_bf16_f32 v221, v218, v219
	global_store_dwordx2 v194, v[220:221], s[26:27] offset:512
	v_mul_f32_e32 v216, v225, v8
	v_mul_f32_e32 v217, v225, v9
	v_mul_f32_e32 v218, v225, v10
	v_mul_f32_e32 v219, v225, v11
	v_fma_f32 v216, v216, v136, v168
	v_fma_f32 v217, v217, v137, v169
	v_fma_f32 v218, v218, v138, v170
	v_fma_f32 v219, v219, v139, v171
	v_cvt_pk_bf16_f32 v196, v216, v217
	v_cvt_pk_bf16_f32 v197, v218, v219
	global_store_dwordx2 v194, v[196:197], s[26:27] offset:1024
	v_mul_f32_e32 v216, v225, v12
	v_mul_f32_e32 v217, v225, v13
	v_mul_f32_e32 v218, v225, v14
	v_mul_f32_e32 v219, v225, v15
	v_fma_f32 v216, v216, v140, v172
	v_fma_f32 v217, v217, v141, v173
	v_fma_f32 v218, v218, v142, v174
	v_fma_f32 v219, v219, v143, v175
	v_cvt_pk_bf16_f32 v220, v216, v217
	v_cvt_pk_bf16_f32 v221, v218, v219
	global_store_dwordx2 v194, v[220:221], s[26:27] offset:1536
	v_mul_f32_e32 v216, v225, v16
	v_mul_f32_e32 v217, v225, v17
	v_mul_f32_e32 v218, v225, v18
	v_mul_f32_e32 v219, v225, v19
	v_fma_f32 v216, v216, v144, v176
	v_fma_f32 v217, v217, v145, v177
	v_fma_f32 v218, v218, v146, v178
	v_fma_f32 v219, v219, v147, v179
	v_cvt_pk_bf16_f32 v196, v216, v217
	v_cvt_pk_bf16_f32 v197, v218, v219
	global_store_dwordx2 v194, v[196:197], s[26:27] offset:2048
	v_mul_f32_e32 v216, v225, v20
	v_mul_f32_e32 v217, v225, v21
	v_mul_f32_e32 v218, v225, v22
	v_mul_f32_e32 v219, v225, v23
	v_fma_f32 v216, v216, v148, v180
	v_fma_f32 v217, v217, v149, v181
	v_fma_f32 v218, v218, v150, v182
	v_fma_f32 v219, v219, v151, v183
	v_cvt_pk_bf16_f32 v220, v216, v217
	v_cvt_pk_bf16_f32 v221, v218, v219
	global_store_dwordx2 v194, v[220:221], s[26:27] offset:2560
	v_mul_f32_e32 v216, v225, v24
	v_mul_f32_e32 v217, v225, v25
	v_mul_f32_e32 v218, v225, v26
	v_mul_f32_e32 v219, v225, v27
	v_fma_f32 v216, v216, v152, v184
	v_fma_f32 v217, v217, v153, v185
	v_fma_f32 v218, v218, v154, v186
	v_fma_f32 v219, v219, v155, v187
	v_cvt_pk_bf16_f32 v196, v216, v217
	v_cvt_pk_bf16_f32 v197, v218, v219
	global_store_dwordx2 v194, v[196:197], s[26:27] offset:3072
	v_mul_f32_e32 v216, v225, v28
	v_mul_f32_e32 v217, v225, v29
	v_mul_f32_e32 v218, v225, v30
	v_mul_f32_e32 v219, v225, v31
	v_fma_f32 v216, v216, v156, v188
	v_fma_f32 v217, v217, v157, v189
	v_fma_f32 v218, v218, v158, v190
	v_fma_f32 v219, v219, v159, v191
	v_cvt_pk_bf16_f32 v220, v216, v217
	v_cvt_pk_bf16_f32 v221, v218, v219
	global_store_dwordx2 v194, v[220:221], s[26:27] offset:3584
	s_add_i32 s0, s6, 2
	s_cmp_lt_u32 s0, 0x4000
	s_cselect_b32 s10, s68, s72
	s_cselect_b32 s11, s69, s73
	s_cselect_b32 s1, 0, 0x4000
	s_sub_i32 s1, s0, s1
	s_lshl_b32 s1, s1, 13
	s_add_u32 s10, s10, s1
	s_addc_u32 s11, s11, 0
	s_add_i32 s0, s6, 2
	s_lshl_b32 s1, s0, 12
	s_add_u32 s22, s84, s1
	s_addc_u32 s23, s85, 0
	s_add_u32 s22, s22, 0x11800000
	s_addc_u32 s23, s23, 0
	global_load_dwordx4 v[0:3], v192, s[10:11] offset:0 nt
	global_load_dwordx4 v[4:7], v192, s[10:11] offset:1024 nt
	global_load_dwordx4 v[8:11], v192, s[10:11] offset:2048 nt
	global_load_dwordx4 v[12:15], v192, s[10:11] offset:3072 nt
	global_load_dwordx4 v[16:19], v193, s[10:11] offset:0 nt
	global_load_dwordx4 v[20:23], v193, s[10:11] offset:1024 nt
	global_load_dwordx4 v[24:27], v193, s[10:11] offset:2048 nt
	global_load_dwordx4 v[28:31], v193, s[10:11] offset:3072 nt
	global_load_dwordx2 v[32:33], v194, s[22:23] offset:0
	global_load_dwordx2 v[34:35], v194, s[22:23] offset:512
	global_load_dwordx2 v[36:37], v194, s[22:23] offset:1024
	global_load_dwordx2 v[38:39], v194, s[22:23] offset:1536
	global_load_dwordx2 v[40:41], v194, s[22:23] offset:2048
	global_load_dwordx2 v[42:43], v194, s[22:23] offset:2560
	global_load_dwordx2 v[44:45], v194, s[22:23] offset:3072
	global_load_dwordx2 v[46:47], v194, s[22:23] offset:3584
	s_add_i32 s0, s6, 1
	s_add_i32 s0, s6, 1
	s_lshr_b32 s8, s0, 11
	s_cmp_lt_u32 s0, 0x4000
	s_cselect_b32 s8, s8, 8
	s_cmp_eq_u32 s8, s7
	s_cbranch_scc1 .Lp6_np1
; __device__ __forceinline__ void modulate_store(const f32x4 (&v)[8], float rstd, const float* pn, const float* modr, bf16_t* orow, int lane) {
; #pragma unroll
;     for (int j = 0; j < 8; ++j) { const int col = 4 * lane + 256 * j;
;         const f32x4 g = *(const f32x4*)(pn + col), sh = *(const f32x4*)(modr + col), sc = *(const f32x4*)(modr + DM + col);
;         const f32x4 hh = v[j] * rstd * g * (sc + 1.f) + sh;
; __global__ void __launch_bounds__(NWAVES * 64, 2) mk_fwd(Args args) {
;     ...
;                 const float* m0 = mod + (size_t)r * 6144;
; #pragma unroll
;                 for (int j = 0; j < 8; ++j) { const int col = 4 * F.lane + 256 * j; const f32x4 gt = *(const f32x4*)(m0 + 2 * DM + col), pn = *(const f32x4*)(post_norm + col);
	s_mov_b32 s7, s8
	s_add_i32 s1, s8, 9
	s_mul_i32 s1, s1, 0x6000
	s_add_u32 s44, s84, s1
	s_addc_u32 s45, s85, 0
	s_add_u32 s44, s44, 0x2000
	s_addc_u32 s45, s45, 0
	s_add_i32 s1, s8, 9
	s_mul_i32 s1, s1, 0x6000
	s_add_u32 s36, s84, s1
	s_addc_u32 s37, s85, 0
	s_add_u32 s38, s80, 0x2000
	s_addc_u32 s39, s81, 0
	s_mul_i32 s1, s8, 0x6000
	s_add_u32 s34, s84, s1
	s_addc_u32 s35, s85, 0
	s_add_u32 s34, s34, 0x4000
	s_addc_u32 s35, s35, 0
	global_load_dwordx4 v[96:99], v192, s[34:35] offset:0
	global_load_dwordx4 v[200:203], v192, s[82:83] offset:0
	global_load_dwordx4 v[100:103], v192, s[34:35] offset:1024
	global_load_dwordx4 v[204:207], v192, s[82:83] offset:1024
	global_load_dwordx4 v[104:107], v192, s[34:35] offset:2048
	global_load_dwordx4 v[208:211], v192, s[82:83] offset:2048
	global_load_dwordx4 v[108:111], v192, s[34:35] offset:3072
	global_load_dwordx4 v[212:215], v192, s[82:83] offset:3072
	s_waitcnt vmcnt(0)
	v_mul_f32_e32 v96, v96, v200
	v_mul_f32_e32 v97, v97, v201
	v_mul_f32_e32 v98, v98, v202
	v_mul_f32_e32 v99, v99, v203
	v_mul_f32_e32 v100, v100, v204
	v_mul_f32_e32 v101, v101, v205
	v_mul_f32_e32 v102, v102, v206
	v_mul_f32_e32 v103, v103, v207
	v_mul_f32_e32 v104, v104, v208
	v_mul_f32_e32 v105, v105, v209
	v_mul_f32_e32 v106, v106, v210
	v_mul_f32_e32 v107, v107, v211
	v_mul_f32_e32 v108, v108, v212
	v_mul_f32_e32 v109, v109, v213
	v_mul_f32_e32 v110, v110, v214
	v_mul_f32_e32 v111, v111, v215
	global_load_dwordx4 v[128:131], v192, s[38:39] offset:0
	global_load_dwordx4 v[200:203], v192, s[44:45] offset:0
	global_load_dwordx4 v[160:163], v192, s[36:37] offset:0
	global_load_dwordx4 v[132:135], v192, s[38:39] offset:1024
	global_load_dwordx4 v[204:207], v192, s[44:45] offset:1024
	global_load_dwordx4 v[164:167], v192, s[36:37] offset:1024
	global_load_dwordx4 v[136:139], v192, s[38:39] offset:2048
	global_load_dwordx4 v[208:211], v192, s[44:45] offset:2048
	global_load_dwordx4 v[168:171], v192, s[36:37] offset:2048
	global_load_dwordx4 v[140:143], v192, s[38:39] offset:3072
	global_load_dwordx4 v[212:215], v192, s[44:45] offset:3072
	global_load_dwordx4 v[172:175], v192, s[36:37] offset:3072
	s_waitcnt vmcnt(0)
	v_add_f32_e32 v200, 1.0, v200
	v_add_f32_e32 v201, 1.0, v201
	v_add_f32_e32 v202, 1.0, v202
	v_add_f32_e32 v203, 1.0, v203
	v_mul_f32_e32 v128, v128, v200
	v_mul_f32_e32 v129, v129, v201
	v_mul_f32_e32 v130, v130, v202
	v_mul_f32_e32 v131, v131, v203
	v_add_f32_e32 v204, 1.0, v204
	v_add_f32_e32 v205, 1.0, v205
	v_add_f32_e32 v206, 1.0, v206
	v_add_f32_e32 v207, 1.0, v207
	v_mul_f32_e32 v132, v132, v204
	v_mul_f32_e32 v133, v133, v205
	v_mul_f32_e32 v134, v134, v206
	v_mul_f32_e32 v135, v135, v207
	v_add_f32_e32 v208, 1.0, v208
	v_add_f32_e32 v209, 1.0, v209
	v_add_f32_e32 v210, 1.0, v210
	v_add_f32_e32 v211, 1.0, v211
	v_mul_f32_e32 v136, v136, v208
	v_mul_f32_e32 v137, v137, v209
	v_mul_f32_e32 v138, v138, v210
	v_mul_f32_e32 v139, v139, v211
	v_add_f32_e32 v212, 1.0, v212
	v_add_f32_e32 v213, 1.0, v213
	v_add_f32_e32 v214, 1.0, v214
	v_add_f32_e32 v215, 1.0, v215
	v_mul_f32_e32 v140, v140, v212
	v_mul_f32_e32 v141, v141, v213
	v_mul_f32_e32 v142, v142, v214
	v_mul_f32_e32 v143, v143, v215
	global_load_dwordx4 v[112:115], v193, s[34:35] offset:0
	global_load_dwordx4 v[200:203], v193, s[82:83] offset:0
	global_load_dwordx4 v[116:119], v193, s[34:35] offset:1024
	global_load_dwordx4 v[204:207], v193, s[82:83] offset:1024
	global_load_dwordx4 v[120:123], v193, s[34:35] offset:2048
	global_load_dwordx4 v[208:211], v193, s[82:83] offset:2048
	global_load_dwordx4 v[124:127], v193, s[34:35] offset:3072
	global_load_dwordx4 v[212:215], v193, s[82:83] offset:3072
	s_waitcnt vmcnt(0)
	v_mul_f32_e32 v112, v112, v200
	v_mul_f32_e32 v113, v113, v201
	v_mul_f32_e32 v114, v114, v202
	v_mul_f32_e32 v115, v115, v203
	v_mul_f32_e32 v116, v116, v204
	v_mul_f32_e32 v117, v117, v205
	v_mul_f32_e32 v118, v118, v206
	v_mul_f32_e32 v119, v119, v207
	v_mul_f32_e32 v120, v120, v208
	v_mul_f32_e32 v121, v121, v209
	v_mul_f32_e32 v122, v122, v210
	v_mul_f32_e32 v123, v123, v211
	v_mul_f32_e32 v124, v124, v212
	v_mul_f32_e32 v125, v125, v213
	v_mul_f32_e32 v126, v126, v214
	v_mul_f32_e32 v127, v127, v215
	global_load_dwordx4 v[144:147], v193, s[38:39] offset:0
	global_load_dwordx4 v[200:203], v193, s[44:45] offset:0
	global_load_dwordx4 v[176:179], v193, s[36:37] offset:0
	global_load_dwordx4 v[148:151], v193, s[38:39] offset:1024
	global_load_dwordx4 v[204:207], v193, s[44:45] offset:1024
	global_load_dwordx4 v[180:183], v193, s[36:37] offset:1024
	global_load_dwordx4 v[152:155], v193, s[38:39] offset:2048
	global_load_dwordx4 v[208:211], v193, s[44:45] offset:2048
	global_load_dwordx4 v[184:187], v193, s[36:37] offset:2048
	global_load_dwordx4 v[156:159], v193, s[38:39] offset:3072
	global_load_dwordx4 v[212:215], v193, s[44:45] offset:3072
	global_load_dwordx4 v[188:191], v193, s[36:37] offset:3072
	s_waitcnt vmcnt(0)
	v_add_f32_e32 v200, 1.0, v200
	v_add_f32_e32 v201, 1.0, v201
	v_add_f32_e32 v202, 1.0, v202
	v_add_f32_e32 v203, 1.0, v203
	v_mul_f32_e32 v144, v144, v200
	v_mul_f32_e32 v145, v145, v201
	v_mul_f32_e32 v146, v146, v202
	v_mul_f32_e32 v147, v147, v203
	v_add_f32_e32 v204, 1.0, v204
	v_add_f32_e32 v205, 1.0, v205
	v_add_f32_e32 v206, 1.0, v206
	v_add_f32_e32 v207, 1.0, v207
	v_mul_f32_e32 v148, v148, v204
	v_mul_f32_e32 v149, v149, v205
	v_mul_f32_e32 v150, v150, v206
	v_mul_f32_e32 v151, v151, v207
	v_add_f32_e32 v208, 1.0, v208
	v_add_f32_e32 v209, 1.0, v209
	v_add_f32_e32 v210, 1.0, v210
	v_add_f32_e32 v211, 1.0, v211
	v_mul_f32_e32 v152, v152, v208
	v_mul_f32_e32 v153, v153, v209
	v_mul_f32_e32 v154, v154, v210
	v_mul_f32_e32 v155, v155, v211
	v_add_f32_e32 v212, 1.0, v212
	v_add_f32_e32 v213, 1.0, v213
	v_add_f32_e32 v214, 1.0, v214
	v_add_f32_e32 v215, 1.0, v215
	v_mul_f32_e32 v156, v156, v212
	v_mul_f32_e32 v157, v157, v213
	v_mul_f32_e32 v158, v158, v214
	v_mul_f32_e32 v159, v159, v215
; __device__ __forceinline__ float bf_lo(unsigned w) { return __uint_as_float(w << 16); }
; __device__ __forceinline__ float bf_hi(unsigned w) { return __uint_as_float(w & 0xffff0000u); }
; __global__ void __launch_bounds__(NWAVES * 64, 2) mk_fwd(Args args) {
;     ...
;             for (int q = 0; q < 3; ++q) { const int row = row0 + q; const bool lat = row < ML; const int r = lat ? row / SEQ : 8;
;                 float sy = 0.f;
; #pragma unroll
;                 for (int j = 0; j < 8; ++j) { const float a = bf_lo(yw[q][j].x), b = bf_hi(yw[q][j].x), c2 = bf_lo(yw[q][j].y), d = bf_hi(yw[q][j].y); sy += (a * a + b * b) + (c2 * c2 + d * d); }
;                 const float rsy = __builtin_amdgcn_rsqf(wave_sum(sy) * (1.f / DM) + EPS);
;                 const float* m0 = mod + (size_t)r * 6144;
; #pragma unroll
;                 for (int j = 0; j < 8; ++j) { const int col = 4 * F.lane + 256 * j; const f32x4 gt = *(const f32x4*)(m0 + 2 * DM + col), pn = *(const f32x4*)(post_norm + col);
;                     const f32x4 y4 = (f32x4){bf_lo(yw[q][j].x), bf_hi(yw[q][j].x), bf_lo(yw[q][j].y), bf_hi(yw[q][j].y)};
;                     v[q][j] = v[q][j] + gt * (y4 * rsy * pn);
.Lp6_np1:
	s_waitcnt vmcnt(24)
	v_lshlrev_b32_e32 v216, 16, v80
	v_and_b32_e32 v217, 0xffff0000, v80
	v_lshlrev_b32_e32 v218, 16, v81
	v_and_b32_e32 v219, 0xffff0000, v81
	v_mul_f32_e32 v222, v216, v216
	v_mul_f32_e32 v223, v217, v217
	v_fmac_f32_e32 v222, v218, v218
	v_fmac_f32_e32 v223, v219, v219
	v_lshlrev_b32_e32 v216, 16, v82
	v_and_b32_e32 v217, 0xffff0000, v82
	v_lshlrev_b32_e32 v218, 16, v83
	v_and_b32_e32 v219, 0xffff0000, v83
	v_fmac_f32_e32 v222, v216, v216
	v_fmac_f32_e32 v223, v217, v217
	v_fmac_f32_e32 v222, v218, v218
	v_fmac_f32_e32 v223, v219, v219
	v_lshlrev_b32_e32 v216, 16, v84
	v_and_b32_e32 v217, 0xffff0000, v84
	v_lshlrev_b32_e32 v218, 16, v85
	v_and_b32_e32 v219, 0xffff0000, v85
	v_fmac_f32_e32 v222, v216, v216
	v_fmac_f32_e32 v223, v217, v217
	v_fmac_f32_e32 v222, v218, v218
	v_fmac_f32_e32 v223, v219, v219
	v_lshlrev_b32_e32 v216, 16, v86
	v_and_b32_e32 v217, 0xffff0000, v86
	v_lshlrev_b32_e32 v218, 16, v87
	v_and_b32_e32 v219, 0xffff0000, v87
	v_fmac_f32_e32 v222, v216, v216
	v_fmac_f32_e32 v223, v217, v217
	v_fmac_f32_e32 v222, v218, v218
	v_fmac_f32_e32 v223, v219, v219
	v_lshlrev_b32_e32 v216, 16, v88
	v_and_b32_e32 v217, 0xffff0000, v88
	v_lshlrev_b32_e32 v218, 16, v89
	v_and_b32_e32 v219, 0xffff0000, v89
	v_fmac_f32_e32 v222, v216, v216
	v_fmac_f32_e32 v223, v217, v217
	v_fmac_f32_e32 v222, v218, v218
	v_fmac_f32_e32 v223, v219, v219
	v_lshlrev_b32_e32 v216, 16, v90
	v_and_b32_e32 v217, 0xffff0000, v90
	v_lshlrev_b32_e32 v218, 16, v91
	v_and_b32_e32 v219, 0xffff0000, v91
	v_fmac_f32_e32 v222, v216, v216
	v_fmac_f32_e32 v223, v217, v217
	v_fmac_f32_e32 v222, v218, v218
	v_fmac_f32_e32 v223, v219, v219
	v_lshlrev_b32_e32 v216, 16, v92
	v_and_b32_e32 v217, 0xffff0000, v92
	v_lshlrev_b32_e32 v218, 16, v93
	v_and_b32_e32 v219, 0xffff0000, v93
	v_fmac_f32_e32 v222, v216, v216
	v_fmac_f32_e32 v223, v217, v217
	v_fmac_f32_e32 v222, v218, v218
	v_fmac_f32_e32 v223, v219, v219
	v_lshlrev_b32_e32 v216, 16, v94
	v_and_b32_e32 v217, 0xffff0000, v94
	v_lshlrev_b32_e32 v218, 16, v95
	v_and_b32_e32 v219, 0xffff0000, v95
	v_fmac_f32_e32 v222, v216, v216
	v_fmac_f32_e32 v223, v217, v217
	v_fmac_f32_e32 v222, v218, v218
	v_fmac_f32_e32 v223, v219, v219
	v_add_f32_e32 v222, v222, v223
	s_nop 1
	v_add_f32_dpp v224, v222, v222 quad_perm:[1,0,3,2] row_mask:0xf bank_mask:0xf
	s_nop 1
	v_add_f32_dpp v224, v224, v224 quad_perm:[2,3,0,1] row_mask:0xf bank_mask:0xf
	s_nop 1
	v_add_f32_dpp v224, v224, v224 row_half_mirror row_mask:0xf bank_mask:0xf
	s_nop 1
	v_add_f32_dpp v224, v224, v224 row_mirror row_mask:0xf bank_mask:0xf
	s_nop 1
	v_readlane_b32 s40, v224, 0
	v_readlane_b32 s41, v224, 16
	v_readlane_b32 s42, v224, 32
	v_readlane_b32 s43, v224, 48
	s_nop 1
	v_mov_b32_e32 v225, s40
	v_add_f32_e32 v225, s41, v225
	v_add_f32_e32 v225, s42, v225
	v_add_f32_e32 v225, s43, v225
	v_fmamk_f32 v225, v225, 0x3a000000, v195
	v_rsq_f32_e32 v225, v225
	s_nop 0
	v_lshlrev_b32_e32 v216, 16, v80
	v_and_b32_e32 v217, 0xffff0000, v80
	v_lshlrev_b32_e32 v218, 16, v81
	v_and_b32_e32 v219, 0xffff0000, v81
	v_mul_f32_e32 v216, v225, v216
	v_mul_f32_e32 v217, v225, v217
	v_mul_f32_e32 v218, v225, v218
	v_mul_f32_e32 v219, v225, v219
	v_fmac_f32_e32 v48, v96, v216
	v_fmac_f32_e32 v49, v97, v217
	v_fmac_f32_e32 v50, v98, v218
	v_fmac_f32_e32 v51, v99, v219
	v_lshlrev_b32_e32 v216, 16, v82
	v_and_b32_e32 v217, 0xffff0000, v82
	v_lshlrev_b32_e32 v218, 16, v83
	v_and_b32_e32 v219, 0xffff0000, v83
	v_mul_f32_e32 v216, v225, v216
	v_mul_f32_e32 v217, v225, v217
	v_mul_f32_e32 v218, v225, v218
	v_mul_f32_e32 v219, v225, v219
	v_fmac_f32_e32 v52, v100, v216
	v_fmac_f32_e32 v53, v101, v217
	v_fmac_f32_e32 v54, v102, v218
	v_fmac_f32_e32 v55, v103, v219
	v_lshlrev_b32_e32 v216, 16, v84
	v_and_b32_e32 v217, 0xffff0000, v84
	v_lshlrev_b32_e32 v218, 16, v85
	v_and_b32_e32 v219, 0xffff0000, v85
	v_mul_f32_e32 v216, v225, v216
	v_mul_f32_e32 v217, v225, v217
	v_mul_f32_e32 v218, v225, v218
	v_mul_f32_e32 v219, v225, v219
	v_fmac_f32_e32 v56, v104, v216
	v_fmac_f32_e32 v57, v105, v217
	v_fmac_f32_e32 v58, v106, v218
	v_fmac_f32_e32 v59, v107, v219
	v_lshlrev_b32_e32 v216, 16, v86
	v_and_b32_e32 v217, 0xffff0000, v86
	v_lshlrev_b32_e32 v218, 16, v87
	v_and_b32_e32 v219, 0xffff0000, v87
	v_mul_f32_e32 v216, v225, v216
	v_mul_f32_e32 v217, v225, v217
	v_mul_f32_e32 v218, v225, v218
	v_mul_f32_e32 v219, v225, v219
	v_fmac_f32_e32 v60, v108, v216
	v_fmac_f32_e32 v61, v109, v217
	v_fmac_f32_e32 v62, v110, v218
	v_fmac_f32_e32 v63, v111, v219
	v_lshlrev_b32_e32 v216, 16, v88
	v_and_b32_e32 v217, 0xffff0000, v88
	v_lshlrev_b32_e32 v218, 16, v89
	v_and_b32_e32 v219, 0xffff0000, v89
	v_mul_f32_e32 v216, v225, v216
	v_mul_f32_e32 v217, v225, v217
	v_mul_f32_e32 v218, v225, v218
	v_mul_f32_e32 v219, v225, v219
	v_fmac_f32_e32 v64, v112, v216
	v_fmac_f32_e32 v65, v113, v217
	v_fmac_f32_e32 v66, v114, v218
	v_fmac_f32_e32 v67, v115, v219
	v_lshlrev_b32_e32 v216, 16, v90
	v_and_b32_e32 v217, 0xffff0000, v90
	v_lshlrev_b32_e32 v218, 16, v91
	v_and_b32_e32 v219, 0xffff0000, v91
	v_mul_f32_e32 v216, v225, v216
	v_mul_f32_e32 v217, v225, v217
	v_mul_f32_e32 v218, v225, v218
	v_mul_f32_e32 v219, v225, v219
	v_fmac_f32_e32 v68, v116, v216
	v_fmac_f32_e32 v69, v117, v217
	v_fmac_f32_e32 v70, v118, v218
	v_fmac_f32_e32 v71, v119, v219
	v_lshlrev_b32_e32 v216, 16, v92
	v_and_b32_e32 v217, 0xffff0000, v92
	v_lshlrev_b32_e32 v218, 16, v93
	v_and_b32_e32 v219, 0xffff0000, v93
	v_mul_f32_e32 v216, v225, v216
	v_mul_f32_e32 v217, v225, v217
	v_mul_f32_e32 v218, v225, v218
	v_mul_f32_e32 v219, v225, v219
	v_fmac_f32_e32 v72, v120, v216
	v_fmac_f32_e32 v73, v121, v217
	v_fmac_f32_e32 v74, v122, v218
; __device__ __forceinline__ unsigned cvt_pk_bf16(float lo, float hi) { unsigned r; asm volatile("v_cvt_pk_bf16_f32 %0, %1, %2" : "=v"(r) : "v"(lo), "v"(hi)); return r; }
; __device__ __forceinline__ float sumsq8(const f32x4 (&v)[8]) {
;     float s = 0.f;
; #pragma unroll
;     for (int j = 0; j < 8; ++j) s += (v[j][0] * v[j][0] + v[j][1] * v[j][1]) + (v[j][2] * v[j][2] + v[j][3] * v[j][3]);
;     return wave_sum(s);
; }
; __device__ __forceinline__ void modulate_store(const f32x4 (&v)[8], float rstd, const float* pn, const float* modr, bf16_t* orow, int lane) {
; #pragma unroll
;     for (int j = 0; j < 8; ++j) { const int col = 4 * lane + 256 * j;
;         const f32x4 g = *(const f32x4*)(pn + col), sh = *(const f32x4*)(modr + col), sc = *(const f32x4*)(modr + DM + col);
;         const f32x4 hh = v[j] * rstd * g * (sc + 1.f) + sh;
;         u32x2 w; w.x = cvt_pk_bf16(hh[0], hh[1]); w.y = cvt_pk_bf16(hh[2], hh[3]);
;         *(u32x2*)(orow + col) = w; }
; }
; __global__ void __launch_bounds__(NWAVES * 64, 2) mk_fwd(Args args) {
;     ...
;         for (int row0 = F.gw * 3; row0 < MT; row0 += F.NGW * 3) {
;             f32x4 v[3][8]; u32x2 yw[3][8];
; #pragma unroll
;             for (int q = 0; q < 3; ++q) { const int row = row0 + q; const float* src = row < ML ? x + (size_t)row * DM : ctx + (size_t)(row - ML) * DM; load_row_f32(src, F.lane, v[q]);
;                 const bf16_t* yr = Y + (size_t)row * DM;
; #pragma unroll
;                 for (int j = 0; j < 8; ++j) yw[q][j] = *(const u32x2*)(yr + 4 * F.lane + 256 * j); }
	v_fmac_f32_e32 v75, v123, v219
	v_lshlrev_b32_e32 v216, 16, v94
	v_and_b32_e32 v217, 0xffff0000, v94
	v_lshlrev_b32_e32 v218, 16, v95
	v_and_b32_e32 v219, 0xffff0000, v95
	v_mul_f32_e32 v216, v225, v216
	v_mul_f32_e32 v217, v225, v217
	v_mul_f32_e32 v218, v225, v218
	v_mul_f32_e32 v219, v225, v219
	v_fmac_f32_e32 v76, v124, v216
	v_fmac_f32_e32 v77, v125, v217
	v_fmac_f32_e32 v78, v126, v218
	v_fmac_f32_e32 v79, v127, v219
	v_mul_f32_e32 v222, v48, v48
	v_mul_f32_e32 v223, v49, v49
	v_fmac_f32_e32 v222, v50, v50
	v_fmac_f32_e32 v223, v51, v51
	v_fmac_f32_e32 v222, v52, v52
	v_fmac_f32_e32 v223, v53, v53
	v_fmac_f32_e32 v222, v54, v54
	v_fmac_f32_e32 v223, v55, v55
	v_fmac_f32_e32 v222, v56, v56
	v_fmac_f32_e32 v223, v57, v57
	v_fmac_f32_e32 v222, v58, v58
	v_fmac_f32_e32 v223, v59, v59
	v_fmac_f32_e32 v222, v60, v60
	v_fmac_f32_e32 v223, v61, v61
	v_fmac_f32_e32 v222, v62, v62
	v_fmac_f32_e32 v223, v63, v63
	v_fmac_f32_e32 v222, v64, v64
	v_fmac_f32_e32 v223, v65, v65
	v_fmac_f32_e32 v222, v66, v66
	v_fmac_f32_e32 v223, v67, v67
	v_fmac_f32_e32 v222, v68, v68
	v_fmac_f32_e32 v223, v69, v69
	v_fmac_f32_e32 v222, v70, v70
	v_fmac_f32_e32 v223, v71, v71
	v_fmac_f32_e32 v222, v72, v72
	v_fmac_f32_e32 v223, v73, v73
	v_fmac_f32_e32 v222, v74, v74
	v_fmac_f32_e32 v223, v75, v75
	v_fmac_f32_e32 v222, v76, v76
	v_fmac_f32_e32 v223, v77, v77
	v_fmac_f32_e32 v222, v78, v78
	v_fmac_f32_e32 v223, v79, v79
	v_add_f32_e32 v222, v222, v223
	s_nop 1
	v_add_f32_dpp v224, v222, v222 quad_perm:[1,0,3,2] row_mask:0xf bank_mask:0xf
	s_nop 1
	v_add_f32_dpp v224, v224, v224 quad_perm:[2,3,0,1] row_mask:0xf bank_mask:0xf
	s_nop 1
	v_add_f32_dpp v224, v224, v224 row_half_mirror row_mask:0xf bank_mask:0xf
	s_nop 1
	v_add_f32_dpp v224, v224, v224 row_mirror row_mask:0xf bank_mask:0xf
	s_nop 1
	v_readlane_b32 s40, v224, 0
	v_readlane_b32 s41, v224, 16
	v_readlane_b32 s42, v224, 32
	v_readlane_b32 s43, v224, 48
	s_nop 1
	v_mov_b32_e32 v225, s40
	v_add_f32_e32 v225, s41, v225
	v_add_f32_e32 v225, s42, v225
	v_add_f32_e32 v225, s43, v225
	v_fmamk_f32 v225, v225, 0x3a000000, v195
	v_rsq_f32_e32 v225, v225
	s_nop 0
	s_add_i32 s0, s6, 1
	s_lshl_b32 s1, s0, 12
	s_add_u32 s26, s84, s1
	s_addc_u32 s27, s85, 0
	s_add_u32 s26, s26, 0x4000000
	s_addc_u32 s27, s27, 0
	v_mul_f32_e32 v216, v225, v48
	v_mul_f32_e32 v217, v225, v49
	v_mul_f32_e32 v218, v225, v50
	v_mul_f32_e32 v219, v225, v51
	v_fma_f32 v216, v216, v128, v160
	v_fma_f32 v217, v217, v129, v161
	v_fma_f32 v218, v218, v130, v162
	v_fma_f32 v219, v219, v131, v163
	v_cvt_pk_bf16_f32 v196, v216, v217
	v_cvt_pk_bf16_f32 v197, v218, v219
	global_store_dwordx2 v194, v[196:197], s[26:27] offset:0
	v_mul_f32_e32 v216, v225, v52
	v_mul_f32_e32 v217, v225, v53
	v_mul_f32_e32 v218, v225, v54
	v_mul_f32_e32 v219, v225, v55
	v_fma_f32 v216, v216, v132, v164
	v_fma_f32 v217, v217, v133, v165
	v_fma_f32 v218, v218, v134, v166
	v_fma_f32 v219, v219, v135, v167
	v_cvt_pk_bf16_f32 v220, v216, v217
	v_cvt_pk_bf16_f32 v221, v218, v219
	global_store_dwordx2 v194, v[220:221], s[26:27] offset:512
	v_mul_f32_e32 v216, v225, v56
	v_mul_f32_e32 v217, v225, v57
	v_mul_f32_e32 v218, v225, v58
	v_mul_f32_e32 v219, v225, v59
	v_fma_f32 v216, v216, v136, v168
	v_fma_f32 v217, v217, v137, v169
	v_fma_f32 v218, v218, v138, v170
	v_fma_f32 v219, v219, v139, v171
	v_cvt_pk_bf16_f32 v196, v216, v217
	v_cvt_pk_bf16_f32 v197, v218, v219
	global_store_dwordx2 v194, v[196:197], s[26:27] offset:1024
	v_mul_f32_e32 v216, v225, v60
	v_mul_f32_e32 v217, v225, v61
	v_mul_f32_e32 v218, v225, v62
	v_mul_f32_e32 v219, v225, v63
	v_fma_f32 v216, v216, v140, v172
	v_fma_f32 v217, v217, v141, v173
	v_fma_f32 v218, v218, v142, v174
	v_fma_f32 v219, v219, v143, v175
	v_cvt_pk_bf16_f32 v220, v216, v217
	v_cvt_pk_bf16_f32 v221, v218, v219
	global_store_dwordx2 v194, v[220:221], s[26:27] offset:1536
	v_mul_f32_e32 v216, v225, v64
	v_mul_f32_e32 v217, v225, v65
	v_mul_f32_e32 v218, v225, v66
	v_mul_f32_e32 v219, v225, v67
	v_fma_f32 v216, v216, v144, v176
	v_fma_f32 v217, v217, v145, v177
	v_fma_f32 v218, v218, v146, v178
	v_fma_f32 v219, v219, v147, v179
	v_cvt_pk_bf16_f32 v196, v216, v217
	v_cvt_pk_bf16_f32 v197, v218, v219
	global_store_dwordx2 v194, v[196:197], s[26:27] offset:2048
	v_mul_f32_e32 v216, v225, v68
	v_mul_f32_e32 v217, v225, v69
	v_mul_f32_e32 v218, v225, v70
	v_mul_f32_e32 v219, v225, v71
	v_fma_f32 v216, v216, v148, v180
	v_fma_f32 v217, v217, v149, v181
	v_fma_f32 v218, v218, v150, v182
	v_fma_f32 v219, v219, v151, v183
	v_cvt_pk_bf16_f32 v220, v216, v217
	v_cvt_pk_bf16_f32 v221, v218, v219
	global_store_dwordx2 v194, v[220:221], s[26:27] offset:2560
	v_mul_f32_e32 v216, v225, v72
	v_mul_f32_e32 v217, v225, v73
	v_mul_f32_e32 v218, v225, v74
	v_mul_f32_e32 v219, v225, v75
	v_fma_f32 v216, v216, v152, v184
	v_fma_f32 v217, v217, v153, v185
	v_fma_f32 v218, v218, v154, v186
	v_fma_f32 v219, v219, v155, v187
	v_cvt_pk_bf16_f32 v196, v216, v217
	v_cvt_pk_bf16_f32 v197, v218, v219
	global_store_dwordx2 v194, v[196:197], s[26:27] offset:3072
	v_mul_f32_e32 v216, v225, v76
	v_mul_f32_e32 v217, v225, v77
	v_mul_f32_e32 v218, v225, v78
	v_mul_f32_e32 v219, v225, v79
	v_fma_f32 v216, v216, v156, v188
	v_fma_f32 v217, v217, v157, v189
	v_fma_f32 v218, v218, v158, v190
	v_fma_f32 v219, v219, v159, v191
	v_cvt_pk_bf16_f32 v220, v216, v217
	v_cvt_pk_bf16_f32 v221, v218, v219
	global_store_dwordx2 v194, v[220:221], s[26:27] offset:3584
	s_add_i32 s0, s6, 3
	s_cmp_lt_u32 s0, 0x4000
	s_cselect_b32 s10, s68, s72
	s_cselect_b32 s11, s69, s73
	s_cselect_b32 s1, 0, 0x4000
	s_sub_i32 s1, s0, s1
	s_lshl_b32 s1, s1, 13
	s_add_u32 s10, s10, s1
	s_addc_u32 s11, s11, 0
	s_add_i32 s0, s6, 3
	s_lshl_b32 s1, s0, 12
	s_add_u32 s22, s84, s1
	s_addc_u32 s23, s85, 0
	s_add_u32 s22, s22, 0x11800000
	s_addc_u32 s23, s23, 0
	global_load_dwordx4 v[48:51], v192, s[10:11] offset:0 nt
	global_load_dwordx4 v[52:55], v192, s[10:11] offset:1024 nt
	global_load_dwordx4 v[56:59], v192, s[10:11] offset:2048 nt
	global_load_dwordx4 v[60:63], v192, s[10:11] offset:3072 nt
	global_load_dwordx4 v[64:67], v193, s[10:11] offset:0 nt
	global_load_dwordx4 v[68:71], v193, s[10:11] offset:1024 nt
	global_load_dwordx4 v[72:75], v193, s[10:11] offset:2048 nt
	global_load_dwordx4 v[76:79], v193, s[10:11] offset:3072 nt
	global_load_dwordx2 v[80:81], v194, s[22:23] offset:0
	global_load_dwordx2 v[82:83], v194, s[22:23] offset:512
	global_load_dwordx2 v[84:85], v194, s[22:23] offset:1024
	global_load_dwordx2 v[86:87], v194, s[22:23] offset:1536
	global_load_dwordx2 v[88:89], v194, s[22:23] offset:2048
	global_load_dwordx2 v[90:91], v194, s[22:23] offset:2560
	global_load_dwordx2 v[92:93], v194, s[22:23] offset:3072
	global_load_dwordx2 v[94:95], v194, s[22:23] offset:3584
	s_add_i32 s0, s6, 2
	s_add_i32 s0, s6, 2
	s_lshr_b32 s8, s0, 11
	s_cmp_lt_u32 s0, 0x4000
	s_cselect_b32 s8, s8, 8
	s_cmp_eq_u32 s8, s7
	s_cbranch_scc1 .Lp6_np2
; __device__ __forceinline__ void modulate_store(const f32x4 (&v)[8], float rstd, const float* pn, const float* modr, bf16_t* orow, int lane) {
; #pragma unroll
;     for (int j = 0; j < 8; ++j) { const int col = 4 * lane + 256 * j;
;         const f32x4 g = *(const f32x4*)(pn + col), sh = *(const f32x4*)(modr + col), sc = *(const f32x4*)(modr + DM + col);
;         const f32x4 hh = v[j] * rstd * g * (sc + 1.f) + sh;
; __global__ void __launch_bounds__(NWAVES * 64, 2) mk_fwd(Args args) {
;     ...
;                 const float* m0 = mod + (size_t)r * 6144;
; #pragma unroll
;                 for (int j = 0; j < 8; ++j) { const int col = 4 * F.lane + 256 * j; const f32x4 gt = *(const f32x4*)(m0 + 2 * DM + col), pn = *(const f32x4*)(post_norm + col);
	s_mov_b32 s7, s8
	s_add_i32 s1, s8, 9
	s_mul_i32 s1, s1, 0x6000
	s_add_u32 s44, s84, s1
	s_addc_u32 s45, s85, 0
	s_add_u32 s44, s44, 0x2000
	s_addc_u32 s45, s45, 0
	s_add_i32 s1, s8, 9
	s_mul_i32 s1, s1, 0x6000
	s_add_u32 s36, s84, s1
	s_addc_u32 s37, s85, 0
	s_add_u32 s38, s80, 0x2000
	s_addc_u32 s39, s81, 0
	s_mul_i32 s1, s8, 0x6000
	s_add_u32 s34, s84, s1
	s_addc_u32 s35, s85, 0
	s_add_u32 s34, s34, 0x4000
	s_addc_u32 s35, s35, 0
	global_load_dwordx4 v[96:99], v192, s[34:35] offset:0
	global_load_dwordx4 v[200:203], v192, s[82:83] offset:0
	global_load_dwordx4 v[100:103], v192, s[34:35] offset:1024
	global_load_dwordx4 v[204:207], v192, s[82:83] offset:1024
	global_load_dwordx4 v[104:107], v192, s[34:35] offset:2048
	global_load_dwordx4 v[208:211], v192, s[82:83] offset:2048
	global_load_dwordx4 v[108:111], v192, s[34:35] offset:3072
	global_load_dwordx4 v[212:215], v192, s[82:83] offset:3072
	s_waitcnt vmcnt(0)
	v_mul_f32_e32 v96, v96, v200
	v_mul_f32_e32 v97, v97, v201
	v_mul_f32_e32 v98, v98, v202
	v_mul_f32_e32 v99, v99, v203
	v_mul_f32_e32 v100, v100, v204
	v_mul_f32_e32 v101, v101, v205
	v_mul_f32_e32 v102, v102, v206
	v_mul_f32_e32 v103, v103, v207
	v_mul_f32_e32 v104, v104, v208
	v_mul_f32_e32 v105, v105, v209
	v_mul_f32_e32 v106, v106, v210
	v_mul_f32_e32 v107, v107, v211
	v_mul_f32_e32 v108, v108, v212
	v_mul_f32_e32 v109, v109, v213
	v_mul_f32_e32 v110, v110, v214
	v_mul_f32_e32 v111, v111, v215
	global_load_dwordx4 v[128:131], v192, s[38:39] offset:0
	global_load_dwordx4 v[200:203], v192, s[44:45] offset:0
	global_load_dwordx4 v[160:163], v192, s[36:37] offset:0
	global_load_dwordx4 v[132:135], v192, s[38:39] offset:1024
	global_load_dwordx4 v[204:207], v192, s[44:45] offset:1024
	global_load_dwordx4 v[164:167], v192, s[36:37] offset:1024
	global_load_dwordx4 v[136:139], v192, s[38:39] offset:2048
	global_load_dwordx4 v[208:211], v192, s[44:45] offset:2048
	global_load_dwordx4 v[168:171], v192, s[36:37] offset:2048
	global_load_dwordx4 v[140:143], v192, s[38:39] offset:3072
	global_load_dwordx4 v[212:215], v192, s[44:45] offset:3072
	global_load_dwordx4 v[172:175], v192, s[36:37] offset:3072
	s_waitcnt vmcnt(0)
	v_add_f32_e32 v200, 1.0, v200
	v_add_f32_e32 v201, 1.0, v201
	v_add_f32_e32 v202, 1.0, v202
	v_add_f32_e32 v203, 1.0, v203
	v_mul_f32_e32 v128, v128, v200
	v_mul_f32_e32 v129, v129, v201
	v_mul_f32_e32 v130, v130, v202
	v_mul_f32_e32 v131, v131, v203
	v_add_f32_e32 v204, 1.0, v204
	v_add_f32_e32 v205, 1.0, v205
	v_add_f32_e32 v206, 1.0, v206
	v_add_f32_e32 v207, 1.0, v207
	v_mul_f32_e32 v132, v132, v204
	v_mul_f32_e32 v133, v133, v205
	v_mul_f32_e32 v134, v134, v206
	v_mul_f32_e32 v135, v135, v207
	v_add_f32_e32 v208, 1.0, v208
	v_add_f32_e32 v209, 1.0, v209
	v_add_f32_e32 v210, 1.0, v210
	v_add_f32_e32 v211, 1.0, v211
	v_mul_f32_e32 v136, v136, v208
	v_mul_f32_e32 v137, v137, v209
	v_mul_f32_e32 v138, v138, v210
	v_mul_f32_e32 v139, v139, v211
	v_add_f32_e32 v212, 1.0, v212
	v_add_f32_e32 v213, 1.0, v213
	v_add_f32_e32 v214, 1.0, v214
	v_add_f32_e32 v215, 1.0, v215
	v_mul_f32_e32 v140, v140, v212
	v_mul_f32_e32 v141, v141, v213
	v_mul_f32_e32 v142, v142, v214
	v_mul_f32_e32 v143, v143, v215
	global_load_dwordx4 v[112:115], v193, s[34:35] offset:0
	global_load_dwordx4 v[200:203], v193, s[82:83] offset:0
	global_load_dwordx4 v[116:119], v193, s[34:35] offset:1024
	global_load_dwordx4 v[204:207], v193, s[82:83] offset:1024
	global_load_dwordx4 v[120:123], v193, s[34:35] offset:2048
	global_load_dwordx4 v[208:211], v193, s[82:83] offset:2048
	global_load_dwordx4 v[124:127], v193, s[34:35] offset:3072
	global_load_dwordx4 v[212:215], v193, s[82:83] offset:3072
	s_waitcnt vmcnt(0)
	v_mul_f32_e32 v112, v112, v200
	v_mul_f32_e32 v113, v113, v201
	v_mul_f32_e32 v114, v114, v202
	v_mul_f32_e32 v115, v115, v203
	v_mul_f32_e32 v116, v116, v204
	v_mul_f32_e32 v117, v117, v205
	v_mul_f32_e32 v118, v118, v206
	v_mul_f32_e32 v119, v119, v207
	v_mul_f32_e32 v120, v120, v208
	v_mul_f32_e32 v121, v121, v209
	v_mul_f32_e32 v122, v122, v210
	v_mul_f32_e32 v123, v123, v211
	v_mul_f32_e32 v124, v124, v212
	v_mul_f32_e32 v125, v125, v213
	v_mul_f32_e32 v126, v126, v214
	v_mul_f32_e32 v127, v127, v215
	global_load_dwordx4 v[144:147], v193, s[38:39] offset:0
	global_load_dwordx4 v[200:203], v193, s[44:45] offset:0
	global_load_dwordx4 v[176:179], v193, s[36:37] offset:0
	global_load_dwordx4 v[148:151], v193, s[38:39] offset:1024
	global_load_dwordx4 v[204:207], v193, s[44:45] offset:1024
	global_load_dwordx4 v[180:183], v193, s[36:37] offset:1024
	global_load_dwordx4 v[152:155], v193, s[38:39] offset:2048
	global_load_dwordx4 v[208:211], v193, s[44:45] offset:2048
	global_load_dwordx4 v[184:187], v193, s[36:37] offset:2048
	global_load_dwordx4 v[156:159], v193, s[38:39] offset:3072
	global_load_dwordx4 v[212:215], v193, s[44:45] offset:3072
	global_load_dwordx4 v[188:191], v193, s[36:37] offset:3072
	s_waitcnt vmcnt(0)
	v_add_f32_e32 v200, 1.0, v200
	v_add_f32_e32 v201, 1.0, v201
	v_add_f32_e32 v202, 1.0, v202
	v_add_f32_e32 v203, 1.0, v203
	v_mul_f32_e32 v144, v144, v200
	v_mul_f32_e32 v145, v145, v201
	v_mul_f32_e32 v146, v146, v202
	v_mul_f32_e32 v147, v147, v203
	v_add_f32_e32 v204, 1.0, v204
	v_add_f32_e32 v205, 1.0, v205
	v_add_f32_e32 v206, 1.0, v206
	v_add_f32_e32 v207, 1.0, v207
	v_mul_f32_e32 v148, v148, v204
	v_mul_f32_e32 v149, v149, v205
	v_mul_f32_e32 v150, v150, v206
	v_mul_f32_e32 v151, v151, v207
	v_add_f32_e32 v208, 1.0, v208
	v_add_f32_e32 v209, 1.0, v209
	v_add_f32_e32 v210, 1.0, v210
	v_add_f32_e32 v211, 1.0, v211
	v_mul_f32_e32 v152, v152, v208
	v_mul_f32_e32 v153, v153, v209
	v_mul_f32_e32 v154, v154, v210
	v_mul_f32_e32 v155, v155, v211
	v_add_f32_e32 v212, 1.0, v212
	v_add_f32_e32 v213, 1.0, v213
	v_add_f32_e32 v214, 1.0, v214
	v_add_f32_e32 v215, 1.0, v215
	v_mul_f32_e32 v156, v156, v212
	v_mul_f32_e32 v157, v157, v213
	v_mul_f32_e32 v158, v158, v214
	v_mul_f32_e32 v159, v159, v215
; __device__ __forceinline__ float bf_lo(unsigned w) { return __uint_as_float(w << 16); }
; __device__ __forceinline__ float bf_hi(unsigned w) { return __uint_as_float(w & 0xffff0000u); }
; __global__ void __launch_bounds__(NWAVES * 64, 2) mk_fwd(Args args) {
;     ...
;             for (int q = 0; q < 3; ++q) { const int row = row0 + q; const bool lat = row < ML; const int r = lat ? row / SEQ : 8;
;                 float sy = 0.f;
; #pragma unroll
;                 for (int j = 0; j < 8; ++j) { const float a = bf_lo(yw[q][j].x), b = bf_hi(yw[q][j].x), c2 = bf_lo(yw[q][j].y), d = bf_hi(yw[q][j].y); sy += (a * a + b * b) + (c2 * c2 + d * d); }
;                 const float rsy = __builtin_amdgcn_rsqf(wave_sum(sy) * (1.f / DM) + EPS);
;                 const float* m0 = mod + (size_t)r * 6144;
; #pragma unroll
;                 for (int j = 0; j < 8; ++j) { const int col = 4 * F.lane + 256 * j; const f32x4 gt = *(const f32x4*)(m0 + 2 * DM + col), pn = *(const f32x4*)(post_norm + col);
;                     const f32x4 y4 = (f32x4){bf_lo(yw[q][j].x), bf_hi(yw[q][j].x), bf_lo(yw[q][j].y), bf_hi(yw[q][j].y)};
;                     v[q][j] = v[q][j] + gt * (y4 * rsy * pn);
.Lp6_np2:
	s_waitcnt vmcnt(24)
	v_lshlrev_b32_e32 v216, 16, v32
	v_and_b32_e32 v217, 0xffff0000, v32
	v_lshlrev_b32_e32 v218, 16, v33
	v_and_b32_e32 v219, 0xffff0000, v33
	v_mul_f32_e32 v222, v216, v216
	v_mul_f32_e32 v223, v217, v217
	v_fmac_f32_e32 v222, v218, v218
	v_fmac_f32_e32 v223, v219, v219
	v_lshlrev_b32_e32 v216, 16, v34
	v_and_b32_e32 v217, 0xffff0000, v34
	v_lshlrev_b32_e32 v218, 16, v35
	v_and_b32_e32 v219, 0xffff0000, v35
	v_fmac_f32_e32 v222, v216, v216
	v_fmac_f32_e32 v223, v217, v217
	v_fmac_f32_e32 v222, v218, v218
	v_fmac_f32_e32 v223, v219, v219
	v_lshlrev_b32_e32 v216, 16, v36
	v_and_b32_e32 v217, 0xffff0000, v36
	v_lshlrev_b32_e32 v218, 16, v37
	v_and_b32_e32 v219, 0xffff0000, v37
	v_fmac_f32_e32 v222, v216, v216
	v_fmac_f32_e32 v223, v217, v217
	v_fmac_f32_e32 v222, v218, v218
	v_fmac_f32_e32 v223, v219, v219
	v_lshlrev_b32_e32 v216, 16, v38
	v_and_b32_e32 v217, 0xffff0000, v38
	v_lshlrev_b32_e32 v218, 16, v39
	v_and_b32_e32 v219, 0xffff0000, v39
	v_fmac_f32_e32 v222, v216, v216
	v_fmac_f32_e32 v223, v217, v217
	v_fmac_f32_e32 v222, v218, v218
	v_fmac_f32_e32 v223, v219, v219
	v_lshlrev_b32_e32 v216, 16, v40
	v_and_b32_e32 v217, 0xffff0000, v40
	v_lshlrev_b32_e32 v218, 16, v41
	v_and_b32_e32 v219, 0xffff0000, v41
	v_fmac_f32_e32 v222, v216, v216
	v_fmac_f32_e32 v223, v217, v217
	v_fmac_f32_e32 v222, v218, v218
	v_fmac_f32_e32 v223, v219, v219
	v_lshlrev_b32_e32 v216, 16, v42
	v_and_b32_e32 v217, 0xffff0000, v42
	v_lshlrev_b32_e32 v218, 16, v43
	v_and_b32_e32 v219, 0xffff0000, v43
	v_fmac_f32_e32 v222, v216, v216
	v_fmac_f32_e32 v223, v217, v217
	v_fmac_f32_e32 v222, v218, v218
	v_fmac_f32_e32 v223, v219, v219
	v_lshlrev_b32_e32 v216, 16, v44
	v_and_b32_e32 v217, 0xffff0000, v44
	v_lshlrev_b32_e32 v218, 16, v45
	v_and_b32_e32 v219, 0xffff0000, v45
	v_fmac_f32_e32 v222, v216, v216
	v_fmac_f32_e32 v223, v217, v217
	v_fmac_f32_e32 v222, v218, v218
	v_fmac_f32_e32 v223, v219, v219
	v_lshlrev_b32_e32 v216, 16, v46
	v_and_b32_e32 v217, 0xffff0000, v46
	v_lshlrev_b32_e32 v218, 16, v47
	v_and_b32_e32 v219, 0xffff0000, v47
	v_fmac_f32_e32 v222, v216, v216
	v_fmac_f32_e32 v223, v217, v217
	v_fmac_f32_e32 v222, v218, v218
	v_fmac_f32_e32 v223, v219, v219
	v_add_f32_e32 v222, v222, v223
	s_nop 1
	v_add_f32_dpp v224, v222, v222 quad_perm:[1,0,3,2] row_mask:0xf bank_mask:0xf
	s_nop 1
	v_add_f32_dpp v224, v224, v224 quad_perm:[2,3,0,1] row_mask:0xf bank_mask:0xf
	s_nop 1
	v_add_f32_dpp v224, v224, v224 row_half_mirror row_mask:0xf bank_mask:0xf
	s_nop 1
	v_add_f32_dpp v224, v224, v224 row_mirror row_mask:0xf bank_mask:0xf
	s_nop 1
	v_readlane_b32 s40, v224, 0
	v_readlane_b32 s41, v224, 16
	v_readlane_b32 s42, v224, 32
	v_readlane_b32 s43, v224, 48
	s_nop 1
	v_mov_b32_e32 v225, s40
	v_add_f32_e32 v225, s41, v225
	v_add_f32_e32 v225, s42, v225
	v_add_f32_e32 v225, s43, v225
	v_fmamk_f32 v225, v225, 0x3a000000, v195
	v_rsq_f32_e32 v225, v225
	s_nop 0
	v_lshlrev_b32_e32 v216, 16, v32
	v_and_b32_e32 v217, 0xffff0000, v32
	v_lshlrev_b32_e32 v218, 16, v33
	v_and_b32_e32 v219, 0xffff0000, v33
	v_mul_f32_e32 v216, v225, v216
	v_mul_f32_e32 v217, v225, v217
	v_mul_f32_e32 v218, v225, v218
	v_mul_f32_e32 v219, v225, v219
	v_fmac_f32_e32 v0, v96, v216
	v_fmac_f32_e32 v1, v97, v217
	v_fmac_f32_e32 v2, v98, v218
	v_fmac_f32_e32 v3, v99, v219
	v_lshlrev_b32_e32 v216, 16, v34
	v_and_b32_e32 v217, 0xffff0000, v34
	v_lshlrev_b32_e32 v218, 16, v35
	v_and_b32_e32 v219, 0xffff0000, v35
	v_mul_f32_e32 v216, v225, v216
	v_mul_f32_e32 v217, v225, v217
	v_mul_f32_e32 v218, v225, v218
	v_mul_f32_e32 v219, v225, v219
	v_fmac_f32_e32 v4, v100, v216
	v_fmac_f32_e32 v5, v101, v217
	v_fmac_f32_e32 v6, v102, v218
	v_fmac_f32_e32 v7, v103, v219
	v_lshlrev_b32_e32 v216, 16, v36
	v_and_b32_e32 v217, 0xffff0000, v36
	v_lshlrev_b32_e32 v218, 16, v37
	v_and_b32_e32 v219, 0xffff0000, v37
	v_mul_f32_e32 v216, v225, v216
	v_mul_f32_e32 v217, v225, v217
	v_mul_f32_e32 v218, v225, v218
	v_mul_f32_e32 v219, v225, v219
	v_fmac_f32_e32 v8, v104, v216
	v_fmac_f32_e32 v9, v105, v217
	v_fmac_f32_e32 v10, v106, v218
	v_fmac_f32_e32 v11, v107, v219
	v_lshlrev_b32_e32 v216, 16, v38
	v_and_b32_e32 v217, 0xffff0000, v38
	v_lshlrev_b32_e32 v218, 16, v39
	v_and_b32_e32 v219, 0xffff0000, v39
	v_mul_f32_e32 v216, v225, v216
	v_mul_f32_e32 v217, v225, v217
	v_mul_f32_e32 v218, v225, v218
	v_mul_f32_e32 v219, v225, v219
	v_fmac_f32_e32 v12, v108, v216
	v_fmac_f32_e32 v13, v109, v217
	v_fmac_f32_e32 v14, v110, v218
	v_fmac_f32_e32 v15, v111, v219
	v_lshlrev_b32_e32 v216, 16, v40
	v_and_b32_e32 v217, 0xffff0000, v40
	v_lshlrev_b32_e32 v218, 16, v41
	v_and_b32_e32 v219, 0xffff0000, v41
	v_mul_f32_e32 v216, v225, v216
	v_mul_f32_e32 v217, v225, v217
	v_mul_f32_e32 v218, v225, v218
	v_mul_f32_e32 v219, v225, v219
	v_fmac_f32_e32 v16, v112, v216
	v_fmac_f32_e32 v17, v113, v217
	v_fmac_f32_e32 v18, v114, v218
	v_fmac_f32_e32 v19, v115, v219
	v_lshlrev_b32_e32 v216, 16, v42
	v_and_b32_e32 v217, 0xffff0000, v42
	v_lshlrev_b32_e32 v218, 16, v43
	v_and_b32_e32 v219, 0xffff0000, v43
	v_mul_f32_e32 v216, v225, v216
	v_mul_f32_e32 v217, v225, v217
	v_mul_f32_e32 v218, v225, v218
	v_mul_f32_e32 v219, v225, v219
	v_fmac_f32_e32 v20, v116, v216
	v_fmac_f32_e32 v21, v117, v217
	v_fmac_f32_e32 v22, v118, v218
	v_fmac_f32_e32 v23, v119, v219
	v_lshlrev_b32_e32 v216, 16, v44
	v_and_b32_e32 v217, 0xffff0000, v44
	v_lshlrev_b32_e32 v218, 16, v45
	v_and_b32_e32 v219, 0xffff0000, v45
	v_mul_f32_e32 v216, v225, v216
	v_mul_f32_e32 v217, v225, v217
	v_mul_f32_e32 v218, v225, v218
	v_mul_f32_e32 v219, v225, v219
	v_fmac_f32_e32 v24, v120, v216
	v_fmac_f32_e32 v25, v121, v217
	v_fmac_f32_e32 v26, v122, v218
; __device__ __forceinline__ unsigned cvt_pk_bf16(float lo, float hi) { unsigned r; asm volatile("v_cvt_pk_bf16_f32 %0, %1, %2" : "=v"(r) : "v"(lo), "v"(hi)); return r; }
; __device__ __forceinline__ float sumsq8(const f32x4 (&v)[8]) {
;     float s = 0.f;
; #pragma unroll
;     for (int j = 0; j < 8; ++j) s += (v[j][0] * v[j][0] + v[j][1] * v[j][1]) + (v[j][2] * v[j][2] + v[j][3] * v[j][3]);
;     return wave_sum(s);
; }
; __device__ __forceinline__ void modulate_store(const f32x4 (&v)[8], float rstd, const float* pn, const float* modr, bf16_t* orow, int lane) {
; #pragma unroll
;     for (int j = 0; j < 8; ++j) { const int col = 4 * lane + 256 * j;
;         const f32x4 g = *(const f32x4*)(pn + col), sh = *(const f32x4*)(modr + col), sc = *(const f32x4*)(modr + DM + col);
;         const f32x4 hh = v[j] * rstd * g * (sc + 1.f) + sh;
;         u32x2 w; w.x = cvt_pk_bf16(hh[0], hh[1]); w.y = cvt_pk_bf16(hh[2], hh[3]);
;         *(u32x2*)(orow + col) = w; }
; }
; __global__ void __launch_bounds__(NWAVES * 64, 2) mk_fwd(Args args) {
;     ...
;         for (int row0 = F.gw * 3; row0 < MT; row0 += F.NGW * 3) {
;             f32x4 v[3][8]; u32x2 yw[3][8];
; #pragma unroll
;             for (int q = 0; q < 3; ++q) { const int row = row0 + q; const float* src = row < ML ? x + (size_t)row * DM : ctx + (size_t)(row - ML) * DM; load_row_f32(src, F.lane, v[q]);
;                 const bf16_t* yr = Y + (size_t)row * DM;
; #pragma unroll
;                 for (int j = 0; j < 8; ++j) yw[q][j] = *(const u32x2*)(yr + 4 * F.lane + 256 * j); }
	v_fmac_f32_e32 v27, v123, v219
	v_lshlrev_b32_e32 v216, 16, v46
	v_and_b32_e32 v217, 0xffff0000, v46
	v_lshlrev_b32_e32 v218, 16, v47
	v_and_b32_e32 v219, 0xffff0000, v47
	v_mul_f32_e32 v216, v225, v216
	v_mul_f32_e32 v217, v225, v217
	v_mul_f32_e32 v218, v225, v218
	v_mul_f32_e32 v219, v225, v219
	v_fmac_f32_e32 v28, v124, v216
	v_fmac_f32_e32 v29, v125, v217
	v_fmac_f32_e32 v30, v126, v218
	v_fmac_f32_e32 v31, v127, v219
	v_mul_f32_e32 v222, v0, v0
	v_mul_f32_e32 v223, v1, v1
	v_fmac_f32_e32 v222, v2, v2
	v_fmac_f32_e32 v223, v3, v3
	v_fmac_f32_e32 v222, v4, v4
	v_fmac_f32_e32 v223, v5, v5
	v_fmac_f32_e32 v222, v6, v6
	v_fmac_f32_e32 v223, v7, v7
	v_fmac_f32_e32 v222, v8, v8
	v_fmac_f32_e32 v223, v9, v9
	v_fmac_f32_e32 v222, v10, v10
	v_fmac_f32_e32 v223, v11, v11
	v_fmac_f32_e32 v222, v12, v12
	v_fmac_f32_e32 v223, v13, v13
	v_fmac_f32_e32 v222, v14, v14
	v_fmac_f32_e32 v223, v15, v15
	v_fmac_f32_e32 v222, v16, v16
	v_fmac_f32_e32 v223, v17, v17
	v_fmac_f32_e32 v222, v18, v18
	v_fmac_f32_e32 v223, v19, v19
	v_fmac_f32_e32 v222, v20, v20
	v_fmac_f32_e32 v223, v21, v21
	v_fmac_f32_e32 v222, v22, v22
	v_fmac_f32_e32 v223, v23, v23
	v_fmac_f32_e32 v222, v24, v24
	v_fmac_f32_e32 v223, v25, v25
	v_fmac_f32_e32 v222, v26, v26
	v_fmac_f32_e32 v223, v27, v27
	v_fmac_f32_e32 v222, v28, v28
	v_fmac_f32_e32 v223, v29, v29
	v_fmac_f32_e32 v222, v30, v30
	v_fmac_f32_e32 v223, v31, v31
	v_add_f32_e32 v222, v222, v223
	s_nop 1
	v_add_f32_dpp v224, v222, v222 quad_perm:[1,0,3,2] row_mask:0xf bank_mask:0xf
	s_nop 1
	v_add_f32_dpp v224, v224, v224 quad_perm:[2,3,0,1] row_mask:0xf bank_mask:0xf
	s_nop 1
	v_add_f32_dpp v224, v224, v224 row_half_mirror row_mask:0xf bank_mask:0xf
	s_nop 1
	v_add_f32_dpp v224, v224, v224 row_mirror row_mask:0xf bank_mask:0xf
	s_nop 1
	v_readlane_b32 s40, v224, 0
	v_readlane_b32 s41, v224, 16
	v_readlane_b32 s42, v224, 32
	v_readlane_b32 s43, v224, 48
	s_nop 1
	v_mov_b32_e32 v225, s40
	v_add_f32_e32 v225, s41, v225
	v_add_f32_e32 v225, s42, v225
	v_add_f32_e32 v225, s43, v225
	v_fmamk_f32 v225, v225, 0x3a000000, v195
	v_rsq_f32_e32 v225, v225
	s_nop 0
	s_add_i32 s0, s6, 2
	s_lshl_b32 s1, s0, 12
	s_add_u32 s26, s84, s1
	s_addc_u32 s27, s85, 0
	s_add_u32 s26, s26, 0x4000000
	s_addc_u32 s27, s27, 0
	v_mul_f32_e32 v216, v225, v0
	v_mul_f32_e32 v217, v225, v1
	v_mul_f32_e32 v218, v225, v2
	v_mul_f32_e32 v219, v225, v3
	v_fma_f32 v216, v216, v128, v160
	v_fma_f32 v217, v217, v129, v161
	v_fma_f32 v218, v218, v130, v162
	v_fma_f32 v219, v219, v131, v163
	v_cvt_pk_bf16_f32 v196, v216, v217
	v_cvt_pk_bf16_f32 v197, v218, v219
	global_store_dwordx2 v194, v[196:197], s[26:27] offset:0
	v_mul_f32_e32 v216, v225, v4
	v_mul_f32_e32 v217, v225, v5
	v_mul_f32_e32 v218, v225, v6
	v_mul_f32_e32 v219, v225, v7
	v_fma_f32 v216, v216, v132, v164
	v_fma_f32 v217, v217, v133, v165
	v_fma_f32 v218, v218, v134, v166
	v_fma_f32 v219, v219, v135, v167
	v_cvt_pk_bf16_f32 v220, v216, v217
	v_cvt_pk_bf16_f32 v221, v218, v219
	global_store_dwordx2 v194, v[220:221], s[26:27] offset:512
	v_mul_f32_e32 v216, v225, v8
	v_mul_f32_e32 v217, v225, v9
	v_mul_f32_e32 v218, v225, v10
	v_mul_f32_e32 v219, v225, v11
	v_fma_f32 v216, v216, v136, v168
	v_fma_f32 v217, v217, v137, v169
	v_fma_f32 v218, v218, v138, v170
	v_fma_f32 v219, v219, v139, v171
	v_cvt_pk_bf16_f32 v196, v216, v217
	v_cvt_pk_bf16_f32 v197, v218, v219
	global_store_dwordx2 v194, v[196:197], s[26:27] offset:1024
	v_mul_f32_e32 v216, v225, v12
	v_mul_f32_e32 v217, v225, v13
	v_mul_f32_e32 v218, v225, v14
	v_mul_f32_e32 v219, v225, v15
	v_fma_f32 v216, v216, v140, v172
	v_fma_f32 v217, v217, v141, v173
	v_fma_f32 v218, v218, v142, v174
	v_fma_f32 v219, v219, v143, v175
	v_cvt_pk_bf16_f32 v220, v216, v217
	v_cvt_pk_bf16_f32 v221, v218, v219
	global_store_dwordx2 v194, v[220:221], s[26:27] offset:1536
	v_mul_f32_e32 v216, v225, v16
	v_mul_f32_e32 v217, v225, v17
	v_mul_f32_e32 v218, v225, v18
	v_mul_f32_e32 v219, v225, v19
	v_fma_f32 v216, v216, v144, v176
	v_fma_f32 v217, v217, v145, v177
	v_fma_f32 v218, v218, v146, v178
	v_fma_f32 v219, v219, v147, v179
	v_cvt_pk_bf16_f32 v196, v216, v217
	v_cvt_pk_bf16_f32 v197, v218, v219
	global_store_dwordx2 v194, v[196:197], s[26:27] offset:2048
	v_mul_f32_e32 v216, v225, v20
	v_mul_f32_e32 v217, v225, v21
	v_mul_f32_e32 v218, v225, v22
	v_mul_f32_e32 v219, v225, v23
	v_fma_f32 v216, v216, v148, v180
	v_fma_f32 v217, v217, v149, v181
	v_fma_f32 v218, v218, v150, v182
	v_fma_f32 v219, v219, v151, v183
	v_cvt_pk_bf16_f32 v220, v216, v217
	v_cvt_pk_bf16_f32 v221, v218, v219
	global_store_dwordx2 v194, v[220:221], s[26:27] offset:2560
	v_mul_f32_e32 v216, v225, v24
	v_mul_f32_e32 v217, v225, v25
	v_mul_f32_e32 v218, v225, v26
	v_mul_f32_e32 v219, v225, v27
	v_fma_f32 v216, v216, v152, v184
	v_fma_f32 v217, v217, v153, v185
	v_fma_f32 v218, v218, v154, v186
	v_fma_f32 v219, v219, v155, v187
	v_cvt_pk_bf16_f32 v196, v216, v217
	v_cvt_pk_bf16_f32 v197, v218, v219
	global_store_dwordx2 v194, v[196:197], s[26:27] offset:3072
	v_mul_f32_e32 v216, v225, v28
	v_mul_f32_e32 v217, v225, v29
	v_mul_f32_e32 v218, v225, v30
	v_mul_f32_e32 v219, v225, v31
	v_fma_f32 v216, v216, v156, v188
	v_fma_f32 v217, v217, v157, v189
	v_fma_f32 v218, v218, v158, v190
	v_fma_f32 v219, v219, v159, v191
	v_cvt_pk_bf16_f32 v220, v216, v217
	v_cvt_pk_bf16_f32 v221, v218, v219
	global_store_dwordx2 v194, v[220:221], s[26:27] offset:3584
	s_add_i32 s0, s6, 4
	s_cmp_lt_u32 s0, 0x4000
	s_cselect_b32 s10, s68, s72
	s_cselect_b32 s11, s69, s73
	s_cselect_b32 s1, 0, 0x4000
	s_sub_i32 s1, s0, s1
	s_lshl_b32 s1, s1, 13
	s_add_u32 s10, s10, s1
	s_addc_u32 s11, s11, 0
	s_add_i32 s0, s6, 4
	s_lshl_b32 s1, s0, 12
	s_add_u32 s22, s84, s1
	s_addc_u32 s23, s85, 0
	s_add_u32 s22, s22, 0x11800000
	s_addc_u32 s23, s23, 0
	global_load_dwordx4 v[0:3], v192, s[10:11] offset:0 nt
	global_load_dwordx4 v[4:7], v192, s[10:11] offset:1024 nt
	global_load_dwordx4 v[8:11], v192, s[10:11] offset:2048 nt
	global_load_dwordx4 v[12:15], v192, s[10:11] offset:3072 nt
	global_load_dwordx4 v[16:19], v193, s[10:11] offset:0 nt
	global_load_dwordx4 v[20:23], v193, s[10:11] offset:1024 nt
	global_load_dwordx4 v[24:27], v193, s[10:11] offset:2048 nt
	global_load_dwordx4 v[28:31], v193, s[10:11] offset:3072 nt
	global_load_dwordx2 v[32:33], v194, s[22:23] offset:0
	global_load_dwordx2 v[34:35], v194, s[22:23] offset:512
	global_load_dwordx2 v[36:37], v194, s[22:23] offset:1024
	global_load_dwordx2 v[38:39], v194, s[22:23] offset:1536
	global_load_dwordx2 v[40:41], v194, s[22:23] offset:2048
	global_load_dwordx2 v[42:43], v194, s[22:23] offset:2560
	global_load_dwordx2 v[44:45], v194, s[22:23] offset:3072
	global_load_dwordx2 v[46:47], v194, s[22:23] offset:3584
	s_add_i32 s0, s6, 3
	s_add_i32 s0, s6, 3
	s_lshr_b32 s8, s0, 11
	s_cmp_lt_u32 s0, 0x4000
	s_cselect_b32 s8, s8, 8
	s_cmp_eq_u32 s8, s7
	s_cbranch_scc1 .Lp6_np3
; __device__ __forceinline__ void modulate_store(const f32x4 (&v)[8], float rstd, const float* pn, const float* modr, bf16_t* orow, int lane) {
; #pragma unroll
;     for (int j = 0; j < 8; ++j) { const int col = 4 * lane + 256 * j;
;         const f32x4 g = *(const f32x4*)(pn + col), sh = *(const f32x4*)(modr + col), sc = *(const f32x4*)(modr + DM + col);
;         const f32x4 hh = v[j] * rstd * g * (sc + 1.f) + sh;
; __global__ void __launch_bounds__(NWAVES * 64, 2) mk_fwd(Args args) {
;     ...
;                 const float* m0 = mod + (size_t)r * 6144;
; #pragma unroll
;                 for (int j = 0; j < 8; ++j) { const int col = 4 * F.lane + 256 * j; const f32x4 gt = *(const f32x4*)(m0 + 2 * DM + col), pn = *(const f32x4*)(post_norm + col);
	s_mov_b32 s7, s8
	s_add_i32 s1, s8, 9
	s_mul_i32 s1, s1, 0x6000
	s_add_u32 s44, s84, s1
	s_addc_u32 s45, s85, 0
	s_add_u32 s44, s44, 0x2000
	s_addc_u32 s45, s45, 0
	s_add_i32 s1, s8, 9
	s_mul_i32 s1, s1, 0x6000
	s_add_u32 s36, s84, s1
	s_addc_u32 s37, s85, 0
	s_add_u32 s38, s80, 0x2000
	s_addc_u32 s39, s81, 0
	s_mul_i32 s1, s8, 0x6000
	s_add_u32 s34, s84, s1
	s_addc_u32 s35, s85, 0
	s_add_u32 s34, s34, 0x4000
	s_addc_u32 s35, s35, 0
	global_load_dwordx4 v[96:99], v192, s[34:35] offset:0
	global_load_dwordx4 v[200:203], v192, s[82:83] offset:0
	global_load_dwordx4 v[100:103], v192, s[34:35] offset:1024
	global_load_dwordx4 v[204:207], v192, s[82:83] offset:1024
	global_load_dwordx4 v[104:107], v192, s[34:35] offset:2048
	global_load_dwordx4 v[208:211], v192, s[82:83] offset:2048
	global_load_dwordx4 v[108:111], v192, s[34:35] offset:3072
	global_load_dwordx4 v[212:215], v192, s[82:83] offset:3072
	s_waitcnt vmcnt(0)
	v_mul_f32_e32 v96, v96, v200
	v_mul_f32_e32 v97, v97, v201
	v_mul_f32_e32 v98, v98, v202
	v_mul_f32_e32 v99, v99, v203
	v_mul_f32_e32 v100, v100, v204
	v_mul_f32_e32 v101, v101, v205
	v_mul_f32_e32 v102, v102, v206
	v_mul_f32_e32 v103, v103, v207
	v_mul_f32_e32 v104, v104, v208
	v_mul_f32_e32 v105, v105, v209
	v_mul_f32_e32 v106, v106, v210
	v_mul_f32_e32 v107, v107, v211
	v_mul_f32_e32 v108, v108, v212
	v_mul_f32_e32 v109, v109, v213
	v_mul_f32_e32 v110, v110, v214
	v_mul_f32_e32 v111, v111, v215
	global_load_dwordx4 v[128:131], v192, s[38:39] offset:0
	global_load_dwordx4 v[200:203], v192, s[44:45] offset:0
	global_load_dwordx4 v[160:163], v192, s[36:37] offset:0
	global_load_dwordx4 v[132:135], v192, s[38:39] offset:1024
	global_load_dwordx4 v[204:207], v192, s[44:45] offset:1024
	global_load_dwordx4 v[164:167], v192, s[36:37] offset:1024
	global_load_dwordx4 v[136:139], v192, s[38:39] offset:2048
	global_load_dwordx4 v[208:211], v192, s[44:45] offset:2048
	global_load_dwordx4 v[168:171], v192, s[36:37] offset:2048
	global_load_dwordx4 v[140:143], v192, s[38:39] offset:3072
	global_load_dwordx4 v[212:215], v192, s[44:45] offset:3072
	global_load_dwordx4 v[172:175], v192, s[36:37] offset:3072
	s_waitcnt vmcnt(0)
	v_add_f32_e32 v200, 1.0, v200
	v_add_f32_e32 v201, 1.0, v201
	v_add_f32_e32 v202, 1.0, v202
	v_add_f32_e32 v203, 1.0, v203
	v_mul_f32_e32 v128, v128, v200
	v_mul_f32_e32 v129, v129, v201
	v_mul_f32_e32 v130, v130, v202
	v_mul_f32_e32 v131, v131, v203
	v_add_f32_e32 v204, 1.0, v204
	v_add_f32_e32 v205, 1.0, v205
	v_add_f32_e32 v206, 1.0, v206
	v_add_f32_e32 v207, 1.0, v207
	v_mul_f32_e32 v132, v132, v204
	v_mul_f32_e32 v133, v133, v205
	v_mul_f32_e32 v134, v134, v206
	v_mul_f32_e32 v135, v135, v207
	v_add_f32_e32 v208, 1.0, v208
	v_add_f32_e32 v209, 1.0, v209
	v_add_f32_e32 v210, 1.0, v210
	v_add_f32_e32 v211, 1.0, v211
	v_mul_f32_e32 v136, v136, v208
	v_mul_f32_e32 v137, v137, v209
	v_mul_f32_e32 v138, v138, v210
	v_mul_f32_e32 v139, v139, v211
	v_add_f32_e32 v212, 1.0, v212
	v_add_f32_e32 v213, 1.0, v213
	v_add_f32_e32 v214, 1.0, v214
	v_add_f32_e32 v215, 1.0, v215
	v_mul_f32_e32 v140, v140, v212
	v_mul_f32_e32 v141, v141, v213
	v_mul_f32_e32 v142, v142, v214
	v_mul_f32_e32 v143, v143, v215
	global_load_dwordx4 v[112:115], v193, s[34:35] offset:0
	global_load_dwordx4 v[200:203], v193, s[82:83] offset:0
	global_load_dwordx4 v[116:119], v193, s[34:35] offset:1024
	global_load_dwordx4 v[204:207], v193, s[82:83] offset:1024
	global_load_dwordx4 v[120:123], v193, s[34:35] offset:2048
	global_load_dwordx4 v[208:211], v193, s[82:83] offset:2048
	global_load_dwordx4 v[124:127], v193, s[34:35] offset:3072
	global_load_dwordx4 v[212:215], v193, s[82:83] offset:3072
	s_waitcnt vmcnt(0)
	v_mul_f32_e32 v112, v112, v200
	v_mul_f32_e32 v113, v113, v201
	v_mul_f32_e32 v114, v114, v202
	v_mul_f32_e32 v115, v115, v203
	v_mul_f32_e32 v116, v116, v204
	v_mul_f32_e32 v117, v117, v205
	v_mul_f32_e32 v118, v118, v206
	v_mul_f32_e32 v119, v119, v207
	v_mul_f32_e32 v120, v120, v208
	v_mul_f32_e32 v121, v121, v209
	v_mul_f32_e32 v122, v122, v210
	v_mul_f32_e32 v123, v123, v211
	v_mul_f32_e32 v124, v124, v212
	v_mul_f32_e32 v125, v125, v213
	v_mul_f32_e32 v126, v126, v214
	v_mul_f32_e32 v127, v127, v215
	global_load_dwordx4 v[144:147], v193, s[38:39] offset:0
	global_load_dwordx4 v[200:203], v193, s[44:45] offset:0
	global_load_dwordx4 v[176:179], v193, s[36:37] offset:0
	global_load_dwordx4 v[148:151], v193, s[38:39] offset:1024
	global_load_dwordx4 v[204:207], v193, s[44:45] offset:1024
	global_load_dwordx4 v[180:183], v193, s[36:37] offset:1024
	global_load_dwordx4 v[152:155], v193, s[38:39] offset:2048
	global_load_dwordx4 v[208:211], v193, s[44:45] offset:2048
	global_load_dwordx4 v[184:187], v193, s[36:37] offset:2048
	global_load_dwordx4 v[156:159], v193, s[38:39] offset:3072
	global_load_dwordx4 v[212:215], v193, s[44:45] offset:3072
	global_load_dwordx4 v[188:191], v193, s[36:37] offset:3072
	s_waitcnt vmcnt(0)
	v_add_f32_e32 v200, 1.0, v200
	v_add_f32_e32 v201, 1.0, v201
	v_add_f32_e32 v202, 1.0, v202
	v_add_f32_e32 v203, 1.0, v203
	v_mul_f32_e32 v144, v144, v200
	v_mul_f32_e32 v145, v145, v201
	v_mul_f32_e32 v146, v146, v202
	v_mul_f32_e32 v147, v147, v203
	v_add_f32_e32 v204, 1.0, v204
	v_add_f32_e32 v205, 1.0, v205
	v_add_f32_e32 v206, 1.0, v206
	v_add_f32_e32 v207, 1.0, v207
	v_mul_f32_e32 v148, v148, v204
	v_mul_f32_e32 v149, v149, v205
	v_mul_f32_e32 v150, v150, v206
	v_mul_f32_e32 v151, v151, v207
	v_add_f32_e32 v208, 1.0, v208
	v_add_f32_e32 v209, 1.0, v209
	v_add_f32_e32 v210, 1.0, v210
	v_add_f32_e32 v211, 1.0, v211
	v_mul_f32_e32 v152, v152, v208
	v_mul_f32_e32 v153, v153, v209
	v_mul_f32_e32 v154, v154, v210
	v_mul_f32_e32 v155, v155, v211
	v_add_f32_e32 v212, 1.0, v212
	v_add_f32_e32 v213, 1.0, v213
	v_add_f32_e32 v214, 1.0, v214
	v_add_f32_e32 v215, 1.0, v215
	v_mul_f32_e32 v156, v156, v212
	v_mul_f32_e32 v157, v157, v213
	v_mul_f32_e32 v158, v158, v214
	v_mul_f32_e32 v159, v159, v215
; __device__ __forceinline__ float bf_lo(unsigned w) { return __uint_as_float(w << 16); }
; __device__ __forceinline__ float bf_hi(unsigned w) { return __uint_as_float(w & 0xffff0000u); }
; __global__ void __launch_bounds__(NWAVES * 64, 2) mk_fwd(Args args) {
;     ...
;             for (int q = 0; q < 3; ++q) { const int row = row0 + q; const bool lat = row < ML; const int r = lat ? row / SEQ : 8;
;                 float sy = 0.f;
; #pragma unroll
;                 for (int j = 0; j < 8; ++j) { const float a = bf_lo(yw[q][j].x), b = bf_hi(yw[q][j].x), c2 = bf_lo(yw[q][j].y), d = bf_hi(yw[q][j].y); sy += (a * a + b * b) + (c2 * c2 + d * d); }
;                 const float rsy = __builtin_amdgcn_rsqf(wave_sum(sy) * (1.f / DM) + EPS);
;                 const float* m0 = mod + (size_t)r * 6144;
; #pragma unroll
;                 for (int j = 0; j < 8; ++j) { const int col = 4 * F.lane + 256 * j; const f32x4 gt = *(const f32x4*)(m0 + 2 * DM + col), pn = *(const f32x4*)(post_norm + col);
;                     const f32x4 y4 = (f32x4){bf_lo(yw[q][j].x), bf_hi(yw[q][j].x), bf_lo(yw[q][j].y), bf_hi(yw[q][j].y)};
;                     v[q][j] = v[q][j] + gt * (y4 * rsy * pn);
.Lp6_np3:
	s_waitcnt vmcnt(24)
	v_lshlrev_b32_e32 v216, 16, v80
	v_and_b32_e32 v217, 0xffff0000, v80
	v_lshlrev_b32_e32 v218, 16, v81
	v_and_b32_e32 v219, 0xffff0000, v81
	v_mul_f32_e32 v222, v216, v216
	v_mul_f32_e32 v223, v217, v217
	v_fmac_f32_e32 v222, v218, v218
	v_fmac_f32_e32 v223, v219, v219
	v_lshlrev_b32_e32 v216, 16, v82
	v_and_b32_e32 v217, 0xffff0000, v82
	v_lshlrev_b32_e32 v218, 16, v83
	v_and_b32_e32 v219, 0xffff0000, v83
	v_fmac_f32_e32 v222, v216, v216
	v_fmac_f32_e32 v223, v217, v217
	v_fmac_f32_e32 v222, v218, v218
	v_fmac_f32_e32 v223, v219, v219
	v_lshlrev_b32_e32 v216, 16, v84
	v_and_b32_e32 v217, 0xffff0000, v84
	v_lshlrev_b32_e32 v218, 16, v85
	v_and_b32_e32 v219, 0xffff0000, v85
	v_fmac_f32_e32 v222, v216, v216
	v_fmac_f32_e32 v223, v217, v217
	v_fmac_f32_e32 v222, v218, v218
	v_fmac_f32_e32 v223, v219, v219
	v_lshlrev_b32_e32 v216, 16, v86
	v_and_b32_e32 v217, 0xffff0000, v86
	v_lshlrev_b32_e32 v218, 16, v87
	v_and_b32_e32 v219, 0xffff0000, v87
	v_fmac_f32_e32 v222, v216, v216
	v_fmac_f32_e32 v223, v217, v217
	v_fmac_f32_e32 v222, v218, v218
	v_fmac_f32_e32 v223, v219, v219
	v_lshlrev_b32_e32 v216, 16, v88
	v_and_b32_e32 v217, 0xffff0000, v88
	v_lshlrev_b32_e32 v218, 16, v89
	v_and_b32_e32 v219, 0xffff0000, v89
	v_fmac_f32_e32 v222, v216, v216
	v_fmac_f32_e32 v223, v217, v217
	v_fmac_f32_e32 v222, v218, v218
	v_fmac_f32_e32 v223, v219, v219
	v_lshlrev_b32_e32 v216, 16, v90
	v_and_b32_e32 v217, 0xffff0000, v90
	v_lshlrev_b32_e32 v218, 16, v91
	v_and_b32_e32 v219, 0xffff0000, v91
	v_fmac_f32_e32 v222, v216, v216
	v_fmac_f32_e32 v223, v217, v217
	v_fmac_f32_e32 v222, v218, v218
	v_fmac_f32_e32 v223, v219, v219
	v_lshlrev_b32_e32 v216, 16, v92
	v_and_b32_e32 v217, 0xffff0000, v92
	v_lshlrev_b32_e32 v218, 16, v93
	v_and_b32_e32 v219, 0xffff0000, v93
	v_fmac_f32_e32 v222, v216, v216
	v_fmac_f32_e32 v223, v217, v217
	v_fmac_f32_e32 v222, v218, v218
	v_fmac_f32_e32 v223, v219, v219
	v_lshlrev_b32_e32 v216, 16, v94
	v_and_b32_e32 v217, 0xffff0000, v94
	v_lshlrev_b32_e32 v218, 16, v95
	v_and_b32_e32 v219, 0xffff0000, v95
	v_fmac_f32_e32 v222, v216, v216
	v_fmac_f32_e32 v223, v217, v217
	v_fmac_f32_e32 v222, v218, v218
	v_fmac_f32_e32 v223, v219, v219
	v_add_f32_e32 v222, v222, v223
	s_nop 1
	v_add_f32_dpp v224, v222, v222 quad_perm:[1,0,3,2] row_mask:0xf bank_mask:0xf
	s_nop 1
	v_add_f32_dpp v224, v224, v224 quad_perm:[2,3,0,1] row_mask:0xf bank_mask:0xf
	s_nop 1
	v_add_f32_dpp v224, v224, v224 row_half_mirror row_mask:0xf bank_mask:0xf
	s_nop 1
	v_add_f32_dpp v224, v224, v224 row_mirror row_mask:0xf bank_mask:0xf
	s_nop 1
	v_readlane_b32 s40, v224, 0
	v_readlane_b32 s41, v224, 16
	v_readlane_b32 s42, v224, 32
	v_readlane_b32 s43, v224, 48
	s_nop 1
	v_mov_b32_e32 v225, s40
	v_add_f32_e32 v225, s41, v225
	v_add_f32_e32 v225, s42, v225
	v_add_f32_e32 v225, s43, v225
	v_fmamk_f32 v225, v225, 0x3a000000, v195
	v_rsq_f32_e32 v225, v225
	s_nop 0
	v_lshlrev_b32_e32 v216, 16, v80
	v_and_b32_e32 v217, 0xffff0000, v80
	v_lshlrev_b32_e32 v218, 16, v81
	v_and_b32_e32 v219, 0xffff0000, v81
	v_mul_f32_e32 v216, v225, v216
	v_mul_f32_e32 v217, v225, v217
	v_mul_f32_e32 v218, v225, v218
	v_mul_f32_e32 v219, v225, v219
	v_fmac_f32_e32 v48, v96, v216
	v_fmac_f32_e32 v49, v97, v217
	v_fmac_f32_e32 v50, v98, v218
	v_fmac_f32_e32 v51, v99, v219
	v_lshlrev_b32_e32 v216, 16, v82
	v_and_b32_e32 v217, 0xffff0000, v82
	v_lshlrev_b32_e32 v218, 16, v83
	v_and_b32_e32 v219, 0xffff0000, v83
	v_mul_f32_e32 v216, v225, v216
	v_mul_f32_e32 v217, v225, v217
	v_mul_f32_e32 v218, v225, v218
	v_mul_f32_e32 v219, v225, v219
	v_fmac_f32_e32 v52, v100, v216
	v_fmac_f32_e32 v53, v101, v217
	v_fmac_f32_e32 v54, v102, v218
	v_fmac_f32_e32 v55, v103, v219
	v_lshlrev_b32_e32 v216, 16, v84
	v_and_b32_e32 v217, 0xffff0000, v84
	v_lshlrev_b32_e32 v218, 16, v85
	v_and_b32_e32 v219, 0xffff0000, v85
	v_mul_f32_e32 v216, v225, v216
	v_mul_f32_e32 v217, v225, v217
	v_mul_f32_e32 v218, v225, v218
	v_mul_f32_e32 v219, v225, v219
	v_fmac_f32_e32 v56, v104, v216
	v_fmac_f32_e32 v57, v105, v217
	v_fmac_f32_e32 v58, v106, v218
	v_fmac_f32_e32 v59, v107, v219
	v_lshlrev_b32_e32 v216, 16, v86
	v_and_b32_e32 v217, 0xffff0000, v86
	v_lshlrev_b32_e32 v218, 16, v87
	v_and_b32_e32 v219, 0xffff0000, v87
	v_mul_f32_e32 v216, v225, v216
	v_mul_f32_e32 v217, v225, v217
	v_mul_f32_e32 v218, v225, v218
	v_mul_f32_e32 v219, v225, v219
	v_fmac_f32_e32 v60, v108, v216
	v_fmac_f32_e32 v61, v109, v217
	v_fmac_f32_e32 v62, v110, v218
	v_fmac_f32_e32 v63, v111, v219
	v_lshlrev_b32_e32 v216, 16, v88
	v_and_b32_e32 v217, 0xffff0000, v88
	v_lshlrev_b32_e32 v218, 16, v89
	v_and_b32_e32 v219, 0xffff0000, v89
	v_mul_f32_e32 v216, v225, v216
	v_mul_f32_e32 v217, v225, v217
	v_mul_f32_e32 v218, v225, v218
	v_mul_f32_e32 v219, v225, v219
	v_fmac_f32_e32 v64, v112, v216
	v_fmac_f32_e32 v65, v113, v217
	v_fmac_f32_e32 v66, v114, v218
	v_fmac_f32_e32 v67, v115, v219
	v_lshlrev_b32_e32 v216, 16, v90
	v_and_b32_e32 v217, 0xffff0000, v90
	v_lshlrev_b32_e32 v218, 16, v91
	v_and_b32_e32 v219, 0xffff0000, v91
	v_mul_f32_e32 v216, v225, v216
	v_mul_f32_e32 v217, v225, v217
	v_mul_f32_e32 v218, v225, v218
	v_mul_f32_e32 v219, v225, v219
	v_fmac_f32_e32 v68, v116, v216
	v_fmac_f32_e32 v69, v117, v217
	v_fmac_f32_e32 v70, v118, v218
	v_fmac_f32_e32 v71, v119, v219
	v_lshlrev_b32_e32 v216, 16, v92
	v_and_b32_e32 v217, 0xffff0000, v92
	v_lshlrev_b32_e32 v218, 16, v93
	v_and_b32_e32 v219, 0xffff0000, v93
	v_mul_f32_e32 v216, v225, v216
	v_mul_f32_e32 v217, v225, v217
	v_mul_f32_e32 v218, v225, v218
	v_mul_f32_e32 v219, v225, v219
	v_fmac_f32_e32 v72, v120, v216
	v_fmac_f32_e32 v73, v121, v217
	v_fmac_f32_e32 v74, v122, v218
; __device__ __forceinline__ unsigned cvt_pk_bf16(float lo, float hi) { unsigned r; asm volatile("v_cvt_pk_bf16_f32 %0, %1, %2" : "=v"(r) : "v"(lo), "v"(hi)); return r; }
; __device__ __forceinline__ float sumsq8(const f32x4 (&v)[8]) {
;     float s = 0.f;
; #pragma unroll
;     for (int j = 0; j < 8; ++j) s += (v[j][0] * v[j][0] + v[j][1] * v[j][1]) + (v[j][2] * v[j][2] + v[j][3] * v[j][3]);
;     return wave_sum(s);
; }
; __device__ __forceinline__ void modulate_store(const f32x4 (&v)[8], float rstd, const float* pn, const float* modr, bf16_t* orow, int lane) {
; #pragma unroll
;     for (int j = 0; j < 8; ++j) { const int col = 4 * lane + 256 * j;
;         const f32x4 g = *(const f32x4*)(pn + col), sh = *(const f32x4*)(modr + col), sc = *(const f32x4*)(modr + DM + col);
;         const f32x4 hh = v[j] * rstd * g * (sc + 1.f) + sh;
;         u32x2 w; w.x = cvt_pk_bf16(hh[0], hh[1]); w.y = cvt_pk_bf16(hh[2], hh[3]);
;         *(u32x2*)(orow + col) = w; }
; }
; __global__ void __launch_bounds__(NWAVES * 64, 2) mk_fwd(Args args) {
;     ...
;         for (int row0 = F.gw * 3; row0 < MT; row0 += F.NGW * 3) {
;             f32x4 v[3][8]; u32x2 yw[3][8];
; #pragma unroll
;             for (int q = 0; q < 3; ++q) { const int row = row0 + q; const float* src = row < ML ? x + (size_t)row * DM : ctx + (size_t)(row - ML) * DM; load_row_f32(src, F.lane, v[q]);
;                 const bf16_t* yr = Y + (size_t)row * DM;
; #pragma unroll
;                 for (int j = 0; j < 8; ++j) yw[q][j] = *(const u32x2*)(yr + 4 * F.lane + 256 * j); }
	v_fmac_f32_e32 v75, v123, v219
	v_lshlrev_b32_e32 v216, 16, v94
	v_and_b32_e32 v217, 0xffff0000, v94
	v_lshlrev_b32_e32 v218, 16, v95
	v_and_b32_e32 v219, 0xffff0000, v95
	v_mul_f32_e32 v216, v225, v216
	v_mul_f32_e32 v217, v225, v217
	v_mul_f32_e32 v218, v225, v218
	v_mul_f32_e32 v219, v225, v219
	v_fmac_f32_e32 v76, v124, v216
	v_fmac_f32_e32 v77, v125, v217
	v_fmac_f32_e32 v78, v126, v218
	v_fmac_f32_e32 v79, v127, v219
	v_mul_f32_e32 v222, v48, v48
	v_mul_f32_e32 v223, v49, v49
	v_fmac_f32_e32 v222, v50, v50
	v_fmac_f32_e32 v223, v51, v51
	v_fmac_f32_e32 v222, v52, v52
	v_fmac_f32_e32 v223, v53, v53
	v_fmac_f32_e32 v222, v54, v54
	v_fmac_f32_e32 v223, v55, v55
	v_fmac_f32_e32 v222, v56, v56
	v_fmac_f32_e32 v223, v57, v57
	v_fmac_f32_e32 v222, v58, v58
	v_fmac_f32_e32 v223, v59, v59
	v_fmac_f32_e32 v222, v60, v60
	v_fmac_f32_e32 v223, v61, v61
	v_fmac_f32_e32 v222, v62, v62
	v_fmac_f32_e32 v223, v63, v63
	v_fmac_f32_e32 v222, v64, v64
	v_fmac_f32_e32 v223, v65, v65
	v_fmac_f32_e32 v222, v66, v66
	v_fmac_f32_e32 v223, v67, v67
	v_fmac_f32_e32 v222, v68, v68
	v_fmac_f32_e32 v223, v69, v69
	v_fmac_f32_e32 v222, v70, v70
	v_fmac_f32_e32 v223, v71, v71
	v_fmac_f32_e32 v222, v72, v72
	v_fmac_f32_e32 v223, v73, v73
	v_fmac_f32_e32 v222, v74, v74
	v_fmac_f32_e32 v223, v75, v75
	v_fmac_f32_e32 v222, v76, v76
	v_fmac_f32_e32 v223, v77, v77
	v_fmac_f32_e32 v222, v78, v78
	v_fmac_f32_e32 v223, v79, v79
	v_add_f32_e32 v222, v222, v223
	s_nop 1
	v_add_f32_dpp v224, v222, v222 quad_perm:[1,0,3,2] row_mask:0xf bank_mask:0xf
	s_nop 1
	v_add_f32_dpp v224, v224, v224 quad_perm:[2,3,0,1] row_mask:0xf bank_mask:0xf
	s_nop 1
	v_add_f32_dpp v224, v224, v224 row_half_mirror row_mask:0xf bank_mask:0xf
	s_nop 1
	v_add_f32_dpp v224, v224, v224 row_mirror row_mask:0xf bank_mask:0xf
	s_nop 1
	v_readlane_b32 s40, v224, 0
	v_readlane_b32 s41, v224, 16
	v_readlane_b32 s42, v224, 32
	v_readlane_b32 s43, v224, 48
	s_nop 1
	v_mov_b32_e32 v225, s40
	v_add_f32_e32 v225, s41, v225
	v_add_f32_e32 v225, s42, v225
	v_add_f32_e32 v225, s43, v225
	v_fmamk_f32 v225, v225, 0x3a000000, v195
	v_rsq_f32_e32 v225, v225
	s_nop 0
	s_add_i32 s0, s6, 3
	s_lshl_b32 s1, s0, 12
	s_add_u32 s26, s84, s1
	s_addc_u32 s27, s85, 0
	s_add_u32 s26, s26, 0x4000000
	s_addc_u32 s27, s27, 0
	v_mul_f32_e32 v216, v225, v48
	v_mul_f32_e32 v217, v225, v49
	v_mul_f32_e32 v218, v225, v50
	v_mul_f32_e32 v219, v225, v51
	v_fma_f32 v216, v216, v128, v160
	v_fma_f32 v217, v217, v129, v161
	v_fma_f32 v218, v218, v130, v162
	v_fma_f32 v219, v219, v131, v163
	v_cvt_pk_bf16_f32 v196, v216, v217
	v_cvt_pk_bf16_f32 v197, v218, v219
	global_store_dwordx2 v194, v[196:197], s[26:27] offset:0
	v_mul_f32_e32 v216, v225, v52
	v_mul_f32_e32 v217, v225, v53
	v_mul_f32_e32 v218, v225, v54
	v_mul_f32_e32 v219, v225, v55
	v_fma_f32 v216, v216, v132, v164
	v_fma_f32 v217, v217, v133, v165
	v_fma_f32 v218, v218, v134, v166
	v_fma_f32 v219, v219, v135, v167
	v_cvt_pk_bf16_f32 v220, v216, v217
	v_cvt_pk_bf16_f32 v221, v218, v219
	global_store_dwordx2 v194, v[220:221], s[26:27] offset:512
	v_mul_f32_e32 v216, v225, v56
	v_mul_f32_e32 v217, v225, v57
	v_mul_f32_e32 v218, v225, v58
	v_mul_f32_e32 v219, v225, v59
	v_fma_f32 v216, v216, v136, v168
	v_fma_f32 v217, v217, v137, v169
	v_fma_f32 v218, v218, v138, v170
	v_fma_f32 v219, v219, v139, v171
	v_cvt_pk_bf16_f32 v196, v216, v217
	v_cvt_pk_bf16_f32 v197, v218, v219
	global_store_dwordx2 v194, v[196:197], s[26:27] offset:1024
	v_mul_f32_e32 v216, v225, v60
	v_mul_f32_e32 v217, v225, v61
	v_mul_f32_e32 v218, v225, v62
	v_mul_f32_e32 v219, v225, v63
	v_fma_f32 v216, v216, v140, v172
	v_fma_f32 v217, v217, v141, v173
	v_fma_f32 v218, v218, v142, v174
	v_fma_f32 v219, v219, v143, v175
	v_cvt_pk_bf16_f32 v220, v216, v217
	v_cvt_pk_bf16_f32 v221, v218, v219
	global_store_dwordx2 v194, v[220:221], s[26:27] offset:1536
	v_mul_f32_e32 v216, v225, v64
	v_mul_f32_e32 v217, v225, v65
	v_mul_f32_e32 v218, v225, v66
	v_mul_f32_e32 v219, v225, v67
	v_fma_f32 v216, v216, v144, v176
	v_fma_f32 v217, v217, v145, v177
	v_fma_f32 v218, v218, v146, v178
	v_fma_f32 v219, v219, v147, v179
	v_cvt_pk_bf16_f32 v196, v216, v217
	v_cvt_pk_bf16_f32 v197, v218, v219
	global_store_dwordx2 v194, v[196:197], s[26:27] offset:2048
	v_mul_f32_e32 v216, v225, v68
	v_mul_f32_e32 v217, v225, v69
	v_mul_f32_e32 v218, v225, v70
	v_mul_f32_e32 v219, v225, v71
	v_fma_f32 v216, v216, v148, v180
	v_fma_f32 v217, v217, v149, v181
	v_fma_f32 v218, v218, v150, v182
	v_fma_f32 v219, v219, v151, v183
	v_cvt_pk_bf16_f32 v220, v216, v217
	v_cvt_pk_bf16_f32 v221, v218, v219
	global_store_dwordx2 v194, v[220:221], s[26:27] offset:2560
	v_mul_f32_e32 v216, v225, v72
	v_mul_f32_e32 v217, v225, v73
	v_mul_f32_e32 v218, v225, v74
	v_mul_f32_e32 v219, v225, v75
	v_fma_f32 v216, v216, v152, v184
	v_fma_f32 v217, v217, v153, v185
	v_fma_f32 v218, v218, v154, v186
	v_fma_f32 v219, v219, v155, v187
	v_cvt_pk_bf16_f32 v196, v216, v217
	v_cvt_pk_bf16_f32 v197, v218, v219
	global_store_dwordx2 v194, v[196:197], s[26:27] offset:3072
	v_mul_f32_e32 v216, v225, v76
	v_mul_f32_e32 v217, v225, v77
	v_mul_f32_e32 v218, v225, v78
	v_mul_f32_e32 v219, v225, v79
	v_fma_f32 v216, v216, v156, v188
	v_fma_f32 v217, v217, v157, v189
	v_fma_f32 v218, v218, v158, v190
	v_fma_f32 v219, v219, v159, v191
	v_cvt_pk_bf16_f32 v220, v216, v217
	v_cvt_pk_bf16_f32 v221, v218, v219
	global_store_dwordx2 v194, v[220:221], s[26:27] offset:3584
	s_add_i32 s0, s6, 5
	s_cmp_lt_u32 s0, 0x4000
	s_cselect_b32 s10, s68, s72
	s_cselect_b32 s11, s69, s73
	s_cselect_b32 s1, 0, 0x4000
	s_sub_i32 s1, s0, s1
	s_lshl_b32 s1, s1, 13
	s_add_u32 s10, s10, s1
	s_addc_u32 s11, s11, 0
	s_add_i32 s0, s6, 5
	s_lshl_b32 s1, s0, 12
	s_add_u32 s22, s84, s1
	s_addc_u32 s23, s85, 0
	s_add_u32 s22, s22, 0x11800000
	s_addc_u32 s23, s23, 0
	global_load_dwordx4 v[48:51], v192, s[10:11] offset:0 nt
	global_load_dwordx4 v[52:55], v192, s[10:11] offset:1024 nt
	global_load_dwordx4 v[56:59], v192, s[10:11] offset:2048 nt
	global_load_dwordx4 v[60:63], v192, s[10:11] offset:3072 nt
	global_load_dwordx4 v[64:67], v193, s[10:11] offset:0 nt
	global_load_dwordx4 v[68:71], v193, s[10:11] offset:1024 nt
	global_load_dwordx4 v[72:75], v193, s[10:11] offset:2048 nt
	global_load_dwordx4 v[76:79], v193, s[10:11] offset:3072 nt
	global_load_dwordx2 v[80:81], v194, s[22:23] offset:0
	global_load_dwordx2 v[82:83], v194, s[22:23] offset:512
	global_load_dwordx2 v[84:85], v194, s[22:23] offset:1024
	global_load_dwordx2 v[86:87], v194, s[22:23] offset:1536
	global_load_dwordx2 v[88:89], v194, s[22:23] offset:2048
	global_load_dwordx2 v[90:91], v194, s[22:23] offset:2560
	global_load_dwordx2 v[92:93], v194, s[22:23] offset:3072
	global_load_dwordx2 v[94:95], v194, s[22:23] offset:3584
	s_add_i32 s0, s6, 4
	s_add_i32 s0, s6, 4
	s_lshr_b32 s8, s0, 11
	s_cmp_lt_u32 s0, 0x4000
	s_cselect_b32 s8, s8, 8
	s_cmp_eq_u32 s8, s7
	s_cbranch_scc1 .Lp6_np4
; __device__ __forceinline__ void modulate_store(const f32x4 (&v)[8], float rstd, const float* pn, const float* modr, bf16_t* orow, int lane) {
; #pragma unroll
;     for (int j = 0; j < 8; ++j) { const int col = 4 * lane + 256 * j;
;         const f32x4 g = *(const f32x4*)(pn + col), sh = *(const f32x4*)(modr + col), sc = *(const f32x4*)(modr + DM + col);
;         const f32x4 hh = v[j] * rstd * g * (sc + 1.f) + sh;
; __global__ void __launch_bounds__(NWAVES * 64, 2) mk_fwd(Args args) {
;     ...
;                 const float* m0 = mod + (size_t)r * 6144;
; #pragma unroll
;                 for (int j = 0; j < 8; ++j) { const int col = 4 * F.lane + 256 * j; const f32x4 gt = *(const f32x4*)(m0 + 2 * DM + col), pn = *(const f32x4*)(post_norm + col);
	s_mov_b32 s7, s8
	s_add_i32 s1, s8, 9
	s_mul_i32 s1, s1, 0x6000
	s_add_u32 s44, s84, s1
	s_addc_u32 s45, s85, 0
	s_add_u32 s44, s44, 0x2000
	s_addc_u32 s45, s45, 0
	s_add_i32 s1, s8, 9
	s_mul_i32 s1, s1, 0x6000
	s_add_u32 s36, s84, s1
	s_addc_u32 s37, s85, 0
	s_add_u32 s38, s80, 0x2000
	s_addc_u32 s39, s81, 0
	s_mul_i32 s1, s8, 0x6000
	s_add_u32 s34, s84, s1
	s_addc_u32 s35, s85, 0
	s_add_u32 s34, s34, 0x4000
	s_addc_u32 s35, s35, 0
	global_load_dwordx4 v[96:99], v192, s[34:35] offset:0
	global_load_dwordx4 v[200:203], v192, s[82:83] offset:0
	global_load_dwordx4 v[100:103], v192, s[34:35] offset:1024
	global_load_dwordx4 v[204:207], v192, s[82:83] offset:1024
	global_load_dwordx4 v[104:107], v192, s[34:35] offset:2048
	global_load_dwordx4 v[208:211], v192, s[82:83] offset:2048
	global_load_dwordx4 v[108:111], v192, s[34:35] offset:3072
	global_load_dwordx4 v[212:215], v192, s[82:83] offset:3072
	s_waitcnt vmcnt(0)
	v_mul_f32_e32 v96, v96, v200
	v_mul_f32_e32 v97, v97, v201
	v_mul_f32_e32 v98, v98, v202
	v_mul_f32_e32 v99, v99, v203
	v_mul_f32_e32 v100, v100, v204
	v_mul_f32_e32 v101, v101, v205
	v_mul_f32_e32 v102, v102, v206
	v_mul_f32_e32 v103, v103, v207
	v_mul_f32_e32 v104, v104, v208
	v_mul_f32_e32 v105, v105, v209
	v_mul_f32_e32 v106, v106, v210
	v_mul_f32_e32 v107, v107, v211
	v_mul_f32_e32 v108, v108, v212
	v_mul_f32_e32 v109, v109, v213
	v_mul_f32_e32 v110, v110, v214
	v_mul_f32_e32 v111, v111, v215
	global_load_dwordx4 v[128:131], v192, s[38:39] offset:0
	global_load_dwordx4 v[200:203], v192, s[44:45] offset:0
	global_load_dwordx4 v[160:163], v192, s[36:37] offset:0
	global_load_dwordx4 v[132:135], v192, s[38:39] offset:1024
	global_load_dwordx4 v[204:207], v192, s[44:45] offset:1024
	global_load_dwordx4 v[164:167], v192, s[36:37] offset:1024
	global_load_dwordx4 v[136:139], v192, s[38:39] offset:2048
	global_load_dwordx4 v[208:211], v192, s[44:45] offset:2048
	global_load_dwordx4 v[168:171], v192, s[36:37] offset:2048
	global_load_dwordx4 v[140:143], v192, s[38:39] offset:3072
	global_load_dwordx4 v[212:215], v192, s[44:45] offset:3072
	global_load_dwordx4 v[172:175], v192, s[36:37] offset:3072
	s_waitcnt vmcnt(0)
	v_add_f32_e32 v200, 1.0, v200
	v_add_f32_e32 v201, 1.0, v201
	v_add_f32_e32 v202, 1.0, v202
	v_add_f32_e32 v203, 1.0, v203
	v_mul_f32_e32 v128, v128, v200
	v_mul_f32_e32 v129, v129, v201
	v_mul_f32_e32 v130, v130, v202
	v_mul_f32_e32 v131, v131, v203
	v_add_f32_e32 v204, 1.0, v204
	v_add_f32_e32 v205, 1.0, v205
	v_add_f32_e32 v206, 1.0, v206
	v_add_f32_e32 v207, 1.0, v207
	v_mul_f32_e32 v132, v132, v204
	v_mul_f32_e32 v133, v133, v205
	v_mul_f32_e32 v134, v134, v206
	v_mul_f32_e32 v135, v135, v207
	v_add_f32_e32 v208, 1.0, v208
	v_add_f32_e32 v209, 1.0, v209
	v_add_f32_e32 v210, 1.0, v210
	v_add_f32_e32 v211, 1.0, v211
	v_mul_f32_e32 v136, v136, v208
	v_mul_f32_e32 v137, v137, v209
	v_mul_f32_e32 v138, v138, v210
	v_mul_f32_e32 v139, v139, v211
	v_add_f32_e32 v212, 1.0, v212
	v_add_f32_e32 v213, 1.0, v213
	v_add_f32_e32 v214, 1.0, v214
	v_add_f32_e32 v215, 1.0, v215
	v_mul_f32_e32 v140, v140, v212
	v_mul_f32_e32 v141, v141, v213
	v_mul_f32_e32 v142, v142, v214
	v_mul_f32_e32 v143, v143, v215
	global_load_dwordx4 v[112:115], v193, s[34:35] offset:0
	global_load_dwordx4 v[200:203], v193, s[82:83] offset:0
	global_load_dwordx4 v[116:119], v193, s[34:35] offset:1024
	global_load_dwordx4 v[204:207], v193, s[82:83] offset:1024
	global_load_dwordx4 v[120:123], v193, s[34:35] offset:2048
	global_load_dwordx4 v[208:211], v193, s[82:83] offset:2048
	global_load_dwordx4 v[124:127], v193, s[34:35] offset:3072
	global_load_dwordx4 v[212:215], v193, s[82:83] offset:3072
	s_waitcnt vmcnt(0)
	v_mul_f32_e32 v112, v112, v200
	v_mul_f32_e32 v113, v113, v201
	v_mul_f32_e32 v114, v114, v202
	v_mul_f32_e32 v115, v115, v203
	v_mul_f32_e32 v116, v116, v204
	v_mul_f32_e32 v117, v117, v205
	v_mul_f32_e32 v118, v118, v206
	v_mul_f32_e32 v119, v119, v207
	v_mul_f32_e32 v120, v120, v208
	v_mul_f32_e32 v121, v121, v209
	v_mul_f32_e32 v122, v122, v210
	v_mul_f32_e32 v123, v123, v211
	v_mul_f32_e32 v124, v124, v212
	v_mul_f32_e32 v125, v125, v213
	v_mul_f32_e32 v126, v126, v214
	v_mul_f32_e32 v127, v127, v215
	global_load_dwordx4 v[144:147], v193, s[38:39] offset:0
	global_load_dwordx4 v[200:203], v193, s[44:45] offset:0
	global_load_dwordx4 v[176:179], v193, s[36:37] offset:0
	global_load_dwordx4 v[148:151], v193, s[38:39] offset:1024
	global_load_dwordx4 v[204:207], v193, s[44:45] offset:1024
	global_load_dwordx4 v[180:183], v193, s[36:37] offset:1024
	global_load_dwordx4 v[152:155], v193, s[38:39] offset:2048
	global_load_dwordx4 v[208:211], v193, s[44:45] offset:2048
	global_load_dwordx4 v[184:187], v193, s[36:37] offset:2048
	global_load_dwordx4 v[156:159], v193, s[38:39] offset:3072
	global_load_dwordx4 v[212:215], v193, s[44:45] offset:3072
	global_load_dwordx4 v[188:191], v193, s[36:37] offset:3072
	s_waitcnt vmcnt(0)
	v_add_f32_e32 v200, 1.0, v200
	v_add_f32_e32 v201, 1.0, v201
	v_add_f32_e32 v202, 1.0, v202
	v_add_f32_e32 v203, 1.0, v203
	v_mul_f32_e32 v144, v144, v200
	v_mul_f32_e32 v145, v145, v201
	v_mul_f32_e32 v146, v146, v202
	v_mul_f32_e32 v147, v147, v203
	v_add_f32_e32 v204, 1.0, v204
	v_add_f32_e32 v205, 1.0, v205
	v_add_f32_e32 v206, 1.0, v206
	v_add_f32_e32 v207, 1.0, v207
	v_mul_f32_e32 v148, v148, v204
	v_mul_f32_e32 v149, v149, v205
	v_mul_f32_e32 v150, v150, v206
	v_mul_f32_e32 v151, v151, v207
	v_add_f32_e32 v208, 1.0, v208
	v_add_f32_e32 v209, 1.0, v209
	v_add_f32_e32 v210, 1.0, v210
	v_add_f32_e32 v211, 1.0, v211
	v_mul_f32_e32 v152, v152, v208
	v_mul_f32_e32 v153, v153, v209
	v_mul_f32_e32 v154, v154, v210
	v_mul_f32_e32 v155, v155, v211
	v_add_f32_e32 v212, 1.0, v212
	v_add_f32_e32 v213, 1.0, v213
	v_add_f32_e32 v214, 1.0, v214
	v_add_f32_e32 v215, 1.0, v215
	v_mul_f32_e32 v156, v156, v212
	v_mul_f32_e32 v157, v157, v213
	v_mul_f32_e32 v158, v158, v214
	v_mul_f32_e32 v159, v159, v215
; __device__ __forceinline__ float bf_lo(unsigned w) { return __uint_as_float(w << 16); }
; __device__ __forceinline__ float bf_hi(unsigned w) { return __uint_as_float(w & 0xffff0000u); }
; __global__ void __launch_bounds__(NWAVES * 64, 2) mk_fwd(Args args) {
;     ...
;             for (int q = 0; q < 3; ++q) { const int row = row0 + q; const bool lat = row < ML; const int r = lat ? row / SEQ : 8;
;                 float sy = 0.f;
; #pragma unroll
;                 for (int j = 0; j < 8; ++j) { const float a = bf_lo(yw[q][j].x), b = bf_hi(yw[q][j].x), c2 = bf_lo(yw[q][j].y), d = bf_hi(yw[q][j].y); sy += (a * a + b * b) + (c2 * c2 + d * d); }
;                 const float rsy = __builtin_amdgcn_rsqf(wave_sum(sy) * (1.f / DM) + EPS);
;                 const float* m0 = mod + (size_t)r * 6144;
; #pragma unroll
;                 for (int j = 0; j < 8; ++j) { const int col = 4 * F.lane + 256 * j; const f32x4 gt = *(const f32x4*)(m0 + 2 * DM + col), pn = *(const f32x4*)(post_norm + col);
;                     const f32x4 y4 = (f32x4){bf_lo(yw[q][j].x), bf_hi(yw[q][j].x), bf_lo(yw[q][j].y), bf_hi(yw[q][j].y)};
;                     v[q][j] = v[q][j] + gt * (y4 * rsy * pn);
.Lp6_np4:
	s_waitcnt vmcnt(24)
	v_lshlrev_b32_e32 v216, 16, v32
	v_and_b32_e32 v217, 0xffff0000, v32
	v_lshlrev_b32_e32 v218, 16, v33
	v_and_b32_e32 v219, 0xffff0000, v33
	v_mul_f32_e32 v222, v216, v216
	v_mul_f32_e32 v223, v217, v217
	v_fmac_f32_e32 v222, v218, v218
	v_fmac_f32_e32 v223, v219, v219
	v_lshlrev_b32_e32 v216, 16, v34
	v_and_b32_e32 v217, 0xffff0000, v34
	v_lshlrev_b32_e32 v218, 16, v35
	v_and_b32_e32 v219, 0xffff0000, v35
	v_fmac_f32_e32 v222, v216, v216
	v_fmac_f32_e32 v223, v217, v217
	v_fmac_f32_e32 v222, v218, v218
	v_fmac_f32_e32 v223, v219, v219
	v_lshlrev_b32_e32 v216, 16, v36
	v_and_b32_e32 v217, 0xffff0000, v36
	v_lshlrev_b32_e32 v218, 16, v37
	v_and_b32_e32 v219, 0xffff0000, v37
	v_fmac_f32_e32 v222, v216, v216
	v_fmac_f32_e32 v223, v217, v217
	v_fmac_f32_e32 v222, v218, v218
	v_fmac_f32_e32 v223, v219, v219
	v_lshlrev_b32_e32 v216, 16, v38
	v_and_b32_e32 v217, 0xffff0000, v38
	v_lshlrev_b32_e32 v218, 16, v39
	v_and_b32_e32 v219, 0xffff0000, v39
	v_fmac_f32_e32 v222, v216, v216
	v_fmac_f32_e32 v223, v217, v217
	v_fmac_f32_e32 v222, v218, v218
	v_fmac_f32_e32 v223, v219, v219
	v_lshlrev_b32_e32 v216, 16, v40
	v_and_b32_e32 v217, 0xffff0000, v40
	v_lshlrev_b32_e32 v218, 16, v41
	v_and_b32_e32 v219, 0xffff0000, v41
	v_fmac_f32_e32 v222, v216, v216
	v_fmac_f32_e32 v223, v217, v217
	v_fmac_f32_e32 v222, v218, v218
	v_fmac_f32_e32 v223, v219, v219
	v_lshlrev_b32_e32 v216, 16, v42
	v_and_b32_e32 v217, 0xffff0000, v42
	v_lshlrev_b32_e32 v218, 16, v43
	v_and_b32_e32 v219, 0xffff0000, v43
	v_fmac_f32_e32 v222, v216, v216
	v_fmac_f32_e32 v223, v217, v217
	v_fmac_f32_e32 v222, v218, v218
	v_fmac_f32_e32 v223, v219, v219
	v_lshlrev_b32_e32 v216, 16, v44
	v_and_b32_e32 v217, 0xffff0000, v44
	v_lshlrev_b32_e32 v218, 16, v45
	v_and_b32_e32 v219, 0xffff0000, v45
	v_fmac_f32_e32 v222, v216, v216
	v_fmac_f32_e32 v223, v217, v217
	v_fmac_f32_e32 v222, v218, v218
	v_fmac_f32_e32 v223, v219, v219
	v_lshlrev_b32_e32 v216, 16, v46
	v_and_b32_e32 v217, 0xffff0000, v46
	v_lshlrev_b32_e32 v218, 16, v47
	v_and_b32_e32 v219, 0xffff0000, v47
	v_fmac_f32_e32 v222, v216, v216
	v_fmac_f32_e32 v223, v217, v217
	v_fmac_f32_e32 v222, v218, v218
	v_fmac_f32_e32 v223, v219, v219
	v_add_f32_e32 v222, v222, v223
	s_nop 1
	v_add_f32_dpp v224, v222, v222 quad_perm:[1,0,3,2] row_mask:0xf bank_mask:0xf
	s_nop 1
	v_add_f32_dpp v224, v224, v224 quad_perm:[2,3,0,1] row_mask:0xf bank_mask:0xf
	s_nop 1
	v_add_f32_dpp v224, v224, v224 row_half_mirror row_mask:0xf bank_mask:0xf
	s_nop 1
	v_add_f32_dpp v224, v224, v224 row_mirror row_mask:0xf bank_mask:0xf
	s_nop 1
	v_readlane_b32 s40, v224, 0
	v_readlane_b32 s41, v224, 16
	v_readlane_b32 s42, v224, 32
	v_readlane_b32 s43, v224, 48
	s_nop 1
	v_mov_b32_e32 v225, s40
	v_add_f32_e32 v225, s41, v225
	v_add_f32_e32 v225, s42, v225
	v_add_f32_e32 v225, s43, v225
	v_fmamk_f32 v225, v225, 0x3a000000, v195
	v_rsq_f32_e32 v225, v225
	s_nop 0
	v_lshlrev_b32_e32 v216, 16, v32
	v_and_b32_e32 v217, 0xffff0000, v32
	v_lshlrev_b32_e32 v218, 16, v33
	v_and_b32_e32 v219, 0xffff0000, v33
	v_mul_f32_e32 v216, v225, v216
	v_mul_f32_e32 v217, v225, v217
	v_mul_f32_e32 v218, v225, v218
	v_mul_f32_e32 v219, v225, v219
	v_fmac_f32_e32 v0, v96, v216
	v_fmac_f32_e32 v1, v97, v217
	v_fmac_f32_e32 v2, v98, v218
	v_fmac_f32_e32 v3, v99, v219
	v_lshlrev_b32_e32 v216, 16, v34
	v_and_b32_e32 v217, 0xffff0000, v34
	v_lshlrev_b32_e32 v218, 16, v35
	v_and_b32_e32 v219, 0xffff0000, v35
	v_mul_f32_e32 v216, v225, v216
	v_mul_f32_e32 v217, v225, v217
	v_mul_f32_e32 v218, v225, v218
	v_mul_f32_e32 v219, v225, v219
	v_fmac_f32_e32 v4, v100, v216
	v_fmac_f32_e32 v5, v101, v217
	v_fmac_f32_e32 v6, v102, v218
	v_fmac_f32_e32 v7, v103, v219
	v_lshlrev_b32_e32 v216, 16, v36
	v_and_b32_e32 v217, 0xffff0000, v36
	v_lshlrev_b32_e32 v218, 16, v37
	v_and_b32_e32 v219, 0xffff0000, v37
	v_mul_f32_e32 v216, v225, v216
	v_mul_f32_e32 v217, v225, v217
	v_mul_f32_e32 v218, v225, v218
	v_mul_f32_e32 v219, v225, v219
	v_fmac_f32_e32 v8, v104, v216
	v_fmac_f32_e32 v9, v105, v217
	v_fmac_f32_e32 v10, v106, v218
	v_fmac_f32_e32 v11, v107, v219
	v_lshlrev_b32_e32 v216, 16, v38
	v_and_b32_e32 v217, 0xffff0000, v38
	v_lshlrev_b32_e32 v218, 16, v39
	v_and_b32_e32 v219, 0xffff0000, v39
	v_mul_f32_e32 v216, v225, v216
	v_mul_f32_e32 v217, v225, v217
	v_mul_f32_e32 v218, v225, v218
	v_mul_f32_e32 v219, v225, v219
	v_fmac_f32_e32 v12, v108, v216
	v_fmac_f32_e32 v13, v109, v217
	v_fmac_f32_e32 v14, v110, v218
	v_fmac_f32_e32 v15, v111, v219
	v_lshlrev_b32_e32 v216, 16, v40
	v_and_b32_e32 v217, 0xffff0000, v40
	v_lshlrev_b32_e32 v218, 16, v41
	v_and_b32_e32 v219, 0xffff0000, v41
	v_mul_f32_e32 v216, v225, v216
	v_mul_f32_e32 v217, v225, v217
	v_mul_f32_e32 v218, v225, v218
	v_mul_f32_e32 v219, v225, v219
	v_fmac_f32_e32 v16, v112, v216
	v_fmac_f32_e32 v17, v113, v217
	v_fmac_f32_e32 v18, v114, v218
	v_fmac_f32_e32 v19, v115, v219
	v_lshlrev_b32_e32 v216, 16, v42
	v_and_b32_e32 v217, 0xffff0000, v42
	v_lshlrev_b32_e32 v218, 16, v43
	v_and_b32_e32 v219, 0xffff0000, v43
	v_mul_f32_e32 v216, v225, v216
	v_mul_f32_e32 v217, v225, v217
	v_mul_f32_e32 v218, v225, v218
	v_mul_f32_e32 v219, v225, v219
	v_fmac_f32_e32 v20, v116, v216
	v_fmac_f32_e32 v21, v117, v217
	v_fmac_f32_e32 v22, v118, v218
	v_fmac_f32_e32 v23, v119, v219
	v_lshlrev_b32_e32 v216, 16, v44
	v_and_b32_e32 v217, 0xffff0000, v44
	v_lshlrev_b32_e32 v218, 16, v45
	v_and_b32_e32 v219, 0xffff0000, v45
	v_mul_f32_e32 v216, v225, v216
	v_mul_f32_e32 v217, v225, v217
	v_mul_f32_e32 v218, v225, v218
	v_mul_f32_e32 v219, v225, v219
	v_fmac_f32_e32 v24, v120, v216
	v_fmac_f32_e32 v25, v121, v217
	v_fmac_f32_e32 v26, v122, v218
; __device__ __forceinline__ unsigned cvt_pk_bf16(float lo, float hi) { unsigned r; asm volatile("v_cvt_pk_bf16_f32 %0, %1, %2" : "=v"(r) : "v"(lo), "v"(hi)); return r; }
; __device__ __forceinline__ float sumsq8(const f32x4 (&v)[8]) {
;     float s = 0.f;
; #pragma unroll
;     for (int j = 0; j < 8; ++j) s += (v[j][0] * v[j][0] + v[j][1] * v[j][1]) + (v[j][2] * v[j][2] + v[j][3] * v[j][3]);
;     return wave_sum(s);
; }
; __device__ __forceinline__ void modulate_store(const f32x4 (&v)[8], float rstd, const float* pn, const float* modr, bf16_t* orow, int lane) {
; #pragma unroll
;     for (int j = 0; j < 8; ++j) { const int col = 4 * lane + 256 * j;
;         const f32x4 g = *(const f32x4*)(pn + col), sh = *(const f32x4*)(modr + col), sc = *(const f32x4*)(modr + DM + col);
;         const f32x4 hh = v[j] * rstd * g * (sc + 1.f) + sh;
;         u32x2 w; w.x = cvt_pk_bf16(hh[0], hh[1]); w.y = cvt_pk_bf16(hh[2], hh[3]);
;         *(u32x2*)(orow + col) = w; }
; }
; __global__ void __launch_bounds__(NWAVES * 64, 2) mk_fwd(Args args) {
;     ...
;         for (int row0 = F.gw * 3; row0 < MT; row0 += F.NGW * 3) {
;             f32x4 v[3][8]; u32x2 yw[3][8];
; #pragma unroll
;             for (int q = 0; q < 3; ++q) { const int row = row0 + q; const float* src = row < ML ? x + (size_t)row * DM : ctx + (size_t)(row - ML) * DM; load_row_f32(src, F.lane, v[q]);
;                 const bf16_t* yr = Y + (size_t)row * DM;
; #pragma unroll
;                 for (int j = 0; j < 8; ++j) yw[q][j] = *(const u32x2*)(yr + 4 * F.lane + 256 * j); }
	v_fmac_f32_e32 v27, v123, v219
	v_lshlrev_b32_e32 v216, 16, v46
	v_and_b32_e32 v217, 0xffff0000, v46
	v_lshlrev_b32_e32 v218, 16, v47
	v_and_b32_e32 v219, 0xffff0000, v47
	v_mul_f32_e32 v216, v225, v216
	v_mul_f32_e32 v217, v225, v217
	v_mul_f32_e32 v218, v225, v218
	v_mul_f32_e32 v219, v225, v219
	v_fmac_f32_e32 v28, v124, v216
	v_fmac_f32_e32 v29, v125, v217
	v_fmac_f32_e32 v30, v126, v218
	v_fmac_f32_e32 v31, v127, v219
	v_mul_f32_e32 v222, v0, v0
	v_mul_f32_e32 v223, v1, v1
	v_fmac_f32_e32 v222, v2, v2
	v_fmac_f32_e32 v223, v3, v3
	v_fmac_f32_e32 v222, v4, v4
	v_fmac_f32_e32 v223, v5, v5
	v_fmac_f32_e32 v222, v6, v6
	v_fmac_f32_e32 v223, v7, v7
	v_fmac_f32_e32 v222, v8, v8
	v_fmac_f32_e32 v223, v9, v9
	v_fmac_f32_e32 v222, v10, v10
	v_fmac_f32_e32 v223, v11, v11
	v_fmac_f32_e32 v222, v12, v12
	v_fmac_f32_e32 v223, v13, v13
	v_fmac_f32_e32 v222, v14, v14
	v_fmac_f32_e32 v223, v15, v15
	v_fmac_f32_e32 v222, v16, v16
	v_fmac_f32_e32 v223, v17, v17
	v_fmac_f32_e32 v222, v18, v18
	v_fmac_f32_e32 v223, v19, v19
	v_fmac_f32_e32 v222, v20, v20
	v_fmac_f32_e32 v223, v21, v21
	v_fmac_f32_e32 v222, v22, v22
	v_fmac_f32_e32 v223, v23, v23
	v_fmac_f32_e32 v222, v24, v24
	v_fmac_f32_e32 v223, v25, v25
	v_fmac_f32_e32 v222, v26, v26
	v_fmac_f32_e32 v223, v27, v27
	v_fmac_f32_e32 v222, v28, v28
	v_fmac_f32_e32 v223, v29, v29
	v_fmac_f32_e32 v222, v30, v30
	v_fmac_f32_e32 v223, v31, v31
	v_add_f32_e32 v222, v222, v223
	s_nop 1
	v_add_f32_dpp v224, v222, v222 quad_perm:[1,0,3,2] row_mask:0xf bank_mask:0xf
	s_nop 1
	v_add_f32_dpp v224, v224, v224 quad_perm:[2,3,0,1] row_mask:0xf bank_mask:0xf
	s_nop 1
	v_add_f32_dpp v224, v224, v224 row_half_mirror row_mask:0xf bank_mask:0xf
	s_nop 1
	v_add_f32_dpp v224, v224, v224 row_mirror row_mask:0xf bank_mask:0xf
	s_nop 1
	v_readlane_b32 s40, v224, 0
	v_readlane_b32 s41, v224, 16
	v_readlane_b32 s42, v224, 32
	v_readlane_b32 s43, v224, 48
	s_nop 1
	v_mov_b32_e32 v225, s40
	v_add_f32_e32 v225, s41, v225
	v_add_f32_e32 v225, s42, v225
	v_add_f32_e32 v225, s43, v225
	v_fmamk_f32 v225, v225, 0x3a000000, v195
	v_rsq_f32_e32 v225, v225
	s_nop 0
	s_add_i32 s0, s6, 4
	s_lshl_b32 s1, s0, 12
	s_add_u32 s26, s84, s1
	s_addc_u32 s27, s85, 0
	s_add_u32 s26, s26, 0x4000000
	s_addc_u32 s27, s27, 0
	v_mul_f32_e32 v216, v225, v0
	v_mul_f32_e32 v217, v225, v1
	v_mul_f32_e32 v218, v225, v2
	v_mul_f32_e32 v219, v225, v3
	v_fma_f32 v216, v216, v128, v160
	v_fma_f32 v217, v217, v129, v161
	v_fma_f32 v218, v218, v130, v162
	v_fma_f32 v219, v219, v131, v163
	v_cvt_pk_bf16_f32 v196, v216, v217
	v_cvt_pk_bf16_f32 v197, v218, v219
	global_store_dwordx2 v194, v[196:197], s[26:27] offset:0
	v_mul_f32_e32 v216, v225, v4
	v_mul_f32_e32 v217, v225, v5
	v_mul_f32_e32 v218, v225, v6
	v_mul_f32_e32 v219, v225, v7
	v_fma_f32 v216, v216, v132, v164
	v_fma_f32 v217, v217, v133, v165
	v_fma_f32 v218, v218, v134, v166
	v_fma_f32 v219, v219, v135, v167
	v_cvt_pk_bf16_f32 v220, v216, v217
	v_cvt_pk_bf16_f32 v221, v218, v219
	global_store_dwordx2 v194, v[220:221], s[26:27] offset:512
	v_mul_f32_e32 v216, v225, v8
	v_mul_f32_e32 v217, v225, v9
	v_mul_f32_e32 v218, v225, v10
	v_mul_f32_e32 v219, v225, v11
	v_fma_f32 v216, v216, v136, v168
	v_fma_f32 v217, v217, v137, v169
	v_fma_f32 v218, v218, v138, v170
	v_fma_f32 v219, v219, v139, v171
	v_cvt_pk_bf16_f32 v196, v216, v217
	v_cvt_pk_bf16_f32 v197, v218, v219
	global_store_dwordx2 v194, v[196:197], s[26:27] offset:1024
	v_mul_f32_e32 v216, v225, v12
	v_mul_f32_e32 v217, v225, v13
	v_mul_f32_e32 v218, v225, v14
	v_mul_f32_e32 v219, v225, v15
	v_fma_f32 v216, v216, v140, v172
	v_fma_f32 v217, v217, v141, v173
	v_fma_f32 v218, v218, v142, v174
	v_fma_f32 v219, v219, v143, v175
	v_cvt_pk_bf16_f32 v220, v216, v217
	v_cvt_pk_bf16_f32 v221, v218, v219
	global_store_dwordx2 v194, v[220:221], s[26:27] offset:1536
	v_mul_f32_e32 v216, v225, v16
	v_mul_f32_e32 v217, v225, v17
	v_mul_f32_e32 v218, v225, v18
	v_mul_f32_e32 v219, v225, v19
	v_fma_f32 v216, v216, v144, v176
	v_fma_f32 v217, v217, v145, v177
	v_fma_f32 v218, v218, v146, v178
	v_fma_f32 v219, v219, v147, v179
	v_cvt_pk_bf16_f32 v196, v216, v217
	v_cvt_pk_bf16_f32 v197, v218, v219
	global_store_dwordx2 v194, v[196:197], s[26:27] offset:2048
	v_mul_f32_e32 v216, v225, v20
	v_mul_f32_e32 v217, v225, v21
	v_mul_f32_e32 v218, v225, v22
	v_mul_f32_e32 v219, v225, v23
	v_fma_f32 v216, v216, v148, v180
	v_fma_f32 v217, v217, v149, v181
	v_fma_f32 v218, v218, v150, v182
	v_fma_f32 v219, v219, v151, v183
	v_cvt_pk_bf16_f32 v220, v216, v217
	v_cvt_pk_bf16_f32 v221, v218, v219
	global_store_dwordx2 v194, v[220:221], s[26:27] offset:2560
	v_mul_f32_e32 v216, v225, v24
	v_mul_f32_e32 v217, v225, v25
	v_mul_f32_e32 v218, v225, v26
	v_mul_f32_e32 v219, v225, v27
	v_fma_f32 v216, v216, v152, v184
	v_fma_f32 v217, v217, v153, v185
	v_fma_f32 v218, v218, v154, v186
	v_fma_f32 v219, v219, v155, v187
	v_cvt_pk_bf16_f32 v196, v216, v217
	v_cvt_pk_bf16_f32 v197, v218, v219
	global_store_dwordx2 v194, v[196:197], s[26:27] offset:3072
	v_mul_f32_e32 v216, v225, v28
	v_mul_f32_e32 v217, v225, v29
	v_mul_f32_e32 v218, v225, v30
	v_mul_f32_e32 v219, v225, v31
	v_fma_f32 v216, v216, v156, v188
	v_fma_f32 v217, v217, v157, v189
	v_fma_f32 v218, v218, v158, v190
	v_fma_f32 v219, v219, v159, v191
	v_cvt_pk_bf16_f32 v220, v216, v217
	v_cvt_pk_bf16_f32 v221, v218, v219
	global_store_dwordx2 v194, v[220:221], s[26:27] offset:3584
	s_add_i32 s0, s6, 6
	s_cmp_lt_u32 s0, 0x4000
	s_cselect_b32 s10, s68, s72
	s_cselect_b32 s11, s69, s73
	s_cselect_b32 s1, 0, 0x4000
	s_sub_i32 s1, s0, s1
	s_lshl_b32 s1, s1, 13
	s_add_u32 s10, s10, s1
	s_addc_u32 s11, s11, 0
	s_add_i32 s0, s6, 6
	s_lshl_b32 s1, s0, 12
	s_add_u32 s22, s84, s1
	s_addc_u32 s23, s85, 0
	s_add_u32 s22, s22, 0x11800000
	s_addc_u32 s23, s23, 0
	global_load_dwordx4 v[0:3], v192, s[10:11] offset:0 nt
	global_load_dwordx4 v[4:7], v192, s[10:11] offset:1024 nt
	global_load_dwordx4 v[8:11], v192, s[10:11] offset:2048 nt
	global_load_dwordx4 v[12:15], v192, s[10:11] offset:3072 nt
	global_load_dwordx4 v[16:19], v193, s[10:11] offset:0 nt
	global_load_dwordx4 v[20:23], v193, s[10:11] offset:1024 nt
	global_load_dwordx4 v[24:27], v193, s[10:11] offset:2048 nt
	global_load_dwordx4 v[28:31], v193, s[10:11] offset:3072 nt
	global_load_dwordx2 v[32:33], v194, s[22:23] offset:0
	global_load_dwordx2 v[34:35], v194, s[22:23] offset:512
	global_load_dwordx2 v[36:37], v194, s[22:23] offset:1024
	global_load_dwordx2 v[38:39], v194, s[22:23] offset:1536
	global_load_dwordx2 v[40:41], v194, s[22:23] offset:2048
	global_load_dwordx2 v[42:43], v194, s[22:23] offset:2560
	global_load_dwordx2 v[44:45], v194, s[22:23] offset:3072
	global_load_dwordx2 v[46:47], v194, s[22:23] offset:3584
	s_add_i32 s0, s6, 5
	s_add_i32 s0, s6, 5
	s_lshr_b32 s8, s0, 11
	s_cmp_lt_u32 s0, 0x4000
	s_cselect_b32 s8, s8, 8
	s_cmp_eq_u32 s8, s7
	s_cbranch_scc1 .Lp6_np5
; __device__ __forceinline__ void modulate_store(const f32x4 (&v)[8], float rstd, const float* pn, const float* modr, bf16_t* orow, int lane) {
; #pragma unroll
;     for (int j = 0; j < 8; ++j) { const int col = 4 * lane + 256 * j;
;         const f32x4 g = *(const f32x4*)(pn + col), sh = *(const f32x4*)(modr + col), sc = *(const f32x4*)(modr + DM + col);
;         const f32x4 hh = v[j] * rstd * g * (sc + 1.f) + sh;
; __global__ void __launch_bounds__(NWAVES * 64, 2) mk_fwd(Args args) {
;     ...
;                 const float* m0 = mod + (size_t)r * 6144;
; #pragma unroll
;                 for (int j = 0; j < 8; ++j) { const int col = 4 * F.lane + 256 * j; const f32x4 gt = *(const f32x4*)(m0 + 2 * DM + col), pn = *(const f32x4*)(post_norm + col);
	s_mov_b32 s7, s8
	s_add_i32 s1, s8, 9
	s_mul_i32 s1, s1, 0x6000
	s_add_u32 s44, s84, s1
	s_addc_u32 s45, s85, 0
	s_add_u32 s44, s44, 0x2000
	s_addc_u32 s45, s45, 0
	s_add_i32 s1, s8, 9
	s_mul_i32 s1, s1, 0x6000
	s_add_u32 s36, s84, s1
	s_addc_u32 s37, s85, 0
	s_add_u32 s38, s80, 0x2000
	s_addc_u32 s39, s81, 0
	s_mul_i32 s1, s8, 0x6000
	s_add_u32 s34, s84, s1
	s_addc_u32 s35, s85, 0
	s_add_u32 s34, s34, 0x4000
	s_addc_u32 s35, s35, 0
	global_load_dwordx4 v[96:99], v192, s[34:35] offset:0
	global_load_dwordx4 v[200:203], v192, s[82:83] offset:0
	global_load_dwordx4 v[100:103], v192, s[34:35] offset:1024
	global_load_dwordx4 v[204:207], v192, s[82:83] offset:1024
	global_load_dwordx4 v[104:107], v192, s[34:35] offset:2048
	global_load_dwordx4 v[208:211], v192, s[82:83] offset:2048
	global_load_dwordx4 v[108:111], v192, s[34:35] offset:3072
	global_load_dwordx4 v[212:215], v192, s[82:83] offset:3072
	s_waitcnt vmcnt(0)
	v_mul_f32_e32 v96, v96, v200
	v_mul_f32_e32 v97, v97, v201
	v_mul_f32_e32 v98, v98, v202
	v_mul_f32_e32 v99, v99, v203
	v_mul_f32_e32 v100, v100, v204
	v_mul_f32_e32 v101, v101, v205
	v_mul_f32_e32 v102, v102, v206
	v_mul_f32_e32 v103, v103, v207
	v_mul_f32_e32 v104, v104, v208
	v_mul_f32_e32 v105, v105, v209
	v_mul_f32_e32 v106, v106, v210
	v_mul_f32_e32 v107, v107, v211
	v_mul_f32_e32 v108, v108, v212
	v_mul_f32_e32 v109, v109, v213
	v_mul_f32_e32 v110, v110, v214
	v_mul_f32_e32 v111, v111, v215
	global_load_dwordx4 v[128:131], v192, s[38:39] offset:0
	global_load_dwordx4 v[200:203], v192, s[44:45] offset:0
	global_load_dwordx4 v[160:163], v192, s[36:37] offset:0
	global_load_dwordx4 v[132:135], v192, s[38:39] offset:1024
	global_load_dwordx4 v[204:207], v192, s[44:45] offset:1024
	global_load_dwordx4 v[164:167], v192, s[36:37] offset:1024
	global_load_dwordx4 v[136:139], v192, s[38:39] offset:2048
	global_load_dwordx4 v[208:211], v192, s[44:45] offset:2048
	global_load_dwordx4 v[168:171], v192, s[36:37] offset:2048
	global_load_dwordx4 v[140:143], v192, s[38:39] offset:3072
	global_load_dwordx4 v[212:215], v192, s[44:45] offset:3072
	global_load_dwordx4 v[172:175], v192, s[36:37] offset:3072
	s_waitcnt vmcnt(0)
	v_add_f32_e32 v200, 1.0, v200
	v_add_f32_e32 v201, 1.0, v201
	v_add_f32_e32 v202, 1.0, v202
	v_add_f32_e32 v203, 1.0, v203
	v_mul_f32_e32 v128, v128, v200
	v_mul_f32_e32 v129, v129, v201
	v_mul_f32_e32 v130, v130, v202
	v_mul_f32_e32 v131, v131, v203
	v_add_f32_e32 v204, 1.0, v204
	v_add_f32_e32 v205, 1.0, v205
	v_add_f32_e32 v206, 1.0, v206
	v_add_f32_e32 v207, 1.0, v207
	v_mul_f32_e32 v132, v132, v204
	v_mul_f32_e32 v133, v133, v205
	v_mul_f32_e32 v134, v134, v206
	v_mul_f32_e32 v135, v135, v207
	v_add_f32_e32 v208, 1.0, v208
	v_add_f32_e32 v209, 1.0, v209
	v_add_f32_e32 v210, 1.0, v210
	v_add_f32_e32 v211, 1.0, v211
	v_mul_f32_e32 v136, v136, v208
	v_mul_f32_e32 v137, v137, v209
	v_mul_f32_e32 v138, v138, v210
	v_mul_f32_e32 v139, v139, v211
	v_add_f32_e32 v212, 1.0, v212
	v_add_f32_e32 v213, 1.0, v213
	v_add_f32_e32 v214, 1.0, v214
	v_add_f32_e32 v215, 1.0, v215
	v_mul_f32_e32 v140, v140, v212
	v_mul_f32_e32 v141, v141, v213
	v_mul_f32_e32 v142, v142, v214
	v_mul_f32_e32 v143, v143, v215
	global_load_dwordx4 v[112:115], v193, s[34:35] offset:0
	global_load_dwordx4 v[200:203], v193, s[82:83] offset:0
	global_load_dwordx4 v[116:119], v193, s[34:35] offset:1024
	global_load_dwordx4 v[204:207], v193, s[82:83] offset:1024
	global_load_dwordx4 v[120:123], v193, s[34:35] offset:2048
	global_load_dwordx4 v[208:211], v193, s[82:83] offset:2048
	global_load_dwordx4 v[124:127], v193, s[34:35] offset:3072
	global_load_dwordx4 v[212:215], v193, s[82:83] offset:3072
	s_waitcnt vmcnt(0)
	v_mul_f32_e32 v112, v112, v200
	v_mul_f32_e32 v113, v113, v201
	v_mul_f32_e32 v114, v114, v202
	v_mul_f32_e32 v115, v115, v203
	v_mul_f32_e32 v116, v116, v204
	v_mul_f32_e32 v117, v117, v205
	v_mul_f32_e32 v118, v118, v206
	v_mul_f32_e32 v119, v119, v207
	v_mul_f32_e32 v120, v120, v208
	v_mul_f32_e32 v121, v121, v209
	v_mul_f32_e32 v122, v122, v210
	v_mul_f32_e32 v123, v123, v211
	v_mul_f32_e32 v124, v124, v212
	v_mul_f32_e32 v125, v125, v213
	v_mul_f32_e32 v126, v126, v214
	v_mul_f32_e32 v127, v127, v215
	global_load_dwordx4 v[144:147], v193, s[38:39] offset:0
	global_load_dwordx4 v[200:203], v193, s[44:45] offset:0
	global_load_dwordx4 v[176:179], v193, s[36:37] offset:0
	global_load_dwordx4 v[148:151], v193, s[38:39] offset:1024
	global_load_dwordx4 v[204:207], v193, s[44:45] offset:1024
	global_load_dwordx4 v[180:183], v193, s[36:37] offset:1024
	global_load_dwordx4 v[152:155], v193, s[38:39] offset:2048
	global_load_dwordx4 v[208:211], v193, s[44:45] offset:2048
	global_load_dwordx4 v[184:187], v193, s[36:37] offset:2048
	global_load_dwordx4 v[156:159], v193, s[38:39] offset:3072
	global_load_dwordx4 v[212:215], v193, s[44:45] offset:3072
	global_load_dwordx4 v[188:191], v193, s[36:37] offset:3072
	s_waitcnt vmcnt(0)
	v_add_f32_e32 v200, 1.0, v200
	v_add_f32_e32 v201, 1.0, v201
	v_add_f32_e32 v202, 1.0, v202
	v_add_f32_e32 v203, 1.0, v203
	v_mul_f32_e32 v144, v144, v200
	v_mul_f32_e32 v145, v145, v201
	v_mul_f32_e32 v146, v146, v202
	v_mul_f32_e32 v147, v147, v203
	v_add_f32_e32 v204, 1.0, v204
	v_add_f32_e32 v205, 1.0, v205
	v_add_f32_e32 v206, 1.0, v206
	v_add_f32_e32 v207, 1.0, v207
	v_mul_f32_e32 v148, v148, v204
	v_mul_f32_e32 v149, v149, v205
	v_mul_f32_e32 v150, v150, v206
	v_mul_f32_e32 v151, v151, v207
	v_add_f32_e32 v208, 1.0, v208
	v_add_f32_e32 v209, 1.0, v209
	v_add_f32_e32 v210, 1.0, v210
	v_add_f32_e32 v211, 1.0, v211
	v_mul_f32_e32 v152, v152, v208
	v_mul_f32_e32 v153, v153, v209
	v_mul_f32_e32 v154, v154, v210
	v_mul_f32_e32 v155, v155, v211
	v_add_f32_e32 v212, 1.0, v212
	v_add_f32_e32 v213, 1.0, v213
	v_add_f32_e32 v214, 1.0, v214
	v_add_f32_e32 v215, 1.0, v215
	v_mul_f32_e32 v156, v156, v212
	v_mul_f32_e32 v157, v157, v213
	v_mul_f32_e32 v158, v158, v214
	v_mul_f32_e32 v159, v159, v215
; __device__ __forceinline__ float bf_lo(unsigned w) { return __uint_as_float(w << 16); }
; __device__ __forceinline__ float bf_hi(unsigned w) { return __uint_as_float(w & 0xffff0000u); }
; __global__ void __launch_bounds__(NWAVES * 64, 2) mk_fwd(Args args) {
;     ...
;             for (int q = 0; q < 3; ++q) { const int row = row0 + q; const bool lat = row < ML; const int r = lat ? row / SEQ : 8;
;                 float sy = 0.f;
; #pragma unroll
;                 for (int j = 0; j < 8; ++j) { const float a = bf_lo(yw[q][j].x), b = bf_hi(yw[q][j].x), c2 = bf_lo(yw[q][j].y), d = bf_hi(yw[q][j].y); sy += (a * a + b * b) + (c2 * c2 + d * d); }
;                 const float rsy = __builtin_amdgcn_rsqf(wave_sum(sy) * (1.f / DM) + EPS);
;                 const float* m0 = mod + (size_t)r * 6144;
; #pragma unroll
;                 for (int j = 0; j < 8; ++j) { const int col = 4 * F.lane + 256 * j; const f32x4 gt = *(const f32x4*)(m0 + 2 * DM + col), pn = *(const f32x4*)(post_norm + col);
;                     const f32x4 y4 = (f32x4){bf_lo(yw[q][j].x), bf_hi(yw[q][j].x), bf_lo(yw[q][j].y), bf_hi(yw[q][j].y)};
;                     v[q][j] = v[q][j] + gt * (y4 * rsy * pn);
.Lp6_np5:
	s_waitcnt vmcnt(24)
	v_lshlrev_b32_e32 v216, 16, v80
	v_and_b32_e32 v217, 0xffff0000, v80
	v_lshlrev_b32_e32 v218, 16, v81
	v_and_b32_e32 v219, 0xffff0000, v81
	v_mul_f32_e32 v222, v216, v216
	v_mul_f32_e32 v223, v217, v217
	v_fmac_f32_e32 v222, v218, v218
	v_fmac_f32_e32 v223, v219, v219
	v_lshlrev_b32_e32 v216, 16, v82
	v_and_b32_e32 v217, 0xffff0000, v82
	v_lshlrev_b32_e32 v218, 16, v83
	v_and_b32_e32 v219, 0xffff0000, v83
	v_fmac_f32_e32 v222, v216, v216
	v_fmac_f32_e32 v223, v217, v217
	v_fmac_f32_e32 v222, v218, v218
	v_fmac_f32_e32 v223, v219, v219
	v_lshlrev_b32_e32 v216, 16, v84
	v_and_b32_e32 v217, 0xffff0000, v84
	v_lshlrev_b32_e32 v218, 16, v85
	v_and_b32_e32 v219, 0xffff0000, v85
	v_fmac_f32_e32 v222, v216, v216
	v_fmac_f32_e32 v223, v217, v217
	v_fmac_f32_e32 v222, v218, v218
	v_fmac_f32_e32 v223, v219, v219
	v_lshlrev_b32_e32 v216, 16, v86
	v_and_b32_e32 v217, 0xffff0000, v86
	v_lshlrev_b32_e32 v218, 16, v87
	v_and_b32_e32 v219, 0xffff0000, v87
	v_fmac_f32_e32 v222, v216, v216
	v_fmac_f32_e32 v223, v217, v217
	v_fmac_f32_e32 v222, v218, v218
	v_fmac_f32_e32 v223, v219, v219
	v_lshlrev_b32_e32 v216, 16, v88
	v_and_b32_e32 v217, 0xffff0000, v88
	v_lshlrev_b32_e32 v218, 16, v89
	v_and_b32_e32 v219, 0xffff0000, v89
	v_fmac_f32_e32 v222, v216, v216
	v_fmac_f32_e32 v223, v217, v217
	v_fmac_f32_e32 v222, v218, v218
	v_fmac_f32_e32 v223, v219, v219
	v_lshlrev_b32_e32 v216, 16, v90
	v_and_b32_e32 v217, 0xffff0000, v90
	v_lshlrev_b32_e32 v218, 16, v91
	v_and_b32_e32 v219, 0xffff0000, v91
	v_fmac_f32_e32 v222, v216, v216
	v_fmac_f32_e32 v223, v217, v217
	v_fmac_f32_e32 v222, v218, v218
	v_fmac_f32_e32 v223, v219, v219
	v_lshlrev_b32_e32 v216, 16, v92
	v_and_b32_e32 v217, 0xffff0000, v92
	v_lshlrev_b32_e32 v218, 16, v93
	v_and_b32_e32 v219, 0xffff0000, v93
	v_fmac_f32_e32 v222, v216, v216
	v_fmac_f32_e32 v223, v217, v217
	v_fmac_f32_e32 v222, v218, v218
	v_fmac_f32_e32 v223, v219, v219
	v_lshlrev_b32_e32 v216, 16, v94
	v_and_b32_e32 v217, 0xffff0000, v94
	v_lshlrev_b32_e32 v218, 16, v95
	v_and_b32_e32 v219, 0xffff0000, v95
	v_fmac_f32_e32 v222, v216, v216
	v_fmac_f32_e32 v223, v217, v217
	v_fmac_f32_e32 v222, v218, v218
	v_fmac_f32_e32 v223, v219, v219
	v_add_f32_e32 v222, v222, v223
	s_nop 1
	v_add_f32_dpp v224, v222, v222 quad_perm:[1,0,3,2] row_mask:0xf bank_mask:0xf
	s_nop 1
	v_add_f32_dpp v224, v224, v224 quad_perm:[2,3,0,1] row_mask:0xf bank_mask:0xf
	s_nop 1
	v_add_f32_dpp v224, v224, v224 row_half_mirror row_mask:0xf bank_mask:0xf
	s_nop 1
	v_add_f32_dpp v224, v224, v224 row_mirror row_mask:0xf bank_mask:0xf
	s_nop 1
	v_readlane_b32 s40, v224, 0
	v_readlane_b32 s41, v224, 16
	v_readlane_b32 s42, v224, 32
	v_readlane_b32 s43, v224, 48
	s_nop 1
	v_mov_b32_e32 v225, s40
	v_add_f32_e32 v225, s41, v225
	v_add_f32_e32 v225, s42, v225
	v_add_f32_e32 v225, s43, v225
	v_fmamk_f32 v225, v225, 0x3a000000, v195
	v_rsq_f32_e32 v225, v225
	s_nop 0
	v_lshlrev_b32_e32 v216, 16, v80
	v_and_b32_e32 v217, 0xffff0000, v80
	v_lshlrev_b32_e32 v218, 16, v81
	v_and_b32_e32 v219, 0xffff0000, v81
	v_mul_f32_e32 v216, v225, v216
	v_mul_f32_e32 v217, v225, v217
	v_mul_f32_e32 v218, v225, v218
	v_mul_f32_e32 v219, v225, v219
	v_fmac_f32_e32 v48, v96, v216
	v_fmac_f32_e32 v49, v97, v217
	v_fmac_f32_e32 v50, v98, v218
	v_fmac_f32_e32 v51, v99, v219
	v_lshlrev_b32_e32 v216, 16, v82
	v_and_b32_e32 v217, 0xffff0000, v82
	v_lshlrev_b32_e32 v218, 16, v83
	v_and_b32_e32 v219, 0xffff0000, v83
	v_mul_f32_e32 v216, v225, v216
	v_mul_f32_e32 v217, v225, v217
	v_mul_f32_e32 v218, v225, v218
	v_mul_f32_e32 v219, v225, v219
	v_fmac_f32_e32 v52, v100, v216
	v_fmac_f32_e32 v53, v101, v217
	v_fmac_f32_e32 v54, v102, v218
	v_fmac_f32_e32 v55, v103, v219
	v_lshlrev_b32_e32 v216, 16, v84
	v_and_b32_e32 v217, 0xffff0000, v84
	v_lshlrev_b32_e32 v218, 16, v85
	v_and_b32_e32 v219, 0xffff0000, v85
	v_mul_f32_e32 v216, v225, v216
	v_mul_f32_e32 v217, v225, v217
	v_mul_f32_e32 v218, v225, v218
	v_mul_f32_e32 v219, v225, v219
	v_fmac_f32_e32 v56, v104, v216
	v_fmac_f32_e32 v57, v105, v217
	v_fmac_f32_e32 v58, v106, v218
	v_fmac_f32_e32 v59, v107, v219
	v_lshlrev_b32_e32 v216, 16, v86
	v_and_b32_e32 v217, 0xffff0000, v86
	v_lshlrev_b32_e32 v218, 16, v87
	v_and_b32_e32 v219, 0xffff0000, v87
	v_mul_f32_e32 v216, v225, v216
	v_mul_f32_e32 v217, v225, v217
	v_mul_f32_e32 v218, v225, v218
	v_mul_f32_e32 v219, v225, v219
	v_fmac_f32_e32 v60, v108, v216
	v_fmac_f32_e32 v61, v109, v217
	v_fmac_f32_e32 v62, v110, v218
	v_fmac_f32_e32 v63, v111, v219
	v_lshlrev_b32_e32 v216, 16, v88
	v_and_b32_e32 v217, 0xffff0000, v88
	v_lshlrev_b32_e32 v218, 16, v89
	v_and_b32_e32 v219, 0xffff0000, v89
	v_mul_f32_e32 v216, v225, v216
	v_mul_f32_e32 v217, v225, v217
	v_mul_f32_e32 v218, v225, v218
	v_mul_f32_e32 v219, v225, v219
	v_fmac_f32_e32 v64, v112, v216
	v_fmac_f32_e32 v65, v113, v217
	v_fmac_f32_e32 v66, v114, v218
	v_fmac_f32_e32 v67, v115, v219
	v_lshlrev_b32_e32 v216, 16, v90
	v_and_b32_e32 v217, 0xffff0000, v90
	v_lshlrev_b32_e32 v218, 16, v91
	v_and_b32_e32 v219, 0xffff0000, v91
	v_mul_f32_e32 v216, v225, v216
	v_mul_f32_e32 v217, v225, v217
	v_mul_f32_e32 v218, v225, v218
	v_mul_f32_e32 v219, v225, v219
	v_fmac_f32_e32 v68, v116, v216
	v_fmac_f32_e32 v69, v117, v217
	v_fmac_f32_e32 v70, v118, v218
	v_fmac_f32_e32 v71, v119, v219
	v_lshlrev_b32_e32 v216, 16, v92
	v_and_b32_e32 v217, 0xffff0000, v92
	v_lshlrev_b32_e32 v218, 16, v93
	v_and_b32_e32 v219, 0xffff0000, v93
	v_mul_f32_e32 v216, v225, v216
	v_mul_f32_e32 v217, v225, v217
	v_mul_f32_e32 v218, v225, v218
	v_mul_f32_e32 v219, v225, v219
	v_fmac_f32_e32 v72, v120, v216
	v_fmac_f32_e32 v73, v121, v217
	v_fmac_f32_e32 v74, v122, v218
; __device__ __forceinline__ unsigned cvt_pk_bf16(float lo, float hi) { unsigned r; asm volatile("v_cvt_pk_bf16_f32 %0, %1, %2" : "=v"(r) : "v"(lo), "v"(hi)); return r; }
; __device__ __forceinline__ float sumsq8(const f32x4 (&v)[8]) {
;     float s = 0.f;
; #pragma unroll
;     for (int j = 0; j < 8; ++j) s += (v[j][0] * v[j][0] + v[j][1] * v[j][1]) + (v[j][2] * v[j][2] + v[j][3] * v[j][3]);
;     return wave_sum(s);
; }
; __device__ __forceinline__ void modulate_store(const f32x4 (&v)[8], float rstd, const float* pn, const float* modr, bf16_t* orow, int lane) {
; #pragma unroll
;     for (int j = 0; j < 8; ++j) { const int col = 4 * lane + 256 * j;
;         const f32x4 g = *(const f32x4*)(pn + col), sh = *(const f32x4*)(modr + col), sc = *(const f32x4*)(modr + DM + col);
;         const f32x4 hh = v[j] * rstd * g * (sc + 1.f) + sh;
;         u32x2 w; w.x = cvt_pk_bf16(hh[0], hh[1]); w.y = cvt_pk_bf16(hh[2], hh[3]);
;         *(u32x2*)(orow + col) = w; }
; }
; __global__ void __launch_bounds__(NWAVES * 64, 2) mk_fwd(Args args) {
;     ...
;         for (int row0 = F.gw * 3; row0 < MT; row0 += F.NGW * 3) {
;             f32x4 v[3][8]; u32x2 yw[3][8];
; #pragma unroll
;             for (int q = 0; q < 3; ++q) { const int row = row0 + q; const float* src = row < ML ? x + (size_t)row * DM : ctx + (size_t)(row - ML) * DM; load_row_f32(src, F.lane, v[q]);
;                 const bf16_t* yr = Y + (size_t)row * DM;
; #pragma unroll
;                 for (int j = 0; j < 8; ++j) yw[q][j] = *(const u32x2*)(yr + 4 * F.lane + 256 * j); }
	v_fmac_f32_e32 v75, v123, v219
	v_lshlrev_b32_e32 v216, 16, v94
	v_and_b32_e32 v217, 0xffff0000, v94
	v_lshlrev_b32_e32 v218, 16, v95
	v_and_b32_e32 v219, 0xffff0000, v95
	v_mul_f32_e32 v216, v225, v216
	v_mul_f32_e32 v217, v225, v217
	v_mul_f32_e32 v218, v225, v218
	v_mul_f32_e32 v219, v225, v219
	v_fmac_f32_e32 v76, v124, v216
	v_fmac_f32_e32 v77, v125, v217
	v_fmac_f32_e32 v78, v126, v218
	v_fmac_f32_e32 v79, v127, v219
	v_mul_f32_e32 v222, v48, v48
	v_mul_f32_e32 v223, v49, v49
	v_fmac_f32_e32 v222, v50, v50
	v_fmac_f32_e32 v223, v51, v51
	v_fmac_f32_e32 v222, v52, v52
	v_fmac_f32_e32 v223, v53, v53
	v_fmac_f32_e32 v222, v54, v54
	v_fmac_f32_e32 v223, v55, v55
	v_fmac_f32_e32 v222, v56, v56
	v_fmac_f32_e32 v223, v57, v57
	v_fmac_f32_e32 v222, v58, v58
	v_fmac_f32_e32 v223, v59, v59
	v_fmac_f32_e32 v222, v60, v60
	v_fmac_f32_e32 v223, v61, v61
	v_fmac_f32_e32 v222, v62, v62
	v_fmac_f32_e32 v223, v63, v63
	v_fmac_f32_e32 v222, v64, v64
	v_fmac_f32_e32 v223, v65, v65
	v_fmac_f32_e32 v222, v66, v66
	v_fmac_f32_e32 v223, v67, v67
	v_fmac_f32_e32 v222, v68, v68
	v_fmac_f32_e32 v223, v69, v69
	v_fmac_f32_e32 v222, v70, v70
	v_fmac_f32_e32 v223, v71, v71
	v_fmac_f32_e32 v222, v72, v72
	v_fmac_f32_e32 v223, v73, v73
	v_fmac_f32_e32 v222, v74, v74
	v_fmac_f32_e32 v223, v75, v75
	v_fmac_f32_e32 v222, v76, v76
	v_fmac_f32_e32 v223, v77, v77
	v_fmac_f32_e32 v222, v78, v78
	v_fmac_f32_e32 v223, v79, v79
	v_add_f32_e32 v222, v222, v223
	s_nop 1
	v_add_f32_dpp v224, v222, v222 quad_perm:[1,0,3,2] row_mask:0xf bank_mask:0xf
	s_nop 1
	v_add_f32_dpp v224, v224, v224 quad_perm:[2,3,0,1] row_mask:0xf bank_mask:0xf
	s_nop 1
	v_add_f32_dpp v224, v224, v224 row_half_mirror row_mask:0xf bank_mask:0xf
	s_nop 1
	v_add_f32_dpp v224, v224, v224 row_mirror row_mask:0xf bank_mask:0xf
	s_nop 1
	v_readlane_b32 s40, v224, 0
	v_readlane_b32 s41, v224, 16
	v_readlane_b32 s42, v224, 32
	v_readlane_b32 s43, v224, 48
	s_nop 1
	v_mov_b32_e32 v225, s40
	v_add_f32_e32 v225, s41, v225
	v_add_f32_e32 v225, s42, v225
	v_add_f32_e32 v225, s43, v225
	v_fmamk_f32 v225, v225, 0x3a000000, v195
	v_rsq_f32_e32 v225, v225
	s_nop 0
	s_add_i32 s0, s6, 5
	s_lshl_b32 s1, s0, 12
	s_add_u32 s26, s84, s1
	s_addc_u32 s27, s85, 0
	s_add_u32 s26, s26, 0x4000000
	s_addc_u32 s27, s27, 0
	v_mul_f32_e32 v216, v225, v48
	v_mul_f32_e32 v217, v225, v49
	v_mul_f32_e32 v218, v225, v50
	v_mul_f32_e32 v219, v225, v51
	v_fma_f32 v216, v216, v128, v160
	v_fma_f32 v217, v217, v129, v161
	v_fma_f32 v218, v218, v130, v162
	v_fma_f32 v219, v219, v131, v163
	v_cvt_pk_bf16_f32 v196, v216, v217
	v_cvt_pk_bf16_f32 v197, v218, v219
	global_store_dwordx2 v194, v[196:197], s[26:27] offset:0
	v_mul_f32_e32 v216, v225, v52
	v_mul_f32_e32 v217, v225, v53
	v_mul_f32_e32 v218, v225, v54
	v_mul_f32_e32 v219, v225, v55
	v_fma_f32 v216, v216, v132, v164
	v_fma_f32 v217, v217, v133, v165
	v_fma_f32 v218, v218, v134, v166
	v_fma_f32 v219, v219, v135, v167
	v_cvt_pk_bf16_f32 v220, v216, v217
	v_cvt_pk_bf16_f32 v221, v218, v219
	global_store_dwordx2 v194, v[220:221], s[26:27] offset:512
	v_mul_f32_e32 v216, v225, v56
	v_mul_f32_e32 v217, v225, v57
	v_mul_f32_e32 v218, v225, v58
	v_mul_f32_e32 v219, v225, v59
	v_fma_f32 v216, v216, v136, v168
	v_fma_f32 v217, v217, v137, v169
	v_fma_f32 v218, v218, v138, v170
	v_fma_f32 v219, v219, v139, v171
	v_cvt_pk_bf16_f32 v196, v216, v217
	v_cvt_pk_bf16_f32 v197, v218, v219
	global_store_dwordx2 v194, v[196:197], s[26:27] offset:1024
	v_mul_f32_e32 v216, v225, v60
	v_mul_f32_e32 v217, v225, v61
	v_mul_f32_e32 v218, v225, v62
	v_mul_f32_e32 v219, v225, v63
	v_fma_f32 v216, v216, v140, v172
	v_fma_f32 v217, v217, v141, v173
	v_fma_f32 v218, v218, v142, v174
	v_fma_f32 v219, v219, v143, v175
	v_cvt_pk_bf16_f32 v220, v216, v217
	v_cvt_pk_bf16_f32 v221, v218, v219
	global_store_dwordx2 v194, v[220:221], s[26:27] offset:1536
	v_mul_f32_e32 v216, v225, v64
	v_mul_f32_e32 v217, v225, v65
	v_mul_f32_e32 v218, v225, v66
	v_mul_f32_e32 v219, v225, v67
	v_fma_f32 v216, v216, v144, v176
	v_fma_f32 v217, v217, v145, v177
	v_fma_f32 v218, v218, v146, v178
	v_fma_f32 v219, v219, v147, v179
	v_cvt_pk_bf16_f32 v196, v216, v217
	v_cvt_pk_bf16_f32 v197, v218, v219
	global_store_dwordx2 v194, v[196:197], s[26:27] offset:2048
	v_mul_f32_e32 v216, v225, v68
	v_mul_f32_e32 v217, v225, v69
	v_mul_f32_e32 v218, v225, v70
	v_mul_f32_e32 v219, v225, v71
	v_fma_f32 v216, v216, v148, v180
	v_fma_f32 v217, v217, v149, v181
	v_fma_f32 v218, v218, v150, v182
	v_fma_f32 v219, v219, v151, v183
	v_cvt_pk_bf16_f32 v220, v216, v217
	v_cvt_pk_bf16_f32 v221, v218, v219
	global_store_dwordx2 v194, v[220:221], s[26:27] offset:2560
	v_mul_f32_e32 v216, v225, v72
	v_mul_f32_e32 v217, v225, v73
	v_mul_f32_e32 v218, v225, v74
	v_mul_f32_e32 v219, v225, v75
	v_fma_f32 v216, v216, v152, v184
	v_fma_f32 v217, v217, v153, v185
	v_fma_f32 v218, v218, v154, v186
	v_fma_f32 v219, v219, v155, v187
	v_cvt_pk_bf16_f32 v196, v216, v217
	v_cvt_pk_bf16_f32 v197, v218, v219
	global_store_dwordx2 v194, v[196:197], s[26:27] offset:3072
	v_mul_f32_e32 v216, v225, v76
	v_mul_f32_e32 v217, v225, v77
	v_mul_f32_e32 v218, v225, v78
	v_mul_f32_e32 v219, v225, v79
	v_fma_f32 v216, v216, v156, v188
	v_fma_f32 v217, v217, v157, v189
	v_fma_f32 v218, v218, v158, v190
	v_fma_f32 v219, v219, v159, v191
	v_cvt_pk_bf16_f32 v220, v216, v217
	v_cvt_pk_bf16_f32 v221, v218, v219
	global_store_dwordx2 v194, v[220:221], s[26:27] offset:3584
	s_add_i32 s0, s6, 7
	s_cmp_lt_u32 s0, 0x4000
	s_cselect_b32 s10, s68, s72
	s_cselect_b32 s11, s69, s73
	s_cselect_b32 s1, 0, 0x4000
	s_sub_i32 s1, s0, s1
	s_lshl_b32 s1, s1, 13
	s_add_u32 s10, s10, s1
	s_addc_u32 s11, s11, 0
	s_add_i32 s0, s6, 7
	s_lshl_b32 s1, s0, 12
	s_add_u32 s22, s84, s1
	s_addc_u32 s23, s85, 0
	s_add_u32 s22, s22, 0x11800000
	s_addc_u32 s23, s23, 0
	global_load_dwordx4 v[48:51], v192, s[10:11] offset:0 nt
	global_load_dwordx4 v[52:55], v192, s[10:11] offset:1024 nt
	global_load_dwordx4 v[56:59], v192, s[10:11] offset:2048 nt
	global_load_dwordx4 v[60:63], v192, s[10:11] offset:3072 nt
	global_load_dwordx4 v[64:67], v193, s[10:11] offset:0 nt
	global_load_dwordx4 v[68:71], v193, s[10:11] offset:1024 nt
	global_load_dwordx4 v[72:75], v193, s[10:11] offset:2048 nt
	global_load_dwordx4 v[76:79], v193, s[10:11] offset:3072 nt
	global_load_dwordx2 v[80:81], v194, s[22:23] offset:0
	global_load_dwordx2 v[82:83], v194, s[22:23] offset:512
	global_load_dwordx2 v[84:85], v194, s[22:23] offset:1024
	global_load_dwordx2 v[86:87], v194, s[22:23] offset:1536
	global_load_dwordx2 v[88:89], v194, s[22:23] offset:2048
	global_load_dwordx2 v[90:91], v194, s[22:23] offset:2560
	global_load_dwordx2 v[92:93], v194, s[22:23] offset:3072
	global_load_dwordx2 v[94:95], v194, s[22:23] offset:3584
	s_add_i32 s0, s6, 6
	s_add_i32 s0, s6, 6
	s_lshr_b32 s8, s0, 11
	s_cmp_lt_u32 s0, 0x4000
	s_cselect_b32 s8, s8, 8
	s_cmp_eq_u32 s8, s7
	s_cbranch_scc1 .Lp6_np6
; __device__ __forceinline__ void modulate_store(const f32x4 (&v)[8], float rstd, const float* pn, const float* modr, bf16_t* orow, int lane) {
; #pragma unroll
;     for (int j = 0; j < 8; ++j) { const int col = 4 * lane + 256 * j;
;         const f32x4 g = *(const f32x4*)(pn + col), sh = *(const f32x4*)(modr + col), sc = *(const f32x4*)(modr + DM + col);
;         const f32x4 hh = v[j] * rstd * g * (sc + 1.f) + sh;
; __global__ void __launch_bounds__(NWAVES * 64, 2) mk_fwd(Args args) {
;     ...
;                 const float* m0 = mod + (size_t)r * 6144;
; #pragma unroll
;                 for (int j = 0; j < 8; ++j) { const int col = 4 * F.lane + 256 * j; const f32x4 gt = *(const f32x4*)(m0 + 2 * DM + col), pn = *(const f32x4*)(post_norm + col);
	s_mov_b32 s7, s8
	s_add_i32 s1, s8, 9
	s_mul_i32 s1, s1, 0x6000
	s_add_u32 s44, s84, s1
	s_addc_u32 s45, s85, 0
	s_add_u32 s44, s44, 0x2000
	s_addc_u32 s45, s45, 0
	s_add_i32 s1, s8, 9
	s_mul_i32 s1, s1, 0x6000
	s_add_u32 s36, s84, s1
	s_addc_u32 s37, s85, 0
	s_add_u32 s38, s80, 0x2000
	s_addc_u32 s39, s81, 0
	s_mul_i32 s1, s8, 0x6000
	s_add_u32 s34, s84, s1
	s_addc_u32 s35, s85, 0
	s_add_u32 s34, s34, 0x4000
	s_addc_u32 s35, s35, 0
	global_load_dwordx4 v[96:99], v192, s[34:35] offset:0
	global_load_dwordx4 v[200:203], v192, s[82:83] offset:0
	global_load_dwordx4 v[100:103], v192, s[34:35] offset:1024
	global_load_dwordx4 v[204:207], v192, s[82:83] offset:1024
	global_load_dwordx4 v[104:107], v192, s[34:35] offset:2048
	global_load_dwordx4 v[208:211], v192, s[82:83] offset:2048
	global_load_dwordx4 v[108:111], v192, s[34:35] offset:3072
	global_load_dwordx4 v[212:215], v192, s[82:83] offset:3072
	s_waitcnt vmcnt(0)
	v_mul_f32_e32 v96, v96, v200
	v_mul_f32_e32 v97, v97, v201
	v_mul_f32_e32 v98, v98, v202
	v_mul_f32_e32 v99, v99, v203
	v_mul_f32_e32 v100, v100, v204
	v_mul_f32_e32 v101, v101, v205
	v_mul_f32_e32 v102, v102, v206
	v_mul_f32_e32 v103, v103, v207
	v_mul_f32_e32 v104, v104, v208
	v_mul_f32_e32 v105, v105, v209
	v_mul_f32_e32 v106, v106, v210
	v_mul_f32_e32 v107, v107, v211
	v_mul_f32_e32 v108, v108, v212
	v_mul_f32_e32 v109, v109, v213
	v_mul_f32_e32 v110, v110, v214
	v_mul_f32_e32 v111, v111, v215
	global_load_dwordx4 v[128:131], v192, s[38:39] offset:0
	global_load_dwordx4 v[200:203], v192, s[44:45] offset:0
	global_load_dwordx4 v[160:163], v192, s[36:37] offset:0
	global_load_dwordx4 v[132:135], v192, s[38:39] offset:1024
	global_load_dwordx4 v[204:207], v192, s[44:45] offset:1024
	global_load_dwordx4 v[164:167], v192, s[36:37] offset:1024
	global_load_dwordx4 v[136:139], v192, s[38:39] offset:2048
	global_load_dwordx4 v[208:211], v192, s[44:45] offset:2048
	global_load_dwordx4 v[168:171], v192, s[36:37] offset:2048
	global_load_dwordx4 v[140:143], v192, s[38:39] offset:3072
	global_load_dwordx4 v[212:215], v192, s[44:45] offset:3072
	global_load_dwordx4 v[172:175], v192, s[36:37] offset:3072
	s_waitcnt vmcnt(0)
	v_add_f32_e32 v200, 1.0, v200
	v_add_f32_e32 v201, 1.0, v201
	v_add_f32_e32 v202, 1.0, v202
	v_add_f32_e32 v203, 1.0, v203
	v_mul_f32_e32 v128, v128, v200
	v_mul_f32_e32 v129, v129, v201
	v_mul_f32_e32 v130, v130, v202
	v_mul_f32_e32 v131, v131, v203
	v_add_f32_e32 v204, 1.0, v204
	v_add_f32_e32 v205, 1.0, v205
	v_add_f32_e32 v206, 1.0, v206
	v_add_f32_e32 v207, 1.0, v207
	v_mul_f32_e32 v132, v132, v204
	v_mul_f32_e32 v133, v133, v205
	v_mul_f32_e32 v134, v134, v206
	v_mul_f32_e32 v135, v135, v207
	v_add_f32_e32 v208, 1.0, v208
	v_add_f32_e32 v209, 1.0, v209
	v_add_f32_e32 v210, 1.0, v210
	v_add_f32_e32 v211, 1.0, v211
	v_mul_f32_e32 v136, v136, v208
	v_mul_f32_e32 v137, v137, v209
	v_mul_f32_e32 v138, v138, v210
	v_mul_f32_e32 v139, v139, v211
	v_add_f32_e32 v212, 1.0, v212
	v_add_f32_e32 v213, 1.0, v213
	v_add_f32_e32 v214, 1.0, v214
	v_add_f32_e32 v215, 1.0, v215
	v_mul_f32_e32 v140, v140, v212
	v_mul_f32_e32 v141, v141, v213
	v_mul_f32_e32 v142, v142, v214
	v_mul_f32_e32 v143, v143, v215
	global_load_dwordx4 v[112:115], v193, s[34:35] offset:0
	global_load_dwordx4 v[200:203], v193, s[82:83] offset:0
	global_load_dwordx4 v[116:119], v193, s[34:35] offset:1024
	global_load_dwordx4 v[204:207], v193, s[82:83] offset:1024
	global_load_dwordx4 v[120:123], v193, s[34:35] offset:2048
	global_load_dwordx4 v[208:211], v193, s[82:83] offset:2048
	global_load_dwordx4 v[124:127], v193, s[34:35] offset:3072
	global_load_dwordx4 v[212:215], v193, s[82:83] offset:3072
	s_waitcnt vmcnt(0)
	v_mul_f32_e32 v112, v112, v200
	v_mul_f32_e32 v113, v113, v201
	v_mul_f32_e32 v114, v114, v202
	v_mul_f32_e32 v115, v115, v203
	v_mul_f32_e32 v116, v116, v204
	v_mul_f32_e32 v117, v117, v205
	v_mul_f32_e32 v118, v118, v206
	v_mul_f32_e32 v119, v119, v207
	v_mul_f32_e32 v120, v120, v208
	v_mul_f32_e32 v121, v121, v209
	v_mul_f32_e32 v122, v122, v210
	v_mul_f32_e32 v123, v123, v211
	v_mul_f32_e32 v124, v124, v212
	v_mul_f32_e32 v125, v125, v213
	v_mul_f32_e32 v126, v126, v214
	v_mul_f32_e32 v127, v127, v215
	global_load_dwordx4 v[144:147], v193, s[38:39] offset:0
	global_load_dwordx4 v[200:203], v193, s[44:45] offset:0
	global_load_dwordx4 v[176:179], v193, s[36:37] offset:0
	global_load_dwordx4 v[148:151], v193, s[38:39] offset:1024
	global_load_dwordx4 v[204:207], v193, s[44:45] offset:1024
	global_load_dwordx4 v[180:183], v193, s[36:37] offset:1024
	global_load_dwordx4 v[152:155], v193, s[38:39] offset:2048
	global_load_dwordx4 v[208:211], v193, s[44:45] offset:2048
	global_load_dwordx4 v[184:187], v193, s[36:37] offset:2048
	global_load_dwordx4 v[156:159], v193, s[38:39] offset:3072
	global_load_dwordx4 v[212:215], v193, s[44:45] offset:3072
	global_load_dwordx4 v[188:191], v193, s[36:37] offset:3072
	s_waitcnt vmcnt(0)
	v_add_f32_e32 v200, 1.0, v200
	v_add_f32_e32 v201, 1.0, v201
	v_add_f32_e32 v202, 1.0, v202
	v_add_f32_e32 v203, 1.0, v203
	v_mul_f32_e32 v144, v144, v200
	v_mul_f32_e32 v145, v145, v201
	v_mul_f32_e32 v146, v146, v202
	v_mul_f32_e32 v147, v147, v203
	v_add_f32_e32 v204, 1.0, v204
	v_add_f32_e32 v205, 1.0, v205
	v_add_f32_e32 v206, 1.0, v206
	v_add_f32_e32 v207, 1.0, v207
	v_mul_f32_e32 v148, v148, v204
	v_mul_f32_e32 v149, v149, v205
	v_mul_f32_e32 v150, v150, v206
	v_mul_f32_e32 v151, v151, v207
	v_add_f32_e32 v208, 1.0, v208
	v_add_f32_e32 v209, 1.0, v209
	v_add_f32_e32 v210, 1.0, v210
	v_add_f32_e32 v211, 1.0, v211
	v_mul_f32_e32 v152, v152, v208
	v_mul_f32_e32 v153, v153, v209
	v_mul_f32_e32 v154, v154, v210
	v_mul_f32_e32 v155, v155, v211
	v_add_f32_e32 v212, 1.0, v212
	v_add_f32_e32 v213, 1.0, v213
	v_add_f32_e32 v214, 1.0, v214
	v_add_f32_e32 v215, 1.0, v215
	v_mul_f32_e32 v156, v156, v212
	v_mul_f32_e32 v157, v157, v213
	v_mul_f32_e32 v158, v158, v214
	v_mul_f32_e32 v159, v159, v215
; __device__ __forceinline__ float bf_lo(unsigned w) { return __uint_as_float(w << 16); }
; __device__ __forceinline__ float bf_hi(unsigned w) { return __uint_as_float(w & 0xffff0000u); }
; __global__ void __launch_bounds__(NWAVES * 64, 2) mk_fwd(Args args) {
;     ...
;             for (int q = 0; q < 3; ++q) { const int row = row0 + q; const bool lat = row < ML; const int r = lat ? row / SEQ : 8;
;                 float sy = 0.f;
; #pragma unroll
;                 for (int j = 0; j < 8; ++j) { const float a = bf_lo(yw[q][j].x), b = bf_hi(yw[q][j].x), c2 = bf_lo(yw[q][j].y), d = bf_hi(yw[q][j].y); sy += (a * a + b * b) + (c2 * c2 + d * d); }
;                 const float rsy = __builtin_amdgcn_rsqf(wave_sum(sy) * (1.f / DM) + EPS);
;                 const float* m0 = mod + (size_t)r * 6144;
; #pragma unroll
;                 for (int j = 0; j < 8; ++j) { const int col = 4 * F.lane + 256 * j; const f32x4 gt = *(const f32x4*)(m0 + 2 * DM + col), pn = *(const f32x4*)(post_norm + col);
;                     const f32x4 y4 = (f32x4){bf_lo(yw[q][j].x), bf_hi(yw[q][j].x), bf_lo(yw[q][j].y), bf_hi(yw[q][j].y)};
;                     v[q][j] = v[q][j] + gt * (y4 * rsy * pn);
.Lp6_np6:
	s_waitcnt vmcnt(24)
	v_lshlrev_b32_e32 v216, 16, v32
	v_and_b32_e32 v217, 0xffff0000, v32
	v_lshlrev_b32_e32 v218, 16, v33
	v_and_b32_e32 v219, 0xffff0000, v33
	v_mul_f32_e32 v222, v216, v216
	v_mul_f32_e32 v223, v217, v217
	v_fmac_f32_e32 v222, v218, v218
	v_fmac_f32_e32 v223, v219, v219
	v_lshlrev_b32_e32 v216, 16, v34
	v_and_b32_e32 v217, 0xffff0000, v34
	v_lshlrev_b32_e32 v218, 16, v35
	v_and_b32_e32 v219, 0xffff0000, v35
	v_fmac_f32_e32 v222, v216, v216
	v_fmac_f32_e32 v223, v217, v217
	v_fmac_f32_e32 v222, v218, v218
	v_fmac_f32_e32 v223, v219, v219
	v_lshlrev_b32_e32 v216, 16, v36
	v_and_b32_e32 v217, 0xffff0000, v36
	v_lshlrev_b32_e32 v218, 16, v37
	v_and_b32_e32 v219, 0xffff0000, v37
	v_fmac_f32_e32 v222, v216, v216
	v_fmac_f32_e32 v223, v217, v217
	v_fmac_f32_e32 v222, v218, v218
	v_fmac_f32_e32 v223, v219, v219
	v_lshlrev_b32_e32 v216, 16, v38
	v_and_b32_e32 v217, 0xffff0000, v38
	v_lshlrev_b32_e32 v218, 16, v39
	v_and_b32_e32 v219, 0xffff0000, v39
	v_fmac_f32_e32 v222, v216, v216
	v_fmac_f32_e32 v223, v217, v217
	v_fmac_f32_e32 v222, v218, v218
	v_fmac_f32_e32 v223, v219, v219
	v_lshlrev_b32_e32 v216, 16, v40
	v_and_b32_e32 v217, 0xffff0000, v40
	v_lshlrev_b32_e32 v218, 16, v41
	v_and_b32_e32 v219, 0xffff0000, v41
	v_fmac_f32_e32 v222, v216, v216
	v_fmac_f32_e32 v223, v217, v217
	v_fmac_f32_e32 v222, v218, v218
	v_fmac_f32_e32 v223, v219, v219
	v_lshlrev_b32_e32 v216, 16, v42
	v_and_b32_e32 v217, 0xffff0000, v42
	v_lshlrev_b32_e32 v218, 16, v43
	v_and_b32_e32 v219, 0xffff0000, v43
	v_fmac_f32_e32 v222, v216, v216
	v_fmac_f32_e32 v223, v217, v217
	v_fmac_f32_e32 v222, v218, v218
	v_fmac_f32_e32 v223, v219, v219
	v_lshlrev_b32_e32 v216, 16, v44
	v_and_b32_e32 v217, 0xffff0000, v44
	v_lshlrev_b32_e32 v218, 16, v45
	v_and_b32_e32 v219, 0xffff0000, v45
	v_fmac_f32_e32 v222, v216, v216
	v_fmac_f32_e32 v223, v217, v217
	v_fmac_f32_e32 v222, v218, v218
	v_fmac_f32_e32 v223, v219, v219
	v_lshlrev_b32_e32 v216, 16, v46
	v_and_b32_e32 v217, 0xffff0000, v46
	v_lshlrev_b32_e32 v218, 16, v47
	v_and_b32_e32 v219, 0xffff0000, v47
	v_fmac_f32_e32 v222, v216, v216
	v_fmac_f32_e32 v223, v217, v217
	v_fmac_f32_e32 v222, v218, v218
	v_fmac_f32_e32 v223, v219, v219
	v_add_f32_e32 v222, v222, v223
	s_nop 1
	v_add_f32_dpp v224, v222, v222 quad_perm:[1,0,3,2] row_mask:0xf bank_mask:0xf
	s_nop 1
	v_add_f32_dpp v224, v224, v224 quad_perm:[2,3,0,1] row_mask:0xf bank_mask:0xf
	s_nop 1
	v_add_f32_dpp v224, v224, v224 row_half_mirror row_mask:0xf bank_mask:0xf
	s_nop 1
	v_add_f32_dpp v224, v224, v224 row_mirror row_mask:0xf bank_mask:0xf
	s_nop 1
	v_readlane_b32 s40, v224, 0
	v_readlane_b32 s41, v224, 16
	v_readlane_b32 s42, v224, 32
	v_readlane_b32 s43, v224, 48
	s_nop 1
	v_mov_b32_e32 v225, s40
	v_add_f32_e32 v225, s41, v225
	v_add_f32_e32 v225, s42, v225
	v_add_f32_e32 v225, s43, v225
	v_fmamk_f32 v225, v225, 0x3a000000, v195
	v_rsq_f32_e32 v225, v225
	s_nop 0
	v_lshlrev_b32_e32 v216, 16, v32
	v_and_b32_e32 v217, 0xffff0000, v32
	v_lshlrev_b32_e32 v218, 16, v33
	v_and_b32_e32 v219, 0xffff0000, v33
	v_mul_f32_e32 v216, v225, v216
	v_mul_f32_e32 v217, v225, v217
	v_mul_f32_e32 v218, v225, v218
	v_mul_f32_e32 v219, v225, v219
	v_fmac_f32_e32 v0, v96, v216
	v_fmac_f32_e32 v1, v97, v217
	v_fmac_f32_e32 v2, v98, v218
	v_fmac_f32_e32 v3, v99, v219
	v_lshlrev_b32_e32 v216, 16, v34
	v_and_b32_e32 v217, 0xffff0000, v34
	v_lshlrev_b32_e32 v218, 16, v35
	v_and_b32_e32 v219, 0xffff0000, v35
	v_mul_f32_e32 v216, v225, v216
	v_mul_f32_e32 v217, v225, v217
	v_mul_f32_e32 v218, v225, v218
	v_mul_f32_e32 v219, v225, v219
	v_fmac_f32_e32 v4, v100, v216
	v_fmac_f32_e32 v5, v101, v217
	v_fmac_f32_e32 v6, v102, v218
	v_fmac_f32_e32 v7, v103, v219
	v_lshlrev_b32_e32 v216, 16, v36
	v_and_b32_e32 v217, 0xffff0000, v36
	v_lshlrev_b32_e32 v218, 16, v37
	v_and_b32_e32 v219, 0xffff0000, v37
	v_mul_f32_e32 v216, v225, v216
	v_mul_f32_e32 v217, v225, v217
	v_mul_f32_e32 v218, v225, v218
	v_mul_f32_e32 v219, v225, v219
	v_fmac_f32_e32 v8, v104, v216
	v_fmac_f32_e32 v9, v105, v217
	v_fmac_f32_e32 v10, v106, v218
	v_fmac_f32_e32 v11, v107, v219
	v_lshlrev_b32_e32 v216, 16, v38
	v_and_b32_e32 v217, 0xffff0000, v38
	v_lshlrev_b32_e32 v218, 16, v39
	v_and_b32_e32 v219, 0xffff0000, v39
	v_mul_f32_e32 v216, v225, v216
	v_mul_f32_e32 v217, v225, v217
	v_mul_f32_e32 v218, v225, v218
	v_mul_f32_e32 v219, v225, v219
	v_fmac_f32_e32 v12, v108, v216
	v_fmac_f32_e32 v13, v109, v217
	v_fmac_f32_e32 v14, v110, v218
	v_fmac_f32_e32 v15, v111, v219
	v_lshlrev_b32_e32 v216, 16, v40
	v_and_b32_e32 v217, 0xffff0000, v40
	v_lshlrev_b32_e32 v218, 16, v41
	v_and_b32_e32 v219, 0xffff0000, v41
	v_mul_f32_e32 v216, v225, v216
	v_mul_f32_e32 v217, v225, v217
	v_mul_f32_e32 v218, v225, v218
	v_mul_f32_e32 v219, v225, v219
	v_fmac_f32_e32 v16, v112, v216
	v_fmac_f32_e32 v17, v113, v217
	v_fmac_f32_e32 v18, v114, v218
	v_fmac_f32_e32 v19, v115, v219
	v_lshlrev_b32_e32 v216, 16, v42
	v_and_b32_e32 v217, 0xffff0000, v42
	v_lshlrev_b32_e32 v218, 16, v43
	v_and_b32_e32 v219, 0xffff0000, v43
	v_mul_f32_e32 v216, v225, v216
	v_mul_f32_e32 v217, v225, v217
	v_mul_f32_e32 v218, v225, v218
	v_mul_f32_e32 v219, v225, v219
	v_fmac_f32_e32 v20, v116, v216
	v_fmac_f32_e32 v21, v117, v217
	v_fmac_f32_e32 v22, v118, v218
	v_fmac_f32_e32 v23, v119, v219
	v_lshlrev_b32_e32 v216, 16, v44
	v_and_b32_e32 v217, 0xffff0000, v44
	v_lshlrev_b32_e32 v218, 16, v45
	v_and_b32_e32 v219, 0xffff0000, v45
	v_mul_f32_e32 v216, v225, v216
	v_mul_f32_e32 v217, v225, v217
	v_mul_f32_e32 v218, v225, v218
	v_mul_f32_e32 v219, v225, v219
	v_fmac_f32_e32 v24, v120, v216
	v_fmac_f32_e32 v25, v121, v217
	v_fmac_f32_e32 v26, v122, v218
; __device__ __forceinline__ unsigned cvt_pk_bf16(float lo, float hi) { unsigned r; asm volatile("v_cvt_pk_bf16_f32 %0, %1, %2" : "=v"(r) : "v"(lo), "v"(hi)); return r; }
; __device__ __forceinline__ float sumsq8(const f32x4 (&v)[8]) {
;     float s = 0.f;
; #pragma unroll
;     for (int j = 0; j < 8; ++j) s += (v[j][0] * v[j][0] + v[j][1] * v[j][1]) + (v[j][2] * v[j][2] + v[j][3] * v[j][3]);
;     return wave_sum(s);
; }
; __device__ __forceinline__ void modulate_store(const f32x4 (&v)[8], float rstd, const float* pn, const float* modr, bf16_t* orow, int lane) {
; #pragma unroll
;     for (int j = 0; j < 8; ++j) { const int col = 4 * lane + 256 * j;
;         const f32x4 g = *(const f32x4*)(pn + col), sh = *(const f32x4*)(modr + col), sc = *(const f32x4*)(modr + DM + col);
;         const f32x4 hh = v[j] * rstd * g * (sc + 1.f) + sh;
;         u32x2 w; w.x = cvt_pk_bf16(hh[0], hh[1]); w.y = cvt_pk_bf16(hh[2], hh[3]);
;         *(u32x2*)(orow + col) = w; }
; }
; __global__ void __launch_bounds__(NWAVES * 64, 2) mk_fwd(Args args) {
;     ...
;         for (int row0 = F.gw * 3; row0 < MT; row0 += F.NGW * 3) {
;             f32x4 v[3][8]; u32x2 yw[3][8];
; #pragma unroll
;             for (int q = 0; q < 3; ++q) { const int row = row0 + q; const float* src = row < ML ? x + (size_t)row * DM : ctx + (size_t)(row - ML) * DM; load_row_f32(src, F.lane, v[q]);
;                 const bf16_t* yr = Y + (size_t)row * DM;
; #pragma unroll
;                 for (int j = 0; j < 8; ++j) yw[q][j] = *(const u32x2*)(yr + 4 * F.lane + 256 * j); }
	v_fmac_f32_e32 v27, v123, v219
	v_lshlrev_b32_e32 v216, 16, v46
	v_and_b32_e32 v217, 0xffff0000, v46
	v_lshlrev_b32_e32 v218, 16, v47
	v_and_b32_e32 v219, 0xffff0000, v47
	v_mul_f32_e32 v216, v225, v216
	v_mul_f32_e32 v217, v225, v217
	v_mul_f32_e32 v218, v225, v218
	v_mul_f32_e32 v219, v225, v219
	v_fmac_f32_e32 v28, v124, v216
	v_fmac_f32_e32 v29, v125, v217
	v_fmac_f32_e32 v30, v126, v218
	v_fmac_f32_e32 v31, v127, v219
	v_mul_f32_e32 v222, v0, v0
	v_mul_f32_e32 v223, v1, v1
	v_fmac_f32_e32 v222, v2, v2
	v_fmac_f32_e32 v223, v3, v3
	v_fmac_f32_e32 v222, v4, v4
	v_fmac_f32_e32 v223, v5, v5
	v_fmac_f32_e32 v222, v6, v6
	v_fmac_f32_e32 v223, v7, v7
	v_fmac_f32_e32 v222, v8, v8
	v_fmac_f32_e32 v223, v9, v9
	v_fmac_f32_e32 v222, v10, v10
	v_fmac_f32_e32 v223, v11, v11
	v_fmac_f32_e32 v222, v12, v12
	v_fmac_f32_e32 v223, v13, v13
	v_fmac_f32_e32 v222, v14, v14
	v_fmac_f32_e32 v223, v15, v15
	v_fmac_f32_e32 v222, v16, v16
	v_fmac_f32_e32 v223, v17, v17
	v_fmac_f32_e32 v222, v18, v18
	v_fmac_f32_e32 v223, v19, v19
	v_fmac_f32_e32 v222, v20, v20
	v_fmac_f32_e32 v223, v21, v21
	v_fmac_f32_e32 v222, v22, v22
	v_fmac_f32_e32 v223, v23, v23
	v_fmac_f32_e32 v222, v24, v24
	v_fmac_f32_e32 v223, v25, v25
	v_fmac_f32_e32 v222, v26, v26
	v_fmac_f32_e32 v223, v27, v27
	v_fmac_f32_e32 v222, v28, v28
	v_fmac_f32_e32 v223, v29, v29
	v_fmac_f32_e32 v222, v30, v30
	v_fmac_f32_e32 v223, v31, v31
	v_add_f32_e32 v222, v222, v223
	s_nop 1
	v_add_f32_dpp v224, v222, v222 quad_perm:[1,0,3,2] row_mask:0xf bank_mask:0xf
	s_nop 1
	v_add_f32_dpp v224, v224, v224 quad_perm:[2,3,0,1] row_mask:0xf bank_mask:0xf
	s_nop 1
	v_add_f32_dpp v224, v224, v224 row_half_mirror row_mask:0xf bank_mask:0xf
	s_nop 1
	v_add_f32_dpp v224, v224, v224 row_mirror row_mask:0xf bank_mask:0xf
	s_nop 1
	v_readlane_b32 s40, v224, 0
	v_readlane_b32 s41, v224, 16
	v_readlane_b32 s42, v224, 32
	v_readlane_b32 s43, v224, 48
	s_nop 1
	v_mov_b32_e32 v225, s40
	v_add_f32_e32 v225, s41, v225
	v_add_f32_e32 v225, s42, v225
	v_add_f32_e32 v225, s43, v225
	v_fmamk_f32 v225, v225, 0x3a000000, v195
	v_rsq_f32_e32 v225, v225
	s_nop 0
	s_add_i32 s0, s6, 6
	s_lshl_b32 s1, s0, 12
	s_add_u32 s26, s84, s1
	s_addc_u32 s27, s85, 0
	s_add_u32 s26, s26, 0x4000000
	s_addc_u32 s27, s27, 0
	v_mul_f32_e32 v216, v225, v0
	v_mul_f32_e32 v217, v225, v1
	v_mul_f32_e32 v218, v225, v2
	v_mul_f32_e32 v219, v225, v3
	v_fma_f32 v216, v216, v128, v160
	v_fma_f32 v217, v217, v129, v161
	v_fma_f32 v218, v218, v130, v162
	v_fma_f32 v219, v219, v131, v163
	v_cvt_pk_bf16_f32 v196, v216, v217
	v_cvt_pk_bf16_f32 v197, v218, v219
	global_store_dwordx2 v194, v[196:197], s[26:27] offset:0
	v_mul_f32_e32 v216, v225, v4
	v_mul_f32_e32 v217, v225, v5
	v_mul_f32_e32 v218, v225, v6
	v_mul_f32_e32 v219, v225, v7
	v_fma_f32 v216, v216, v132, v164
	v_fma_f32 v217, v217, v133, v165
	v_fma_f32 v218, v218, v134, v166
	v_fma_f32 v219, v219, v135, v167
	v_cvt_pk_bf16_f32 v220, v216, v217
	v_cvt_pk_bf16_f32 v221, v218, v219
	global_store_dwordx2 v194, v[220:221], s[26:27] offset:512
	v_mul_f32_e32 v216, v225, v8
	v_mul_f32_e32 v217, v225, v9
	v_mul_f32_e32 v218, v225, v10
	v_mul_f32_e32 v219, v225, v11
	v_fma_f32 v216, v216, v136, v168
	v_fma_f32 v217, v217, v137, v169
	v_fma_f32 v218, v218, v138, v170
	v_fma_f32 v219, v219, v139, v171
	v_cvt_pk_bf16_f32 v196, v216, v217
	v_cvt_pk_bf16_f32 v197, v218, v219
	global_store_dwordx2 v194, v[196:197], s[26:27] offset:1024
	v_mul_f32_e32 v216, v225, v12
	v_mul_f32_e32 v217, v225, v13
	v_mul_f32_e32 v218, v225, v14
	v_mul_f32_e32 v219, v225, v15
	v_fma_f32 v216, v216, v140, v172
	v_fma_f32 v217, v217, v141, v173
	v_fma_f32 v218, v218, v142, v174
	v_fma_f32 v219, v219, v143, v175
	v_cvt_pk_bf16_f32 v220, v216, v217
	v_cvt_pk_bf16_f32 v221, v218, v219
	global_store_dwordx2 v194, v[220:221], s[26:27] offset:1536
	v_mul_f32_e32 v216, v225, v16
	v_mul_f32_e32 v217, v225, v17
	v_mul_f32_e32 v218, v225, v18
	v_mul_f32_e32 v219, v225, v19
	v_fma_f32 v216, v216, v144, v176
	v_fma_f32 v217, v217, v145, v177
	v_fma_f32 v218, v218, v146, v178
	v_fma_f32 v219, v219, v147, v179
	v_cvt_pk_bf16_f32 v196, v216, v217
	v_cvt_pk_bf16_f32 v197, v218, v219
	global_store_dwordx2 v194, v[196:197], s[26:27] offset:2048
	v_mul_f32_e32 v216, v225, v20
	v_mul_f32_e32 v217, v225, v21
	v_mul_f32_e32 v218, v225, v22
	v_mul_f32_e32 v219, v225, v23
	v_fma_f32 v216, v216, v148, v180
	v_fma_f32 v217, v217, v149, v181
	v_fma_f32 v218, v218, v150, v182
	v_fma_f32 v219, v219, v151, v183
	v_cvt_pk_bf16_f32 v220, v216, v217
	v_cvt_pk_bf16_f32 v221, v218, v219
	global_store_dwordx2 v194, v[220:221], s[26:27] offset:2560
	v_mul_f32_e32 v216, v225, v24
	v_mul_f32_e32 v217, v225, v25
	v_mul_f32_e32 v218, v225, v26
	v_mul_f32_e32 v219, v225, v27
	v_fma_f32 v216, v216, v152, v184
	v_fma_f32 v217, v217, v153, v185
	v_fma_f32 v218, v218, v154, v186
	v_fma_f32 v219, v219, v155, v187
	v_cvt_pk_bf16_f32 v196, v216, v217
	v_cvt_pk_bf16_f32 v197, v218, v219
	global_store_dwordx2 v194, v[196:197], s[26:27] offset:3072
	v_mul_f32_e32 v216, v225, v28
	v_mul_f32_e32 v217, v225, v29
	v_mul_f32_e32 v218, v225, v30
	v_mul_f32_e32 v219, v225, v31
	v_fma_f32 v216, v216, v156, v188
	v_fma_f32 v217, v217, v157, v189
	v_fma_f32 v218, v218, v158, v190
	v_fma_f32 v219, v219, v159, v191
	v_cvt_pk_bf16_f32 v220, v216, v217
	v_cvt_pk_bf16_f32 v221, v218, v219
	global_store_dwordx2 v194, v[220:221], s[26:27] offset:3584
	s_add_i32 s0, s6, 8
	s_cmp_lt_u32 s0, 0x4000
	s_cselect_b32 s10, s68, s72
	s_cselect_b32 s11, s69, s73
	s_cselect_b32 s1, 0, 0x4000
	s_sub_i32 s1, s0, s1
	s_lshl_b32 s1, s1, 13
	s_add_u32 s10, s10, s1
	s_addc_u32 s11, s11, 0
	s_add_i32 s0, s6, 8
	s_lshl_b32 s1, s0, 12
	s_add_u32 s22, s84, s1
	s_addc_u32 s23, s85, 0
	s_add_u32 s22, s22, 0x11800000
	s_addc_u32 s23, s23, 0
	global_load_dwordx4 v[0:3], v192, s[10:11] offset:0 nt
	global_load_dwordx4 v[4:7], v192, s[10:11] offset:1024 nt
	global_load_dwordx4 v[8:11], v192, s[10:11] offset:2048 nt
	global_load_dwordx4 v[12:15], v192, s[10:11] offset:3072 nt
	global_load_dwordx4 v[16:19], v193, s[10:11] offset:0 nt
	global_load_dwordx4 v[20:23], v193, s[10:11] offset:1024 nt
	global_load_dwordx4 v[24:27], v193, s[10:11] offset:2048 nt
	global_load_dwordx4 v[28:31], v193, s[10:11] offset:3072 nt
	global_load_dwordx2 v[32:33], v194, s[22:23] offset:0
	global_load_dwordx2 v[34:35], v194, s[22:23] offset:512
	global_load_dwordx2 v[36:37], v194, s[22:23] offset:1024
	global_load_dwordx2 v[38:39], v194, s[22:23] offset:1536
	global_load_dwordx2 v[40:41], v194, s[22:23] offset:2048
	global_load_dwordx2 v[42:43], v194, s[22:23] offset:2560
	global_load_dwordx2 v[44:45], v194, s[22:23] offset:3072
	global_load_dwordx2 v[46:47], v194, s[22:23] offset:3584
	s_add_i32 s0, s6, 7
	s_add_i32 s0, s6, 7
	s_lshr_b32 s8, s0, 11
	s_cmp_lt_u32 s0, 0x4000
	s_cselect_b32 s8, s8, 8
	s_cmp_eq_u32 s8, s7
	s_cbranch_scc1 .Lp6_np7
; __device__ __forceinline__ void modulate_store(const f32x4 (&v)[8], float rstd, const float* pn, const float* modr, bf16_t* orow, int lane) {
; #pragma unroll
;     for (int j = 0; j < 8; ++j) { const int col = 4 * lane + 256 * j;
;         const f32x4 g = *(const f32x4*)(pn + col), sh = *(const f32x4*)(modr + col), sc = *(const f32x4*)(modr + DM + col);
;         const f32x4 hh = v[j] * rstd * g * (sc + 1.f) + sh;
; __global__ void __launch_bounds__(NWAVES * 64, 2) mk_fwd(Args args) {
;     ...
;                 const float* m0 = mod + (size_t)r * 6144;
; #pragma unroll
;                 for (int j = 0; j < 8; ++j) { const int col = 4 * F.lane + 256 * j; const f32x4 gt = *(const f32x4*)(m0 + 2 * DM + col), pn = *(const f32x4*)(post_norm + col);
	s_mov_b32 s7, s8
	s_add_i32 s1, s8, 9
	s_mul_i32 s1, s1, 0x6000
	s_add_u32 s44, s84, s1
	s_addc_u32 s45, s85, 0
	s_add_u32 s44, s44, 0x2000
	s_addc_u32 s45, s45, 0
	s_add_i32 s1, s8, 9
	s_mul_i32 s1, s1, 0x6000
	s_add_u32 s36, s84, s1
	s_addc_u32 s37, s85, 0
	s_add_u32 s38, s80, 0x2000
	s_addc_u32 s39, s81, 0
	s_mul_i32 s1, s8, 0x6000
	s_add_u32 s34, s84, s1
	s_addc_u32 s35, s85, 0
	s_add_u32 s34, s34, 0x4000
	s_addc_u32 s35, s35, 0
	global_load_dwordx4 v[96:99], v192, s[34:35] offset:0
	global_load_dwordx4 v[200:203], v192, s[82:83] offset:0
	global_load_dwordx4 v[100:103], v192, s[34:35] offset:1024
	global_load_dwordx4 v[204:207], v192, s[82:83] offset:1024
	global_load_dwordx4 v[104:107], v192, s[34:35] offset:2048
	global_load_dwordx4 v[208:211], v192, s[82:83] offset:2048
	global_load_dwordx4 v[108:111], v192, s[34:35] offset:3072
	global_load_dwordx4 v[212:215], v192, s[82:83] offset:3072
	s_waitcnt vmcnt(0)
	v_mul_f32_e32 v96, v96, v200
	v_mul_f32_e32 v97, v97, v201
	v_mul_f32_e32 v98, v98, v202
	v_mul_f32_e32 v99, v99, v203
	v_mul_f32_e32 v100, v100, v204
	v_mul_f32_e32 v101, v101, v205
	v_mul_f32_e32 v102, v102, v206
	v_mul_f32_e32 v103, v103, v207
	v_mul_f32_e32 v104, v104, v208
	v_mul_f32_e32 v105, v105, v209
	v_mul_f32_e32 v106, v106, v210
	v_mul_f32_e32 v107, v107, v211
	v_mul_f32_e32 v108, v108, v212
	v_mul_f32_e32 v109, v109, v213
	v_mul_f32_e32 v110, v110, v214
	v_mul_f32_e32 v111, v111, v215
	global_load_dwordx4 v[128:131], v192, s[38:39] offset:0
	global_load_dwordx4 v[200:203], v192, s[44:45] offset:0
	global_load_dwordx4 v[160:163], v192, s[36:37] offset:0
	global_load_dwordx4 v[132:135], v192, s[38:39] offset:1024
	global_load_dwordx4 v[204:207], v192, s[44:45] offset:1024
	global_load_dwordx4 v[164:167], v192, s[36:37] offset:1024
	global_load_dwordx4 v[136:139], v192, s[38:39] offset:2048
	global_load_dwordx4 v[208:211], v192, s[44:45] offset:2048
	global_load_dwordx4 v[168:171], v192, s[36:37] offset:2048
	global_load_dwordx4 v[140:143], v192, s[38:39] offset:3072
	global_load_dwordx4 v[212:215], v192, s[44:45] offset:3072
	global_load_dwordx4 v[172:175], v192, s[36:37] offset:3072
	s_waitcnt vmcnt(0)
	v_add_f32_e32 v200, 1.0, v200
	v_add_f32_e32 v201, 1.0, v201
	v_add_f32_e32 v202, 1.0, v202
	v_add_f32_e32 v203, 1.0, v203
	v_mul_f32_e32 v128, v128, v200
	v_mul_f32_e32 v129, v129, v201
	v_mul_f32_e32 v130, v130, v202
	v_mul_f32_e32 v131, v131, v203
	v_add_f32_e32 v204, 1.0, v204
	v_add_f32_e32 v205, 1.0, v205
	v_add_f32_e32 v206, 1.0, v206
	v_add_f32_e32 v207, 1.0, v207
	v_mul_f32_e32 v132, v132, v204
	v_mul_f32_e32 v133, v133, v205
	v_mul_f32_e32 v134, v134, v206
	v_mul_f32_e32 v135, v135, v207
	v_add_f32_e32 v208, 1.0, v208
	v_add_f32_e32 v209, 1.0, v209
	v_add_f32_e32 v210, 1.0, v210
	v_add_f32_e32 v211, 1.0, v211
	v_mul_f32_e32 v136, v136, v208
	v_mul_f32_e32 v137, v137, v209
	v_mul_f32_e32 v138, v138, v210
	v_mul_f32_e32 v139, v139, v211
	v_add_f32_e32 v212, 1.0, v212
	v_add_f32_e32 v213, 1.0, v213
	v_add_f32_e32 v214, 1.0, v214
	v_add_f32_e32 v215, 1.0, v215
	v_mul_f32_e32 v140, v140, v212
	v_mul_f32_e32 v141, v141, v213
	v_mul_f32_e32 v142, v142, v214
	v_mul_f32_e32 v143, v143, v215
	global_load_dwordx4 v[112:115], v193, s[34:35] offset:0
	global_load_dwordx4 v[200:203], v193, s[82:83] offset:0
	global_load_dwordx4 v[116:119], v193, s[34:35] offset:1024
	global_load_dwordx4 v[204:207], v193, s[82:83] offset:1024
	global_load_dwordx4 v[120:123], v193, s[34:35] offset:2048
	global_load_dwordx4 v[208:211], v193, s[82:83] offset:2048
	global_load_dwordx4 v[124:127], v193, s[34:35] offset:3072
	global_load_dwordx4 v[212:215], v193, s[82:83] offset:3072
	s_waitcnt vmcnt(0)
	v_mul_f32_e32 v112, v112, v200
	v_mul_f32_e32 v113, v113, v201
	v_mul_f32_e32 v114, v114, v202
	v_mul_f32_e32 v115, v115, v203
	v_mul_f32_e32 v116, v116, v204
	v_mul_f32_e32 v117, v117, v205
	v_mul_f32_e32 v118, v118, v206
	v_mul_f32_e32 v119, v119, v207
	v_mul_f32_e32 v120, v120, v208
	v_mul_f32_e32 v121, v121, v209
	v_mul_f32_e32 v122, v122, v210
	v_mul_f32_e32 v123, v123, v211
	v_mul_f32_e32 v124, v124, v212
	v_mul_f32_e32 v125, v125, v213
	v_mul_f32_e32 v126, v126, v214
	v_mul_f32_e32 v127, v127, v215
	global_load_dwordx4 v[144:147], v193, s[38:39] offset:0
	global_load_dwordx4 v[200:203], v193, s[44:45] offset:0
	global_load_dwordx4 v[176:179], v193, s[36:37] offset:0
	global_load_dwordx4 v[148:151], v193, s[38:39] offset:1024
	global_load_dwordx4 v[204:207], v193, s[44:45] offset:1024
	global_load_dwordx4 v[180:183], v193, s[36:37] offset:1024
	global_load_dwordx4 v[152:155], v193, s[38:39] offset:2048
	global_load_dwordx4 v[208:211], v193, s[44:45] offset:2048
	global_load_dwordx4 v[184:187], v193, s[36:37] offset:2048
	global_load_dwordx4 v[156:159], v193, s[38:39] offset:3072
	global_load_dwordx4 v[212:215], v193, s[44:45] offset:3072
	global_load_dwordx4 v[188:191], v193, s[36:37] offset:3072
	s_waitcnt vmcnt(0)
	v_add_f32_e32 v200, 1.0, v200
	v_add_f32_e32 v201, 1.0, v201
	v_add_f32_e32 v202, 1.0, v202
	v_add_f32_e32 v203, 1.0, v203
	v_mul_f32_e32 v144, v144, v200
	v_mul_f32_e32 v145, v145, v201
	v_mul_f32_e32 v146, v146, v202
	v_mul_f32_e32 v147, v147, v203
	v_add_f32_e32 v204, 1.0, v204
	v_add_f32_e32 v205, 1.0, v205
	v_add_f32_e32 v206, 1.0, v206
	v_add_f32_e32 v207, 1.0, v207
	v_mul_f32_e32 v148, v148, v204
	v_mul_f32_e32 v149, v149, v205
	v_mul_f32_e32 v150, v150, v206
	v_mul_f32_e32 v151, v151, v207
	v_add_f32_e32 v208, 1.0, v208
	v_add_f32_e32 v209, 1.0, v209
	v_add_f32_e32 v210, 1.0, v210
	v_add_f32_e32 v211, 1.0, v211
	v_mul_f32_e32 v152, v152, v208
	v_mul_f32_e32 v153, v153, v209
	v_mul_f32_e32 v154, v154, v210
	v_mul_f32_e32 v155, v155, v211
	v_add_f32_e32 v212, 1.0, v212
	v_add_f32_e32 v213, 1.0, v213
	v_add_f32_e32 v214, 1.0, v214
	v_add_f32_e32 v215, 1.0, v215
	v_mul_f32_e32 v156, v156, v212
	v_mul_f32_e32 v157, v157, v213
	v_mul_f32_e32 v158, v158, v214
	v_mul_f32_e32 v159, v159, v215

; #define FRESH() int gtid; do { int t_ = threadIdx.x; asm volatile("" : "+v"(t_)); F.tid = t_; F.lane = t_ & 63; gtid = blockIdx.x * (NWAVES * 64) + t_; (void)gtid; } while (0)
; __global__ void __launch_bounds__(NWAVES * 64, 2) mk_fwd(Args args) {
;     ...
;     if (IN(11)) { FRESH();
;         const int per = (ML + F.NGW - 1) / F.NGW, per2 = (per + 1) & ~1, rbeg = F.gw * per2;
;         int rcur = -1; f32x4 PA[8];
;         for (int row0 = rbeg; row0 < rbeg + per2 && row0 < ML; row0 += 2) {
;             f32x4 v[2][8]; u32x2 yw[2][8];
; #pragma unroll
;             for (int q = 0; q < 2; ++q) { const int row = row0 + q; load_row_f32(args.out + (size_t)row * DM, F.lane, v[q]);
;                 const bf16_t* yr = Y + (size_t)row * DM;
; #pragma unroll
;                 for (int j = 0; j < 8; ++j) yw[q][j] = *(const u32x2*)(yr + 4 * F.lane + 256 * j); }
; #pragma unroll
;             for (int q = 0; q < 2; ++q) { const int row = row0 + q; const int r = row / SEQ;
;                 if (r != rcur) { const float* m1 = mod + (size_t)(9 + r) * 6144; rcur = r;
; #pragma unroll
;                     for (int j = 0; j < 8; ++j) { const int col = 4 * F.lane + 256 * j; PA[j] = *(const f32x4*)(m1 + 2 * DM + col) * *(const f32x4*)(post_norm + DM + col); } }
.LBB0_1288:
	s_cmp_gt_i32 s86, 11
	s_cselect_b64 s[2:3], -1, 0
	s_xor_b64 s[0:1], s[0:1], -1
	s_or_b64 s[0:1], s[2:3], s[0:1]
	s_and_b64 vcc, exec, s[0:1]
	s_cbranch_vccnz .LBB0_1296
	s_cmpk_lg_i32 s63, 0x100
	s_cbranch_scc1 .Lp11_generic
	v_and_b32_e32 v194, 63, v198
	v_lshlrev_b32_e32 v192, 4, v194
	v_add_u32_e32 v193, 0x1000, v192
	v_lshlrev_b32_e32 v194, 3, v194
	v_mov_b32_e32 v195, 0x358637bd
	s_lshr_b32 s0, s33, 8
	s_mul_i32 s1, s0, 0x6000
	s_add_u32 s8, s84, s1
	s_addc_u32 s9, s85, 0
	s_add_u32 s8, s8, 0x4000
	s_addc_u32 s9, s9, 0
	s_add_u32 s10, s8, 0x36000
	s_addc_u32 s11, s9, 0
	s_add_u32 s12, s82, 0x2000
	s_addc_u32 s13, s83, 0
	s_lshl_b32 s0, s33, 16
	s_add_u32 s14, s68, s0
	s_addc_u32 s15, s69, 0
	s_add_u32 s18, s94, s0
	s_addc_u32 s19, s95, 0
	s_lshl_b32 s0, s33, 15
	s_add_u32 s16, s84, s0
	s_addc_u32 s17, s85, 0
	s_add_u32 s22, s16, 0x8800000
	s_addc_u32 s23, s17, 0
	s_add_u32 s16, s16, 0x11800000
	s_addc_u32 s17, s17, 0
	global_load_dwordx4 v[128:131], v192, s[8:9] offset:0
	global_load_dwordx4 v[132:135], v192, s[8:9] offset:1024
	global_load_dwordx4 v[136:139], v192, s[8:9] offset:2048
	global_load_dwordx4 v[140:143], v192, s[8:9] offset:3072
	global_load_dwordx4 v[144:147], v193, s[8:9] offset:0
	global_load_dwordx4 v[148:151], v193, s[8:9] offset:1024
	global_load_dwordx4 v[152:155], v193, s[8:9] offset:2048
	global_load_dwordx4 v[156:159], v193, s[8:9] offset:3072
	global_load_dwordx4 v[32:35], v192, s[82:83] offset:0
	global_load_dwordx4 v[36:39], v192, s[82:83] offset:1024
	global_load_dwordx4 v[40:43], v192, s[82:83] offset:2048
	global_load_dwordx4 v[44:47], v192, s[82:83] offset:3072
	global_load_dwordx4 v[48:51], v193, s[82:83] offset:0
	global_load_dwordx4 v[52:55], v193, s[82:83] offset:1024
	global_load_dwordx4 v[56:59], v193, s[82:83] offset:2048
	global_load_dwordx4 v[60:63], v193, s[82:83] offset:3072
	global_load_dwordx4 v[160:163], v192, s[10:11] offset:0
	global_load_dwordx4 v[164:167], v192, s[10:11] offset:1024
	global_load_dwordx4 v[168:171], v192, s[10:11] offset:2048
	global_load_dwordx4 v[172:175], v192, s[10:11] offset:3072
	global_load_dwordx4 v[176:179], v193, s[10:11] offset:0
	global_load_dwordx4 v[180:183], v193, s[10:11] offset:1024
	global_load_dwordx4 v[184:187], v193, s[10:11] offset:2048
	global_load_dwordx4 v[188:191], v193, s[10:11] offset:3072
	global_load_dwordx4 v[96:99], v192, s[12:13] offset:0
	global_load_dwordx4 v[100:103], v192, s[12:13] offset:1024
	global_load_dwordx4 v[104:107], v192, s[12:13] offset:2048
	global_load_dwordx4 v[108:111], v192, s[12:13] offset:3072
	global_load_dwordx4 v[112:115], v193, s[12:13] offset:0
	global_load_dwordx4 v[116:119], v193, s[12:13] offset:1024
	global_load_dwordx4 v[120:123], v193, s[12:13] offset:2048
	global_load_dwordx4 v[124:127], v193, s[12:13] offset:3072
	s_waitcnt vmcnt(0)
	v_mul_f32_e32 v128, v128, v32
	v_mul_f32_e32 v129, v129, v33
	v_mul_f32_e32 v130, v130, v34
	v_mul_f32_e32 v131, v131, v35
	v_mul_f32_e32 v132, v132, v36
	v_mul_f32_e32 v133, v133, v37
	v_mul_f32_e32 v134, v134, v38
	v_mul_f32_e32 v135, v135, v39
	v_mul_f32_e32 v136, v136, v40
	v_mul_f32_e32 v137, v137, v41
	v_mul_f32_e32 v138, v138, v42
	v_mul_f32_e32 v139, v139, v43
	v_mul_f32_e32 v140, v140, v44
	v_mul_f32_e32 v141, v141, v45
	v_mul_f32_e32 v142, v142, v46
	v_mul_f32_e32 v143, v143, v47
	v_mul_f32_e32 v144, v144, v48
	v_mul_f32_e32 v145, v145, v49
	v_mul_f32_e32 v146, v146, v50
	v_mul_f32_e32 v147, v147, v51
	v_mul_f32_e32 v148, v148, v52
	v_mul_f32_e32 v149, v149, v53
	v_mul_f32_e32 v150, v150, v54
	v_mul_f32_e32 v151, v151, v55
	v_mul_f32_e32 v152, v152, v56
	v_mul_f32_e32 v153, v153, v57
	v_mul_f32_e32 v154, v154, v58
	v_mul_f32_e32 v155, v155, v59
	v_mul_f32_e32 v156, v156, v60
	v_mul_f32_e32 v157, v157, v61
	v_mul_f32_e32 v158, v158, v62
	v_mul_f32_e32 v159, v159, v63
	v_mul_f32_e32 v160, v160, v96
	v_mul_f32_e32 v161, v161, v97
	v_mul_f32_e32 v162, v162, v98
	v_mul_f32_e32 v163, v163, v99
	v_mul_f32_e32 v164, v164, v100
	v_mul_f32_e32 v165, v165, v101
	v_mul_f32_e32 v166, v166, v102
	v_mul_f32_e32 v167, v167, v103
	v_mul_f32_e32 v168, v168, v104
	v_mul_f32_e32 v169, v169, v105
	v_mul_f32_e32 v170, v170, v106
	v_mul_f32_e32 v171, v171, v107
	v_mul_f32_e32 v172, v172, v108
	v_mul_f32_e32 v173, v173, v109
	v_mul_f32_e32 v174, v174, v110
	v_mul_f32_e32 v175, v175, v111
	v_mul_f32_e32 v176, v176, v112
	v_mul_f32_e32 v177, v177, v113
	v_mul_f32_e32 v178, v178, v114
	v_mul_f32_e32 v179, v179, v115
	v_mul_f32_e32 v180, v180, v116
	v_mul_f32_e32 v181, v181, v117
	v_mul_f32_e32 v182, v182, v118
	v_mul_f32_e32 v183, v183, v119
	v_mul_f32_e32 v184, v184, v120
	v_mul_f32_e32 v185, v185, v121
	v_mul_f32_e32 v186, v186, v122
	v_mul_f32_e32 v187, v187, v123
	v_mul_f32_e32 v188, v188, v124
	v_mul_f32_e32 v189, v189, v125
	v_mul_f32_e32 v190, v190, v126
	v_mul_f32_e32 v191, v191, v127
	global_load_dwordx4 v[0:3], v192, s[14:15] offset:0 nt
	global_load_dwordx4 v[4:7], v192, s[14:15] offset:1024 nt
	global_load_dwordx4 v[8:11], v192, s[14:15] offset:2048 nt
	global_load_dwordx4 v[12:15], v192, s[14:15] offset:3072 nt
	global_load_dwordx4 v[16:19], v193, s[14:15] offset:0 nt
	global_load_dwordx4 v[20:23], v193, s[14:15] offset:1024 nt
	global_load_dwordx4 v[24:27], v193, s[14:15] offset:2048 nt
	global_load_dwordx4 v[28:31], v193, s[14:15] offset:3072 nt
	global_load_dwordx2 v[64:65], v194, s[16:17] offset:0
	global_load_dwordx2 v[66:67], v194, s[16:17] offset:512
	global_load_dwordx2 v[68:69], v194, s[16:17] offset:1024
	global_load_dwordx2 v[70:71], v194, s[16:17] offset:1536
	global_load_dwordx2 v[72:73], v194, s[16:17] offset:2048
	global_load_dwordx2 v[74:75], v194, s[16:17] offset:2560
; __device__ __forceinline__ float bf_lo(unsigned w) { return __uint_as_float(w << 16); }
; __device__ __forceinline__ float bf_hi(unsigned w) { return __uint_as_float(w & 0xffff0000u); }
; __global__ void __launch_bounds__(NWAVES * 64, 2) mk_fwd(Args args) {
;     ...
;             for (int q = 0; q < 2; ++q) { const int row = row0 + q; load_row_f32(args.out + (size_t)row * DM, F.lane, v[q]);
;                 const bf16_t* yr = Y + (size_t)row * DM;
; #pragma unroll
;                 for (int j = 0; j < 8; ++j) yw[q][j] = *(const u32x2*)(yr + 4 * F.lane + 256 * j); }
;     ...
;                 float sy = 0.f;
; #pragma unroll
;                 for (int j = 0; j < 8; ++j) { const float a = bf_lo(yw[q][j].x), b = bf_hi(yw[q][j].x), c2 = bf_lo(yw[q][j].y), d = bf_hi(yw[q][j].y); sy += (a * a + b * b) + (c2 * c2 + d * d); }
	global_load_dwordx2 v[76:77], v194, s[16:17] offset:3072
	global_load_dwordx2 v[78:79], v194, s[16:17] offset:3584
	global_load_dwordx2 v[96:97], v194, s[22:23] offset:0
	global_load_dwordx2 v[98:99], v194, s[22:23] offset:512
	global_load_dwordx2 v[100:101], v194, s[22:23] offset:1024
	global_load_dwordx2 v[102:103], v194, s[22:23] offset:1536
	global_load_dwordx2 v[104:105], v194, s[22:23] offset:2048
	global_load_dwordx2 v[106:107], v194, s[22:23] offset:2560
	global_load_dwordx2 v[108:109], v194, s[22:23] offset:3072
	global_load_dwordx2 v[110:111], v194, s[22:23] offset:3584
	s_add_u32 s14, s14, 0x2000
	s_addc_u32 s15, s15, 0
	s_add_u32 s16, s16, 0x1000
	s_addc_u32 s17, s17, 0
	s_add_u32 s22, s22, 0x1000
	s_addc_u32 s23, s23, 0
	global_load_dwordx4 v[32:35], v192, s[14:15] offset:0 nt
	global_load_dwordx4 v[36:39], v192, s[14:15] offset:1024 nt
	global_load_dwordx4 v[40:43], v192, s[14:15] offset:2048 nt
	global_load_dwordx4 v[44:47], v192, s[14:15] offset:3072 nt
	global_load_dwordx4 v[48:51], v193, s[14:15] offset:0 nt
	global_load_dwordx4 v[52:55], v193, s[14:15] offset:1024 nt
	global_load_dwordx4 v[56:59], v193, s[14:15] offset:2048 nt
	global_load_dwordx4 v[60:63], v193, s[14:15] offset:3072 nt
	global_load_dwordx2 v[80:81], v194, s[16:17] offset:0
	global_load_dwordx2 v[82:83], v194, s[16:17] offset:512
	global_load_dwordx2 v[84:85], v194, s[16:17] offset:1024
	global_load_dwordx2 v[86:87], v194, s[16:17] offset:1536
	global_load_dwordx2 v[88:89], v194, s[16:17] offset:2048
	global_load_dwordx2 v[90:91], v194, s[16:17] offset:2560
	global_load_dwordx2 v[92:93], v194, s[16:17] offset:3072
	global_load_dwordx2 v[94:95], v194, s[16:17] offset:3584
	global_load_dwordx2 v[112:113], v194, s[22:23] offset:0
	global_load_dwordx2 v[114:115], v194, s[22:23] offset:512
	global_load_dwordx2 v[116:117], v194, s[22:23] offset:1024
	global_load_dwordx2 v[118:119], v194, s[22:23] offset:1536
	global_load_dwordx2 v[120:121], v194, s[22:23] offset:2048
	global_load_dwordx2 v[122:123], v194, s[22:23] offset:2560
	global_load_dwordx2 v[124:125], v194, s[22:23] offset:3072
	global_load_dwordx2 v[126:127], v194, s[22:23] offset:3584
	s_add_u32 s14, s14, 0x2000
	s_addc_u32 s15, s15, 0
	s_add_u32 s16, s16, 0x1000
	s_addc_u32 s17, s17, 0
	s_add_u32 s22, s22, 0x1000
	s_addc_u32 s23, s23, 0
	s_waitcnt vmcnt(24)
	v_lshlrev_b32_e32 v200, 16, v64
	v_and_b32_e32 v201, 0xffff0000, v64
	v_lshlrev_b32_e32 v202, 16, v65
	v_and_b32_e32 v203, 0xffff0000, v65
	v_mul_f32_e32 v208, v200, v200
	v_mul_f32_e32 v209, v201, v201
	v_fmac_f32_e32 v208, v202, v202
	v_fmac_f32_e32 v209, v203, v203
	v_lshlrev_b32_e32 v204, 16, v96
	v_and_b32_e32 v205, 0xffff0000, v96
	v_lshlrev_b32_e32 v206, 16, v97
	v_and_b32_e32 v207, 0xffff0000, v97
	v_mul_f32_e32 v210, v204, v204
	v_mul_f32_e32 v211, v205, v205
	v_fmac_f32_e32 v210, v206, v206
	v_fmac_f32_e32 v211, v207, v207
	v_lshlrev_b32_e32 v200, 16, v66
	v_and_b32_e32 v201, 0xffff0000, v66
	v_lshlrev_b32_e32 v202, 16, v67
	v_and_b32_e32 v203, 0xffff0000, v67
	v_fmac_f32_e32 v208, v200, v200
	v_fmac_f32_e32 v209, v201, v201
	v_fmac_f32_e32 v208, v202, v202
	v_fmac_f32_e32 v209, v203, v203
	v_lshlrev_b32_e32 v204, 16, v98
	v_and_b32_e32 v205, 0xffff0000, v98
	v_lshlrev_b32_e32 v206, 16, v99
	v_and_b32_e32 v207, 0xffff0000, v99
	v_fmac_f32_e32 v210, v204, v204
	v_fmac_f32_e32 v211, v205, v205
	v_fmac_f32_e32 v210, v206, v206
	v_fmac_f32_e32 v211, v207, v207
	v_lshlrev_b32_e32 v200, 16, v68
	v_and_b32_e32 v201, 0xffff0000, v68
	v_lshlrev_b32_e32 v202, 16, v69
	v_and_b32_e32 v203, 0xffff0000, v69
	v_fmac_f32_e32 v208, v200, v200
	v_fmac_f32_e32 v209, v201, v201
	v_fmac_f32_e32 v208, v202, v202
	v_fmac_f32_e32 v209, v203, v203
	v_lshlrev_b32_e32 v204, 16, v100
	v_and_b32_e32 v205, 0xffff0000, v100
	v_lshlrev_b32_e32 v206, 16, v101
	v_and_b32_e32 v207, 0xffff0000, v101
	v_fmac_f32_e32 v210, v204, v204
	v_fmac_f32_e32 v211, v205, v205
	v_fmac_f32_e32 v210, v206, v206
	v_fmac_f32_e32 v211, v207, v207
	v_lshlrev_b32_e32 v200, 16, v70
	v_and_b32_e32 v201, 0xffff0000, v70
	v_lshlrev_b32_e32 v202, 16, v71
	v_and_b32_e32 v203, 0xffff0000, v71
	v_fmac_f32_e32 v208, v200, v200
	v_fmac_f32_e32 v209, v201, v201
	v_fmac_f32_e32 v208, v202, v202
	v_fmac_f32_e32 v209, v203, v203
	v_lshlrev_b32_e32 v204, 16, v102
	v_and_b32_e32 v205, 0xffff0000, v102
	v_lshlrev_b32_e32 v206, 16, v103
	v_and_b32_e32 v207, 0xffff0000, v103
	v_fmac_f32_e32 v210, v204, v204
	v_fmac_f32_e32 v211, v205, v205
	v_fmac_f32_e32 v210, v206, v206
	v_fmac_f32_e32 v211, v207, v207
	v_lshlrev_b32_e32 v200, 16, v72
	v_and_b32_e32 v201, 0xffff0000, v72
	v_lshlrev_b32_e32 v202, 16, v73
	v_and_b32_e32 v203, 0xffff0000, v73
	v_fmac_f32_e32 v208, v200, v200
	v_fmac_f32_e32 v209, v201, v201
	v_fmac_f32_e32 v208, v202, v202
	v_fmac_f32_e32 v209, v203, v203
	v_lshlrev_b32_e32 v204, 16, v104
	v_and_b32_e32 v205, 0xffff0000, v104
	v_lshlrev_b32_e32 v206, 16, v105
	v_and_b32_e32 v207, 0xffff0000, v105
	v_fmac_f32_e32 v210, v204, v204
	v_fmac_f32_e32 v211, v205, v205
	v_fmac_f32_e32 v210, v206, v206
	v_fmac_f32_e32 v211, v207, v207
	v_lshlrev_b32_e32 v200, 16, v74
	v_and_b32_e32 v201, 0xffff0000, v74
	v_lshlrev_b32_e32 v202, 16, v75
	v_and_b32_e32 v203, 0xffff0000, v75
	v_fmac_f32_e32 v208, v200, v200
	v_fmac_f32_e32 v209, v201, v201
	v_fmac_f32_e32 v208, v202, v202
	v_fmac_f32_e32 v209, v203, v203
	v_lshlrev_b32_e32 v204, 16, v106
	v_and_b32_e32 v205, 0xffff0000, v106
	v_lshlrev_b32_e32 v206, 16, v107
	v_and_b32_e32 v207, 0xffff0000, v107
	v_fmac_f32_e32 v210, v204, v204
	v_fmac_f32_e32 v211, v205, v205
	v_fmac_f32_e32 v210, v206, v206
	v_fmac_f32_e32 v211, v207, v207
	v_lshlrev_b32_e32 v200, 16, v76
; __device__ __forceinline__ float bf_lo(unsigned w) { return __uint_as_float(w << 16); }
; __device__ __forceinline__ float bf_hi(unsigned w) { return __uint_as_float(w & 0xffff0000u); }
; __global__ void __launch_bounds__(NWAVES * 64, 2) mk_fwd(Args args) {
;     ...
;                 float sy = 0.f;
; #pragma unroll
;                 for (int j = 0; j < 8; ++j) { const float a = bf_lo(yw[q][j].x), b = bf_hi(yw[q][j].x), c2 = bf_lo(yw[q][j].y), d = bf_hi(yw[q][j].y); sy += (a * a + b * b) + (c2 * c2 + d * d); }
;                 const float rsy = __builtin_amdgcn_rsqf(wave_sum(sy) * (1.f / DM) + EPS);
; #pragma unroll
;                 for (int j = 0; j < 8; ++j) { const int col = 4 * F.lane + 256 * j;
;                     const f32x4 y4 = (f32x4){bf_lo(yw[q][j].x), bf_hi(yw[q][j].x), bf_lo(yw[q][j].y), bf_hi(yw[q][j].y)};
;                     *(f32x4*)(args.out + (size_t)row * DM + col) = v[q][j] + PA[j] * (y4 * rsy); }
	v_and_b32_e32 v201, 0xffff0000, v76
	v_lshlrev_b32_e32 v202, 16, v77
	v_and_b32_e32 v203, 0xffff0000, v77
	v_fmac_f32_e32 v208, v200, v200
	v_fmac_f32_e32 v209, v201, v201
	v_fmac_f32_e32 v208, v202, v202
	v_fmac_f32_e32 v209, v203, v203
	v_lshlrev_b32_e32 v204, 16, v108
	v_and_b32_e32 v205, 0xffff0000, v108
	v_lshlrev_b32_e32 v206, 16, v109
	v_and_b32_e32 v207, 0xffff0000, v109
	v_fmac_f32_e32 v210, v204, v204
	v_fmac_f32_e32 v211, v205, v205
	v_fmac_f32_e32 v210, v206, v206
	v_fmac_f32_e32 v211, v207, v207
	v_lshlrev_b32_e32 v200, 16, v78
	v_and_b32_e32 v201, 0xffff0000, v78
	v_lshlrev_b32_e32 v202, 16, v79
	v_and_b32_e32 v203, 0xffff0000, v79
	v_fmac_f32_e32 v208, v200, v200
	v_fmac_f32_e32 v209, v201, v201
	v_fmac_f32_e32 v208, v202, v202
	v_fmac_f32_e32 v209, v203, v203
	v_lshlrev_b32_e32 v204, 16, v110
	v_and_b32_e32 v205, 0xffff0000, v110
	v_lshlrev_b32_e32 v206, 16, v111
	v_and_b32_e32 v207, 0xffff0000, v111
	v_fmac_f32_e32 v210, v204, v204
	v_fmac_f32_e32 v211, v205, v205
	v_fmac_f32_e32 v210, v206, v206
	v_fmac_f32_e32 v211, v207, v207
	v_add_f32_e32 v208, v208, v209
	v_add_f32_e32 v210, v210, v211
	s_nop 0
	v_add_f32_dpp v212, v208, v208 quad_perm:[1,0,3,2] row_mask:0xf bank_mask:0xf
	v_add_f32_dpp v213, v210, v210 quad_perm:[1,0,3,2] row_mask:0xf bank_mask:0xf
	s_nop 0
	v_add_f32_dpp v212, v212, v212 quad_perm:[2,3,0,1] row_mask:0xf bank_mask:0xf
	v_add_f32_dpp v213, v213, v213 quad_perm:[2,3,0,1] row_mask:0xf bank_mask:0xf
	s_nop 0
	v_add_f32_dpp v212, v212, v212 row_half_mirror row_mask:0xf bank_mask:0xf
	v_add_f32_dpp v213, v213, v213 row_half_mirror row_mask:0xf bank_mask:0xf
	s_nop 0
	v_add_f32_dpp v212, v212, v212 row_mirror row_mask:0xf bank_mask:0xf
	v_add_f32_dpp v213, v213, v213 row_mirror row_mask:0xf bank_mask:0xf
	s_nop 0
	v_readlane_b32 s4, v212, 0
	v_readlane_b32 s5, v212, 16
	v_readlane_b32 s6, v212, 32
	v_readlane_b32 s7, v212, 48
	v_readlane_b32 s24, v213, 0
	v_readlane_b32 s25, v213, 16
	v_readlane_b32 s26, v213, 32
	v_readlane_b32 s27, v213, 48
	s_nop 1
	v_mov_b32_e32 v214, s4
	v_mov_b32_e32 v215, s24
	v_add_f32_e32 v214, s5, v214
	v_add_f32_e32 v215, s25, v215
	v_add_f32_e32 v214, s6, v214
	v_add_f32_e32 v215, s26, v215
	v_add_f32_e32 v214, s7, v214
	v_add_f32_e32 v215, s27, v215
	v_fmamk_f32 v214, v214, 0x3a000000, v195
	v_fmamk_f32 v215, v215, 0x3a000000, v195
	v_rsq_f32_e32 v214, v214
	v_rsq_f32_e32 v215, v215
	s_nop 0
	v_lshlrev_b32_e32 v200, 16, v64
	v_and_b32_e32 v201, 0xffff0000, v64
	v_lshlrev_b32_e32 v202, 16, v65
	v_and_b32_e32 v203, 0xffff0000, v65
	v_lshlrev_b32_e32 v204, 16, v96
	v_and_b32_e32 v205, 0xffff0000, v96
	v_lshlrev_b32_e32 v206, 16, v97
	v_and_b32_e32 v207, 0xffff0000, v97
	v_mul_f32_e32 v200, v214, v200
	v_mul_f32_e32 v201, v214, v201
	v_mul_f32_e32 v202, v214, v202
	v_mul_f32_e32 v203, v214, v203
	v_mul_f32_e32 v204, v215, v204
	v_mul_f32_e32 v205, v215, v205
	v_mul_f32_e32 v206, v215, v206
	v_mul_f32_e32 v207, v215, v207
	v_fmac_f32_e32 v0, v128, v200
	v_fmac_f32_e32 v1, v129, v201
	v_fmac_f32_e32 v2, v130, v202
	v_fmac_f32_e32 v3, v131, v203
	v_fmac_f32_e32 v0, v160, v204
	v_fmac_f32_e32 v1, v161, v205
	v_fmac_f32_e32 v2, v162, v206
	v_fmac_f32_e32 v3, v163, v207
	global_store_dwordx4 v192, v[0:3], s[18:19] offset:0 nt
	v_lshlrev_b32_e32 v200, 16, v66
	v_and_b32_e32 v201, 0xffff0000, v66
	v_lshlrev_b32_e32 v202, 16, v67
	v_and_b32_e32 v203, 0xffff0000, v67
	v_lshlrev_b32_e32 v204, 16, v98
	v_and_b32_e32 v205, 0xffff0000, v98
	v_lshlrev_b32_e32 v206, 16, v99
	v_and_b32_e32 v207, 0xffff0000, v99
	v_mul_f32_e32 v200, v214, v200
	v_mul_f32_e32 v201, v214, v201
	v_mul_f32_e32 v202, v214, v202
	v_mul_f32_e32 v203, v214, v203
	v_mul_f32_e32 v204, v215, v204
	v_mul_f32_e32 v205, v215, v205
	v_mul_f32_e32 v206, v215, v206
	v_mul_f32_e32 v207, v215, v207
	v_fmac_f32_e32 v4, v132, v200
	v_fmac_f32_e32 v5, v133, v201
	v_fmac_f32_e32 v6, v134, v202
	v_fmac_f32_e32 v7, v135, v203
	v_fmac_f32_e32 v4, v164, v204
	v_fmac_f32_e32 v5, v165, v205
	v_fmac_f32_e32 v6, v166, v206
	v_fmac_f32_e32 v7, v167, v207
	global_store_dwordx4 v192, v[4:7], s[18:19] offset:1024 nt
	v_lshlrev_b32_e32 v200, 16, v68
	v_and_b32_e32 v201, 0xffff0000, v68
	v_lshlrev_b32_e32 v202, 16, v69
	v_and_b32_e32 v203, 0xffff0000, v69
	v_lshlrev_b32_e32 v204, 16, v100
	v_and_b32_e32 v205, 0xffff0000, v100
	v_lshlrev_b32_e32 v206, 16, v101
	v_and_b32_e32 v207, 0xffff0000, v101
	v_mul_f32_e32 v200, v214, v200
	v_mul_f32_e32 v201, v214, v201
	v_mul_f32_e32 v202, v214, v202
	v_mul_f32_e32 v203, v214, v203
	v_mul_f32_e32 v204, v215, v204
	v_mul_f32_e32 v205, v215, v205
	v_mul_f32_e32 v206, v215, v206
	v_mul_f32_e32 v207, v215, v207
	v_fmac_f32_e32 v8, v136, v200
	v_fmac_f32_e32 v9, v137, v201
	v_fmac_f32_e32 v10, v138, v202
	v_fmac_f32_e32 v11, v139, v203
	v_fmac_f32_e32 v8, v168, v204
	v_fmac_f32_e32 v9, v169, v205
	v_fmac_f32_e32 v10, v170, v206
	v_fmac_f32_e32 v11, v171, v207
	global_store_dwordx4 v192, v[8:11], s[18:19] offset:2048 nt
	v_lshlrev_b32_e32 v200, 16, v70
	v_and_b32_e32 v201, 0xffff0000, v70
	v_lshlrev_b32_e32 v202, 16, v71
	v_and_b32_e32 v203, 0xffff0000, v71
	v_lshlrev_b32_e32 v204, 16, v102
	v_and_b32_e32 v205, 0xffff0000, v102
	v_lshlrev_b32_e32 v206, 16, v103
	v_and_b32_e32 v207, 0xffff0000, v103
	v_mul_f32_e32 v200, v214, v200
	v_mul_f32_e32 v201, v214, v201
	v_mul_f32_e32 v202, v214, v202
	v_mul_f32_e32 v203, v214, v203
	v_mul_f32_e32 v204, v215, v204
	v_mul_f32_e32 v205, v215, v205
	v_mul_f32_e32 v206, v215, v206
	v_mul_f32_e32 v207, v215, v207
	v_fmac_f32_e32 v12, v140, v200
	v_fmac_f32_e32 v13, v141, v201
	v_fmac_f32_e32 v14, v142, v202
	v_fmac_f32_e32 v15, v143, v203
	v_fmac_f32_e32 v12, v172, v204
; __device__ __forceinline__ float bf_lo(unsigned w) { return __uint_as_float(w << 16); }
; __device__ __forceinline__ float bf_hi(unsigned w) { return __uint_as_float(w & 0xffff0000u); }
; __global__ void __launch_bounds__(NWAVES * 64, 2) mk_fwd(Args args) {
;     ...
;             for (int q = 0; q < 2; ++q) { const int row = row0 + q; load_row_f32(args.out + (size_t)row * DM, F.lane, v[q]);
;                 const bf16_t* yr = Y + (size_t)row * DM;
; #pragma unroll
;                 for (int j = 0; j < 8; ++j) yw[q][j] = *(const u32x2*)(yr + 4 * F.lane + 256 * j); }
;     ...
;                 for (int j = 0; j < 8; ++j) { const int col = 4 * F.lane + 256 * j;
;                     const f32x4 y4 = (f32x4){bf_lo(yw[q][j].x), bf_hi(yw[q][j].x), bf_lo(yw[q][j].y), bf_hi(yw[q][j].y)};
;                     *(f32x4*)(args.out + (size_t)row * DM + col) = v[q][j] + PA[j] * (y4 * rsy); }
	v_fmac_f32_e32 v13, v173, v205
	v_fmac_f32_e32 v14, v174, v206
	v_fmac_f32_e32 v15, v175, v207
	global_store_dwordx4 v192, v[12:15], s[18:19] offset:3072 nt
	v_lshlrev_b32_e32 v200, 16, v72
	v_and_b32_e32 v201, 0xffff0000, v72
	v_lshlrev_b32_e32 v202, 16, v73
	v_and_b32_e32 v203, 0xffff0000, v73
	v_lshlrev_b32_e32 v204, 16, v104
	v_and_b32_e32 v205, 0xffff0000, v104
	v_lshlrev_b32_e32 v206, 16, v105
	v_and_b32_e32 v207, 0xffff0000, v105
	v_mul_f32_e32 v200, v214, v200
	v_mul_f32_e32 v201, v214, v201
	v_mul_f32_e32 v202, v214, v202
	v_mul_f32_e32 v203, v214, v203
	v_mul_f32_e32 v204, v215, v204
	v_mul_f32_e32 v205, v215, v205
	v_mul_f32_e32 v206, v215, v206
	v_mul_f32_e32 v207, v215, v207
	v_fmac_f32_e32 v16, v144, v200
	v_fmac_f32_e32 v17, v145, v201
	v_fmac_f32_e32 v18, v146, v202
	v_fmac_f32_e32 v19, v147, v203
	v_fmac_f32_e32 v16, v176, v204
	v_fmac_f32_e32 v17, v177, v205
	v_fmac_f32_e32 v18, v178, v206
	v_fmac_f32_e32 v19, v179, v207
	global_store_dwordx4 v193, v[16:19], s[18:19] offset:0 nt
	v_lshlrev_b32_e32 v200, 16, v74
	v_and_b32_e32 v201, 0xffff0000, v74
	v_lshlrev_b32_e32 v202, 16, v75
	v_and_b32_e32 v203, 0xffff0000, v75
	v_lshlrev_b32_e32 v204, 16, v106
	v_and_b32_e32 v205, 0xffff0000, v106
	v_lshlrev_b32_e32 v206, 16, v107
	v_and_b32_e32 v207, 0xffff0000, v107
	v_mul_f32_e32 v200, v214, v200
	v_mul_f32_e32 v201, v214, v201
	v_mul_f32_e32 v202, v214, v202
	v_mul_f32_e32 v203, v214, v203
	v_mul_f32_e32 v204, v215, v204
	v_mul_f32_e32 v205, v215, v205
	v_mul_f32_e32 v206, v215, v206
	v_mul_f32_e32 v207, v215, v207
	v_fmac_f32_e32 v20, v148, v200
	v_fmac_f32_e32 v21, v149, v201
	v_fmac_f32_e32 v22, v150, v202
	v_fmac_f32_e32 v23, v151, v203
	v_fmac_f32_e32 v20, v180, v204
	v_fmac_f32_e32 v21, v181, v205
	v_fmac_f32_e32 v22, v182, v206
	v_fmac_f32_e32 v23, v183, v207
	global_store_dwordx4 v193, v[20:23], s[18:19] offset:1024 nt
	v_lshlrev_b32_e32 v200, 16, v76
	v_and_b32_e32 v201, 0xffff0000, v76
	v_lshlrev_b32_e32 v202, 16, v77
	v_and_b32_e32 v203, 0xffff0000, v77
	v_lshlrev_b32_e32 v204, 16, v108
	v_and_b32_e32 v205, 0xffff0000, v108
	v_lshlrev_b32_e32 v206, 16, v109
	v_and_b32_e32 v207, 0xffff0000, v109
	v_mul_f32_e32 v200, v214, v200
	v_mul_f32_e32 v201, v214, v201
	v_mul_f32_e32 v202, v214, v202
	v_mul_f32_e32 v203, v214, v203
	v_mul_f32_e32 v204, v215, v204
	v_mul_f32_e32 v205, v215, v205
	v_mul_f32_e32 v206, v215, v206
	v_mul_f32_e32 v207, v215, v207
	v_fmac_f32_e32 v24, v152, v200
	v_fmac_f32_e32 v25, v153, v201
	v_fmac_f32_e32 v26, v154, v202
	v_fmac_f32_e32 v27, v155, v203
	v_fmac_f32_e32 v24, v184, v204
	v_fmac_f32_e32 v25, v185, v205
	v_fmac_f32_e32 v26, v186, v206
	v_fmac_f32_e32 v27, v187, v207
	global_store_dwordx4 v193, v[24:27], s[18:19] offset:2048 nt
	v_lshlrev_b32_e32 v200, 16, v78
	v_and_b32_e32 v201, 0xffff0000, v78
	v_lshlrev_b32_e32 v202, 16, v79
	v_and_b32_e32 v203, 0xffff0000, v79
	v_lshlrev_b32_e32 v204, 16, v110
	v_and_b32_e32 v205, 0xffff0000, v110
	v_lshlrev_b32_e32 v206, 16, v111
	v_and_b32_e32 v207, 0xffff0000, v111
	v_mul_f32_e32 v200, v214, v200
	v_mul_f32_e32 v201, v214, v201
	v_mul_f32_e32 v202, v214, v202
	v_mul_f32_e32 v203, v214, v203
	v_mul_f32_e32 v204, v215, v204
	v_mul_f32_e32 v205, v215, v205
	v_mul_f32_e32 v206, v215, v206
	v_mul_f32_e32 v207, v215, v207
	v_fmac_f32_e32 v28, v156, v200
	v_fmac_f32_e32 v29, v157, v201
	v_fmac_f32_e32 v30, v158, v202
	v_fmac_f32_e32 v31, v159, v203
	v_fmac_f32_e32 v28, v188, v204
	v_fmac_f32_e32 v29, v189, v205
	v_fmac_f32_e32 v30, v190, v206
	v_fmac_f32_e32 v31, v191, v207
	global_store_dwordx4 v193, v[28:31], s[18:19] offset:3072 nt
	s_add_u32 s18, s18, 0x2000
	s_addc_u32 s19, s19, 0
	global_load_dwordx4 v[0:3], v192, s[14:15] offset:0 nt
	global_load_dwordx4 v[4:7], v192, s[14:15] offset:1024 nt
	global_load_dwordx4 v[8:11], v192, s[14:15] offset:2048 nt
	global_load_dwordx4 v[12:15], v192, s[14:15] offset:3072 nt
	global_load_dwordx4 v[16:19], v193, s[14:15] offset:0 nt
	global_load_dwordx4 v[20:23], v193, s[14:15] offset:1024 nt
	global_load_dwordx4 v[24:27], v193, s[14:15] offset:2048 nt
	global_load_dwordx4 v[28:31], v193, s[14:15] offset:3072 nt
	global_load_dwordx2 v[64:65], v194, s[16:17] offset:0
	global_load_dwordx2 v[66:67], v194, s[16:17] offset:512
	global_load_dwordx2 v[68:69], v194, s[16:17] offset:1024
	global_load_dwordx2 v[70:71], v194, s[16:17] offset:1536
	global_load_dwordx2 v[72:73], v194, s[16:17] offset:2048
	global_load_dwordx2 v[74:75], v194, s[16:17] offset:2560
	global_load_dwordx2 v[76:77], v194, s[16:17] offset:3072
	global_load_dwordx2 v[78:79], v194, s[16:17] offset:3584
	global_load_dwordx2 v[96:97], v194, s[22:23] offset:0
	global_load_dwordx2 v[98:99], v194, s[22:23] offset:512
	global_load_dwordx2 v[100:101], v194, s[22:23] offset:1024
	global_load_dwordx2 v[102:103], v194, s[22:23] offset:1536
	global_load_dwordx2 v[104:105], v194, s[22:23] offset:2048
	global_load_dwordx2 v[106:107], v194, s[22:23] offset:2560
	global_load_dwordx2 v[108:109], v194, s[22:23] offset:3072
	global_load_dwordx2 v[110:111], v194, s[22:23] offset:3584
	s_add_u32 s14, s14, 0x2000
	s_addc_u32 s15, s15, 0
	s_add_u32 s16, s16, 0x1000
	s_addc_u32 s17, s17, 0
	s_add_u32 s22, s22, 0x1000
	s_addc_u32 s23, s23, 0
	s_waitcnt vmcnt(32)
; __device__ __forceinline__ float bf_lo(unsigned w) { return __uint_as_float(w << 16); }
; __device__ __forceinline__ float bf_hi(unsigned w) { return __uint_as_float(w & 0xffff0000u); }
; __global__ void __launch_bounds__(NWAVES * 64, 2) mk_fwd(Args args) {
;     ...
;                 float sy = 0.f;
; #pragma unroll
;                 for (int j = 0; j < 8; ++j) { const float a = bf_lo(yw[q][j].x), b = bf_hi(yw[q][j].x), c2 = bf_lo(yw[q][j].y), d = bf_hi(yw[q][j].y); sy += (a * a + b * b) + (c2 * c2 + d * d); }
;                 const float rsy = __builtin_amdgcn_rsqf(wave_sum(sy) * (1.f / DM) + EPS);
	v_lshlrev_b32_e32 v200, 16, v80
	v_and_b32_e32 v201, 0xffff0000, v80
	v_lshlrev_b32_e32 v202, 16, v81
	v_and_b32_e32 v203, 0xffff0000, v81
	v_mul_f32_e32 v208, v200, v200
	v_mul_f32_e32 v209, v201, v201
	v_fmac_f32_e32 v208, v202, v202
	v_fmac_f32_e32 v209, v203, v203
	v_lshlrev_b32_e32 v204, 16, v112
	v_and_b32_e32 v205, 0xffff0000, v112
	v_lshlrev_b32_e32 v206, 16, v113
	v_and_b32_e32 v207, 0xffff0000, v113
	v_mul_f32_e32 v210, v204, v204
	v_mul_f32_e32 v211, v205, v205
	v_fmac_f32_e32 v210, v206, v206
	v_fmac_f32_e32 v211, v207, v207
	v_lshlrev_b32_e32 v200, 16, v82
	v_and_b32_e32 v201, 0xffff0000, v82
	v_lshlrev_b32_e32 v202, 16, v83
	v_and_b32_e32 v203, 0xffff0000, v83
	v_fmac_f32_e32 v208, v200, v200
	v_fmac_f32_e32 v209, v201, v201
	v_fmac_f32_e32 v208, v202, v202
	v_fmac_f32_e32 v209, v203, v203
	v_lshlrev_b32_e32 v204, 16, v114
	v_and_b32_e32 v205, 0xffff0000, v114
	v_lshlrev_b32_e32 v206, 16, v115
	v_and_b32_e32 v207, 0xffff0000, v115
	v_fmac_f32_e32 v210, v204, v204
	v_fmac_f32_e32 v211, v205, v205
	v_fmac_f32_e32 v210, v206, v206
	v_fmac_f32_e32 v211, v207, v207
	v_lshlrev_b32_e32 v200, 16, v84
	v_and_b32_e32 v201, 0xffff0000, v84
	v_lshlrev_b32_e32 v202, 16, v85
	v_and_b32_e32 v203, 0xffff0000, v85
	v_fmac_f32_e32 v208, v200, v200
	v_fmac_f32_e32 v209, v201, v201
	v_fmac_f32_e32 v208, v202, v202
	v_fmac_f32_e32 v209, v203, v203
	v_lshlrev_b32_e32 v204, 16, v116
	v_and_b32_e32 v205, 0xffff0000, v116
	v_lshlrev_b32_e32 v206, 16, v117
	v_and_b32_e32 v207, 0xffff0000, v117
	v_fmac_f32_e32 v210, v204, v204
	v_fmac_f32_e32 v211, v205, v205
	v_fmac_f32_e32 v210, v206, v206
	v_fmac_f32_e32 v211, v207, v207
	v_lshlrev_b32_e32 v200, 16, v86
	v_and_b32_e32 v201, 0xffff0000, v86
	v_lshlrev_b32_e32 v202, 16, v87
	v_and_b32_e32 v203, 0xffff0000, v87
	v_fmac_f32_e32 v208, v200, v200
	v_fmac_f32_e32 v209, v201, v201
	v_fmac_f32_e32 v208, v202, v202
	v_fmac_f32_e32 v209, v203, v203
	v_lshlrev_b32_e32 v204, 16, v118
	v_and_b32_e32 v205, 0xffff0000, v118
	v_lshlrev_b32_e32 v206, 16, v119
	v_and_b32_e32 v207, 0xffff0000, v119
	v_fmac_f32_e32 v210, v204, v204
	v_fmac_f32_e32 v211, v205, v205
	v_fmac_f32_e32 v210, v206, v206
	v_fmac_f32_e32 v211, v207, v207
	v_lshlrev_b32_e32 v200, 16, v88
	v_and_b32_e32 v201, 0xffff0000, v88
	v_lshlrev_b32_e32 v202, 16, v89
	v_and_b32_e32 v203, 0xffff0000, v89
	v_fmac_f32_e32 v208, v200, v200
	v_fmac_f32_e32 v209, v201, v201
	v_fmac_f32_e32 v208, v202, v202
	v_fmac_f32_e32 v209, v203, v203
	v_lshlrev_b32_e32 v204, 16, v120
	v_and_b32_e32 v205, 0xffff0000, v120
	v_lshlrev_b32_e32 v206, 16, v121
	v_and_b32_e32 v207, 0xffff0000, v121
	v_fmac_f32_e32 v210, v204, v204
	v_fmac_f32_e32 v211, v205, v205
	v_fmac_f32_e32 v210, v206, v206
	v_fmac_f32_e32 v211, v207, v207
	v_lshlrev_b32_e32 v200, 16, v90
	v_and_b32_e32 v201, 0xffff0000, v90
	v_lshlrev_b32_e32 v202, 16, v91
	v_and_b32_e32 v203, 0xffff0000, v91
	v_fmac_f32_e32 v208, v200, v200
	v_fmac_f32_e32 v209, v201, v201
	v_fmac_f32_e32 v208, v202, v202
	v_fmac_f32_e32 v209, v203, v203
	v_lshlrev_b32_e32 v204, 16, v122
	v_and_b32_e32 v205, 0xffff0000, v122
	v_lshlrev_b32_e32 v206, 16, v123
	v_and_b32_e32 v207, 0xffff0000, v123
	v_fmac_f32_e32 v210, v204, v204
	v_fmac_f32_e32 v211, v205, v205
	v_fmac_f32_e32 v210, v206, v206
	v_fmac_f32_e32 v211, v207, v207
	v_lshlrev_b32_e32 v200, 16, v92
	v_and_b32_e32 v201, 0xffff0000, v92
	v_lshlrev_b32_e32 v202, 16, v93
	v_and_b32_e32 v203, 0xffff0000, v93
	v_fmac_f32_e32 v208, v200, v200
	v_fmac_f32_e32 v209, v201, v201
	v_fmac_f32_e32 v208, v202, v202
	v_fmac_f32_e32 v209, v203, v203
	v_lshlrev_b32_e32 v204, 16, v124
	v_and_b32_e32 v205, 0xffff0000, v124
	v_lshlrev_b32_e32 v206, 16, v125
	v_and_b32_e32 v207, 0xffff0000, v125
	v_fmac_f32_e32 v210, v204, v204
	v_fmac_f32_e32 v211, v205, v205
	v_fmac_f32_e32 v210, v206, v206
	v_fmac_f32_e32 v211, v207, v207
	v_lshlrev_b32_e32 v200, 16, v94
	v_and_b32_e32 v201, 0xffff0000, v94
	v_lshlrev_b32_e32 v202, 16, v95
	v_and_b32_e32 v203, 0xffff0000, v95
	v_fmac_f32_e32 v208, v200, v200
	v_fmac_f32_e32 v209, v201, v201
	v_fmac_f32_e32 v208, v202, v202
	v_fmac_f32_e32 v209, v203, v203
	v_lshlrev_b32_e32 v204, 16, v126
	v_and_b32_e32 v205, 0xffff0000, v126
	v_lshlrev_b32_e32 v206, 16, v127
	v_and_b32_e32 v207, 0xffff0000, v127
	v_fmac_f32_e32 v210, v204, v204
	v_fmac_f32_e32 v211, v205, v205
	v_fmac_f32_e32 v210, v206, v206
	v_fmac_f32_e32 v211, v207, v207
	v_add_f32_e32 v208, v208, v209
	v_add_f32_e32 v210, v210, v211
	s_nop 0
	v_add_f32_dpp v212, v208, v208 quad_perm:[1,0,3,2] row_mask:0xf bank_mask:0xf
	v_add_f32_dpp v213, v210, v210 quad_perm:[1,0,3,2] row_mask:0xf bank_mask:0xf
	s_nop 0
	v_add_f32_dpp v212, v212, v212 quad_perm:[2,3,0,1] row_mask:0xf bank_mask:0xf
	v_add_f32_dpp v213, v213, v213 quad_perm:[2,3,0,1] row_mask:0xf bank_mask:0xf
	s_nop 0
	v_add_f32_dpp v212, v212, v212 row_half_mirror row_mask:0xf bank_mask:0xf
	v_add_f32_dpp v213, v213, v213 row_half_mirror row_mask:0xf bank_mask:0xf
	s_nop 0
	v_add_f32_dpp v212, v212, v212 row_mirror row_mask:0xf bank_mask:0xf
	v_add_f32_dpp v213, v213, v213 row_mirror row_mask:0xf bank_mask:0xf
	s_nop 0
	v_readlane_b32 s4, v212, 0
	v_readlane_b32 s5, v212, 16
	v_readlane_b32 s6, v212, 32
	v_readlane_b32 s7, v212, 48
	v_readlane_b32 s24, v213, 0
	v_readlane_b32 s25, v213, 16
	v_readlane_b32 s26, v213, 32
	v_readlane_b32 s27, v213, 48
	s_nop 1
	v_mov_b32_e32 v214, s4
	v_mov_b32_e32 v215, s24
	v_add_f32_e32 v214, s5, v214
	v_add_f32_e32 v215, s25, v215
	v_add_f32_e32 v214, s6, v214
	v_add_f32_e32 v215, s26, v215
	v_add_f32_e32 v214, s7, v214
	v_add_f32_e32 v215, s27, v215
	v_fmamk_f32 v214, v214, 0x3a000000, v195
	v_fmamk_f32 v215, v215, 0x3a000000, v195
; __device__ __forceinline__ float bf_lo(unsigned w) { return __uint_as_float(w << 16); }
; __device__ __forceinline__ float bf_hi(unsigned w) { return __uint_as_float(w & 0xffff0000u); }
; __global__ void __launch_bounds__(NWAVES * 64, 2) mk_fwd(Args args) {
;     ...
;                 const float rsy = __builtin_amdgcn_rsqf(wave_sum(sy) * (1.f / DM) + EPS);
; #pragma unroll
;                 for (int j = 0; j < 8; ++j) { const int col = 4 * F.lane + 256 * j;
;                     const f32x4 y4 = (f32x4){bf_lo(yw[q][j].x), bf_hi(yw[q][j].x), bf_lo(yw[q][j].y), bf_hi(yw[q][j].y)};
;                     *(f32x4*)(args.out + (size_t)row * DM + col) = v[q][j] + PA[j] * (y4 * rsy); }
	v_rsq_f32_e32 v214, v214
	v_rsq_f32_e32 v215, v215
	s_nop 0
	v_lshlrev_b32_e32 v200, 16, v80
	v_and_b32_e32 v201, 0xffff0000, v80
	v_lshlrev_b32_e32 v202, 16, v81
	v_and_b32_e32 v203, 0xffff0000, v81
	v_lshlrev_b32_e32 v204, 16, v112
	v_and_b32_e32 v205, 0xffff0000, v112
	v_lshlrev_b32_e32 v206, 16, v113
	v_and_b32_e32 v207, 0xffff0000, v113
	v_mul_f32_e32 v200, v214, v200
	v_mul_f32_e32 v201, v214, v201
	v_mul_f32_e32 v202, v214, v202
	v_mul_f32_e32 v203, v214, v203
	v_mul_f32_e32 v204, v215, v204
	v_mul_f32_e32 v205, v215, v205
	v_mul_f32_e32 v206, v215, v206
	v_mul_f32_e32 v207, v215, v207
	v_fmac_f32_e32 v32, v128, v200
	v_fmac_f32_e32 v33, v129, v201
	v_fmac_f32_e32 v34, v130, v202
	v_fmac_f32_e32 v35, v131, v203
	v_fmac_f32_e32 v32, v160, v204
	v_fmac_f32_e32 v33, v161, v205
	v_fmac_f32_e32 v34, v162, v206
	v_fmac_f32_e32 v35, v163, v207
	global_store_dwordx4 v192, v[32:35], s[18:19] offset:0 nt
	v_lshlrev_b32_e32 v200, 16, v82
	v_and_b32_e32 v201, 0xffff0000, v82
	v_lshlrev_b32_e32 v202, 16, v83
	v_and_b32_e32 v203, 0xffff0000, v83
	v_lshlrev_b32_e32 v204, 16, v114
	v_and_b32_e32 v205, 0xffff0000, v114
	v_lshlrev_b32_e32 v206, 16, v115
	v_and_b32_e32 v207, 0xffff0000, v115
	v_mul_f32_e32 v200, v214, v200
	v_mul_f32_e32 v201, v214, v201
	v_mul_f32_e32 v202, v214, v202
	v_mul_f32_e32 v203, v214, v203
	v_mul_f32_e32 v204, v215, v204
	v_mul_f32_e32 v205, v215, v205
	v_mul_f32_e32 v206, v215, v206
	v_mul_f32_e32 v207, v215, v207
	v_fmac_f32_e32 v36, v132, v200
	v_fmac_f32_e32 v37, v133, v201
	v_fmac_f32_e32 v38, v134, v202
	v_fmac_f32_e32 v39, v135, v203
	v_fmac_f32_e32 v36, v164, v204
	v_fmac_f32_e32 v37, v165, v205
	v_fmac_f32_e32 v38, v166, v206
	v_fmac_f32_e32 v39, v167, v207
	global_store_dwordx4 v192, v[36:39], s[18:19] offset:1024 nt
	v_lshlrev_b32_e32 v200, 16, v84
	v_and_b32_e32 v201, 0xffff0000, v84
	v_lshlrev_b32_e32 v202, 16, v85
	v_and_b32_e32 v203, 0xffff0000, v85
	v_lshlrev_b32_e32 v204, 16, v116
	v_and_b32_e32 v205, 0xffff0000, v116
	v_lshlrev_b32_e32 v206, 16, v117
	v_and_b32_e32 v207, 0xffff0000, v117
	v_mul_f32_e32 v200, v214, v200
	v_mul_f32_e32 v201, v214, v201
	v_mul_f32_e32 v202, v214, v202
	v_mul_f32_e32 v203, v214, v203
	v_mul_f32_e32 v204, v215, v204
	v_mul_f32_e32 v205, v215, v205
	v_mul_f32_e32 v206, v215, v206
	v_mul_f32_e32 v207, v215, v207
	v_fmac_f32_e32 v40, v136, v200
	v_fmac_f32_e32 v41, v137, v201
	v_fmac_f32_e32 v42, v138, v202
	v_fmac_f32_e32 v43, v139, v203
	v_fmac_f32_e32 v40, v168, v204
	v_fmac_f32_e32 v41, v169, v205
	v_fmac_f32_e32 v42, v170, v206
	v_fmac_f32_e32 v43, v171, v207
	global_store_dwordx4 v192, v[40:43], s[18:19] offset:2048 nt
	v_lshlrev_b32_e32 v200, 16, v86
	v_and_b32_e32 v201, 0xffff0000, v86
	v_lshlrev_b32_e32 v202, 16, v87
	v_and_b32_e32 v203, 0xffff0000, v87
	v_lshlrev_b32_e32 v204, 16, v118
	v_and_b32_e32 v205, 0xffff0000, v118
	v_lshlrev_b32_e32 v206, 16, v119
	v_and_b32_e32 v207, 0xffff0000, v119
	v_mul_f32_e32 v200, v214, v200
	v_mul_f32_e32 v201, v214, v201
	v_mul_f32_e32 v202, v214, v202
	v_mul_f32_e32 v203, v214, v203
	v_mul_f32_e32 v204, v215, v204
	v_mul_f32_e32 v205, v215, v205
	v_mul_f32_e32 v206, v215, v206
	v_mul_f32_e32 v207, v215, v207
	v_fmac_f32_e32 v44, v140, v200
	v_fmac_f32_e32 v45, v141, v201
	v_fmac_f32_e32 v46, v142, v202
	v_fmac_f32_e32 v47, v143, v203
	v_fmac_f32_e32 v44, v172, v204
	v_fmac_f32_e32 v45, v173, v205
	v_fmac_f32_e32 v46, v174, v206
	v_fmac_f32_e32 v47, v175, v207
	global_store_dwordx4 v192, v[44:47], s[18:19] offset:3072 nt
	v_lshlrev_b32_e32 v200, 16, v88
	v_and_b32_e32 v201, 0xffff0000, v88
	v_lshlrev_b32_e32 v202, 16, v89
	v_and_b32_e32 v203, 0xffff0000, v89
	v_lshlrev_b32_e32 v204, 16, v120
	v_and_b32_e32 v205, 0xffff0000, v120
	v_lshlrev_b32_e32 v206, 16, v121
	v_and_b32_e32 v207, 0xffff0000, v121
	v_mul_f32_e32 v200, v214, v200
	v_mul_f32_e32 v201, v214, v201
	v_mul_f32_e32 v202, v214, v202
	v_mul_f32_e32 v203, v214, v203
	v_mul_f32_e32 v204, v215, v204
	v_mul_f32_e32 v205, v215, v205
	v_mul_f32_e32 v206, v215, v206
	v_mul_f32_e32 v207, v215, v207
	v_fmac_f32_e32 v48, v144, v200
	v_fmac_f32_e32 v49, v145, v201
	v_fmac_f32_e32 v50, v146, v202
	v_fmac_f32_e32 v51, v147, v203
	v_fmac_f32_e32 v48, v176, v204
	v_fmac_f32_e32 v49, v177, v205
	v_fmac_f32_e32 v50, v178, v206
	v_fmac_f32_e32 v51, v179, v207
	global_store_dwordx4 v193, v[48:51], s[18:19] offset:0 nt
	v_lshlrev_b32_e32 v200, 16, v90
	v_and_b32_e32 v201, 0xffff0000, v90
	v_lshlrev_b32_e32 v202, 16, v91
	v_and_b32_e32 v203, 0xffff0000, v91
	v_lshlrev_b32_e32 v204, 16, v122
	v_and_b32_e32 v205, 0xffff0000, v122
	v_lshlrev_b32_e32 v206, 16, v123
	v_and_b32_e32 v207, 0xffff0000, v123
	v_mul_f32_e32 v200, v214, v200
	v_mul_f32_e32 v201, v214, v201
	v_mul_f32_e32 v202, v214, v202
	v_mul_f32_e32 v203, v214, v203
	v_mul_f32_e32 v204, v215, v204
	v_mul_f32_e32 v205, v215, v205
	v_mul_f32_e32 v206, v215, v206
	v_mul_f32_e32 v207, v215, v207
	v_fmac_f32_e32 v52, v148, v200
	v_fmac_f32_e32 v53, v149, v201
	v_fmac_f32_e32 v54, v150, v202
	v_fmac_f32_e32 v55, v151, v203
	v_fmac_f32_e32 v52, v180, v204
	v_fmac_f32_e32 v53, v181, v205
	v_fmac_f32_e32 v54, v182, v206
	v_fmac_f32_e32 v55, v183, v207
	global_store_dwordx4 v193, v[52:55], s[18:19] offset:1024 nt
	v_lshlrev_b32_e32 v200, 16, v92
	v_and_b32_e32 v201, 0xffff0000, v92
	v_lshlrev_b32_e32 v202, 16, v93
	v_and_b32_e32 v203, 0xffff0000, v93
	v_lshlrev_b32_e32 v204, 16, v124
	v_and_b32_e32 v205, 0xffff0000, v124
	v_lshlrev_b32_e32 v206, 16, v125
	v_and_b32_e32 v207, 0xffff0000, v125
	v_mul_f32_e32 v200, v214, v200
	v_mul_f32_e32 v201, v214, v201
	v_mul_f32_e32 v202, v214, v202
	v_mul_f32_e32 v203, v214, v203
	v_mul_f32_e32 v204, v215, v204
; __device__ __forceinline__ float bf_lo(unsigned w) { return __uint_as_float(w << 16); }
; __device__ __forceinline__ float bf_hi(unsigned w) { return __uint_as_float(w & 0xffff0000u); }
; __global__ void __launch_bounds__(NWAVES * 64, 2) mk_fwd(Args args) {
;     ...
;             for (int q = 0; q < 2; ++q) { const int row = row0 + q; load_row_f32(args.out + (size_t)row * DM, F.lane, v[q]);
;                 const bf16_t* yr = Y + (size_t)row * DM;
; #pragma unroll
;                 for (int j = 0; j < 8; ++j) yw[q][j] = *(const u32x2*)(yr + 4 * F.lane + 256 * j); }
;     ...
;                 float sy = 0.f;
; #pragma unroll
;                 for (int j = 0; j < 8; ++j) { const float a = bf_lo(yw[q][j].x), b = bf_hi(yw[q][j].x), c2 = bf_lo(yw[q][j].y), d = bf_hi(yw[q][j].y); sy += (a * a + b * b) + (c2 * c2 + d * d); }
;     ...
;                 for (int j = 0; j < 8; ++j) { const int col = 4 * F.lane + 256 * j;
;                     const f32x4 y4 = (f32x4){bf_lo(yw[q][j].x), bf_hi(yw[q][j].x), bf_lo(yw[q][j].y), bf_hi(yw[q][j].y)};
;                     *(f32x4*)(args.out + (size_t)row * DM + col) = v[q][j] + PA[j] * (y4 * rsy); }
	v_mul_f32_e32 v205, v215, v205
	v_mul_f32_e32 v206, v215, v206
	v_mul_f32_e32 v207, v215, v207
	v_fmac_f32_e32 v56, v152, v200
	v_fmac_f32_e32 v57, v153, v201
	v_fmac_f32_e32 v58, v154, v202
	v_fmac_f32_e32 v59, v155, v203
	v_fmac_f32_e32 v56, v184, v204
	v_fmac_f32_e32 v57, v185, v205
	v_fmac_f32_e32 v58, v186, v206
	v_fmac_f32_e32 v59, v187, v207
	global_store_dwordx4 v193, v[56:59], s[18:19] offset:2048 nt
	v_lshlrev_b32_e32 v200, 16, v94
	v_and_b32_e32 v201, 0xffff0000, v94
	v_lshlrev_b32_e32 v202, 16, v95
	v_and_b32_e32 v203, 0xffff0000, v95
	v_lshlrev_b32_e32 v204, 16, v126
	v_and_b32_e32 v205, 0xffff0000, v126
	v_lshlrev_b32_e32 v206, 16, v127
	v_and_b32_e32 v207, 0xffff0000, v127
	v_mul_f32_e32 v200, v214, v200
	v_mul_f32_e32 v201, v214, v201
	v_mul_f32_e32 v202, v214, v202
	v_mul_f32_e32 v203, v214, v203
	v_mul_f32_e32 v204, v215, v204
	v_mul_f32_e32 v205, v215, v205
	v_mul_f32_e32 v206, v215, v206
	v_mul_f32_e32 v207, v215, v207
	v_fmac_f32_e32 v60, v156, v200
	v_fmac_f32_e32 v61, v157, v201
	v_fmac_f32_e32 v62, v158, v202
	v_fmac_f32_e32 v63, v159, v203
	v_fmac_f32_e32 v60, v188, v204
	v_fmac_f32_e32 v61, v189, v205
	v_fmac_f32_e32 v62, v190, v206
	v_fmac_f32_e32 v63, v191, v207
	global_store_dwordx4 v193, v[60:63], s[18:19] offset:3072 nt
	s_add_u32 s18, s18, 0x2000
	s_addc_u32 s19, s19, 0
	global_load_dwordx4 v[32:35], v192, s[14:15] offset:0 nt
	global_load_dwordx4 v[36:39], v192, s[14:15] offset:1024 nt
	global_load_dwordx4 v[40:43], v192, s[14:15] offset:2048 nt
	global_load_dwordx4 v[44:47], v192, s[14:15] offset:3072 nt
	global_load_dwordx4 v[48:51], v193, s[14:15] offset:0 nt
	global_load_dwordx4 v[52:55], v193, s[14:15] offset:1024 nt
	global_load_dwordx4 v[56:59], v193, s[14:15] offset:2048 nt
	global_load_dwordx4 v[60:63], v193, s[14:15] offset:3072 nt
	global_load_dwordx2 v[80:81], v194, s[16:17] offset:0
	global_load_dwordx2 v[82:83], v194, s[16:17] offset:512
	global_load_dwordx2 v[84:85], v194, s[16:17] offset:1024
	global_load_dwordx2 v[86:87], v194, s[16:17] offset:1536
	global_load_dwordx2 v[88:89], v194, s[16:17] offset:2048
	global_load_dwordx2 v[90:91], v194, s[16:17] offset:2560
	global_load_dwordx2 v[92:93], v194, s[16:17] offset:3072
	global_load_dwordx2 v[94:95], v194, s[16:17] offset:3584
	global_load_dwordx2 v[112:113], v194, s[22:23] offset:0
	global_load_dwordx2 v[114:115], v194, s[22:23] offset:512
	global_load_dwordx2 v[116:117], v194, s[22:23] offset:1024
	global_load_dwordx2 v[118:119], v194, s[22:23] offset:1536
	global_load_dwordx2 v[120:121], v194, s[22:23] offset:2048
	global_load_dwordx2 v[122:123], v194, s[22:23] offset:2560
	global_load_dwordx2 v[124:125], v194, s[22:23] offset:3072
	global_load_dwordx2 v[126:127], v194, s[22:23] offset:3584
	s_add_u32 s14, s14, 0x2000
	s_addc_u32 s15, s15, 0
	s_add_u32 s16, s16, 0x1000
	s_addc_u32 s17, s17, 0
	s_add_u32 s22, s22, 0x1000
	s_addc_u32 s23, s23, 0
	s_waitcnt vmcnt(32)
	v_lshlrev_b32_e32 v200, 16, v64
	v_and_b32_e32 v201, 0xffff0000, v64
	v_lshlrev_b32_e32 v202, 16, v65
	v_and_b32_e32 v203, 0xffff0000, v65
	v_mul_f32_e32 v208, v200, v200
	v_mul_f32_e32 v209, v201, v201
	v_fmac_f32_e32 v208, v202, v202
	v_fmac_f32_e32 v209, v203, v203
	v_lshlrev_b32_e32 v204, 16, v96
	v_and_b32_e32 v205, 0xffff0000, v96
	v_lshlrev_b32_e32 v206, 16, v97
	v_and_b32_e32 v207, 0xffff0000, v97
	v_mul_f32_e32 v210, v204, v204
	v_mul_f32_e32 v211, v205, v205
	v_fmac_f32_e32 v210, v206, v206
	v_fmac_f32_e32 v211, v207, v207
	v_lshlrev_b32_e32 v200, 16, v66
	v_and_b32_e32 v201, 0xffff0000, v66
	v_lshlrev_b32_e32 v202, 16, v67
	v_and_b32_e32 v203, 0xffff0000, v67
	v_fmac_f32_e32 v208, v200, v200
	v_fmac_f32_e32 v209, v201, v201
	v_fmac_f32_e32 v208, v202, v202
	v_fmac_f32_e32 v209, v203, v203
	v_lshlrev_b32_e32 v204, 16, v98
	v_and_b32_e32 v205, 0xffff0000, v98
	v_lshlrev_b32_e32 v206, 16, v99
	v_and_b32_e32 v207, 0xffff0000, v99
	v_fmac_f32_e32 v210, v204, v204
	v_fmac_f32_e32 v211, v205, v205
	v_fmac_f32_e32 v210, v206, v206
	v_fmac_f32_e32 v211, v207, v207
	v_lshlrev_b32_e32 v200, 16, v68
	v_and_b32_e32 v201, 0xffff0000, v68
	v_lshlrev_b32_e32 v202, 16, v69
	v_and_b32_e32 v203, 0xffff0000, v69
	v_fmac_f32_e32 v208, v200, v200
	v_fmac_f32_e32 v209, v201, v201
	v_fmac_f32_e32 v208, v202, v202
	v_fmac_f32_e32 v209, v203, v203
	v_lshlrev_b32_e32 v204, 16, v100
	v_and_b32_e32 v205, 0xffff0000, v100
	v_lshlrev_b32_e32 v206, 16, v101
	v_and_b32_e32 v207, 0xffff0000, v101
	v_fmac_f32_e32 v210, v204, v204
	v_fmac_f32_e32 v211, v205, v205
	v_fmac_f32_e32 v210, v206, v206
	v_fmac_f32_e32 v211, v207, v207
	v_lshlrev_b32_e32 v200, 16, v70
	v_and_b32_e32 v201, 0xffff0000, v70
	v_lshlrev_b32_e32 v202, 16, v71
	v_and_b32_e32 v203, 0xffff0000, v71
	v_fmac_f32_e32 v208, v200, v200
	v_fmac_f32_e32 v209, v201, v201
	v_fmac_f32_e32 v208, v202, v202
	v_fmac_f32_e32 v209, v203, v203
	v_lshlrev_b32_e32 v204, 16, v102
	v_and_b32_e32 v205, 0xffff0000, v102
	v_lshlrev_b32_e32 v206, 16, v103
	v_and_b32_e32 v207, 0xffff0000, v103
	v_fmac_f32_e32 v210, v204, v204
	v_fmac_f32_e32 v211, v205, v205
	v_fmac_f32_e32 v210, v206, v206
	v_fmac_f32_e32 v211, v207, v207
	v_lshlrev_b32_e32 v200, 16, v72
	v_and_b32_e32 v201, 0xffff0000, v72
	v_lshlrev_b32_e32 v202, 16, v73
	v_and_b32_e32 v203, 0xffff0000, v73
	v_fmac_f32_e32 v208, v200, v200
	v_fmac_f32_e32 v209, v201, v201
	v_fmac_f32_e32 v208, v202, v202
	v_fmac_f32_e32 v209, v203, v203
	v_lshlrev_b32_e32 v204, 16, v104
	v_and_b32_e32 v205, 0xffff0000, v104
	v_lshlrev_b32_e32 v206, 16, v105
	v_and_b32_e32 v207, 0xffff0000, v105
	v_fmac_f32_e32 v210, v204, v204
	v_fmac_f32_e32 v211, v205, v205
	v_fmac_f32_e32 v210, v206, v206
	v_fmac_f32_e32 v211, v207, v207
; __device__ __forceinline__ float bf_lo(unsigned w) { return __uint_as_float(w << 16); }
; __device__ __forceinline__ float bf_hi(unsigned w) { return __uint_as_float(w & 0xffff0000u); }
; __global__ void __launch_bounds__(NWAVES * 64, 2) mk_fwd(Args args) {
;     ...
;                 for (int j = 0; j < 8; ++j) { const float a = bf_lo(yw[q][j].x), b = bf_hi(yw[q][j].x), c2 = bf_lo(yw[q][j].y), d = bf_hi(yw[q][j].y); sy += (a * a + b * b) + (c2 * c2 + d * d); }
;                 const float rsy = __builtin_amdgcn_rsqf(wave_sum(sy) * (1.f / DM) + EPS);
; #pragma unroll
;                 for (int j = 0; j < 8; ++j) { const int col = 4 * F.lane + 256 * j;
;                     const f32x4 y4 = (f32x4){bf_lo(yw[q][j].x), bf_hi(yw[q][j].x), bf_lo(yw[q][j].y), bf_hi(yw[q][j].y)};
;                     *(f32x4*)(args.out + (size_t)row * DM + col) = v[q][j] + PA[j] * (y4 * rsy); }
	v_lshlrev_b32_e32 v200, 16, v74
	v_and_b32_e32 v201, 0xffff0000, v74
	v_lshlrev_b32_e32 v202, 16, v75
	v_and_b32_e32 v203, 0xffff0000, v75
	v_fmac_f32_e32 v208, v200, v200
	v_fmac_f32_e32 v209, v201, v201
	v_fmac_f32_e32 v208, v202, v202
	v_fmac_f32_e32 v209, v203, v203
	v_lshlrev_b32_e32 v204, 16, v106
	v_and_b32_e32 v205, 0xffff0000, v106
	v_lshlrev_b32_e32 v206, 16, v107
	v_and_b32_e32 v207, 0xffff0000, v107
	v_fmac_f32_e32 v210, v204, v204
	v_fmac_f32_e32 v211, v205, v205
	v_fmac_f32_e32 v210, v206, v206
	v_fmac_f32_e32 v211, v207, v207
	v_lshlrev_b32_e32 v200, 16, v76
	v_and_b32_e32 v201, 0xffff0000, v76
	v_lshlrev_b32_e32 v202, 16, v77
	v_and_b32_e32 v203, 0xffff0000, v77
	v_fmac_f32_e32 v208, v200, v200
	v_fmac_f32_e32 v209, v201, v201
	v_fmac_f32_e32 v208, v202, v202
	v_fmac_f32_e32 v209, v203, v203
	v_lshlrev_b32_e32 v204, 16, v108
	v_and_b32_e32 v205, 0xffff0000, v108
	v_lshlrev_b32_e32 v206, 16, v109
	v_and_b32_e32 v207, 0xffff0000, v109
	v_fmac_f32_e32 v210, v204, v204
	v_fmac_f32_e32 v211, v205, v205
	v_fmac_f32_e32 v210, v206, v206
	v_fmac_f32_e32 v211, v207, v207
	v_lshlrev_b32_e32 v200, 16, v78
	v_and_b32_e32 v201, 0xffff0000, v78
	v_lshlrev_b32_e32 v202, 16, v79
	v_and_b32_e32 v203, 0xffff0000, v79
	v_fmac_f32_e32 v208, v200, v200
	v_fmac_f32_e32 v209, v201, v201
	v_fmac_f32_e32 v208, v202, v202
	v_fmac_f32_e32 v209, v203, v203
	v_lshlrev_b32_e32 v204, 16, v110
	v_and_b32_e32 v205, 0xffff0000, v110
	v_lshlrev_b32_e32 v206, 16, v111
	v_and_b32_e32 v207, 0xffff0000, v111
	v_fmac_f32_e32 v210, v204, v204
	v_fmac_f32_e32 v211, v205, v205
	v_fmac_f32_e32 v210, v206, v206
	v_fmac_f32_e32 v211, v207, v207
	v_add_f32_e32 v208, v208, v209
	v_add_f32_e32 v210, v210, v211
	s_nop 0
	v_add_f32_dpp v212, v208, v208 quad_perm:[1,0,3,2] row_mask:0xf bank_mask:0xf
	v_add_f32_dpp v213, v210, v210 quad_perm:[1,0,3,2] row_mask:0xf bank_mask:0xf
	s_nop 0
	v_add_f32_dpp v212, v212, v212 quad_perm:[2,3,0,1] row_mask:0xf bank_mask:0xf
	v_add_f32_dpp v213, v213, v213 quad_perm:[2,3,0,1] row_mask:0xf bank_mask:0xf
	s_nop 0
	v_add_f32_dpp v212, v212, v212 row_half_mirror row_mask:0xf bank_mask:0xf
	v_add_f32_dpp v213, v213, v213 row_half_mirror row_mask:0xf bank_mask:0xf
	s_nop 0
	v_add_f32_dpp v212, v212, v212 row_mirror row_mask:0xf bank_mask:0xf
	v_add_f32_dpp v213, v213, v213 row_mirror row_mask:0xf bank_mask:0xf
	s_nop 0
	v_readlane_b32 s4, v212, 0
	v_readlane_b32 s5, v212, 16
	v_readlane_b32 s6, v212, 32
	v_readlane_b32 s7, v212, 48
	v_readlane_b32 s24, v213, 0
	v_readlane_b32 s25, v213, 16
	v_readlane_b32 s26, v213, 32
	v_readlane_b32 s27, v213, 48
	s_nop 1
	v_mov_b32_e32 v214, s4
	v_mov_b32_e32 v215, s24
	v_add_f32_e32 v214, s5, v214
	v_add_f32_e32 v215, s25, v215
	v_add_f32_e32 v214, s6, v214
	v_add_f32_e32 v215, s26, v215
	v_add_f32_e32 v214, s7, v214
	v_add_f32_e32 v215, s27, v215
	v_fmamk_f32 v214, v214, 0x3a000000, v195
	v_fmamk_f32 v215, v215, 0x3a000000, v195
	v_rsq_f32_e32 v214, v214
	v_rsq_f32_e32 v215, v215
	s_nop 0
	v_lshlrev_b32_e32 v200, 16, v64
	v_and_b32_e32 v201, 0xffff0000, v64
	v_lshlrev_b32_e32 v202, 16, v65
	v_and_b32_e32 v203, 0xffff0000, v65
	v_lshlrev_b32_e32 v204, 16, v96
	v_and_b32_e32 v205, 0xffff0000, v96
	v_lshlrev_b32_e32 v206, 16, v97
	v_and_b32_e32 v207, 0xffff0000, v97
	v_mul_f32_e32 v200, v214, v200
	v_mul_f32_e32 v201, v214, v201
	v_mul_f32_e32 v202, v214, v202
	v_mul_f32_e32 v203, v214, v203
	v_mul_f32_e32 v204, v215, v204
	v_mul_f32_e32 v205, v215, v205
	v_mul_f32_e32 v206, v215, v206
	v_mul_f32_e32 v207, v215, v207
	v_fmac_f32_e32 v0, v128, v200
	v_fmac_f32_e32 v1, v129, v201
	v_fmac_f32_e32 v2, v130, v202
	v_fmac_f32_e32 v3, v131, v203
	v_fmac_f32_e32 v0, v160, v204
	v_fmac_f32_e32 v1, v161, v205
	v_fmac_f32_e32 v2, v162, v206
	v_fmac_f32_e32 v3, v163, v207
	global_store_dwordx4 v192, v[0:3], s[18:19] offset:0 nt
	v_lshlrev_b32_e32 v200, 16, v66
	v_and_b32_e32 v201, 0xffff0000, v66
	v_lshlrev_b32_e32 v202, 16, v67
	v_and_b32_e32 v203, 0xffff0000, v67
	v_lshlrev_b32_e32 v204, 16, v98
	v_and_b32_e32 v205, 0xffff0000, v98
	v_lshlrev_b32_e32 v206, 16, v99
	v_and_b32_e32 v207, 0xffff0000, v99
	v_mul_f32_e32 v200, v214, v200
	v_mul_f32_e32 v201, v214, v201
	v_mul_f32_e32 v202, v214, v202
	v_mul_f32_e32 v203, v214, v203
	v_mul_f32_e32 v204, v215, v204
	v_mul_f32_e32 v205, v215, v205
	v_mul_f32_e32 v206, v215, v206
	v_mul_f32_e32 v207, v215, v207
	v_fmac_f32_e32 v4, v132, v200
	v_fmac_f32_e32 v5, v133, v201
	v_fmac_f32_e32 v6, v134, v202
	v_fmac_f32_e32 v7, v135, v203
	v_fmac_f32_e32 v4, v164, v204
	v_fmac_f32_e32 v5, v165, v205
	v_fmac_f32_e32 v6, v166, v206
	v_fmac_f32_e32 v7, v167, v207
	global_store_dwordx4 v192, v[4:7], s[18:19] offset:1024 nt
	v_lshlrev_b32_e32 v200, 16, v68
	v_and_b32_e32 v201, 0xffff0000, v68
	v_lshlrev_b32_e32 v202, 16, v69
	v_and_b32_e32 v203, 0xffff0000, v69
	v_lshlrev_b32_e32 v204, 16, v100
	v_and_b32_e32 v205, 0xffff0000, v100
	v_lshlrev_b32_e32 v206, 16, v101
	v_and_b32_e32 v207, 0xffff0000, v101
	v_mul_f32_e32 v200, v214, v200
	v_mul_f32_e32 v201, v214, v201
	v_mul_f32_e32 v202, v214, v202
	v_mul_f32_e32 v203, v214, v203
	v_mul_f32_e32 v204, v215, v204
	v_mul_f32_e32 v205, v215, v205
	v_mul_f32_e32 v206, v215, v206
	v_mul_f32_e32 v207, v215, v207
	v_fmac_f32_e32 v8, v136, v200
	v_fmac_f32_e32 v9, v137, v201
	v_fmac_f32_e32 v10, v138, v202
	v_fmac_f32_e32 v11, v139, v203
	v_fmac_f32_e32 v8, v168, v204
	v_fmac_f32_e32 v9, v169, v205
	v_fmac_f32_e32 v10, v170, v206
	v_fmac_f32_e32 v11, v171, v207
	global_store_dwordx4 v192, v[8:11], s[18:19] offset:2048 nt
	v_lshlrev_b32_e32 v200, 16, v70
	v_and_b32_e32 v201, 0xffff0000, v70
	v_lshlrev_b32_e32 v202, 16, v71
	v_and_b32_e32 v203, 0xffff0000, v71
; __device__ __forceinline__ float bf_lo(unsigned w) { return __uint_as_float(w << 16); }
; __device__ __forceinline__ float bf_hi(unsigned w) { return __uint_as_float(w & 0xffff0000u); }
; __global__ void __launch_bounds__(NWAVES * 64, 2) mk_fwd(Args args) {
;     ...
;             for (int q = 0; q < 2; ++q) { const int row = row0 + q; load_row_f32(args.out + (size_t)row * DM, F.lane, v[q]);
;                 const bf16_t* yr = Y + (size_t)row * DM;
; #pragma unroll
;                 for (int j = 0; j < 8; ++j) yw[q][j] = *(const u32x2*)(yr + 4 * F.lane + 256 * j); }
;     ...
;                 for (int j = 0; j < 8; ++j) { const int col = 4 * F.lane + 256 * j;
;                     const f32x4 y4 = (f32x4){bf_lo(yw[q][j].x), bf_hi(yw[q][j].x), bf_lo(yw[q][j].y), bf_hi(yw[q][j].y)};
;                     *(f32x4*)(args.out + (size_t)row * DM + col) = v[q][j] + PA[j] * (y4 * rsy); }
	v_lshlrev_b32_e32 v204, 16, v102
	v_and_b32_e32 v205, 0xffff0000, v102
	v_lshlrev_b32_e32 v206, 16, v103
	v_and_b32_e32 v207, 0xffff0000, v103
	v_mul_f32_e32 v200, v214, v200
	v_mul_f32_e32 v201, v214, v201
	v_mul_f32_e32 v202, v214, v202
	v_mul_f32_e32 v203, v214, v203
	v_mul_f32_e32 v204, v215, v204
	v_mul_f32_e32 v205, v215, v205
	v_mul_f32_e32 v206, v215, v206
	v_mul_f32_e32 v207, v215, v207
	v_fmac_f32_e32 v12, v140, v200
	v_fmac_f32_e32 v13, v141, v201
	v_fmac_f32_e32 v14, v142, v202
	v_fmac_f32_e32 v15, v143, v203
	v_fmac_f32_e32 v12, v172, v204
	v_fmac_f32_e32 v13, v173, v205
	v_fmac_f32_e32 v14, v174, v206
	v_fmac_f32_e32 v15, v175, v207
	global_store_dwordx4 v192, v[12:15], s[18:19] offset:3072 nt
	v_lshlrev_b32_e32 v200, 16, v72
	v_and_b32_e32 v201, 0xffff0000, v72
	v_lshlrev_b32_e32 v202, 16, v73
	v_and_b32_e32 v203, 0xffff0000, v73
	v_lshlrev_b32_e32 v204, 16, v104
	v_and_b32_e32 v205, 0xffff0000, v104
	v_lshlrev_b32_e32 v206, 16, v105
	v_and_b32_e32 v207, 0xffff0000, v105
	v_mul_f32_e32 v200, v214, v200
	v_mul_f32_e32 v201, v214, v201
	v_mul_f32_e32 v202, v214, v202
	v_mul_f32_e32 v203, v214, v203
	v_mul_f32_e32 v204, v215, v204
	v_mul_f32_e32 v205, v215, v205
	v_mul_f32_e32 v206, v215, v206
	v_mul_f32_e32 v207, v215, v207
	v_fmac_f32_e32 v16, v144, v200
	v_fmac_f32_e32 v17, v145, v201
	v_fmac_f32_e32 v18, v146, v202
	v_fmac_f32_e32 v19, v147, v203
	v_fmac_f32_e32 v16, v176, v204
	v_fmac_f32_e32 v17, v177, v205
	v_fmac_f32_e32 v18, v178, v206
	v_fmac_f32_e32 v19, v179, v207
	global_store_dwordx4 v193, v[16:19], s[18:19] offset:0 nt
	v_lshlrev_b32_e32 v200, 16, v74
	v_and_b32_e32 v201, 0xffff0000, v74
	v_lshlrev_b32_e32 v202, 16, v75
	v_and_b32_e32 v203, 0xffff0000, v75
	v_lshlrev_b32_e32 v204, 16, v106
	v_and_b32_e32 v205, 0xffff0000, v106
	v_lshlrev_b32_e32 v206, 16, v107
	v_and_b32_e32 v207, 0xffff0000, v107
	v_mul_f32_e32 v200, v214, v200
	v_mul_f32_e32 v201, v214, v201
	v_mul_f32_e32 v202, v214, v202
	v_mul_f32_e32 v203, v214, v203
	v_mul_f32_e32 v204, v215, v204
	v_mul_f32_e32 v205, v215, v205
	v_mul_f32_e32 v206, v215, v206
	v_mul_f32_e32 v207, v215, v207
	v_fmac_f32_e32 v20, v148, v200
	v_fmac_f32_e32 v21, v149, v201
	v_fmac_f32_e32 v22, v150, v202
	v_fmac_f32_e32 v23, v151, v203
	v_fmac_f32_e32 v20, v180, v204
	v_fmac_f32_e32 v21, v181, v205
	v_fmac_f32_e32 v22, v182, v206
	v_fmac_f32_e32 v23, v183, v207
	global_store_dwordx4 v193, v[20:23], s[18:19] offset:1024 nt
	v_lshlrev_b32_e32 v200, 16, v76
	v_and_b32_e32 v201, 0xffff0000, v76
	v_lshlrev_b32_e32 v202, 16, v77
	v_and_b32_e32 v203, 0xffff0000, v77
	v_lshlrev_b32_e32 v204, 16, v108
	v_and_b32_e32 v205, 0xffff0000, v108
	v_lshlrev_b32_e32 v206, 16, v109
	v_and_b32_e32 v207, 0xffff0000, v109
	v_mul_f32_e32 v200, v214, v200
	v_mul_f32_e32 v201, v214, v201
	v_mul_f32_e32 v202, v214, v202
	v_mul_f32_e32 v203, v214, v203
	v_mul_f32_e32 v204, v215, v204
	v_mul_f32_e32 v205, v215, v205
	v_mul_f32_e32 v206, v215, v206
	v_mul_f32_e32 v207, v215, v207
	v_fmac_f32_e32 v24, v152, v200
	v_fmac_f32_e32 v25, v153, v201
	v_fmac_f32_e32 v26, v154, v202
	v_fmac_f32_e32 v27, v155, v203
	v_fmac_f32_e32 v24, v184, v204
	v_fmac_f32_e32 v25, v185, v205
	v_fmac_f32_e32 v26, v186, v206
	v_fmac_f32_e32 v27, v187, v207
	global_store_dwordx4 v193, v[24:27], s[18:19] offset:2048 nt
	v_lshlrev_b32_e32 v200, 16, v78
	v_and_b32_e32 v201, 0xffff0000, v78
	v_lshlrev_b32_e32 v202, 16, v79
	v_and_b32_e32 v203, 0xffff0000, v79
	v_lshlrev_b32_e32 v204, 16, v110
	v_and_b32_e32 v205, 0xffff0000, v110
	v_lshlrev_b32_e32 v206, 16, v111
	v_and_b32_e32 v207, 0xffff0000, v111
	v_mul_f32_e32 v200, v214, v200
	v_mul_f32_e32 v201, v214, v201
	v_mul_f32_e32 v202, v214, v202
	v_mul_f32_e32 v203, v214, v203
	v_mul_f32_e32 v204, v215, v204
	v_mul_f32_e32 v205, v215, v205
	v_mul_f32_e32 v206, v215, v206
	v_mul_f32_e32 v207, v215, v207
	v_fmac_f32_e32 v28, v156, v200
	v_fmac_f32_e32 v29, v157, v201
	v_fmac_f32_e32 v30, v158, v202
	v_fmac_f32_e32 v31, v159, v203
	v_fmac_f32_e32 v28, v188, v204
	v_fmac_f32_e32 v29, v189, v205
	v_fmac_f32_e32 v30, v190, v206
	v_fmac_f32_e32 v31, v191, v207
	global_store_dwordx4 v193, v[28:31], s[18:19] offset:3072 nt
	s_add_u32 s18, s18, 0x2000
	s_addc_u32 s19, s19, 0
	global_load_dwordx4 v[0:3], v192, s[14:15] offset:0 nt
	global_load_dwordx4 v[4:7], v192, s[14:15] offset:1024 nt
	global_load_dwordx4 v[8:11], v192, s[14:15] offset:2048 nt
	global_load_dwordx4 v[12:15], v192, s[14:15] offset:3072 nt
	global_load_dwordx4 v[16:19], v193, s[14:15] offset:0 nt
	global_load_dwordx4 v[20:23], v193, s[14:15] offset:1024 nt
	global_load_dwordx4 v[24:27], v193, s[14:15] offset:2048 nt
	global_load_dwordx4 v[28:31], v193, s[14:15] offset:3072 nt
	global_load_dwordx2 v[64:65], v194, s[16:17] offset:0
	global_load_dwordx2 v[66:67], v194, s[16:17] offset:512
	global_load_dwordx2 v[68:69], v194, s[16:17] offset:1024
	global_load_dwordx2 v[70:71], v194, s[16:17] offset:1536
	global_load_dwordx2 v[72:73], v194, s[16:17] offset:2048
	global_load_dwordx2 v[74:75], v194, s[16:17] offset:2560
	global_load_dwordx2 v[76:77], v194, s[16:17] offset:3072
	global_load_dwordx2 v[78:79], v194, s[16:17] offset:3584
	global_load_dwordx2 v[96:97], v194, s[22:23] offset:0
	global_load_dwordx2 v[98:99], v194, s[22:23] offset:512
	global_load_dwordx2 v[100:101], v194, s[22:23] offset:1024
	global_load_dwordx2 v[102:103], v194, s[22:23] offset:1536
	global_load_dwordx2 v[104:105], v194, s[22:23] offset:2048
	global_load_dwordx2 v[106:107], v194, s[22:23] offset:2560
	global_load_dwordx2 v[108:109], v194, s[22:23] offset:3072
	global_load_dwordx2 v[110:111], v194, s[22:23] offset:3584
	s_add_u32 s14, s14, 0x2000
	s_addc_u32 s15, s15, 0
	s_add_u32 s16, s16, 0x1000
	s_addc_u32 s17, s17, 0
	s_add_u32 s22, s22, 0x1000
	s_addc_u32 s23, s23, 0
	s_waitcnt vmcnt(32)
; __device__ __forceinline__ float bf_lo(unsigned w) { return __uint_as_float(w << 16); }
; __device__ __forceinline__ float bf_hi(unsigned w) { return __uint_as_float(w & 0xffff0000u); }
; __global__ void __launch_bounds__(NWAVES * 64, 2) mk_fwd(Args args) {
;     ...
;                 float sy = 0.f;
; #pragma unroll
;                 for (int j = 0; j < 8; ++j) { const float a = bf_lo(yw[q][j].x), b = bf_hi(yw[q][j].x), c2 = bf_lo(yw[q][j].y), d = bf_hi(yw[q][j].y); sy += (a * a + b * b) + (c2 * c2 + d * d); }
;                 const float rsy = __builtin_amdgcn_rsqf(wave_sum(sy) * (1.f / DM) + EPS);
	v_lshlrev_b32_e32 v200, 16, v80
	v_and_b32_e32 v201, 0xffff0000, v80
	v_lshlrev_b32_e32 v202, 16, v81
	v_and_b32_e32 v203, 0xffff0000, v81
	v_mul_f32_e32 v208, v200, v200
	v_mul_f32_e32 v209, v201, v201
	v_fmac_f32_e32 v208, v202, v202
	v_fmac_f32_e32 v209, v203, v203
	v_lshlrev_b32_e32 v204, 16, v112
	v_and_b32_e32 v205, 0xffff0000, v112
	v_lshlrev_b32_e32 v206, 16, v113
	v_and_b32_e32 v207, 0xffff0000, v113
	v_mul_f32_e32 v210, v204, v204
	v_mul_f32_e32 v211, v205, v205
	v_fmac_f32_e32 v210, v206, v206
	v_fmac_f32_e32 v211, v207, v207
	v_lshlrev_b32_e32 v200, 16, v82
	v_and_b32_e32 v201, 0xffff0000, v82
	v_lshlrev_b32_e32 v202, 16, v83
	v_and_b32_e32 v203, 0xffff0000, v83
	v_fmac_f32_e32 v208, v200, v200
	v_fmac_f32_e32 v209, v201, v201
	v_fmac_f32_e32 v208, v202, v202
	v_fmac_f32_e32 v209, v203, v203
	v_lshlrev_b32_e32 v204, 16, v114
	v_and_b32_e32 v205, 0xffff0000, v114
	v_lshlrev_b32_e32 v206, 16, v115
	v_and_b32_e32 v207, 0xffff0000, v115
	v_fmac_f32_e32 v210, v204, v204
	v_fmac_f32_e32 v211, v205, v205
	v_fmac_f32_e32 v210, v206, v206
	v_fmac_f32_e32 v211, v207, v207
	v_lshlrev_b32_e32 v200, 16, v84
	v_and_b32_e32 v201, 0xffff0000, v84
	v_lshlrev_b32_e32 v202, 16, v85
	v_and_b32_e32 v203, 0xffff0000, v85
	v_fmac_f32_e32 v208, v200, v200
	v_fmac_f32_e32 v209, v201, v201
	v_fmac_f32_e32 v208, v202, v202
	v_fmac_f32_e32 v209, v203, v203
	v_lshlrev_b32_e32 v204, 16, v116
	v_and_b32_e32 v205, 0xffff0000, v116
	v_lshlrev_b32_e32 v206, 16, v117
	v_and_b32_e32 v207, 0xffff0000, v117
	v_fmac_f32_e32 v210, v204, v204
	v_fmac_f32_e32 v211, v205, v205
	v_fmac_f32_e32 v210, v206, v206
	v_fmac_f32_e32 v211, v207, v207
	v_lshlrev_b32_e32 v200, 16, v86
	v_and_b32_e32 v201, 0xffff0000, v86
	v_lshlrev_b32_e32 v202, 16, v87
	v_and_b32_e32 v203, 0xffff0000, v87
	v_fmac_f32_e32 v208, v200, v200
	v_fmac_f32_e32 v209, v201, v201
	v_fmac_f32_e32 v208, v202, v202
	v_fmac_f32_e32 v209, v203, v203
	v_lshlrev_b32_e32 v204, 16, v118
	v_and_b32_e32 v205, 0xffff0000, v118
	v_lshlrev_b32_e32 v206, 16, v119
	v_and_b32_e32 v207, 0xffff0000, v119
	v_fmac_f32_e32 v210, v204, v204
	v_fmac_f32_e32 v211, v205, v205
	v_fmac_f32_e32 v210, v206, v206
	v_fmac_f32_e32 v211, v207, v207
	v_lshlrev_b32_e32 v200, 16, v88
	v_and_b32_e32 v201, 0xffff0000, v88
	v_lshlrev_b32_e32 v202, 16, v89
	v_and_b32_e32 v203, 0xffff0000, v89
	v_fmac_f32_e32 v208, v200, v200
	v_fmac_f32_e32 v209, v201, v201
	v_fmac_f32_e32 v208, v202, v202
	v_fmac_f32_e32 v209, v203, v203
	v_lshlrev_b32_e32 v204, 16, v120
	v_and_b32_e32 v205, 0xffff0000, v120
	v_lshlrev_b32_e32 v206, 16, v121
	v_and_b32_e32 v207, 0xffff0000, v121
	v_fmac_f32_e32 v210, v204, v204
	v_fmac_f32_e32 v211, v205, v205
	v_fmac_f32_e32 v210, v206, v206
	v_fmac_f32_e32 v211, v207, v207
	v_lshlrev_b32_e32 v200, 16, v90
	v_and_b32_e32 v201, 0xffff0000, v90
	v_lshlrev_b32_e32 v202, 16, v91
	v_and_b32_e32 v203, 0xffff0000, v91
	v_fmac_f32_e32 v208, v200, v200
	v_fmac_f32_e32 v209, v201, v201
	v_fmac_f32_e32 v208, v202, v202
	v_fmac_f32_e32 v209, v203, v203
	v_lshlrev_b32_e32 v204, 16, v122
	v_and_b32_e32 v205, 0xffff0000, v122
	v_lshlrev_b32_e32 v206, 16, v123
	v_and_b32_e32 v207, 0xffff0000, v123
	v_fmac_f32_e32 v210, v204, v204
	v_fmac_f32_e32 v211, v205, v205
	v_fmac_f32_e32 v210, v206, v206
	v_fmac_f32_e32 v211, v207, v207
	v_lshlrev_b32_e32 v200, 16, v92
	v_and_b32_e32 v201, 0xffff0000, v92
	v_lshlrev_b32_e32 v202, 16, v93
	v_and_b32_e32 v203, 0xffff0000, v93
	v_fmac_f32_e32 v208, v200, v200
	v_fmac_f32_e32 v209, v201, v201
	v_fmac_f32_e32 v208, v202, v202
	v_fmac_f32_e32 v209, v203, v203
	v_lshlrev_b32_e32 v204, 16, v124
	v_and_b32_e32 v205, 0xffff0000, v124
	v_lshlrev_b32_e32 v206, 16, v125
	v_and_b32_e32 v207, 0xffff0000, v125
	v_fmac_f32_e32 v210, v204, v204
	v_fmac_f32_e32 v211, v205, v205
	v_fmac_f32_e32 v210, v206, v206
	v_fmac_f32_e32 v211, v207, v207
	v_lshlrev_b32_e32 v200, 16, v94
	v_and_b32_e32 v201, 0xffff0000, v94
	v_lshlrev_b32_e32 v202, 16, v95
	v_and_b32_e32 v203, 0xffff0000, v95
	v_fmac_f32_e32 v208, v200, v200
	v_fmac_f32_e32 v209, v201, v201
	v_fmac_f32_e32 v208, v202, v202
	v_fmac_f32_e32 v209, v203, v203
	v_lshlrev_b32_e32 v204, 16, v126
	v_and_b32_e32 v205, 0xffff0000, v126
	v_lshlrev_b32_e32 v206, 16, v127
	v_and_b32_e32 v207, 0xffff0000, v127
	v_fmac_f32_e32 v210, v204, v204
	v_fmac_f32_e32 v211, v205, v205
	v_fmac_f32_e32 v210, v206, v206
	v_fmac_f32_e32 v211, v207, v207
	v_add_f32_e32 v208, v208, v209
	v_add_f32_e32 v210, v210, v211
	s_nop 0
	v_add_f32_dpp v212, v208, v208 quad_perm:[1,0,3,2] row_mask:0xf bank_mask:0xf
	v_add_f32_dpp v213, v210, v210 quad_perm:[1,0,3,2] row_mask:0xf bank_mask:0xf
	s_nop 0
	v_add_f32_dpp v212, v212, v212 quad_perm:[2,3,0,1] row_mask:0xf bank_mask:0xf
	v_add_f32_dpp v213, v213, v213 quad_perm:[2,3,0,1] row_mask:0xf bank_mask:0xf
	s_nop 0
	v_add_f32_dpp v212, v212, v212 row_half_mirror row_mask:0xf bank_mask:0xf
	v_add_f32_dpp v213, v213, v213 row_half_mirror row_mask:0xf bank_mask:0xf
	s_nop 0
	v_add_f32_dpp v212, v212, v212 row_mirror row_mask:0xf bank_mask:0xf
	v_add_f32_dpp v213, v213, v213 row_mirror row_mask:0xf bank_mask:0xf
	s_nop 0
	v_readlane_b32 s4, v212, 0
	v_readlane_b32 s5, v212, 16
	v_readlane_b32 s6, v212, 32
	v_readlane_b32 s7, v212, 48
	v_readlane_b32 s24, v213, 0
	v_readlane_b32 s25, v213, 16
	v_readlane_b32 s26, v213, 32
	v_readlane_b32 s27, v213, 48
	s_nop 1
	v_mov_b32_e32 v214, s4
	v_mov_b32_e32 v215, s24
	v_add_f32_e32 v214, s5, v214
	v_add_f32_e32 v215, s25, v215
	v_add_f32_e32 v214, s6, v214
	v_add_f32_e32 v215, s26, v215
	v_add_f32_e32 v214, s7, v214
	v_add_f32_e32 v215, s27, v215
	v_fmamk_f32 v214, v214, 0x3a000000, v195
	v_fmamk_f32 v215, v215, 0x3a000000, v195
; __device__ __forceinline__ float bf_lo(unsigned w) { return __uint_as_float(w << 16); }
; __device__ __forceinline__ float bf_hi(unsigned w) { return __uint_as_float(w & 0xffff0000u); }
; __global__ void __launch_bounds__(NWAVES * 64, 2) mk_fwd(Args args) {
;     ...
;                 const float rsy = __builtin_amdgcn_rsqf(wave_sum(sy) * (1.f / DM) + EPS);
; #pragma unroll
;                 for (int j = 0; j < 8; ++j) { const int col = 4 * F.lane + 256 * j;
;                     const f32x4 y4 = (f32x4){bf_lo(yw[q][j].x), bf_hi(yw[q][j].x), bf_lo(yw[q][j].y), bf_hi(yw[q][j].y)};
;                     *(f32x4*)(args.out + (size_t)row * DM + col) = v[q][j] + PA[j] * (y4 * rsy); }
	v_rsq_f32_e32 v214, v214
	v_rsq_f32_e32 v215, v215
	s_nop 0
	v_lshlrev_b32_e32 v200, 16, v80
	v_and_b32_e32 v201, 0xffff0000, v80
	v_lshlrev_b32_e32 v202, 16, v81
	v_and_b32_e32 v203, 0xffff0000, v81
	v_lshlrev_b32_e32 v204, 16, v112
	v_and_b32_e32 v205, 0xffff0000, v112
	v_lshlrev_b32_e32 v206, 16, v113
	v_and_b32_e32 v207, 0xffff0000, v113
	v_mul_f32_e32 v200, v214, v200
	v_mul_f32_e32 v201, v214, v201
	v_mul_f32_e32 v202, v214, v202
	v_mul_f32_e32 v203, v214, v203
	v_mul_f32_e32 v204, v215, v204
	v_mul_f32_e32 v205, v215, v205
	v_mul_f32_e32 v206, v215, v206
	v_mul_f32_e32 v207, v215, v207
	v_fmac_f32_e32 v32, v128, v200
	v_fmac_f32_e32 v33, v129, v201
	v_fmac_f32_e32 v34, v130, v202
	v_fmac_f32_e32 v35, v131, v203
	v_fmac_f32_e32 v32, v160, v204
	v_fmac_f32_e32 v33, v161, v205
	v_fmac_f32_e32 v34, v162, v206
	v_fmac_f32_e32 v35, v163, v207
	global_store_dwordx4 v192, v[32:35], s[18:19] offset:0 nt
	v_lshlrev_b32_e32 v200, 16, v82
	v_and_b32_e32 v201, 0xffff0000, v82
	v_lshlrev_b32_e32 v202, 16, v83
	v_and_b32_e32 v203, 0xffff0000, v83
	v_lshlrev_b32_e32 v204, 16, v114
	v_and_b32_e32 v205, 0xffff0000, v114
	v_lshlrev_b32_e32 v206, 16, v115
	v_and_b32_e32 v207, 0xffff0000, v115
	v_mul_f32_e32 v200, v214, v200
	v_mul_f32_e32 v201, v214, v201
	v_mul_f32_e32 v202, v214, v202
	v_mul_f32_e32 v203, v214, v203
	v_mul_f32_e32 v204, v215, v204
	v_mul_f32_e32 v205, v215, v205
	v_mul_f32_e32 v206, v215, v206
	v_mul_f32_e32 v207, v215, v207
	v_fmac_f32_e32 v36, v132, v200
	v_fmac_f32_e32 v37, v133, v201
	v_fmac_f32_e32 v38, v134, v202
	v_fmac_f32_e32 v39, v135, v203
	v_fmac_f32_e32 v36, v164, v204
	v_fmac_f32_e32 v37, v165, v205
	v_fmac_f32_e32 v38, v166, v206
	v_fmac_f32_e32 v39, v167, v207
	global_store_dwordx4 v192, v[36:39], s[18:19] offset:1024 nt
	v_lshlrev_b32_e32 v200, 16, v84
	v_and_b32_e32 v201, 0xffff0000, v84
	v_lshlrev_b32_e32 v202, 16, v85
	v_and_b32_e32 v203, 0xffff0000, v85
	v_lshlrev_b32_e32 v204, 16, v116
	v_and_b32_e32 v205, 0xffff0000, v116
	v_lshlrev_b32_e32 v206, 16, v117
	v_and_b32_e32 v207, 0xffff0000, v117
	v_mul_f32_e32 v200, v214, v200
	v_mul_f32_e32 v201, v214, v201
	v_mul_f32_e32 v202, v214, v202
	v_mul_f32_e32 v203, v214, v203
	v_mul_f32_e32 v204, v215, v204
	v_mul_f32_e32 v205, v215, v205
	v_mul_f32_e32 v206, v215, v206
	v_mul_f32_e32 v207, v215, v207
	v_fmac_f32_e32 v40, v136, v200
	v_fmac_f32_e32 v41, v137, v201
	v_fmac_f32_e32 v42, v138, v202
	v_fmac_f32_e32 v43, v139, v203
	v_fmac_f32_e32 v40, v168, v204
	v_fmac_f32_e32 v41, v169, v205
	v_fmac_f32_e32 v42, v170, v206
	v_fmac_f32_e32 v43, v171, v207
	global_store_dwordx4 v192, v[40:43], s[18:19] offset:2048 nt
	v_lshlrev_b32_e32 v200, 16, v86
	v_and_b32_e32 v201, 0xffff0000, v86
	v_lshlrev_b32_e32 v202, 16, v87
	v_and_b32_e32 v203, 0xffff0000, v87
	v_lshlrev_b32_e32 v204, 16, v118
	v_and_b32_e32 v205, 0xffff0000, v118
	v_lshlrev_b32_e32 v206, 16, v119
	v_and_b32_e32 v207, 0xffff0000, v119
	v_mul_f32_e32 v200, v214, v200
	v_mul_f32_e32 v201, v214, v201
	v_mul_f32_e32 v202, v214, v202
	v_mul_f32_e32 v203, v214, v203
	v_mul_f32_e32 v204, v215, v204
	v_mul_f32_e32 v205, v215, v205
	v_mul_f32_e32 v206, v215, v206
	v_mul_f32_e32 v207, v215, v207
	v_fmac_f32_e32 v44, v140, v200
	v_fmac_f32_e32 v45, v141, v201
	v_fmac_f32_e32 v46, v142, v202
	v_fmac_f32_e32 v47, v143, v203
	v_fmac_f32_e32 v44, v172, v204
	v_fmac_f32_e32 v45, v173, v205
	v_fmac_f32_e32 v46, v174, v206
	v_fmac_f32_e32 v47, v175, v207
	global_store_dwordx4 v192, v[44:47], s[18:19] offset:3072 nt
	v_lshlrev_b32_e32 v200, 16, v88
	v_and_b32_e32 v201, 0xffff0000, v88
	v_lshlrev_b32_e32 v202, 16, v89
	v_and_b32_e32 v203, 0xffff0000, v89
	v_lshlrev_b32_e32 v204, 16, v120
	v_and_b32_e32 v205, 0xffff0000, v120
	v_lshlrev_b32_e32 v206, 16, v121
	v_and_b32_e32 v207, 0xffff0000, v121
	v_mul_f32_e32 v200, v214, v200
	v_mul_f32_e32 v201, v214, v201
	v_mul_f32_e32 v202, v214, v202
	v_mul_f32_e32 v203, v214, v203
	v_mul_f32_e32 v204, v215, v204
	v_mul_f32_e32 v205, v215, v205
	v_mul_f32_e32 v206, v215, v206
	v_mul_f32_e32 v207, v215, v207
	v_fmac_f32_e32 v48, v144, v200
	v_fmac_f32_e32 v49, v145, v201
	v_fmac_f32_e32 v50, v146, v202
	v_fmac_f32_e32 v51, v147, v203
	v_fmac_f32_e32 v48, v176, v204
	v_fmac_f32_e32 v49, v177, v205
	v_fmac_f32_e32 v50, v178, v206
	v_fmac_f32_e32 v51, v179, v207
	global_store_dwordx4 v193, v[48:51], s[18:19] offset:0 nt
	v_lshlrev_b32_e32 v200, 16, v90
	v_and_b32_e32 v201, 0xffff0000, v90
	v_lshlrev_b32_e32 v202, 16, v91
	v_and_b32_e32 v203, 0xffff0000, v91
	v_lshlrev_b32_e32 v204, 16, v122
	v_and_b32_e32 v205, 0xffff0000, v122
	v_lshlrev_b32_e32 v206, 16, v123
	v_and_b32_e32 v207, 0xffff0000, v123
	v_mul_f32_e32 v200, v214, v200
	v_mul_f32_e32 v201, v214, v201
	v_mul_f32_e32 v202, v214, v202
	v_mul_f32_e32 v203, v214, v203
	v_mul_f32_e32 v204, v215, v204
	v_mul_f32_e32 v205, v215, v205
	v_mul_f32_e32 v206, v215, v206
	v_mul_f32_e32 v207, v215, v207
	v_fmac_f32_e32 v52, v148, v200
	v_fmac_f32_e32 v53, v149, v201
	v_fmac_f32_e32 v54, v150, v202
	v_fmac_f32_e32 v55, v151, v203
	v_fmac_f32_e32 v52, v180, v204
	v_fmac_f32_e32 v53, v181, v205
	v_fmac_f32_e32 v54, v182, v206
	v_fmac_f32_e32 v55, v183, v207
	global_store_dwordx4 v193, v[52:55], s[18:19] offset:1024 nt
	v_lshlrev_b32_e32 v200, 16, v92
	v_and_b32_e32 v201, 0xffff0000, v92
	v_lshlrev_b32_e32 v202, 16, v93
	v_and_b32_e32 v203, 0xffff0000, v93
	v_lshlrev_b32_e32 v204, 16, v124
	v_and_b32_e32 v205, 0xffff0000, v124
	v_lshlrev_b32_e32 v206, 16, v125
	v_and_b32_e32 v207, 0xffff0000, v125
	v_mul_f32_e32 v200, v214, v200
	v_mul_f32_e32 v201, v214, v201
	v_mul_f32_e32 v202, v214, v202
	v_mul_f32_e32 v203, v214, v203
	v_mul_f32_e32 v204, v215, v204
; __device__ __forceinline__ float bf_lo(unsigned w) { return __uint_as_float(w << 16); }
; __device__ __forceinline__ float bf_hi(unsigned w) { return __uint_as_float(w & 0xffff0000u); }
; __global__ void __launch_bounds__(NWAVES * 64, 2) mk_fwd(Args args) {
;     ...
;             for (int q = 0; q < 2; ++q) { const int row = row0 + q; load_row_f32(args.out + (size_t)row * DM, F.lane, v[q]);
;                 const bf16_t* yr = Y + (size_t)row * DM;
; #pragma unroll
;                 for (int j = 0; j < 8; ++j) yw[q][j] = *(const u32x2*)(yr + 4 * F.lane + 256 * j); }
;     ...
;                 float sy = 0.f;
; #pragma unroll
;                 for (int j = 0; j < 8; ++j) { const float a = bf_lo(yw[q][j].x), b = bf_hi(yw[q][j].x), c2 = bf_lo(yw[q][j].y), d = bf_hi(yw[q][j].y); sy += (a * a + b * b) + (c2 * c2 + d * d); }
;     ...
;                 for (int j = 0; j < 8; ++j) { const int col = 4 * F.lane + 256 * j;
;                     const f32x4 y4 = (f32x4){bf_lo(yw[q][j].x), bf_hi(yw[q][j].x), bf_lo(yw[q][j].y), bf_hi(yw[q][j].y)};
;                     *(f32x4*)(args.out + (size_t)row * DM + col) = v[q][j] + PA[j] * (y4 * rsy); }
	v_mul_f32_e32 v205, v215, v205
	v_mul_f32_e32 v206, v215, v206
	v_mul_f32_e32 v207, v215, v207
	v_fmac_f32_e32 v56, v152, v200
	v_fmac_f32_e32 v57, v153, v201
	v_fmac_f32_e32 v58, v154, v202
	v_fmac_f32_e32 v59, v155, v203
	v_fmac_f32_e32 v56, v184, v204
	v_fmac_f32_e32 v57, v185, v205
	v_fmac_f32_e32 v58, v186, v206
	v_fmac_f32_e32 v59, v187, v207
	global_store_dwordx4 v193, v[56:59], s[18:19] offset:2048 nt
	v_lshlrev_b32_e32 v200, 16, v94
	v_and_b32_e32 v201, 0xffff0000, v94
	v_lshlrev_b32_e32 v202, 16, v95
	v_and_b32_e32 v203, 0xffff0000, v95
	v_lshlrev_b32_e32 v204, 16, v126
	v_and_b32_e32 v205, 0xffff0000, v126
	v_lshlrev_b32_e32 v206, 16, v127
	v_and_b32_e32 v207, 0xffff0000, v127
	v_mul_f32_e32 v200, v214, v200
	v_mul_f32_e32 v201, v214, v201
	v_mul_f32_e32 v202, v214, v202
	v_mul_f32_e32 v203, v214, v203
	v_mul_f32_e32 v204, v215, v204
	v_mul_f32_e32 v205, v215, v205
	v_mul_f32_e32 v206, v215, v206
	v_mul_f32_e32 v207, v215, v207
	v_fmac_f32_e32 v60, v156, v200
	v_fmac_f32_e32 v61, v157, v201
	v_fmac_f32_e32 v62, v158, v202
	v_fmac_f32_e32 v63, v159, v203
	v_fmac_f32_e32 v60, v188, v204
	v_fmac_f32_e32 v61, v189, v205
	v_fmac_f32_e32 v62, v190, v206
	v_fmac_f32_e32 v63, v191, v207
	global_store_dwordx4 v193, v[60:63], s[18:19] offset:3072 nt
	s_add_u32 s18, s18, 0x2000
	s_addc_u32 s19, s19, 0
	global_load_dwordx4 v[32:35], v192, s[14:15] offset:0 nt
	global_load_dwordx4 v[36:39], v192, s[14:15] offset:1024 nt
	global_load_dwordx4 v[40:43], v192, s[14:15] offset:2048 nt
	global_load_dwordx4 v[44:47], v192, s[14:15] offset:3072 nt
	global_load_dwordx4 v[48:51], v193, s[14:15] offset:0 nt
	global_load_dwordx4 v[52:55], v193, s[14:15] offset:1024 nt
	global_load_dwordx4 v[56:59], v193, s[14:15] offset:2048 nt
	global_load_dwordx4 v[60:63], v193, s[14:15] offset:3072 nt
	global_load_dwordx2 v[80:81], v194, s[16:17] offset:0
	global_load_dwordx2 v[82:83], v194, s[16:17] offset:512
	global_load_dwordx2 v[84:85], v194, s[16:17] offset:1024
	global_load_dwordx2 v[86:87], v194, s[16:17] offset:1536
	global_load_dwordx2 v[88:89], v194, s[16:17] offset:2048
	global_load_dwordx2 v[90:91], v194, s[16:17] offset:2560
	global_load_dwordx2 v[92:93], v194, s[16:17] offset:3072
	global_load_dwordx2 v[94:95], v194, s[16:17] offset:3584
	global_load_dwordx2 v[112:113], v194, s[22:23] offset:0
	global_load_dwordx2 v[114:115], v194, s[22:23] offset:512
	global_load_dwordx2 v[116:117], v194, s[22:23] offset:1024
	global_load_dwordx2 v[118:119], v194, s[22:23] offset:1536
	global_load_dwordx2 v[120:121], v194, s[22:23] offset:2048
	global_load_dwordx2 v[122:123], v194, s[22:23] offset:2560
	global_load_dwordx2 v[124:125], v194, s[22:23] offset:3072
	global_load_dwordx2 v[126:127], v194, s[22:23] offset:3584
	s_add_u32 s14, s14, 0x2000
	s_addc_u32 s15, s15, 0
	s_add_u32 s16, s16, 0x1000
	s_addc_u32 s17, s17, 0
	s_add_u32 s22, s22, 0x1000
	s_addc_u32 s23, s23, 0
	s_waitcnt vmcnt(32)
	v_lshlrev_b32_e32 v200, 16, v64
	v_and_b32_e32 v201, 0xffff0000, v64
	v_lshlrev_b32_e32 v202, 16, v65
	v_and_b32_e32 v203, 0xffff0000, v65
	v_mul_f32_e32 v208, v200, v200
	v_mul_f32_e32 v209, v201, v201
	v_fmac_f32_e32 v208, v202, v202
	v_fmac_f32_e32 v209, v203, v203
	v_lshlrev_b32_e32 v204, 16, v96
	v_and_b32_e32 v205, 0xffff0000, v96
	v_lshlrev_b32_e32 v206, 16, v97
	v_and_b32_e32 v207, 0xffff0000, v97
	v_mul_f32_e32 v210, v204, v204
	v_mul_f32_e32 v211, v205, v205
	v_fmac_f32_e32 v210, v206, v206
	v_fmac_f32_e32 v211, v207, v207
	v_lshlrev_b32_e32 v200, 16, v66
	v_and_b32_e32 v201, 0xffff0000, v66
	v_lshlrev_b32_e32 v202, 16, v67
	v_and_b32_e32 v203, 0xffff0000, v67
	v_fmac_f32_e32 v208, v200, v200
	v_fmac_f32_e32 v209, v201, v201
	v_fmac_f32_e32 v208, v202, v202
	v_fmac_f32_e32 v209, v203, v203
	v_lshlrev_b32_e32 v204, 16, v98
	v_and_b32_e32 v205, 0xffff0000, v98
	v_lshlrev_b32_e32 v206, 16, v99
	v_and_b32_e32 v207, 0xffff0000, v99
	v_fmac_f32_e32 v210, v204, v204
	v_fmac_f32_e32 v211, v205, v205
	v_fmac_f32_e32 v210, v206, v206
	v_fmac_f32_e32 v211, v207, v207
	v_lshlrev_b32_e32 v200, 16, v68
	v_and_b32_e32 v201, 0xffff0000, v68
	v_lshlrev_b32_e32 v202, 16, v69
	v_and_b32_e32 v203, 0xffff0000, v69
	v_fmac_f32_e32 v208, v200, v200
	v_fmac_f32_e32 v209, v201, v201
	v_fmac_f32_e32 v208, v202, v202
	v_fmac_f32_e32 v209, v203, v203
	v_lshlrev_b32_e32 v204, 16, v100
	v_and_b32_e32 v205, 0xffff0000, v100
	v_lshlrev_b32_e32 v206, 16, v101
	v_and_b32_e32 v207, 0xffff0000, v101
	v_fmac_f32_e32 v210, v204, v204
	v_fmac_f32_e32 v211, v205, v205
	v_fmac_f32_e32 v210, v206, v206
	v_fmac_f32_e32 v211, v207, v207
	v_lshlrev_b32_e32 v200, 16, v70
	v_and_b32_e32 v201, 0xffff0000, v70
	v_lshlrev_b32_e32 v202, 16, v71
	v_and_b32_e32 v203, 0xffff0000, v71
	v_fmac_f32_e32 v208, v200, v200
	v_fmac_f32_e32 v209, v201, v201
	v_fmac_f32_e32 v208, v202, v202
	v_fmac_f32_e32 v209, v203, v203
	v_lshlrev_b32_e32 v204, 16, v102
	v_and_b32_e32 v205, 0xffff0000, v102
	v_lshlrev_b32_e32 v206, 16, v103
	v_and_b32_e32 v207, 0xffff0000, v103
	v_fmac_f32_e32 v210, v204, v204
	v_fmac_f32_e32 v211, v205, v205
	v_fmac_f32_e32 v210, v206, v206
	v_fmac_f32_e32 v211, v207, v207
	v_lshlrev_b32_e32 v200, 16, v72
	v_and_b32_e32 v201, 0xffff0000, v72
	v_lshlrev_b32_e32 v202, 16, v73
	v_and_b32_e32 v203, 0xffff0000, v73
	v_fmac_f32_e32 v208, v200, v200
	v_fmac_f32_e32 v209, v201, v201
	v_fmac_f32_e32 v208, v202, v202
	v_fmac_f32_e32 v209, v203, v203
	v_lshlrev_b32_e32 v204, 16, v104
	v_and_b32_e32 v205, 0xffff0000, v104
	v_lshlrev_b32_e32 v206, 16, v105
	v_and_b32_e32 v207, 0xffff0000, v105
	v_fmac_f32_e32 v210, v204, v204
	v_fmac_f32_e32 v211, v205, v205
	v_fmac_f32_e32 v210, v206, v206
	v_fmac_f32_e32 v211, v207, v207
; __device__ __forceinline__ float bf_lo(unsigned w) { return __uint_as_float(w << 16); }
; __device__ __forceinline__ float bf_hi(unsigned w) { return __uint_as_float(w & 0xffff0000u); }
; __global__ void __launch_bounds__(NWAVES * 64, 2) mk_fwd(Args args) {
;     ...
;                 for (int j = 0; j < 8; ++j) { const float a = bf_lo(yw[q][j].x), b = bf_hi(yw[q][j].x), c2 = bf_lo(yw[q][j].y), d = bf_hi(yw[q][j].y); sy += (a * a + b * b) + (c2 * c2 + d * d); }
;                 const float rsy = __builtin_amdgcn_rsqf(wave_sum(sy) * (1.f / DM) + EPS);
; #pragma unroll
;                 for (int j = 0; j < 8; ++j) { const int col = 4 * F.lane + 256 * j;
;                     const f32x4 y4 = (f32x4){bf_lo(yw[q][j].x), bf_hi(yw[q][j].x), bf_lo(yw[q][j].y), bf_hi(yw[q][j].y)};
;                     *(f32x4*)(args.out + (size_t)row * DM + col) = v[q][j] + PA[j] * (y4 * rsy); }
	v_lshlrev_b32_e32 v200, 16, v74
	v_and_b32_e32 v201, 0xffff0000, v74
	v_lshlrev_b32_e32 v202, 16, v75
	v_and_b32_e32 v203, 0xffff0000, v75
	v_fmac_f32_e32 v208, v200, v200
	v_fmac_f32_e32 v209, v201, v201
	v_fmac_f32_e32 v208, v202, v202
	v_fmac_f32_e32 v209, v203, v203
	v_lshlrev_b32_e32 v204, 16, v106
	v_and_b32_e32 v205, 0xffff0000, v106
	v_lshlrev_b32_e32 v206, 16, v107
	v_and_b32_e32 v207, 0xffff0000, v107
	v_fmac_f32_e32 v210, v204, v204
	v_fmac_f32_e32 v211, v205, v205
	v_fmac_f32_e32 v210, v206, v206
	v_fmac_f32_e32 v211, v207, v207
	v_lshlrev_b32_e32 v200, 16, v76
	v_and_b32_e32 v201, 0xffff0000, v76
	v_lshlrev_b32_e32 v202, 16, v77
	v_and_b32_e32 v203, 0xffff0000, v77
	v_fmac_f32_e32 v208, v200, v200
	v_fmac_f32_e32 v209, v201, v201
	v_fmac_f32_e32 v208, v202, v202
	v_fmac_f32_e32 v209, v203, v203
	v_lshlrev_b32_e32 v204, 16, v108
	v_and_b32_e32 v205, 0xffff0000, v108
	v_lshlrev_b32_e32 v206, 16, v109
	v_and_b32_e32 v207, 0xffff0000, v109
	v_fmac_f32_e32 v210, v204, v204
	v_fmac_f32_e32 v211, v205, v205
	v_fmac_f32_e32 v210, v206, v206
	v_fmac_f32_e32 v211, v207, v207
	v_lshlrev_b32_e32 v200, 16, v78
	v_and_b32_e32 v201, 0xffff0000, v78
	v_lshlrev_b32_e32 v202, 16, v79
	v_and_b32_e32 v203, 0xffff0000, v79
	v_fmac_f32_e32 v208, v200, v200
	v_fmac_f32_e32 v209, v201, v201
	v_fmac_f32_e32 v208, v202, v202
	v_fmac_f32_e32 v209, v203, v203
	v_lshlrev_b32_e32 v204, 16, v110
	v_and_b32_e32 v205, 0xffff0000, v110
	v_lshlrev_b32_e32 v206, 16, v111
	v_and_b32_e32 v207, 0xffff0000, v111
	v_fmac_f32_e32 v210, v204, v204
	v_fmac_f32_e32 v211, v205, v205
	v_fmac_f32_e32 v210, v206, v206
	v_fmac_f32_e32 v211, v207, v207
	v_add_f32_e32 v208, v208, v209
	v_add_f32_e32 v210, v210, v211
	s_nop 0
	v_add_f32_dpp v212, v208, v208 quad_perm:[1,0,3,2] row_mask:0xf bank_mask:0xf
	v_add_f32_dpp v213, v210, v210 quad_perm:[1,0,3,2] row_mask:0xf bank_mask:0xf
	s_nop 0
	v_add_f32_dpp v212, v212, v212 quad_perm:[2,3,0,1] row_mask:0xf bank_mask:0xf
	v_add_f32_dpp v213, v213, v213 quad_perm:[2,3,0,1] row_mask:0xf bank_mask:0xf
	s_nop 0
	v_add_f32_dpp v212, v212, v212 row_half_mirror row_mask:0xf bank_mask:0xf
	v_add_f32_dpp v213, v213, v213 row_half_mirror row_mask:0xf bank_mask:0xf
	s_nop 0
	v_add_f32_dpp v212, v212, v212 row_mirror row_mask:0xf bank_mask:0xf
	v_add_f32_dpp v213, v213, v213 row_mirror row_mask:0xf bank_mask:0xf
	s_nop 0
	v_readlane_b32 s4, v212, 0
	v_readlane_b32 s5, v212, 16
	v_readlane_b32 s6, v212, 32
	v_readlane_b32 s7, v212, 48
	v_readlane_b32 s24, v213, 0
	v_readlane_b32 s25, v213, 16
	v_readlane_b32 s26, v213, 32
	v_readlane_b32 s27, v213, 48
	s_nop 1
	v_mov_b32_e32 v214, s4
	v_mov_b32_e32 v215, s24
	v_add_f32_e32 v214, s5, v214
	v_add_f32_e32 v215, s25, v215
	v_add_f32_e32 v214, s6, v214
	v_add_f32_e32 v215, s26, v215
	v_add_f32_e32 v214, s7, v214
	v_add_f32_e32 v215, s27, v215
	v_fmamk_f32 v214, v214, 0x3a000000, v195
	v_fmamk_f32 v215, v215, 0x3a000000, v195
	v_rsq_f32_e32 v214, v214
	v_rsq_f32_e32 v215, v215
	s_nop 0
	v_lshlrev_b32_e32 v200, 16, v64
	v_and_b32_e32 v201, 0xffff0000, v64
	v_lshlrev_b32_e32 v202, 16, v65
	v_and_b32_e32 v203, 0xffff0000, v65
	v_lshlrev_b32_e32 v204, 16, v96
	v_and_b32_e32 v205, 0xffff0000, v96
	v_lshlrev_b32_e32 v206, 16, v97
	v_and_b32_e32 v207, 0xffff0000, v97
	v_mul_f32_e32 v200, v214, v200
	v_mul_f32_e32 v201, v214, v201
	v_mul_f32_e32 v202, v214, v202
	v_mul_f32_e32 v203, v214, v203
	v_mul_f32_e32 v204, v215, v204
	v_mul_f32_e32 v205, v215, v205
	v_mul_f32_e32 v206, v215, v206
	v_mul_f32_e32 v207, v215, v207
	v_fmac_f32_e32 v0, v128, v200
	v_fmac_f32_e32 v1, v129, v201
	v_fmac_f32_e32 v2, v130, v202
	v_fmac_f32_e32 v3, v131, v203
	v_fmac_f32_e32 v0, v160, v204
	v_fmac_f32_e32 v1, v161, v205
	v_fmac_f32_e32 v2, v162, v206
	v_fmac_f32_e32 v3, v163, v207
	global_store_dwordx4 v192, v[0:3], s[18:19] offset:0 nt
	v_lshlrev_b32_e32 v200, 16, v66
	v_and_b32_e32 v201, 0xffff0000, v66
	v_lshlrev_b32_e32 v202, 16, v67
	v_and_b32_e32 v203, 0xffff0000, v67
	v_lshlrev_b32_e32 v204, 16, v98
	v_and_b32_e32 v205, 0xffff0000, v98
	v_lshlrev_b32_e32 v206, 16, v99
	v_and_b32_e32 v207, 0xffff0000, v99
	v_mul_f32_e32 v200, v214, v200
	v_mul_f32_e32 v201, v214, v201
	v_mul_f32_e32 v202, v214, v202
	v_mul_f32_e32 v203, v214, v203
	v_mul_f32_e32 v204, v215, v204
	v_mul_f32_e32 v205, v215, v205
	v_mul_f32_e32 v206, v215, v206
	v_mul_f32_e32 v207, v215, v207
	v_fmac_f32_e32 v4, v132, v200
	v_fmac_f32_e32 v5, v133, v201
	v_fmac_f32_e32 v6, v134, v202
	v_fmac_f32_e32 v7, v135, v203
	v_fmac_f32_e32 v4, v164, v204
	v_fmac_f32_e32 v5, v165, v205
	v_fmac_f32_e32 v6, v166, v206
	v_fmac_f32_e32 v7, v167, v207
	global_store_dwordx4 v192, v[4:7], s[18:19] offset:1024 nt
	v_lshlrev_b32_e32 v200, 16, v68
	v_and_b32_e32 v201, 0xffff0000, v68
	v_lshlrev_b32_e32 v202, 16, v69
	v_and_b32_e32 v203, 0xffff0000, v69
	v_lshlrev_b32_e32 v204, 16, v100
	v_and_b32_e32 v205, 0xffff0000, v100
	v_lshlrev_b32_e32 v206, 16, v101
	v_and_b32_e32 v207, 0xffff0000, v101
	v_mul_f32_e32 v200, v214, v200
	v_mul_f32_e32 v201, v214, v201
	v_mul_f32_e32 v202, v214, v202
	v_mul_f32_e32 v203, v214, v203
	v_mul_f32_e32 v204, v215, v204
	v_mul_f32_e32 v205, v215, v205
	v_mul_f32_e32 v206, v215, v206
	v_mul_f32_e32 v207, v215, v207
	v_fmac_f32_e32 v8, v136, v200
	v_fmac_f32_e32 v9, v137, v201
	v_fmac_f32_e32 v10, v138, v202
	v_fmac_f32_e32 v11, v139, v203
	v_fmac_f32_e32 v8, v168, v204
	v_fmac_f32_e32 v9, v169, v205
	v_fmac_f32_e32 v10, v170, v206
	v_fmac_f32_e32 v11, v171, v207
	global_store_dwordx4 v192, v[8:11], s[18:19] offset:2048 nt
	v_lshlrev_b32_e32 v200, 16, v70
	v_and_b32_e32 v201, 0xffff0000, v70
	v_lshlrev_b32_e32 v202, 16, v71
	v_and_b32_e32 v203, 0xffff0000, v71
; __device__ __forceinline__ float bf_lo(unsigned w) { return __uint_as_float(w << 16); }
; __device__ __forceinline__ float bf_hi(unsigned w) { return __uint_as_float(w & 0xffff0000u); }
; __global__ void __launch_bounds__(NWAVES * 64, 2) mk_fwd(Args args) {
;     ...
;             for (int q = 0; q < 2; ++q) { const int row = row0 + q; load_row_f32(args.out + (size_t)row * DM, F.lane, v[q]);
;                 const bf16_t* yr = Y + (size_t)row * DM;
; #pragma unroll
;                 for (int j = 0; j < 8; ++j) yw[q][j] = *(const u32x2*)(yr + 4 * F.lane + 256 * j); }
;     ...
;                 for (int j = 0; j < 8; ++j) { const int col = 4 * F.lane + 256 * j;
;                     const f32x4 y4 = (f32x4){bf_lo(yw[q][j].x), bf_hi(yw[q][j].x), bf_lo(yw[q][j].y), bf_hi(yw[q][j].y)};
;                     *(f32x4*)(args.out + (size_t)row * DM + col) = v[q][j] + PA[j] * (y4 * rsy); }
	v_lshlrev_b32_e32 v204, 16, v102
	v_and_b32_e32 v205, 0xffff0000, v102
	v_lshlrev_b32_e32 v206, 16, v103
	v_and_b32_e32 v207, 0xffff0000, v103
	v_mul_f32_e32 v200, v214, v200
	v_mul_f32_e32 v201, v214, v201
	v_mul_f32_e32 v202, v214, v202
	v_mul_f32_e32 v203, v214, v203
	v_mul_f32_e32 v204, v215, v204
	v_mul_f32_e32 v205, v215, v205
	v_mul_f32_e32 v206, v215, v206
	v_mul_f32_e32 v207, v215, v207
	v_fmac_f32_e32 v12, v140, v200
	v_fmac_f32_e32 v13, v141, v201
	v_fmac_f32_e32 v14, v142, v202
	v_fmac_f32_e32 v15, v143, v203
	v_fmac_f32_e32 v12, v172, v204
	v_fmac_f32_e32 v13, v173, v205
	v_fmac_f32_e32 v14, v174, v206
	v_fmac_f32_e32 v15, v175, v207
	global_store_dwordx4 v192, v[12:15], s[18:19] offset:3072 nt
	v_lshlrev_b32_e32 v200, 16, v72
	v_and_b32_e32 v201, 0xffff0000, v72
	v_lshlrev_b32_e32 v202, 16, v73
	v_and_b32_e32 v203, 0xffff0000, v73
	v_lshlrev_b32_e32 v204, 16, v104
	v_and_b32_e32 v205, 0xffff0000, v104
	v_lshlrev_b32_e32 v206, 16, v105
	v_and_b32_e32 v207, 0xffff0000, v105
	v_mul_f32_e32 v200, v214, v200
	v_mul_f32_e32 v201, v214, v201
	v_mul_f32_e32 v202, v214, v202
	v_mul_f32_e32 v203, v214, v203
	v_mul_f32_e32 v204, v215, v204
	v_mul_f32_e32 v205, v215, v205
	v_mul_f32_e32 v206, v215, v206
	v_mul_f32_e32 v207, v215, v207
	v_fmac_f32_e32 v16, v144, v200
	v_fmac_f32_e32 v17, v145, v201
	v_fmac_f32_e32 v18, v146, v202
	v_fmac_f32_e32 v19, v147, v203
	v_fmac_f32_e32 v16, v176, v204
	v_fmac_f32_e32 v17, v177, v205
	v_fmac_f32_e32 v18, v178, v206
	v_fmac_f32_e32 v19, v179, v207
	global_store_dwordx4 v193, v[16:19], s[18:19] offset:0 nt
	v_lshlrev_b32_e32 v200, 16, v74
	v_and_b32_e32 v201, 0xffff0000, v74
	v_lshlrev_b32_e32 v202, 16, v75
	v_and_b32_e32 v203, 0xffff0000, v75
	v_lshlrev_b32_e32 v204, 16, v106
	v_and_b32_e32 v205, 0xffff0000, v106
	v_lshlrev_b32_e32 v206, 16, v107
	v_and_b32_e32 v207, 0xffff0000, v107
	v_mul_f32_e32 v200, v214, v200
	v_mul_f32_e32 v201, v214, v201
	v_mul_f32_e32 v202, v214, v202
	v_mul_f32_e32 v203, v214, v203
	v_mul_f32_e32 v204, v215, v204
	v_mul_f32_e32 v205, v215, v205
	v_mul_f32_e32 v206, v215, v206
	v_mul_f32_e32 v207, v215, v207
	v_fmac_f32_e32 v20, v148, v200
	v_fmac_f32_e32 v21, v149, v201
	v_fmac_f32_e32 v22, v150, v202
	v_fmac_f32_e32 v23, v151, v203
	v_fmac_f32_e32 v20, v180, v204
	v_fmac_f32_e32 v21, v181, v205
	v_fmac_f32_e32 v22, v182, v206
	v_fmac_f32_e32 v23, v183, v207
	global_store_dwordx4 v193, v[20:23], s[18:19] offset:1024 nt
	v_lshlrev_b32_e32 v200, 16, v76
	v_and_b32_e32 v201, 0xffff0000, v76
	v_lshlrev_b32_e32 v202, 16, v77
	v_and_b32_e32 v203, 0xffff0000, v77
	v_lshlrev_b32_e32 v204, 16, v108
	v_and_b32_e32 v205, 0xffff0000, v108
	v_lshlrev_b32_e32 v206, 16, v109
	v_and_b32_e32 v207, 0xffff0000, v109
	v_mul_f32_e32 v200, v214, v200
	v_mul_f32_e32 v201, v214, v201
	v_mul_f32_e32 v202, v214, v202
	v_mul_f32_e32 v203, v214, v203
	v_mul_f32_e32 v204, v215, v204
	v_mul_f32_e32 v205, v215, v205
	v_mul_f32_e32 v206, v215, v206
	v_mul_f32_e32 v207, v215, v207
	v_fmac_f32_e32 v24, v152, v200
	v_fmac_f32_e32 v25, v153, v201
	v_fmac_f32_e32 v26, v154, v202
	v_fmac_f32_e32 v27, v155, v203
	v_fmac_f32_e32 v24, v184, v204
	v_fmac_f32_e32 v25, v185, v205
	v_fmac_f32_e32 v26, v186, v206
	v_fmac_f32_e32 v27, v187, v207
	global_store_dwordx4 v193, v[24:27], s[18:19] offset:2048 nt
	v_lshlrev_b32_e32 v200, 16, v78
	v_and_b32_e32 v201, 0xffff0000, v78
	v_lshlrev_b32_e32 v202, 16, v79
	v_and_b32_e32 v203, 0xffff0000, v79
	v_lshlrev_b32_e32 v204, 16, v110
	v_and_b32_e32 v205, 0xffff0000, v110
	v_lshlrev_b32_e32 v206, 16, v111
	v_and_b32_e32 v207, 0xffff0000, v111
	v_mul_f32_e32 v200, v214, v200
	v_mul_f32_e32 v201, v214, v201
	v_mul_f32_e32 v202, v214, v202
	v_mul_f32_e32 v203, v214, v203
	v_mul_f32_e32 v204, v215, v204
	v_mul_f32_e32 v205, v215, v205
	v_mul_f32_e32 v206, v215, v206
	v_mul_f32_e32 v207, v215, v207
	v_fmac_f32_e32 v28, v156, v200
	v_fmac_f32_e32 v29, v157, v201
	v_fmac_f32_e32 v30, v158, v202
	v_fmac_f32_e32 v31, v159, v203
	v_fmac_f32_e32 v28, v188, v204
	v_fmac_f32_e32 v29, v189, v205
	v_fmac_f32_e32 v30, v190, v206
	v_fmac_f32_e32 v31, v191, v207
	global_store_dwordx4 v193, v[28:31], s[18:19] offset:3072 nt
	s_add_u32 s18, s18, 0x2000
	s_addc_u32 s19, s19, 0
	global_load_dwordx4 v[0:3], v192, s[14:15] offset:0 nt
	global_load_dwordx4 v[4:7], v192, s[14:15] offset:1024 nt
	global_load_dwordx4 v[8:11], v192, s[14:15] offset:2048 nt
	global_load_dwordx4 v[12:15], v192, s[14:15] offset:3072 nt
	global_load_dwordx4 v[16:19], v193, s[14:15] offset:0 nt
	global_load_dwordx4 v[20:23], v193, s[14:15] offset:1024 nt
	global_load_dwordx4 v[24:27], v193, s[14:15] offset:2048 nt
	global_load_dwordx4 v[28:31], v193, s[14:15] offset:3072 nt
	global_load_dwordx2 v[64:65], v194, s[16:17] offset:0
	global_load_dwordx2 v[66:67], v194, s[16:17] offset:512
	global_load_dwordx2 v[68:69], v194, s[16:17] offset:1024
	global_load_dwordx2 v[70:71], v194, s[16:17] offset:1536
	global_load_dwordx2 v[72:73], v194, s[16:17] offset:2048
	global_load_dwordx2 v[74:75], v194, s[16:17] offset:2560
	global_load_dwordx2 v[76:77], v194, s[16:17] offset:3072
	global_load_dwordx2 v[78:79], v194, s[16:17] offset:3584
	global_load_dwordx2 v[96:97], v194, s[22:23] offset:0
	global_load_dwordx2 v[98:99], v194, s[22:23] offset:512
	global_load_dwordx2 v[100:101], v194, s[22:23] offset:1024
	global_load_dwordx2 v[102:103], v194, s[22:23] offset:1536
	global_load_dwordx2 v[104:105], v194, s[22:23] offset:2048
	global_load_dwordx2 v[106:107], v194, s[22:23] offset:2560
	global_load_dwordx2 v[108:109], v194, s[22:23] offset:3072
	global_load_dwordx2 v[110:111], v194, s[22:23] offset:3584
	s_add_u32 s14, s14, 0x2000
	s_addc_u32 s15, s15, 0
	s_add_u32 s16, s16, 0x1000
	s_addc_u32 s17, s17, 0
	s_add_u32 s22, s22, 0x1000
	s_addc_u32 s23, s23, 0
	s_waitcnt vmcnt(32)
; __device__ __forceinline__ float bf_lo(unsigned w) { return __uint_as_float(w << 16); }
; __device__ __forceinline__ float bf_hi(unsigned w) { return __uint_as_float(w & 0xffff0000u); }
; __global__ void __launch_bounds__(NWAVES * 64, 2) mk_fwd(Args args) {
;     ...
;                 float sy = 0.f;
; #pragma unroll
;                 for (int j = 0; j < 8; ++j) { const float a = bf_lo(yw[q][j].x), b = bf_hi(yw[q][j].x), c2 = bf_lo(yw[q][j].y), d = bf_hi(yw[q][j].y); sy += (a * a + b * b) + (c2 * c2 + d * d); }
;                 const float rsy = __builtin_amdgcn_rsqf(wave_sum(sy) * (1.f / DM) + EPS);
	v_lshlrev_b32_e32 v200, 16, v80
	v_and_b32_e32 v201, 0xffff0000, v80
	v_lshlrev_b32_e32 v202, 16, v81
	v_and_b32_e32 v203, 0xffff0000, v81
	v_mul_f32_e32 v208, v200, v200
	v_mul_f32_e32 v209, v201, v201
	v_fmac_f32_e32 v208, v202, v202
	v_fmac_f32_e32 v209, v203, v203
	v_lshlrev_b32_e32 v204, 16, v112
	v_and_b32_e32 v205, 0xffff0000, v112
	v_lshlrev_b32_e32 v206, 16, v113
	v_and_b32_e32 v207, 0xffff0000, v113
	v_mul_f32_e32 v210, v204, v204
	v_mul_f32_e32 v211, v205, v205
	v_fmac_f32_e32 v210, v206, v206
	v_fmac_f32_e32 v211, v207, v207
	v_lshlrev_b32_e32 v200, 16, v82
	v_and_b32_e32 v201, 0xffff0000, v82
	v_lshlrev_b32_e32 v202, 16, v83
	v_and_b32_e32 v203, 0xffff0000, v83
	v_fmac_f32_e32 v208, v200, v200
	v_fmac_f32_e32 v209, v201, v201
	v_fmac_f32_e32 v208, v202, v202
	v_fmac_f32_e32 v209, v203, v203
	v_lshlrev_b32_e32 v204, 16, v114
	v_and_b32_e32 v205, 0xffff0000, v114
	v_lshlrev_b32_e32 v206, 16, v115
	v_and_b32_e32 v207, 0xffff0000, v115
	v_fmac_f32_e32 v210, v204, v204
	v_fmac_f32_e32 v211, v205, v205
	v_fmac_f32_e32 v210, v206, v206
	v_fmac_f32_e32 v211, v207, v207
	v_lshlrev_b32_e32 v200, 16, v84
	v_and_b32_e32 v201, 0xffff0000, v84
	v_lshlrev_b32_e32 v202, 16, v85
	v_and_b32_e32 v203, 0xffff0000, v85
	v_fmac_f32_e32 v208, v200, v200
	v_fmac_f32_e32 v209, v201, v201
	v_fmac_f32_e32 v208, v202, v202
	v_fmac_f32_e32 v209, v203, v203
	v_lshlrev_b32_e32 v204, 16, v116
	v_and_b32_e32 v205, 0xffff0000, v116
	v_lshlrev_b32_e32 v206, 16, v117
	v_and_b32_e32 v207, 0xffff0000, v117
	v_fmac_f32_e32 v210, v204, v204
	v_fmac_f32_e32 v211, v205, v205
	v_fmac_f32_e32 v210, v206, v206
	v_fmac_f32_e32 v211, v207, v207
	v_lshlrev_b32_e32 v200, 16, v86
	v_and_b32_e32 v201, 0xffff0000, v86
	v_lshlrev_b32_e32 v202, 16, v87
	v_and_b32_e32 v203, 0xffff0000, v87
	v_fmac_f32_e32 v208, v200, v200
	v_fmac_f32_e32 v209, v201, v201
	v_fmac_f32_e32 v208, v202, v202
	v_fmac_f32_e32 v209, v203, v203
	v_lshlrev_b32_e32 v204, 16, v118
	v_and_b32_e32 v205, 0xffff0000, v118
	v_lshlrev_b32_e32 v206, 16, v119
	v_and_b32_e32 v207, 0xffff0000, v119
	v_fmac_f32_e32 v210, v204, v204
	v_fmac_f32_e32 v211, v205, v205
	v_fmac_f32_e32 v210, v206, v206
	v_fmac_f32_e32 v211, v207, v207
	v_lshlrev_b32_e32 v200, 16, v88
	v_and_b32_e32 v201, 0xffff0000, v88
	v_lshlrev_b32_e32 v202, 16, v89
	v_and_b32_e32 v203, 0xffff0000, v89
	v_fmac_f32_e32 v208, v200, v200
	v_fmac_f32_e32 v209, v201, v201
	v_fmac_f32_e32 v208, v202, v202
	v_fmac_f32_e32 v209, v203, v203
	v_lshlrev_b32_e32 v204, 16, v120
	v_and_b32_e32 v205, 0xffff0000, v120
	v_lshlrev_b32_e32 v206, 16, v121
	v_and_b32_e32 v207, 0xffff0000, v121
	v_fmac_f32_e32 v210, v204, v204
	v_fmac_f32_e32 v211, v205, v205
	v_fmac_f32_e32 v210, v206, v206
	v_fmac_f32_e32 v211, v207, v207
	v_lshlrev_b32_e32 v200, 16, v90
	v_and_b32_e32 v201, 0xffff0000, v90
	v_lshlrev_b32_e32 v202, 16, v91
	v_and_b32_e32 v203, 0xffff0000, v91
	v_fmac_f32_e32 v208, v200, v200
	v_fmac_f32_e32 v209, v201, v201
	v_fmac_f32_e32 v208, v202, v202
	v_fmac_f32_e32 v209, v203, v203
	v_lshlrev_b32_e32 v204, 16, v122
	v_and_b32_e32 v205, 0xffff0000, v122
	v_lshlrev_b32_e32 v206, 16, v123
	v_and_b32_e32 v207, 0xffff0000, v123
	v_fmac_f32_e32 v210, v204, v204
	v_fmac_f32_e32 v211, v205, v205
	v_fmac_f32_e32 v210, v206, v206
	v_fmac_f32_e32 v211, v207, v207
	v_lshlrev_b32_e32 v200, 16, v92
	v_and_b32_e32 v201, 0xffff0000, v92
	v_lshlrev_b32_e32 v202, 16, v93
	v_and_b32_e32 v203, 0xffff0000, v93
	v_fmac_f32_e32 v208, v200, v200
	v_fmac_f32_e32 v209, v201, v201
	v_fmac_f32_e32 v208, v202, v202
	v_fmac_f32_e32 v209, v203, v203
	v_lshlrev_b32_e32 v204, 16, v124
	v_and_b32_e32 v205, 0xffff0000, v124
	v_lshlrev_b32_e32 v206, 16, v125
	v_and_b32_e32 v207, 0xffff0000, v125
	v_fmac_f32_e32 v210, v204, v204
	v_fmac_f32_e32 v211, v205, v205
	v_fmac_f32_e32 v210, v206, v206
	v_fmac_f32_e32 v211, v207, v207
	v_lshlrev_b32_e32 v200, 16, v94
	v_and_b32_e32 v201, 0xffff0000, v94
	v_lshlrev_b32_e32 v202, 16, v95
	v_and_b32_e32 v203, 0xffff0000, v95
	v_fmac_f32_e32 v208, v200, v200
	v_fmac_f32_e32 v209, v201, v201
	v_fmac_f32_e32 v208, v202, v202
	v_fmac_f32_e32 v209, v203, v203
	v_lshlrev_b32_e32 v204, 16, v126
	v_and_b32_e32 v205, 0xffff0000, v126
	v_lshlrev_b32_e32 v206, 16, v127
	v_and_b32_e32 v207, 0xffff0000, v127
	v_fmac_f32_e32 v210, v204, v204
	v_fmac_f32_e32 v211, v205, v205
	v_fmac_f32_e32 v210, v206, v206
	v_fmac_f32_e32 v211, v207, v207
	v_add_f32_e32 v208, v208, v209
	v_add_f32_e32 v210, v210, v211
	s_nop 0
	v_add_f32_dpp v212, v208, v208 quad_perm:[1,0,3,2] row_mask:0xf bank_mask:0xf
	v_add_f32_dpp v213, v210, v210 quad_perm:[1,0,3,2] row_mask:0xf bank_mask:0xf
	s_nop 0
	v_add_f32_dpp v212, v212, v212 quad_perm:[2,3,0,1] row_mask:0xf bank_mask:0xf
	v_add_f32_dpp v213, v213, v213 quad_perm:[2,3,0,1] row_mask:0xf bank_mask:0xf
	s_nop 0
	v_add_f32_dpp v212, v212, v212 row_half_mirror row_mask:0xf bank_mask:0xf
	v_add_f32_dpp v213, v213, v213 row_half_mirror row_mask:0xf bank_mask:0xf
	s_nop 0
	v_add_f32_dpp v212, v212, v212 row_mirror row_mask:0xf bank_mask:0xf
	v_add_f32_dpp v213, v213, v213 row_mirror row_mask:0xf bank_mask:0xf
	s_nop 0
	v_readlane_b32 s4, v212, 0
	v_readlane_b32 s5, v212, 16
	v_readlane_b32 s6, v212, 32
	v_readlane_b32 s7, v212, 48
	v_readlane_b32 s24, v213, 0
	v_readlane_b32 s25, v213, 16
	v_readlane_b32 s26, v213, 32
	v_readlane_b32 s27, v213, 48
	s_nop 1
	v_mov_b32_e32 v214, s4
	v_mov_b32_e32 v215, s24
	v_add_f32_e32 v214, s5, v214
	v_add_f32_e32 v215, s25, v215
	v_add_f32_e32 v214, s6, v214
	v_add_f32_e32 v215, s26, v215
	v_add_f32_e32 v214, s7, v214
	v_add_f32_e32 v215, s27, v215
	v_fmamk_f32 v214, v214, 0x3a000000, v195
	v_fmamk_f32 v215, v215, 0x3a000000, v195
; __device__ __forceinline__ float bf_lo(unsigned w) { return __uint_as_float(w << 16); }
; __device__ __forceinline__ float bf_hi(unsigned w) { return __uint_as_float(w & 0xffff0000u); }
; __global__ void __launch_bounds__(NWAVES * 64, 2) mk_fwd(Args args) {
;     ...
;                 const float rsy = __builtin_amdgcn_rsqf(wave_sum(sy) * (1.f / DM) + EPS);
; #pragma unroll
;                 for (int j = 0; j < 8; ++j) { const int col = 4 * F.lane + 256 * j;
;                     const f32x4 y4 = (f32x4){bf_lo(yw[q][j].x), bf_hi(yw[q][j].x), bf_lo(yw[q][j].y), bf_hi(yw[q][j].y)};
;                     *(f32x4*)(args.out + (size_t)row * DM + col) = v[q][j] + PA[j] * (y4 * rsy); }
	v_rsq_f32_e32 v214, v214
	v_rsq_f32_e32 v215, v215
	s_nop 0
	v_lshlrev_b32_e32 v200, 16, v80
	v_and_b32_e32 v201, 0xffff0000, v80
	v_lshlrev_b32_e32 v202, 16, v81
	v_and_b32_e32 v203, 0xffff0000, v81
	v_lshlrev_b32_e32 v204, 16, v112
	v_and_b32_e32 v205, 0xffff0000, v112
	v_lshlrev_b32_e32 v206, 16, v113
	v_and_b32_e32 v207, 0xffff0000, v113
	v_mul_f32_e32 v200, v214, v200
	v_mul_f32_e32 v201, v214, v201
	v_mul_f32_e32 v202, v214, v202
	v_mul_f32_e32 v203, v214, v203
	v_mul_f32_e32 v204, v215, v204
	v_mul_f32_e32 v205, v215, v205
	v_mul_f32_e32 v206, v215, v206
	v_mul_f32_e32 v207, v215, v207
	v_fmac_f32_e32 v32, v128, v200
	v_fmac_f32_e32 v33, v129, v201
	v_fmac_f32_e32 v34, v130, v202
	v_fmac_f32_e32 v35, v131, v203
	v_fmac_f32_e32 v32, v160, v204
	v_fmac_f32_e32 v33, v161, v205
	v_fmac_f32_e32 v34, v162, v206
	v_fmac_f32_e32 v35, v163, v207
	global_store_dwordx4 v192, v[32:35], s[18:19] offset:0 nt
	v_lshlrev_b32_e32 v200, 16, v82
	v_and_b32_e32 v201, 0xffff0000, v82
	v_lshlrev_b32_e32 v202, 16, v83
	v_and_b32_e32 v203, 0xffff0000, v83
	v_lshlrev_b32_e32 v204, 16, v114
	v_and_b32_e32 v205, 0xffff0000, v114
	v_lshlrev_b32_e32 v206, 16, v115
	v_and_b32_e32 v207, 0xffff0000, v115
	v_mul_f32_e32 v200, v214, v200
	v_mul_f32_e32 v201, v214, v201
	v_mul_f32_e32 v202, v214, v202
	v_mul_f32_e32 v203, v214, v203
	v_mul_f32_e32 v204, v215, v204
	v_mul_f32_e32 v205, v215, v205
	v_mul_f32_e32 v206, v215, v206
	v_mul_f32_e32 v207, v215, v207
	v_fmac_f32_e32 v36, v132, v200
	v_fmac_f32_e32 v37, v133, v201
	v_fmac_f32_e32 v38, v134, v202
	v_fmac_f32_e32 v39, v135, v203
	v_fmac_f32_e32 v36, v164, v204
	v_fmac_f32_e32 v37, v165, v205
	v_fmac_f32_e32 v38, v166, v206
	v_fmac_f32_e32 v39, v167, v207
	global_store_dwordx4 v192, v[36:39], s[18:19] offset:1024 nt
	v_lshlrev_b32_e32 v200, 16, v84
	v_and_b32_e32 v201, 0xffff0000, v84
	v_lshlrev_b32_e32 v202, 16, v85
	v_and_b32_e32 v203, 0xffff0000, v85
	v_lshlrev_b32_e32 v204, 16, v116
	v_and_b32_e32 v205, 0xffff0000, v116
	v_lshlrev_b32_e32 v206, 16, v117
	v_and_b32_e32 v207, 0xffff0000, v117
	v_mul_f32_e32 v200, v214, v200
	v_mul_f32_e32 v201, v214, v201
	v_mul_f32_e32 v202, v214, v202
	v_mul_f32_e32 v203, v214, v203
	v_mul_f32_e32 v204, v215, v204
	v_mul_f32_e32 v205, v215, v205
	v_mul_f32_e32 v206, v215, v206
	v_mul_f32_e32 v207, v215, v207
	v_fmac_f32_e32 v40, v136, v200
	v_fmac_f32_e32 v41, v137, v201
	v_fmac_f32_e32 v42, v138, v202
	v_fmac_f32_e32 v43, v139, v203
	v_fmac_f32_e32 v40, v168, v204
	v_fmac_f32_e32 v41, v169, v205
	v_fmac_f32_e32 v42, v170, v206
	v_fmac_f32_e32 v43, v171, v207
	global_store_dwordx4 v192, v[40:43], s[18:19] offset:2048 nt
	v_lshlrev_b32_e32 v200, 16, v86
	v_and_b32_e32 v201, 0xffff0000, v86
	v_lshlrev_b32_e32 v202, 16, v87
	v_and_b32_e32 v203, 0xffff0000, v87
	v_lshlrev_b32_e32 v204, 16, v118
	v_and_b32_e32 v205, 0xffff0000, v118
	v_lshlrev_b32_e32 v206, 16, v119
	v_and_b32_e32 v207, 0xffff0000, v119
	v_mul_f32_e32 v200, v214, v200
	v_mul_f32_e32 v201, v214, v201
	v_mul_f32_e32 v202, v214, v202
	v_mul_f32_e32 v203, v214, v203
	v_mul_f32_e32 v204, v215, v204
	v_mul_f32_e32 v205, v215, v205
	v_mul_f32_e32 v206, v215, v206
	v_mul_f32_e32 v207, v215, v207
	v_fmac_f32_e32 v44, v140, v200
	v_fmac_f32_e32 v45, v141, v201
	v_fmac_f32_e32 v46, v142, v202
	v_fmac_f32_e32 v47, v143, v203
	v_fmac_f32_e32 v44, v172, v204
	v_fmac_f32_e32 v45, v173, v205
	v_fmac_f32_e32 v46, v174, v206
	v_fmac_f32_e32 v47, v175, v207
	global_store_dwordx4 v192, v[44:47], s[18:19] offset:3072 nt
	v_lshlrev_b32_e32 v200, 16, v88
	v_and_b32_e32 v201, 0xffff0000, v88
	v_lshlrev_b32_e32 v202, 16, v89
	v_and_b32_e32 v203, 0xffff0000, v89
	v_lshlrev_b32_e32 v204, 16, v120
	v_and_b32_e32 v205, 0xffff0000, v120
	v_lshlrev_b32_e32 v206, 16, v121
	v_and_b32_e32 v207, 0xffff0000, v121
	v_mul_f32_e32 v200, v214, v200
	v_mul_f32_e32 v201, v214, v201
	v_mul_f32_e32 v202, v214, v202
	v_mul_f32_e32 v203, v214, v203
	v_mul_f32_e32 v204, v215, v204
	v_mul_f32_e32 v205, v215, v205
	v_mul_f32_e32 v206, v215, v206
	v_mul_f32_e32 v207, v215, v207
	v_fmac_f32_e32 v48, v144, v200
	v_fmac_f32_e32 v49, v145, v201
	v_fmac_f32_e32 v50, v146, v202
	v_fmac_f32_e32 v51, v147, v203
	v_fmac_f32_e32 v48, v176, v204
	v_fmac_f32_e32 v49, v177, v205
	v_fmac_f32_e32 v50, v178, v206
	v_fmac_f32_e32 v51, v179, v207
	global_store_dwordx4 v193, v[48:51], s[18:19] offset:0 nt
	v_lshlrev_b32_e32 v200, 16, v90
	v_and_b32_e32 v201, 0xffff0000, v90
	v_lshlrev_b32_e32 v202, 16, v91
	v_and_b32_e32 v203, 0xffff0000, v91
	v_lshlrev_b32_e32 v204, 16, v122
	v_and_b32_e32 v205, 0xffff0000, v122
	v_lshlrev_b32_e32 v206, 16, v123
	v_and_b32_e32 v207, 0xffff0000, v123
	v_mul_f32_e32 v200, v214, v200
	v_mul_f32_e32 v201, v214, v201
	v_mul_f32_e32 v202, v214, v202
	v_mul_f32_e32 v203, v214, v203
	v_mul_f32_e32 v204, v215, v204
	v_mul_f32_e32 v205, v215, v205
	v_mul_f32_e32 v206, v215, v206
	v_mul_f32_e32 v207, v215, v207
	v_fmac_f32_e32 v52, v148, v200
	v_fmac_f32_e32 v53, v149, v201
	v_fmac_f32_e32 v54, v150, v202
	v_fmac_f32_e32 v55, v151, v203
	v_fmac_f32_e32 v52, v180, v204
	v_fmac_f32_e32 v53, v181, v205
	v_fmac_f32_e32 v54, v182, v206
	v_fmac_f32_e32 v55, v183, v207
	global_store_dwordx4 v193, v[52:55], s[18:19] offset:1024 nt
	v_lshlrev_b32_e32 v200, 16, v92
	v_and_b32_e32 v201, 0xffff0000, v92
	v_lshlrev_b32_e32 v202, 16, v93
	v_and_b32_e32 v203, 0xffff0000, v93
	v_lshlrev_b32_e32 v204, 16, v124
	v_and_b32_e32 v205, 0xffff0000, v124
	v_lshlrev_b32_e32 v206, 16, v125
	v_and_b32_e32 v207, 0xffff0000, v125
	v_mul_f32_e32 v200, v214, v200
	v_mul_f32_e32 v201, v214, v201
	v_mul_f32_e32 v202, v214, v202
	v_mul_f32_e32 v203, v214, v203
	v_mul_f32_e32 v204, v215, v204
; __device__ __forceinline__ float bf_lo(unsigned w) { return __uint_as_float(w << 16); }
; __device__ __forceinline__ float bf_hi(unsigned w) { return __uint_as_float(w & 0xffff0000u); }
; __global__ void __launch_bounds__(NWAVES * 64, 2) mk_fwd(Args args) {
;     ...
;             for (int q = 0; q < 2; ++q) { const int row = row0 + q; load_row_f32(args.out + (size_t)row * DM, F.lane, v[q]);
;                 const bf16_t* yr = Y + (size_t)row * DM;
; #pragma unroll
;                 for (int j = 0; j < 8; ++j) yw[q][j] = *(const u32x2*)(yr + 4 * F.lane + 256 * j); }
;     ...
;                 float sy = 0.f;
; #pragma unroll
;                 for (int j = 0; j < 8; ++j) { const float a = bf_lo(yw[q][j].x), b = bf_hi(yw[q][j].x), c2 = bf_lo(yw[q][j].y), d = bf_hi(yw[q][j].y); sy += (a * a + b * b) + (c2 * c2 + d * d); }
;     ...
;                 for (int j = 0; j < 8; ++j) { const int col = 4 * F.lane + 256 * j;
;                     const f32x4 y4 = (f32x4){bf_lo(yw[q][j].x), bf_hi(yw[q][j].x), bf_lo(yw[q][j].y), bf_hi(yw[q][j].y)};
;                     *(f32x4*)(args.out + (size_t)row * DM + col) = v[q][j] + PA[j] * (y4 * rsy); }
	v_mul_f32_e32 v205, v215, v205
	v_mul_f32_e32 v206, v215, v206
	v_mul_f32_e32 v207, v215, v207
	v_fmac_f32_e32 v56, v152, v200
	v_fmac_f32_e32 v57, v153, v201
	v_fmac_f32_e32 v58, v154, v202
	v_fmac_f32_e32 v59, v155, v203
	v_fmac_f32_e32 v56, v184, v204
	v_fmac_f32_e32 v57, v185, v205
	v_fmac_f32_e32 v58, v186, v206
	v_fmac_f32_e32 v59, v187, v207
	global_store_dwordx4 v193, v[56:59], s[18:19] offset:2048 nt
	v_lshlrev_b32_e32 v200, 16, v94
	v_and_b32_e32 v201, 0xffff0000, v94
	v_lshlrev_b32_e32 v202, 16, v95
	v_and_b32_e32 v203, 0xffff0000, v95
	v_lshlrev_b32_e32 v204, 16, v126
	v_and_b32_e32 v205, 0xffff0000, v126
	v_lshlrev_b32_e32 v206, 16, v127
	v_and_b32_e32 v207, 0xffff0000, v127
	v_mul_f32_e32 v200, v214, v200
	v_mul_f32_e32 v201, v214, v201
	v_mul_f32_e32 v202, v214, v202
	v_mul_f32_e32 v203, v214, v203
	v_mul_f32_e32 v204, v215, v204
	v_mul_f32_e32 v205, v215, v205
	v_mul_f32_e32 v206, v215, v206
	v_mul_f32_e32 v207, v215, v207
	v_fmac_f32_e32 v60, v156, v200
	v_fmac_f32_e32 v61, v157, v201
	v_fmac_f32_e32 v62, v158, v202
	v_fmac_f32_e32 v63, v159, v203
	v_fmac_f32_e32 v60, v188, v204
	v_fmac_f32_e32 v61, v189, v205
	v_fmac_f32_e32 v62, v190, v206
	v_fmac_f32_e32 v63, v191, v207
	global_store_dwordx4 v193, v[60:63], s[18:19] offset:3072 nt
	s_add_u32 s18, s18, 0x2000
	s_addc_u32 s19, s19, 0
	global_load_dwordx4 v[32:35], v192, s[14:15] offset:0 nt
	global_load_dwordx4 v[36:39], v192, s[14:15] offset:1024 nt
	global_load_dwordx4 v[40:43], v192, s[14:15] offset:2048 nt
	global_load_dwordx4 v[44:47], v192, s[14:15] offset:3072 nt
	global_load_dwordx4 v[48:51], v193, s[14:15] offset:0 nt
	global_load_dwordx4 v[52:55], v193, s[14:15] offset:1024 nt
	global_load_dwordx4 v[56:59], v193, s[14:15] offset:2048 nt
	global_load_dwordx4 v[60:63], v193, s[14:15] offset:3072 nt
	global_load_dwordx2 v[80:81], v194, s[16:17] offset:0
	global_load_dwordx2 v[82:83], v194, s[16:17] offset:512
	global_load_dwordx2 v[84:85], v194, s[16:17] offset:1024
	global_load_dwordx2 v[86:87], v194, s[16:17] offset:1536
	global_load_dwordx2 v[88:89], v194, s[16:17] offset:2048
	global_load_dwordx2 v[90:91], v194, s[16:17] offset:2560
	global_load_dwordx2 v[92:93], v194, s[16:17] offset:3072
	global_load_dwordx2 v[94:95], v194, s[16:17] offset:3584
	global_load_dwordx2 v[112:113], v194, s[22:23] offset:0
	global_load_dwordx2 v[114:115], v194, s[22:23] offset:512
	global_load_dwordx2 v[116:117], v194, s[22:23] offset:1024
	global_load_dwordx2 v[118:119], v194, s[22:23] offset:1536
	global_load_dwordx2 v[120:121], v194, s[22:23] offset:2048
	global_load_dwordx2 v[122:123], v194, s[22:23] offset:2560
	global_load_dwordx2 v[124:125], v194, s[22:23] offset:3072
	global_load_dwordx2 v[126:127], v194, s[22:23] offset:3584
	s_add_u32 s14, s14, 0x2000
	s_addc_u32 s15, s15, 0
	s_add_u32 s16, s16, 0x1000
	s_addc_u32 s17, s17, 0
	s_add_u32 s22, s22, 0x1000
	s_addc_u32 s23, s23, 0
	s_waitcnt vmcnt(32)
	v_lshlrev_b32_e32 v200, 16, v64
	v_and_b32_e32 v201, 0xffff0000, v64
	v_lshlrev_b32_e32 v202, 16, v65
	v_and_b32_e32 v203, 0xffff0000, v65
	v_mul_f32_e32 v208, v200, v200
	v_mul_f32_e32 v209, v201, v201
	v_fmac_f32_e32 v208, v202, v202
	v_fmac_f32_e32 v209, v203, v203
	v_lshlrev_b32_e32 v204, 16, v96
	v_and_b32_e32 v205, 0xffff0000, v96
	v_lshlrev_b32_e32 v206, 16, v97
	v_and_b32_e32 v207, 0xffff0000, v97
	v_mul_f32_e32 v210, v204, v204
	v_mul_f32_e32 v211, v205, v205
	v_fmac_f32_e32 v210, v206, v206
	v_fmac_f32_e32 v211, v207, v207
	v_lshlrev_b32_e32 v200, 16, v66
	v_and_b32_e32 v201, 0xffff0000, v66
	v_lshlrev_b32_e32 v202, 16, v67
	v_and_b32_e32 v203, 0xffff0000, v67
	v_fmac_f32_e32 v208, v200, v200
	v_fmac_f32_e32 v209, v201, v201
	v_fmac_f32_e32 v208, v202, v202
	v_fmac_f32_e32 v209, v203, v203
	v_lshlrev_b32_e32 v204, 16, v98
	v_and_b32_e32 v205, 0xffff0000, v98
	v_lshlrev_b32_e32 v206, 16, v99
	v_and_b32_e32 v207, 0xffff0000, v99
	v_fmac_f32_e32 v210, v204, v204
	v_fmac_f32_e32 v211, v205, v205
	v_fmac_f32_e32 v210, v206, v206
	v_fmac_f32_e32 v211, v207, v207
	v_lshlrev_b32_e32 v200, 16, v68
	v_and_b32_e32 v201, 0xffff0000, v68
	v_lshlrev_b32_e32 v202, 16, v69
	v_and_b32_e32 v203, 0xffff0000, v69
	v_fmac_f32_e32 v208, v200, v200
	v_fmac_f32_e32 v209, v201, v201
	v_fmac_f32_e32 v208, v202, v202
	v_fmac_f32_e32 v209, v203, v203
	v_lshlrev_b32_e32 v204, 16, v100
	v_and_b32_e32 v205, 0xffff0000, v100
	v_lshlrev_b32_e32 v206, 16, v101
	v_and_b32_e32 v207, 0xffff0000, v101
	v_fmac_f32_e32 v210, v204, v204
	v_fmac_f32_e32 v211, v205, v205
	v_fmac_f32_e32 v210, v206, v206
	v_fmac_f32_e32 v211, v207, v207
	v_lshlrev_b32_e32 v200, 16, v70
	v_and_b32_e32 v201, 0xffff0000, v70
	v_lshlrev_b32_e32 v202, 16, v71
	v_and_b32_e32 v203, 0xffff0000, v71
	v_fmac_f32_e32 v208, v200, v200
	v_fmac_f32_e32 v209, v201, v201
	v_fmac_f32_e32 v208, v202, v202
	v_fmac_f32_e32 v209, v203, v203
	v_lshlrev_b32_e32 v204, 16, v102
	v_and_b32_e32 v205, 0xffff0000, v102
	v_lshlrev_b32_e32 v206, 16, v103
	v_and_b32_e32 v207, 0xffff0000, v103
	v_fmac_f32_e32 v210, v204, v204
	v_fmac_f32_e32 v211, v205, v205
	v_fmac_f32_e32 v210, v206, v206
	v_fmac_f32_e32 v211, v207, v207
	v_lshlrev_b32_e32 v200, 16, v72
	v_and_b32_e32 v201, 0xffff0000, v72
	v_lshlrev_b32_e32 v202, 16, v73
	v_and_b32_e32 v203, 0xffff0000, v73
	v_fmac_f32_e32 v208, v200, v200
	v_fmac_f32_e32 v209, v201, v201
	v_fmac_f32_e32 v208, v202, v202
	v_fmac_f32_e32 v209, v203, v203
	v_lshlrev_b32_e32 v204, 16, v104
	v_and_b32_e32 v205, 0xffff0000, v104
	v_lshlrev_b32_e32 v206, 16, v105
	v_and_b32_e32 v207, 0xffff0000, v105
	v_fmac_f32_e32 v210, v204, v204
	v_fmac_f32_e32 v211, v205, v205
	v_fmac_f32_e32 v210, v206, v206
	v_fmac_f32_e32 v211, v207, v207
; __device__ __forceinline__ float bf_lo(unsigned w) { return __uint_as_float(w << 16); }
; __device__ __forceinline__ float bf_hi(unsigned w) { return __uint_as_float(w & 0xffff0000u); }
; __global__ void __launch_bounds__(NWAVES * 64, 2) mk_fwd(Args args) {
;     ...
;                 for (int j = 0; j < 8; ++j) { const float a = bf_lo(yw[q][j].x), b = bf_hi(yw[q][j].x), c2 = bf_lo(yw[q][j].y), d = bf_hi(yw[q][j].y); sy += (a * a + b * b) + (c2 * c2 + d * d); }
;                 const float rsy = __builtin_amdgcn_rsqf(wave_sum(sy) * (1.f / DM) + EPS);
; #pragma unroll
;                 for (int j = 0; j < 8; ++j) { const int col = 4 * F.lane + 256 * j;
;                     const f32x4 y4 = (f32x4){bf_lo(yw[q][j].x), bf_hi(yw[q][j].x), bf_lo(yw[q][j].y), bf_hi(yw[q][j].y)};
;                     *(f32x4*)(args.out + (size_t)row * DM + col) = v[q][j] + PA[j] * (y4 * rsy); }
	v_lshlrev_b32_e32 v200, 16, v74
	v_and_b32_e32 v201, 0xffff0000, v74
	v_lshlrev_b32_e32 v202, 16, v75
	v_and_b32_e32 v203, 0xffff0000, v75
	v_fmac_f32_e32 v208, v200, v200
	v_fmac_f32_e32 v209, v201, v201
	v_fmac_f32_e32 v208, v202, v202
	v_fmac_f32_e32 v209, v203, v203
	v_lshlrev_b32_e32 v204, 16, v106
	v_and_b32_e32 v205, 0xffff0000, v106
	v_lshlrev_b32_e32 v206, 16, v107
	v_and_b32_e32 v207, 0xffff0000, v107
	v_fmac_f32_e32 v210, v204, v204
	v_fmac_f32_e32 v211, v205, v205
	v_fmac_f32_e32 v210, v206, v206
	v_fmac_f32_e32 v211, v207, v207
	v_lshlrev_b32_e32 v200, 16, v76
	v_and_b32_e32 v201, 0xffff0000, v76
	v_lshlrev_b32_e32 v202, 16, v77
	v_and_b32_e32 v203, 0xffff0000, v77
	v_fmac_f32_e32 v208, v200, v200
	v_fmac_f32_e32 v209, v201, v201
	v_fmac_f32_e32 v208, v202, v202
	v_fmac_f32_e32 v209, v203, v203
	v_lshlrev_b32_e32 v204, 16, v108
	v_and_b32_e32 v205, 0xffff0000, v108
	v_lshlrev_b32_e32 v206, 16, v109
	v_and_b32_e32 v207, 0xffff0000, v109
	v_fmac_f32_e32 v210, v204, v204
	v_fmac_f32_e32 v211, v205, v205
	v_fmac_f32_e32 v210, v206, v206
	v_fmac_f32_e32 v211, v207, v207
	v_lshlrev_b32_e32 v200, 16, v78
	v_and_b32_e32 v201, 0xffff0000, v78
	v_lshlrev_b32_e32 v202, 16, v79
	v_and_b32_e32 v203, 0xffff0000, v79
	v_fmac_f32_e32 v208, v200, v200
	v_fmac_f32_e32 v209, v201, v201
	v_fmac_f32_e32 v208, v202, v202
	v_fmac_f32_e32 v209, v203, v203
	v_lshlrev_b32_e32 v204, 16, v110
	v_and_b32_e32 v205, 0xffff0000, v110
	v_lshlrev_b32_e32 v206, 16, v111
	v_and_b32_e32 v207, 0xffff0000, v111
	v_fmac_f32_e32 v210, v204, v204
	v_fmac_f32_e32 v211, v205, v205
	v_fmac_f32_e32 v210, v206, v206
	v_fmac_f32_e32 v211, v207, v207
	v_add_f32_e32 v208, v208, v209
	v_add_f32_e32 v210, v210, v211
	s_nop 0
	v_add_f32_dpp v212, v208, v208 quad_perm:[1,0,3,2] row_mask:0xf bank_mask:0xf
	v_add_f32_dpp v213, v210, v210 quad_perm:[1,0,3,2] row_mask:0xf bank_mask:0xf
	s_nop 0
	v_add_f32_dpp v212, v212, v212 quad_perm:[2,3,0,1] row_mask:0xf bank_mask:0xf
	v_add_f32_dpp v213, v213, v213 quad_perm:[2,3,0,1] row_mask:0xf bank_mask:0xf
	s_nop 0
	v_add_f32_dpp v212, v212, v212 row_half_mirror row_mask:0xf bank_mask:0xf
	v_add_f32_dpp v213, v213, v213 row_half_mirror row_mask:0xf bank_mask:0xf
	s_nop 0
	v_add_f32_dpp v212, v212, v212 row_mirror row_mask:0xf bank_mask:0xf
	v_add_f32_dpp v213, v213, v213 row_mirror row_mask:0xf bank_mask:0xf
	s_nop 0
	v_readlane_b32 s4, v212, 0
	v_readlane_b32 s5, v212, 16
	v_readlane_b32 s6, v212, 32
	v_readlane_b32 s7, v212, 48
	v_readlane_b32 s24, v213, 0
	v_readlane_b32 s25, v213, 16
	v_readlane_b32 s26, v213, 32
	v_readlane_b32 s27, v213, 48
	s_nop 1
	v_mov_b32_e32 v214, s4
	v_mov_b32_e32 v215, s24
	v_add_f32_e32 v214, s5, v214
	v_add_f32_e32 v215, s25, v215
	v_add_f32_e32 v214, s6, v214
	v_add_f32_e32 v215, s26, v215
	v_add_f32_e32 v214, s7, v214
	v_add_f32_e32 v215, s27, v215
	v_fmamk_f32 v214, v214, 0x3a000000, v195
	v_fmamk_f32 v215, v215, 0x3a000000, v195
	v_rsq_f32_e32 v214, v214
	v_rsq_f32_e32 v215, v215
	s_nop 0
	v_lshlrev_b32_e32 v200, 16, v64
	v_and_b32_e32 v201, 0xffff0000, v64
	v_lshlrev_b32_e32 v202, 16, v65
	v_and_b32_e32 v203, 0xffff0000, v65
	v_lshlrev_b32_e32 v204, 16, v96
	v_and_b32_e32 v205, 0xffff0000, v96
	v_lshlrev_b32_e32 v206, 16, v97
	v_and_b32_e32 v207, 0xffff0000, v97
	v_mul_f32_e32 v200, v214, v200
	v_mul_f32_e32 v201, v214, v201
	v_mul_f32_e32 v202, v214, v202
	v_mul_f32_e32 v203, v214, v203
	v_mul_f32_e32 v204, v215, v204
	v_mul_f32_e32 v205, v215, v205
	v_mul_f32_e32 v206, v215, v206
	v_mul_f32_e32 v207, v215, v207
	v_fmac_f32_e32 v0, v128, v200
	v_fmac_f32_e32 v1, v129, v201
	v_fmac_f32_e32 v2, v130, v202
	v_fmac_f32_e32 v3, v131, v203
	v_fmac_f32_e32 v0, v160, v204
	v_fmac_f32_e32 v1, v161, v205
	v_fmac_f32_e32 v2, v162, v206
	v_fmac_f32_e32 v3, v163, v207
	global_store_dwordx4 v192, v[0:3], s[18:19] offset:0 nt
	v_lshlrev_b32_e32 v200, 16, v66
	v_and_b32_e32 v201, 0xffff0000, v66
	v_lshlrev_b32_e32 v202, 16, v67
	v_and_b32_e32 v203, 0xffff0000, v67
	v_lshlrev_b32_e32 v204, 16, v98
	v_and_b32_e32 v205, 0xffff0000, v98
	v_lshlrev_b32_e32 v206, 16, v99
	v_and_b32_e32 v207, 0xffff0000, v99
	v_mul_f32_e32 v200, v214, v200
	v_mul_f32_e32 v201, v214, v201
	v_mul_f32_e32 v202, v214, v202
	v_mul_f32_e32 v203, v214, v203
	v_mul_f32_e32 v204, v215, v204
	v_mul_f32_e32 v205, v215, v205
	v_mul_f32_e32 v206, v215, v206
	v_mul_f32_e32 v207, v215, v207
	v_fmac_f32_e32 v4, v132, v200
	v_fmac_f32_e32 v5, v133, v201
	v_fmac_f32_e32 v6, v134, v202
	v_fmac_f32_e32 v7, v135, v203
	v_fmac_f32_e32 v4, v164, v204
	v_fmac_f32_e32 v5, v165, v205
	v_fmac_f32_e32 v6, v166, v206
	v_fmac_f32_e32 v7, v167, v207
	global_store_dwordx4 v192, v[4:7], s[18:19] offset:1024 nt
	v_lshlrev_b32_e32 v200, 16, v68
	v_and_b32_e32 v201, 0xffff0000, v68
	v_lshlrev_b32_e32 v202, 16, v69
	v_and_b32_e32 v203, 0xffff0000, v69
	v_lshlrev_b32_e32 v204, 16, v100
	v_and_b32_e32 v205, 0xffff0000, v100
	v_lshlrev_b32_e32 v206, 16, v101
	v_and_b32_e32 v207, 0xffff0000, v101
	v_mul_f32_e32 v200, v214, v200
	v_mul_f32_e32 v201, v214, v201
	v_mul_f32_e32 v202, v214, v202
	v_mul_f32_e32 v203, v214, v203
	v_mul_f32_e32 v204, v215, v204
	v_mul_f32_e32 v205, v215, v205
	v_mul_f32_e32 v206, v215, v206
	v_mul_f32_e32 v207, v215, v207
	v_fmac_f32_e32 v8, v136, v200
	v_fmac_f32_e32 v9, v137, v201
	v_fmac_f32_e32 v10, v138, v202
	v_fmac_f32_e32 v11, v139, v203
	v_fmac_f32_e32 v8, v168, v204
	v_fmac_f32_e32 v9, v169, v205
	v_fmac_f32_e32 v10, v170, v206
	v_fmac_f32_e32 v11, v171, v207
	global_store_dwordx4 v192, v[8:11], s[18:19] offset:2048 nt
	v_lshlrev_b32_e32 v200, 16, v70
	v_and_b32_e32 v201, 0xffff0000, v70
	v_lshlrev_b32_e32 v202, 16, v71
	v_and_b32_e32 v203, 0xffff0000, v71
; __device__ __forceinline__ float bf_lo(unsigned w) { return __uint_as_float(w << 16); }
; __device__ __forceinline__ float bf_hi(unsigned w) { return __uint_as_float(w & 0xffff0000u); }
; __global__ void __launch_bounds__(NWAVES * 64, 2) mk_fwd(Args args) {
;     ...
;                 float sy = 0.f;
; #pragma unroll
;                 for (int j = 0; j < 8; ++j) { const float a = bf_lo(yw[q][j].x), b = bf_hi(yw[q][j].x), c2 = bf_lo(yw[q][j].y), d = bf_hi(yw[q][j].y); sy += (a * a + b * b) + (c2 * c2 + d * d); }
;     ...
;                 for (int j = 0; j < 8; ++j) { const int col = 4 * F.lane + 256 * j;
;                     const f32x4 y4 = (f32x4){bf_lo(yw[q][j].x), bf_hi(yw[q][j].x), bf_lo(yw[q][j].y), bf_hi(yw[q][j].y)};
;                     *(f32x4*)(args.out + (size_t)row * DM + col) = v[q][j] + PA[j] * (y4 * rsy); }
	v_lshlrev_b32_e32 v204, 16, v102
	v_and_b32_e32 v205, 0xffff0000, v102
	v_lshlrev_b32_e32 v206, 16, v103
	v_and_b32_e32 v207, 0xffff0000, v103
	v_mul_f32_e32 v200, v214, v200
	v_mul_f32_e32 v201, v214, v201
	v_mul_f32_e32 v202, v214, v202
	v_mul_f32_e32 v203, v214, v203
	v_mul_f32_e32 v204, v215, v204
	v_mul_f32_e32 v205, v215, v205
	v_mul_f32_e32 v206, v215, v206
	v_mul_f32_e32 v207, v215, v207
	v_fmac_f32_e32 v12, v140, v200
	v_fmac_f32_e32 v13, v141, v201
	v_fmac_f32_e32 v14, v142, v202
	v_fmac_f32_e32 v15, v143, v203
	v_fmac_f32_e32 v12, v172, v204
	v_fmac_f32_e32 v13, v173, v205
	v_fmac_f32_e32 v14, v174, v206
	v_fmac_f32_e32 v15, v175, v207
	global_store_dwordx4 v192, v[12:15], s[18:19] offset:3072 nt
	v_lshlrev_b32_e32 v200, 16, v72
	v_and_b32_e32 v201, 0xffff0000, v72
	v_lshlrev_b32_e32 v202, 16, v73
	v_and_b32_e32 v203, 0xffff0000, v73
	v_lshlrev_b32_e32 v204, 16, v104
	v_and_b32_e32 v205, 0xffff0000, v104
	v_lshlrev_b32_e32 v206, 16, v105
	v_and_b32_e32 v207, 0xffff0000, v105
	v_mul_f32_e32 v200, v214, v200
	v_mul_f32_e32 v201, v214, v201
	v_mul_f32_e32 v202, v214, v202
	v_mul_f32_e32 v203, v214, v203
	v_mul_f32_e32 v204, v215, v204
	v_mul_f32_e32 v205, v215, v205
	v_mul_f32_e32 v206, v215, v206
	v_mul_f32_e32 v207, v215, v207
	v_fmac_f32_e32 v16, v144, v200
	v_fmac_f32_e32 v17, v145, v201
	v_fmac_f32_e32 v18, v146, v202
	v_fmac_f32_e32 v19, v147, v203
	v_fmac_f32_e32 v16, v176, v204
	v_fmac_f32_e32 v17, v177, v205
	v_fmac_f32_e32 v18, v178, v206
	v_fmac_f32_e32 v19, v179, v207
	global_store_dwordx4 v193, v[16:19], s[18:19] offset:0 nt
	v_lshlrev_b32_e32 v200, 16, v74
	v_and_b32_e32 v201, 0xffff0000, v74
	v_lshlrev_b32_e32 v202, 16, v75
	v_and_b32_e32 v203, 0xffff0000, v75
	v_lshlrev_b32_e32 v204, 16, v106
	v_and_b32_e32 v205, 0xffff0000, v106
	v_lshlrev_b32_e32 v206, 16, v107
	v_and_b32_e32 v207, 0xffff0000, v107
	v_mul_f32_e32 v200, v214, v200
	v_mul_f32_e32 v201, v214, v201
	v_mul_f32_e32 v202, v214, v202
	v_mul_f32_e32 v203, v214, v203
	v_mul_f32_e32 v204, v215, v204
	v_mul_f32_e32 v205, v215, v205
	v_mul_f32_e32 v206, v215, v206
	v_mul_f32_e32 v207, v215, v207
	v_fmac_f32_e32 v20, v148, v200
	v_fmac_f32_e32 v21, v149, v201
	v_fmac_f32_e32 v22, v150, v202
	v_fmac_f32_e32 v23, v151, v203
	v_fmac_f32_e32 v20, v180, v204
	v_fmac_f32_e32 v21, v181, v205
	v_fmac_f32_e32 v22, v182, v206
	v_fmac_f32_e32 v23, v183, v207
	global_store_dwordx4 v193, v[20:23], s[18:19] offset:1024 nt
	v_lshlrev_b32_e32 v200, 16, v76
	v_and_b32_e32 v201, 0xffff0000, v76
	v_lshlrev_b32_e32 v202, 16, v77
	v_and_b32_e32 v203, 0xffff0000, v77
	v_lshlrev_b32_e32 v204, 16, v108
	v_and_b32_e32 v205, 0xffff0000, v108
	v_lshlrev_b32_e32 v206, 16, v109
	v_and_b32_e32 v207, 0xffff0000, v109
	v_mul_f32_e32 v200, v214, v200
	v_mul_f32_e32 v201, v214, v201
	v_mul_f32_e32 v202, v214, v202
	v_mul_f32_e32 v203, v214, v203
	v_mul_f32_e32 v204, v215, v204
	v_mul_f32_e32 v205, v215, v205
	v_mul_f32_e32 v206, v215, v206
	v_mul_f32_e32 v207, v215, v207
	v_fmac_f32_e32 v24, v152, v200
	v_fmac_f32_e32 v25, v153, v201
	v_fmac_f32_e32 v26, v154, v202
	v_fmac_f32_e32 v27, v155, v203
	v_fmac_f32_e32 v24, v184, v204
	v_fmac_f32_e32 v25, v185, v205
	v_fmac_f32_e32 v26, v186, v206
	v_fmac_f32_e32 v27, v187, v207
	global_store_dwordx4 v193, v[24:27], s[18:19] offset:2048 nt
	v_lshlrev_b32_e32 v200, 16, v78
	v_and_b32_e32 v201, 0xffff0000, v78
	v_lshlrev_b32_e32 v202, 16, v79
	v_and_b32_e32 v203, 0xffff0000, v79
	v_lshlrev_b32_e32 v204, 16, v110
	v_and_b32_e32 v205, 0xffff0000, v110
	v_lshlrev_b32_e32 v206, 16, v111
	v_and_b32_e32 v207, 0xffff0000, v111
	v_mul_f32_e32 v200, v214, v200
	v_mul_f32_e32 v201, v214, v201
	v_mul_f32_e32 v202, v214, v202
	v_mul_f32_e32 v203, v214, v203
	v_mul_f32_e32 v204, v215, v204
	v_mul_f32_e32 v205, v215, v205
	v_mul_f32_e32 v206, v215, v206
	v_mul_f32_e32 v207, v215, v207
	v_fmac_f32_e32 v28, v156, v200
	v_fmac_f32_e32 v29, v157, v201
	v_fmac_f32_e32 v30, v158, v202
	v_fmac_f32_e32 v31, v159, v203
	v_fmac_f32_e32 v28, v188, v204
	v_fmac_f32_e32 v29, v189, v205
	v_fmac_f32_e32 v30, v190, v206
	v_fmac_f32_e32 v31, v191, v207
	global_store_dwordx4 v193, v[28:31], s[18:19] offset:3072 nt
	s_add_u32 s18, s18, 0x2000
	s_addc_u32 s19, s19, 0
	s_waitcnt vmcnt(8)
	v_lshlrev_b32_e32 v200, 16, v80
	v_and_b32_e32 v201, 0xffff0000, v80
	v_lshlrev_b32_e32 v202, 16, v81
	v_and_b32_e32 v203, 0xffff0000, v81
	v_mul_f32_e32 v208, v200, v200
	v_mul_f32_e32 v209, v201, v201
	v_fmac_f32_e32 v208, v202, v202
	v_fmac_f32_e32 v209, v203, v203
	v_lshlrev_b32_e32 v204, 16, v112
	v_and_b32_e32 v205, 0xffff0000, v112
	v_lshlrev_b32_e32 v206, 16, v113
	v_and_b32_e32 v207, 0xffff0000, v113
	v_mul_f32_e32 v210, v204, v204
	v_mul_f32_e32 v211, v205, v205
	v_fmac_f32_e32 v210, v206, v206
	v_fmac_f32_e32 v211, v207, v207
	v_lshlrev_b32_e32 v200, 16, v82
	v_and_b32_e32 v201, 0xffff0000, v82
	v_lshlrev_b32_e32 v202, 16, v83
	v_and_b32_e32 v203, 0xffff0000, v83
	v_fmac_f32_e32 v208, v200, v200
	v_fmac_f32_e32 v209, v201, v201
	v_fmac_f32_e32 v208, v202, v202
	v_fmac_f32_e32 v209, v203, v203
	v_lshlrev_b32_e32 v204, 16, v114
	v_and_b32_e32 v205, 0xffff0000, v114
	v_lshlrev_b32_e32 v206, 16, v115
	v_and_b32_e32 v207, 0xffff0000, v115
	v_fmac_f32_e32 v210, v204, v204
	v_fmac_f32_e32 v211, v205, v205
	v_fmac_f32_e32 v210, v206, v206
	v_fmac_f32_e32 v211, v207, v207
	v_lshlrev_b32_e32 v200, 16, v84
	v_and_b32_e32 v201, 0xffff0000, v84
	v_lshlrev_b32_e32 v202, 16, v85
	v_and_b32_e32 v203, 0xffff0000, v85
	v_fmac_f32_e32 v208, v200, v200
	v_fmac_f32_e32 v209, v201, v201
	v_fmac_f32_e32 v208, v202, v202
	v_fmac_f32_e32 v209, v203, v203
	v_lshlrev_b32_e32 v204, 16, v116
	v_and_b32_e32 v205, 0xffff0000, v116
; __device__ __forceinline__ float bf_lo(unsigned w) { return __uint_as_float(w << 16); }
; __device__ __forceinline__ float bf_hi(unsigned w) { return __uint_as_float(w & 0xffff0000u); }
; __global__ void __launch_bounds__(NWAVES * 64, 2) mk_fwd(Args args) {
;     ...
;                 for (int j = 0; j < 8; ++j) { const float a = bf_lo(yw[q][j].x), b = bf_hi(yw[q][j].x), c2 = bf_lo(yw[q][j].y), d = bf_hi(yw[q][j].y); sy += (a * a + b * b) + (c2 * c2 + d * d); }
;                 const float rsy = __builtin_amdgcn_rsqf(wave_sum(sy) * (1.f / DM) + EPS);
; #pragma unroll
;                 for (int j = 0; j < 8; ++j) { const int col = 4 * F.lane + 256 * j;
;                     const f32x4 y4 = (f32x4){bf_lo(yw[q][j].x), bf_hi(yw[q][j].x), bf_lo(yw[q][j].y), bf_hi(yw[q][j].y)};
;                     *(f32x4*)(args.out + (size_t)row * DM + col) = v[q][j] + PA[j] * (y4 * rsy); }
	v_lshlrev_b32_e32 v206, 16, v117
	v_and_b32_e32 v207, 0xffff0000, v117
	v_fmac_f32_e32 v210, v204, v204
	v_fmac_f32_e32 v211, v205, v205
	v_fmac_f32_e32 v210, v206, v206
	v_fmac_f32_e32 v211, v207, v207
	v_lshlrev_b32_e32 v200, 16, v86
	v_and_b32_e32 v201, 0xffff0000, v86
	v_lshlrev_b32_e32 v202, 16, v87
	v_and_b32_e32 v203, 0xffff0000, v87
	v_fmac_f32_e32 v208, v200, v200
	v_fmac_f32_e32 v209, v201, v201
	v_fmac_f32_e32 v208, v202, v202
	v_fmac_f32_e32 v209, v203, v203
	v_lshlrev_b32_e32 v204, 16, v118
	v_and_b32_e32 v205, 0xffff0000, v118
	v_lshlrev_b32_e32 v206, 16, v119
	v_and_b32_e32 v207, 0xffff0000, v119
	v_fmac_f32_e32 v210, v204, v204
	v_fmac_f32_e32 v211, v205, v205
	v_fmac_f32_e32 v210, v206, v206
	v_fmac_f32_e32 v211, v207, v207
	v_lshlrev_b32_e32 v200, 16, v88
	v_and_b32_e32 v201, 0xffff0000, v88
	v_lshlrev_b32_e32 v202, 16, v89
	v_and_b32_e32 v203, 0xffff0000, v89
	v_fmac_f32_e32 v208, v200, v200
	v_fmac_f32_e32 v209, v201, v201
	v_fmac_f32_e32 v208, v202, v202
	v_fmac_f32_e32 v209, v203, v203
	v_lshlrev_b32_e32 v204, 16, v120
	v_and_b32_e32 v205, 0xffff0000, v120
	v_lshlrev_b32_e32 v206, 16, v121
	v_and_b32_e32 v207, 0xffff0000, v121
	v_fmac_f32_e32 v210, v204, v204
	v_fmac_f32_e32 v211, v205, v205
	v_fmac_f32_e32 v210, v206, v206
	v_fmac_f32_e32 v211, v207, v207
	v_lshlrev_b32_e32 v200, 16, v90
	v_and_b32_e32 v201, 0xffff0000, v90
	v_lshlrev_b32_e32 v202, 16, v91
	v_and_b32_e32 v203, 0xffff0000, v91
	v_fmac_f32_e32 v208, v200, v200
	v_fmac_f32_e32 v209, v201, v201
	v_fmac_f32_e32 v208, v202, v202
	v_fmac_f32_e32 v209, v203, v203
	v_lshlrev_b32_e32 v204, 16, v122
	v_and_b32_e32 v205, 0xffff0000, v122
	v_lshlrev_b32_e32 v206, 16, v123
	v_and_b32_e32 v207, 0xffff0000, v123
	v_fmac_f32_e32 v210, v204, v204
	v_fmac_f32_e32 v211, v205, v205
	v_fmac_f32_e32 v210, v206, v206
	v_fmac_f32_e32 v211, v207, v207
	v_lshlrev_b32_e32 v200, 16, v92
	v_and_b32_e32 v201, 0xffff0000, v92
	v_lshlrev_b32_e32 v202, 16, v93
	v_and_b32_e32 v203, 0xffff0000, v93
	v_fmac_f32_e32 v208, v200, v200
	v_fmac_f32_e32 v209, v201, v201
	v_fmac_f32_e32 v208, v202, v202
	v_fmac_f32_e32 v209, v203, v203
	v_lshlrev_b32_e32 v204, 16, v124
	v_and_b32_e32 v205, 0xffff0000, v124
	v_lshlrev_b32_e32 v206, 16, v125
	v_and_b32_e32 v207, 0xffff0000, v125
	v_fmac_f32_e32 v210, v204, v204
	v_fmac_f32_e32 v211, v205, v205
	v_fmac_f32_e32 v210, v206, v206
	v_fmac_f32_e32 v211, v207, v207
	v_lshlrev_b32_e32 v200, 16, v94
	v_and_b32_e32 v201, 0xffff0000, v94
	v_lshlrev_b32_e32 v202, 16, v95
	v_and_b32_e32 v203, 0xffff0000, v95
	v_fmac_f32_e32 v208, v200, v200
	v_fmac_f32_e32 v209, v201, v201
	v_fmac_f32_e32 v208, v202, v202
	v_fmac_f32_e32 v209, v203, v203
	v_lshlrev_b32_e32 v204, 16, v126
	v_and_b32_e32 v205, 0xffff0000, v126
	v_lshlrev_b32_e32 v206, 16, v127
	v_and_b32_e32 v207, 0xffff0000, v127
	v_fmac_f32_e32 v210, v204, v204
	v_fmac_f32_e32 v211, v205, v205
	v_fmac_f32_e32 v210, v206, v206
	v_fmac_f32_e32 v211, v207, v207
	v_add_f32_e32 v208, v208, v209
	v_add_f32_e32 v210, v210, v211
	s_nop 0
	v_add_f32_dpp v212, v208, v208 quad_perm:[1,0,3,2] row_mask:0xf bank_mask:0xf
	v_add_f32_dpp v213, v210, v210 quad_perm:[1,0,3,2] row_mask:0xf bank_mask:0xf
	s_nop 0
	v_add_f32_dpp v212, v212, v212 quad_perm:[2,3,0,1] row_mask:0xf bank_mask:0xf
	v_add_f32_dpp v213, v213, v213 quad_perm:[2,3,0,1] row_mask:0xf bank_mask:0xf
	s_nop 0
	v_add_f32_dpp v212, v212, v212 row_half_mirror row_mask:0xf bank_mask:0xf
	v_add_f32_dpp v213, v213, v213 row_half_mirror row_mask:0xf bank_mask:0xf
	s_nop 0
	v_add_f32_dpp v212, v212, v212 row_mirror row_mask:0xf bank_mask:0xf
	v_add_f32_dpp v213, v213, v213 row_mirror row_mask:0xf bank_mask:0xf
	s_nop 0
	v_readlane_b32 s4, v212, 0
	v_readlane_b32 s5, v212, 16
	v_readlane_b32 s6, v212, 32
	v_readlane_b32 s7, v212, 48
	v_readlane_b32 s24, v213, 0
	v_readlane_b32 s25, v213, 16
	v_readlane_b32 s26, v213, 32
	v_readlane_b32 s27, v213, 48
	s_nop 1
	v_mov_b32_e32 v214, s4
	v_mov_b32_e32 v215, s24
	v_add_f32_e32 v214, s5, v214
	v_add_f32_e32 v215, s25, v215
	v_add_f32_e32 v214, s6, v214
	v_add_f32_e32 v215, s26, v215
	v_add_f32_e32 v214, s7, v214
	v_add_f32_e32 v215, s27, v215
	v_fmamk_f32 v214, v214, 0x3a000000, v195
	v_fmamk_f32 v215, v215, 0x3a000000, v195
	v_rsq_f32_e32 v214, v214
	v_rsq_f32_e32 v215, v215
	s_nop 0
	v_lshlrev_b32_e32 v200, 16, v80
	v_and_b32_e32 v201, 0xffff0000, v80
	v_lshlrev_b32_e32 v202, 16, v81
	v_and_b32_e32 v203, 0xffff0000, v81
	v_lshlrev_b32_e32 v204, 16, v112
	v_and_b32_e32 v205, 0xffff0000, v112
	v_lshlrev_b32_e32 v206, 16, v113
	v_and_b32_e32 v207, 0xffff0000, v113
	v_mul_f32_e32 v200, v214, v200
	v_mul_f32_e32 v201, v214, v201
	v_mul_f32_e32 v202, v214, v202
	v_mul_f32_e32 v203, v214, v203
	v_mul_f32_e32 v204, v215, v204
	v_mul_f32_e32 v205, v215, v205
	v_mul_f32_e32 v206, v215, v206
	v_mul_f32_e32 v207, v215, v207
	v_fmac_f32_e32 v32, v128, v200
	v_fmac_f32_e32 v33, v129, v201
	v_fmac_f32_e32 v34, v130, v202
	v_fmac_f32_e32 v35, v131, v203
	v_fmac_f32_e32 v32, v160, v204
	v_fmac_f32_e32 v33, v161, v205
	v_fmac_f32_e32 v34, v162, v206
	v_fmac_f32_e32 v35, v163, v207
	global_store_dwordx4 v192, v[32:35], s[18:19] offset:0 nt
	v_lshlrev_b32_e32 v200, 16, v82
	v_and_b32_e32 v201, 0xffff0000, v82
	v_lshlrev_b32_e32 v202, 16, v83
	v_and_b32_e32 v203, 0xffff0000, v83
	v_lshlrev_b32_e32 v204, 16, v114
	v_and_b32_e32 v205, 0xffff0000, v114
	v_lshlrev_b32_e32 v206, 16, v115
	v_and_b32_e32 v207, 0xffff0000, v115
	v_mul_f32_e32 v200, v214, v200
	v_mul_f32_e32 v201, v214, v201
	v_mul_f32_e32 v202, v214, v202
	v_mul_f32_e32 v203, v214, v203
	v_mul_f32_e32 v204, v215, v204
	v_mul_f32_e32 v205, v215, v205
; __device__ __forceinline__ float bf_lo(unsigned w) { return __uint_as_float(w << 16); }
; __device__ __forceinline__ float bf_hi(unsigned w) { return __uint_as_float(w & 0xffff0000u); }
; __global__ void __launch_bounds__(NWAVES * 64, 2) mk_fwd(Args args) {
;     ...
;                 for (int j = 0; j < 8; ++j) { const int col = 4 * F.lane + 256 * j;
;                     const f32x4 y4 = (f32x4){bf_lo(yw[q][j].x), bf_hi(yw[q][j].x), bf_lo(yw[q][j].y), bf_hi(yw[q][j].y)};
;                     *(f32x4*)(args.out + (size_t)row * DM + col) = v[q][j] + PA[j] * (y4 * rsy); }
	v_mul_f32_e32 v206, v215, v206
	v_mul_f32_e32 v207, v215, v207
	v_fmac_f32_e32 v36, v132, v200
	v_fmac_f32_e32 v37, v133, v201
	v_fmac_f32_e32 v38, v134, v202
	v_fmac_f32_e32 v39, v135, v203
	v_fmac_f32_e32 v36, v164, v204
	v_fmac_f32_e32 v37, v165, v205
	v_fmac_f32_e32 v38, v166, v206
	v_fmac_f32_e32 v39, v167, v207
	global_store_dwordx4 v192, v[36:39], s[18:19] offset:1024 nt
	v_lshlrev_b32_e32 v200, 16, v84
	v_and_b32_e32 v201, 0xffff0000, v84
	v_lshlrev_b32_e32 v202, 16, v85
	v_and_b32_e32 v203, 0xffff0000, v85
	v_lshlrev_b32_e32 v204, 16, v116
	v_and_b32_e32 v205, 0xffff0000, v116
	v_lshlrev_b32_e32 v206, 16, v117
	v_and_b32_e32 v207, 0xffff0000, v117
	v_mul_f32_e32 v200, v214, v200
	v_mul_f32_e32 v201, v214, v201
	v_mul_f32_e32 v202, v214, v202
	v_mul_f32_e32 v203, v214, v203
	v_mul_f32_e32 v204, v215, v204
	v_mul_f32_e32 v205, v215, v205
	v_mul_f32_e32 v206, v215, v206
	v_mul_f32_e32 v207, v215, v207
	v_fmac_f32_e32 v40, v136, v200
	v_fmac_f32_e32 v41, v137, v201
	v_fmac_f32_e32 v42, v138, v202
	v_fmac_f32_e32 v43, v139, v203
	v_fmac_f32_e32 v40, v168, v204
	v_fmac_f32_e32 v41, v169, v205
	v_fmac_f32_e32 v42, v170, v206
	v_fmac_f32_e32 v43, v171, v207
	global_store_dwordx4 v192, v[40:43], s[18:19] offset:2048 nt
	v_lshlrev_b32_e32 v200, 16, v86
	v_and_b32_e32 v201, 0xffff0000, v86
	v_lshlrev_b32_e32 v202, 16, v87
	v_and_b32_e32 v203, 0xffff0000, v87
	v_lshlrev_b32_e32 v204, 16, v118
	v_and_b32_e32 v205, 0xffff0000, v118
	v_lshlrev_b32_e32 v206, 16, v119
	v_and_b32_e32 v207, 0xffff0000, v119
	v_mul_f32_e32 v200, v214, v200
	v_mul_f32_e32 v201, v214, v201
	v_mul_f32_e32 v202, v214, v202
	v_mul_f32_e32 v203, v214, v203
	v_mul_f32_e32 v204, v215, v204
	v_mul_f32_e32 v205, v215, v205
	v_mul_f32_e32 v206, v215, v206
	v_mul_f32_e32 v207, v215, v207
	v_fmac_f32_e32 v44, v140, v200
	v_fmac_f32_e32 v45, v141, v201
	v_fmac_f32_e32 v46, v142, v202
	v_fmac_f32_e32 v47, v143, v203
	v_fmac_f32_e32 v44, v172, v204
	v_fmac_f32_e32 v45, v173, v205
	v_fmac_f32_e32 v46, v174, v206
	v_fmac_f32_e32 v47, v175, v207
	global_store_dwordx4 v192, v[44:47], s[18:19] offset:3072 nt
	v_lshlrev_b32_e32 v200, 16, v88
	v_and_b32_e32 v201, 0xffff0000, v88
	v_lshlrev_b32_e32 v202, 16, v89
	v_and_b32_e32 v203, 0xffff0000, v89
	v_lshlrev_b32_e32 v204, 16, v120
	v_and_b32_e32 v205, 0xffff0000, v120
	v_lshlrev_b32_e32 v206, 16, v121
	v_and_b32_e32 v207, 0xffff0000, v121
	v_mul_f32_e32 v200, v214, v200
	v_mul_f32_e32 v201, v214, v201
	v_mul_f32_e32 v202, v214, v202
	v_mul_f32_e32 v203, v214, v203
	v_mul_f32_e32 v204, v215, v204
	v_mul_f32_e32 v205, v215, v205
	v_mul_f32_e32 v206, v215, v206
	v_mul_f32_e32 v207, v215, v207
	v_fmac_f32_e32 v48, v144, v200
	v_fmac_f32_e32 v49, v145, v201
	v_fmac_f32_e32 v50, v146, v202
	v_fmac_f32_e32 v51, v147, v203
	v_fmac_f32_e32 v48, v176, v204
	v_fmac_f32_e32 v49, v177, v205
	v_fmac_f32_e32 v50, v178, v206
	v_fmac_f32_e32 v51, v179, v207
	global_store_dwordx4 v193, v[48:51], s[18:19] offset:0 nt
	v_lshlrev_b32_e32 v200, 16, v90
	v_and_b32_e32 v201, 0xffff0000, v90
	v_lshlrev_b32_e32 v202, 16, v91
	v_and_b32_e32 v203, 0xffff0000, v91
	v_lshlrev_b32_e32 v204, 16, v122
	v_and_b32_e32 v205, 0xffff0000, v122
	v_lshlrev_b32_e32 v206, 16, v123
	v_and_b32_e32 v207, 0xffff0000, v123
	v_mul_f32_e32 v200, v214, v200
	v_mul_f32_e32 v201, v214, v201
	v_mul_f32_e32 v202, v214, v202
	v_mul_f32_e32 v203, v214, v203
	v_mul_f32_e32 v204, v215, v204
	v_mul_f32_e32 v205, v215, v205
	v_mul_f32_e32 v206, v215, v206
	v_mul_f32_e32 v207, v215, v207
	v_fmac_f32_e32 v52, v148, v200
	v_fmac_f32_e32 v53, v149, v201
	v_fmac_f32_e32 v54, v150, v202
	v_fmac_f32_e32 v55, v151, v203
	v_fmac_f32_e32 v52, v180, v204
	v_fmac_f32_e32 v53, v181, v205
	v_fmac_f32_e32 v54, v182, v206
	v_fmac_f32_e32 v55, v183, v207
	global_store_dwordx4 v193, v[52:55], s[18:19] offset:1024 nt
	v_lshlrev_b32_e32 v200, 16, v92
	v_and_b32_e32 v201, 0xffff0000, v92
	v_lshlrev_b32_e32 v202, 16, v93
	v_and_b32_e32 v203, 0xffff0000, v93
	v_lshlrev_b32_e32 v204, 16, v124
	v_and_b32_e32 v205, 0xffff0000, v124
	v_lshlrev_b32_e32 v206, 16, v125
	v_and_b32_e32 v207, 0xffff0000, v125
	v_mul_f32_e32 v200, v214, v200
	v_mul_f32_e32 v201, v214, v201
	v_mul_f32_e32 v202, v214, v202
	v_mul_f32_e32 v203, v214, v203
	v_mul_f32_e32 v204, v215, v204
	v_mul_f32_e32 v205, v215, v205
	v_mul_f32_e32 v206, v215, v206
	v_mul_f32_e32 v207, v215, v207
	v_fmac_f32_e32 v56, v152, v200
	v_fmac_f32_e32 v57, v153, v201
	v_fmac_f32_e32 v58, v154, v202
	v_fmac_f32_e32 v59, v155, v203
	v_fmac_f32_e32 v56, v184, v204
	v_fmac_f32_e32 v57, v185, v205
	v_fmac_f32_e32 v58, v186, v206
	v_fmac_f32_e32 v59, v187, v207
	global_store_dwordx4 v193, v[56:59], s[18:19] offset:2048 nt
	v_lshlrev_b32_e32 v200, 16, v94
	v_and_b32_e32 v201, 0xffff0000, v94
	v_lshlrev_b32_e32 v202, 16, v95
	v_and_b32_e32 v203, 0xffff0000, v95
	v_lshlrev_b32_e32 v204, 16, v126
	v_and_b32_e32 v205, 0xffff0000, v126
	v_lshlrev_b32_e32 v206, 16, v127
	v_and_b32_e32 v207, 0xffff0000, v127
	v_mul_f32_e32 v200, v214, v200
	v_mul_f32_e32 v201, v214, v201
	v_mul_f32_e32 v202, v214, v202
	v_mul_f32_e32 v203, v214, v203
	v_mul_f32_e32 v204, v215, v204
	v_mul_f32_e32 v205, v215, v205
	v_mul_f32_e32 v206, v215, v206
	v_mul_f32_e32 v207, v215, v207
	v_fmac_f32_e32 v60, v156, v200
	v_fmac_f32_e32 v61, v157, v201
	v_fmac_f32_e32 v62, v158, v202
	v_fmac_f32_e32 v63, v159, v203
	v_fmac_f32_e32 v60, v188, v204
	v_fmac_f32_e32 v61, v189, v205
	v_fmac_f32_e32 v62, v190, v206
	v_fmac_f32_e32 v63, v191, v207
	global_store_dwordx4 v193, v[60:63], s[18:19] offset:3072 nt
	s_add_u32 s18, s18, 0x2000
	s_addc_u32 s19, s19, 0
	s_branch .LBB0_1296
